# GEMM main loops: delete the compiler's duplicate s_waitcnt lgkmcnt(0) after each explicit one (54 sites, 6 per loop iteration)
# speedup vs baseline: 1.0053x; 1.0053x over previous
; #define PG8_STAGE(bufoff, gbase, voff) do { _Pragma("unroll") for (int _i = 0; _i < 2; ++_i) \
;         __builtin_amdgcn_global_load_lds((const unsigned*)((const char*)(gbase) + (voff)[_i]), (LAS unsigned*)(lds + (bufoff) + ldsw + _i * 8192), 16, 0, 0); } while (0)
; #define PG8_LDA(dst, b, h) do { _Pragma("unroll") for (int m = 0; m < 4; ++m) _Pragma("unroll") for (int k = 0; k < 2; ++k) dst[m][k] = *(const LAS bf16x8*)(lds + PG8_SA(b, h) + aoff + m * 2048 + k * 1024); } while (0)
; #define PG8_LDB(dst, b, h) do { _Pragma("unroll") for (int n = 0; n < 2; ++n) _Pragma("unroll") for (int k = 0; k < 2; ++k) dst[n][k] = *(const LAS bf16x8*)(lds + PG8_SB(b, h) + boff + n * 2048 + k * 1024); } while (0)
; #define PG8_MMA(ai, bj, At, Bt) do { __builtin_amdgcn_s_setprio(1); _Pragma("unroll") for (int m = 0; m < 4; ++m) _Pragma("unroll") for (int n = 0; n < 2; ++n) _Pragma("unroll") for (int k = 0; k < 2; ++k) \
;         acc[ai][bj][m][n] = MmaOp<Epi::I8>::run(Bt[n][k], At[m][k], acc[ai][bj][m][n]); __builtin_amdgcn_s_setprio(0); } while (0)
; #define PG8_WAIT_V(n) asm volatile("s_waitcnt vmcnt(" #n ")" ::: "memory")
; #define PG8_WAIT_L(n) asm volatile("s_waitcnt lgkmcnt(" #n ")" ::: "memory")
; #define PG8_BAR __builtin_amdgcn_s_barrier()
; #define PG8_SCHED __builtin_amdgcn_sched_barrier(0)
; template <class Epi, class Sched>
; __device__ __forceinline__ void gemm_phase(LAS unsigned char* lds, const Gemm g, const Sched& S, const Epi& E) {
;     ...
;             PG8_LDB(B0, 0, 0); PG8_SCHED; PG8_LDA(At, 0, 0); PG8_STAGE(PG8_SA(1, 1), a1 + hstepA, voffA);
;             PG8_WAIT_L(8); PG8_BAR; PG8_WAIT_L(0); PG8_MMA(0, 0, At, B0); PG8_BAR; PG8_SCHED;
;             PG8_LDB(B1, 0, 1); PG8_STAGE(PG8_SB(0, 0), b2, voffB);
;             PG8_BAR; PG8_WAIT_L(0); PG8_MMA(0, 1, At, B1); PG8_BAR;
;             PG8_LDA(At, 0, 1); PG8_STAGE(PG8_SA(0, 0), a2, voffA);
;             PG8_BAR; PG8_WAIT_L(0); PG8_MMA(1, 0, At, B0); PG8_BAR; PG8_SCHED;
;             PG8_STAGE(PG8_SB(0, 1), b2 + hstepB, voffB);
;             PG8_WAIT_V(6); PG8_BAR; PG8_MMA(1, 1, At, B1); PG8_BAR;
.LBB0_115:
	ds_read_b128 v[40:43], v167
	ds_read_b128 v[52:55], v167 offset:1024
	ds_read_b128 v[136:139], v167 offset:2048
	ds_read_b128 v[172:175], v167 offset:3072
	s_add_u32 s28, s26, 0xfffc0080
	s_addc_u32 s29, s27, -1
	s_cmp_eq_u32 s53, 12
	s_cselect_b32 s31, s19, s29
	s_cselect_b32 s30, s48, s28
	s_cselect_b32 s29, s17, s51
	s_cselect_b32 s28, s49, s50
	v_lshl_add_u64 v[156:157], s[26:27], 0, v[148:149]
	s_add_i32 m0, s25, 0xc000
	ds_read_b128 v[178:181], v169
	ds_read_b128 v[182:185], v169 offset:1024
	ds_read_b128 v[186:189], v169 offset:2048
	ds_read_b128 v[190:193], v169 offset:3072
	ds_read_b128 v[194:197], v169 offset:4096
	ds_read_b128 v[198:201], v169 offset:5120
	ds_read_b128 v[202:205], v169 offset:6144
	ds_read_b128 v[206:209], v169 offset:7168
	global_load_lds_dwordx4 v[156:157], off
	v_lshl_add_u64 v[156:157], s[26:27], 0, v[150:151]
	s_add_i32 m0, s25, 0xe000
	s_nop 0
	global_load_lds_dwordx4 v[156:157], off
	s_waitcnt lgkmcnt(8)
	s_barrier
	s_waitcnt lgkmcnt(0)
	s_setprio 1
	v_mfma_i32_16x16x64_i8 v[132:135], v[40:43], v[178:181], v[132:135]
	v_mfma_i32_16x16x64_i8 v[124:127], v[136:139], v[178:181], v[124:127]
	v_mfma_i32_16x16x64_i8 v[116:119], v[40:43], v[186:189], v[116:119]
	v_mfma_i32_16x16x64_i8 v[108:111], v[136:139], v[186:189], v[108:111]
	v_mfma_i32_16x16x64_i8 v[100:103], v[40:43], v[194:197], v[100:103]
	v_mfma_i32_16x16x64_i8 v[92:95], v[136:139], v[194:197], v[92:95]
	v_mfma_i32_16x16x64_i8 v[84:87], v[40:43], v[202:205], v[84:87]
	v_mfma_i32_16x16x64_i8 v[76:79], v[136:139], v[202:205], v[76:79]
	v_mfma_i32_16x16x64_i8 v[132:135], v[52:55], v[182:185], v[132:135]
	v_mfma_i32_16x16x64_i8 v[124:127], v[172:175], v[182:185], v[124:127]
	v_mfma_i32_16x16x64_i8 v[116:119], v[52:55], v[190:193], v[116:119]
	v_mfma_i32_16x16x64_i8 v[108:111], v[172:175], v[190:193], v[108:111]
	v_mfma_i32_16x16x64_i8 v[100:103], v[52:55], v[198:201], v[100:103]
	v_mfma_i32_16x16x64_i8 v[92:95], v[172:175], v[198:201], v[92:95]
	v_mfma_i32_16x16x64_i8 v[84:87], v[52:55], v[206:209], v[84:87]
	v_mfma_i32_16x16x64_i8 v[76:79], v[172:175], v[206:209], v[76:79]
	s_setprio 0
	s_barrier
	s_add_i32 s54, s44, s34
	v_lshl_add_u64 v[156:157], s[28:29], 0, v[144:145]
	s_mov_b32 m0, s54
	ds_read_b128 v[210:213], v171
	ds_read_b128 v[214:217], v171 offset:1024
	ds_read_b128 v[218:221], v171 offset:2048
	ds_read_b128 v[222:225], v171 offset:3072
	global_load_lds_dwordx4 v[156:157], off
	v_lshl_add_u64 v[160:161], s[28:29], 0, v[140:141]
	s_add_i32 m0, s54, 0x2000
	s_nop 0
	global_load_lds_dwordx4 v[160:161], off
	s_barrier
	s_waitcnt lgkmcnt(0)
	s_setprio 1
	v_mfma_i32_16x16x64_i8 v[128:131], v[210:213], v[178:181], v[128:131]
	v_mfma_i32_16x16x64_i8 v[120:123], v[218:221], v[178:181], v[120:123]
	v_mfma_i32_16x16x64_i8 v[112:115], v[210:213], v[186:189], v[112:115]
	v_mfma_i32_16x16x64_i8 v[104:107], v[218:221], v[186:189], v[104:107]
	v_mfma_i32_16x16x64_i8 v[96:99], v[210:213], v[194:197], v[96:99]
	v_mfma_i32_16x16x64_i8 v[88:91], v[218:221], v[194:197], v[88:91]
	v_mfma_i32_16x16x64_i8 v[80:83], v[210:213], v[202:205], v[80:83]
	v_mfma_i32_16x16x64_i8 v[72:75], v[218:221], v[202:205], v[72:75]
	v_mfma_i32_16x16x64_i8 v[128:131], v[214:217], v[182:185], v[128:131]
	v_mfma_i32_16x16x64_i8 v[120:123], v[222:225], v[182:185], v[120:123]
	v_mfma_i32_16x16x64_i8 v[112:115], v[214:217], v[190:193], v[112:115]
	v_mfma_i32_16x16x64_i8 v[104:107], v[222:225], v[190:193], v[104:107]
	v_mfma_i32_16x16x64_i8 v[96:99], v[214:217], v[198:201], v[96:99]
	v_mfma_i32_16x16x64_i8 v[88:91], v[222:225], v[198:201], v[88:91]
	v_mfma_i32_16x16x64_i8 v[80:83], v[214:217], v[206:209], v[80:83]
	v_mfma_i32_16x16x64_i8 v[72:75], v[222:225], v[206:209], v[72:75]
	s_setprio 0
	s_mov_b32 m0, s25
	v_lshl_add_u64 v[226:227], s[30:31], 0, v[146:147]
	s_barrier
	ds_read_b128 v[178:181], v169 offset:16384
	ds_read_b128 v[182:185], v169 offset:17408
	ds_read_b128 v[186:189], v169 offset:18432
	ds_read_b128 v[190:193], v169 offset:19456
	ds_read_b128 v[194:197], v169 offset:20480
	ds_read_b128 v[198:201], v169 offset:21504
	ds_read_b128 v[202:205], v169 offset:22528
	ds_read_b128 v[206:209], v169 offset:23552
	global_load_lds_dwordx4 v[226:227], off
	v_lshl_add_u64 v[228:229], s[30:31], 0, v[142:143]
	s_mov_b32 m0, s37
	s_nop 0
	global_load_lds_dwordx4 v[228:229], off
	s_barrier
	s_waitcnt lgkmcnt(0)
	s_setprio 1
	v_mfma_i32_16x16x64_i8 v[68:71], v[40:43], v[178:181], v[68:71]
	v_mfma_i32_16x16x64_i8 v[60:63], v[136:139], v[178:181], v[60:63]
	v_mfma_i32_16x16x64_i8 v[48:51], v[40:43], v[186:189], v[48:51]
	v_mfma_i32_16x16x64_i8 v[36:39], v[136:139], v[186:189], v[36:39]
	v_mfma_i32_16x16x64_i8 v[28:31], v[40:43], v[194:197], v[28:31]
	v_mfma_i32_16x16x64_i8 v[20:23], v[136:139], v[194:197], v[20:23]
	v_mfma_i32_16x16x64_i8 v[12:15], v[40:43], v[202:205], v[12:15]
	v_mfma_i32_16x16x64_i8 v[4:7], v[136:139], v[202:205], v[4:7]
	v_mfma_i32_16x16x64_i8 v[68:71], v[52:55], v[182:185], v[68:71]
	v_mfma_i32_16x16x64_i8 v[60:63], v[172:175], v[182:185], v[60:63]
	v_mfma_i32_16x16x64_i8 v[48:51], v[52:55], v[190:193], v[48:51]
	v_mfma_i32_16x16x64_i8 v[36:39], v[172:175], v[190:193], v[36:39]
	v_mfma_i32_16x16x64_i8 v[28:31], v[52:55], v[198:201], v[28:31]
	v_mfma_i32_16x16x64_i8 v[20:23], v[172:175], v[198:201], v[20:23]
	v_mfma_i32_16x16x64_i8 v[12:15], v[52:55], v[206:209], v[12:15]
	v_mfma_i32_16x16x64_i8 v[4:7], v[172:175], v[206:209], v[4:7]
	s_setprio 0
	s_barrier
	s_add_u32 s54, s28, 0x40000
	s_addc_u32 s55, s29, 0
	s_add_i32 s56, s45, s34
	v_lshl_add_u64 v[40:41], s[54:55], 0, v[144:145]
	s_mov_b32 m0, s56
	s_nop 0
	global_load_lds_dwordx4 v[40:41], off
	v_lshl_add_u64 v[40:41], s[54:55], 0, v[140:141]
	s_add_i32 m0, s56, 0x2000
	s_nop 0
	global_load_lds_dwordx4 v[40:41], off
	s_waitcnt vmcnt(6)
	s_barrier
; #define PG8_STAGE(bufoff, gbase, voff) do { _Pragma("unroll") for (int _i = 0; _i < 2; ++_i) \
;         __builtin_amdgcn_global_load_lds((const unsigned*)((const char*)(gbase) + (voff)[_i]), (LAS unsigned*)(lds + (bufoff) + ldsw + _i * 8192), 16, 0, 0); } while (0)
; #define PG8_LDA(dst, b, h) do { _Pragma("unroll") for (int m = 0; m < 4; ++m) _Pragma("unroll") for (int k = 0; k < 2; ++k) dst[m][k] = *(const LAS bf16x8*)(lds + PG8_SA(b, h) + aoff + m * 2048 + k * 1024); } while (0)
; #define PG8_LDB(dst, b, h) do { _Pragma("unroll") for (int n = 0; n < 2; ++n) _Pragma("unroll") for (int k = 0; k < 2; ++k) dst[n][k] = *(const LAS bf16x8*)(lds + PG8_SB(b, h) + boff + n * 2048 + k * 1024); } while (0)
; #define PG8_MMA(ai, bj, At, Bt) do { __builtin_amdgcn_s_setprio(1); _Pragma("unroll") for (int m = 0; m < 4; ++m) _Pragma("unroll") for (int n = 0; n < 2; ++n) _Pragma("unroll") for (int k = 0; k < 2; ++k) \
;         acc[ai][bj][m][n] = MmaOp<Epi::I8>::run(Bt[n][k], At[m][k], acc[ai][bj][m][n]); __builtin_amdgcn_s_setprio(0); } while (0)
; #define PG8_WAIT_V(n) asm volatile("s_waitcnt vmcnt(" #n ")" ::: "memory")
; #define PG8_WAIT_L(n) asm volatile("s_waitcnt lgkmcnt(" #n ")" ::: "memory")
; #define PG8_BAR __builtin_amdgcn_s_barrier()
; #define PG8_SCHED __builtin_amdgcn_sched_barrier(0)
; template <class Epi, class Sched>
; __device__ __forceinline__ void gemm_phase(LAS unsigned char* lds, const Gemm g, const Sched& S, const Epi& E) {
;     ...
;             PG8_WAIT_V(6); PG8_BAR; PG8_MMA(1, 1, At, B1); PG8_BAR;
;             PG8_LDB(B0, 1, 0); PG8_SCHED; PG8_LDA(At, 1, 0); PG8_STAGE(PG8_SA(0, 1), a2 + hstepA, voffA);
;             PG8_WAIT_L(8); PG8_BAR; PG8_WAIT_L(0); PG8_MMA(0, 0, At, B0); PG8_BAR; PG8_SCHED;
;             PG8_LDB(B1, 1, 1); PG8_STAGE(PG8_SB(1, 0), b3, voffB);
;             PG8_BAR; PG8_WAIT_L(0); PG8_MMA(0, 1, At, B1); PG8_BAR;
;             PG8_LDA(At, 1, 1); PG8_STAGE(PG8_SA(1, 0), a3, voffA);
	s_setprio 1
	v_mfma_i32_16x16x64_i8 v[44:47], v[210:213], v[186:189], v[44:47]
	v_mfma_i32_16x16x64_i8 v[32:35], v[218:221], v[186:189], v[32:35]
	v_mfma_i32_16x16x64_i8 v[24:27], v[210:213], v[194:197], v[24:27]
	v_mfma_i32_16x16x64_i8 v[16:19], v[218:221], v[194:197], v[16:19]
	v_mfma_i32_16x16x64_i8 v[8:11], v[210:213], v[202:205], v[8:11]
	v_mfma_i32_16x16x64_i8 v[0:3], v[218:221], v[202:205], v[0:3]
	v_mfma_i32_16x16x64_i8 v[40:43], v[210:213], v[178:181], v[64:67]
	v_mfma_i32_16x16x64_i8 v[52:55], v[218:221], v[178:181], v[56:59]
	v_mfma_i32_16x16x64_i8 v[44:47], v[214:217], v[190:193], v[44:47]
	v_mfma_i32_16x16x64_i8 v[32:35], v[222:225], v[190:193], v[32:35]
	v_mfma_i32_16x16x64_i8 v[24:27], v[214:217], v[198:201], v[24:27]
	v_mfma_i32_16x16x64_i8 v[16:19], v[222:225], v[198:201], v[16:19]
	v_mfma_i32_16x16x64_i8 v[8:11], v[214:217], v[206:209], v[8:11]
	v_mfma_i32_16x16x64_i8 v[0:3], v[222:225], v[206:209], v[0:3]
	v_mfma_i32_16x16x64_i8 v[40:43], v[214:217], v[182:185], v[40:43]
	v_mfma_i32_16x16x64_i8 v[52:55], v[222:225], v[182:185], v[52:55]
	s_setprio 0
	s_add_i32 s54, 0, 0x18000
	v_add_u32_e32 v158, s54, v163
	s_barrier
	ds_read_b128 v[56:59], v158
	ds_read_b128 v[64:67], v158 offset:1024
	ds_read_b128 v[136:139], v158 offset:2048
	ds_read_b128 v[172:175], v158 offset:3072
	s_add_u32 s30, s30, 0x40000
	s_addc_u32 s31, s31, 0
	s_mov_b32 m0, s38
	v_lshl_add_u64 v[210:211], s[30:31], 0, v[146:147]
	ds_read_b128 v[178:181], v169 offset:32768
	ds_read_b128 v[182:185], v169 offset:33792
	ds_read_b128 v[186:189], v169 offset:34816
	ds_read_b128 v[190:193], v169 offset:35840
	ds_read_b128 v[194:197], v169 offset:36864
	ds_read_b128 v[198:201], v169 offset:37888
	ds_read_b128 v[202:205], v169 offset:38912
	ds_read_b128 v[206:209], v169 offset:39936
	global_load_lds_dwordx4 v[210:211], off
	v_lshl_add_u64 v[210:211], s[30:31], 0, v[142:143]
	s_mov_b32 m0, s39
	s_nop 0
	global_load_lds_dwordx4 v[210:211], off
	s_waitcnt lgkmcnt(8)
	s_barrier
	s_waitcnt lgkmcnt(0)
	s_setprio 1
	v_mfma_i32_16x16x64_i8 v[132:135], v[56:59], v[178:181], v[132:135]
	v_mfma_i32_16x16x64_i8 v[124:127], v[136:139], v[178:181], v[124:127]
	v_mfma_i32_16x16x64_i8 v[116:119], v[56:59], v[186:189], v[116:119]
	v_mfma_i32_16x16x64_i8 v[108:111], v[136:139], v[186:189], v[108:111]
	v_mfma_i32_16x16x64_i8 v[100:103], v[56:59], v[194:197], v[100:103]
	v_mfma_i32_16x16x64_i8 v[92:95], v[136:139], v[194:197], v[92:95]
	v_mfma_i32_16x16x64_i8 v[84:87], v[56:59], v[202:205], v[84:87]
	v_mfma_i32_16x16x64_i8 v[76:79], v[136:139], v[202:205], v[76:79]
	v_mfma_i32_16x16x64_i8 v[132:135], v[64:67], v[182:185], v[132:135]
	v_mfma_i32_16x16x64_i8 v[124:127], v[172:175], v[182:185], v[124:127]
	v_mfma_i32_16x16x64_i8 v[116:119], v[64:67], v[190:193], v[116:119]
	v_mfma_i32_16x16x64_i8 v[108:111], v[172:175], v[190:193], v[108:111]
	v_mfma_i32_16x16x64_i8 v[100:103], v[64:67], v[198:201], v[100:103]
	v_mfma_i32_16x16x64_i8 v[92:95], v[172:175], v[198:201], v[92:95]
	v_mfma_i32_16x16x64_i8 v[84:87], v[64:67], v[206:209], v[84:87]
	v_mfma_i32_16x16x64_i8 v[76:79], v[172:175], v[206:209], v[76:79]
	s_setprio 0
	s_barrier
	s_add_i32 s30, 0, 0x1c000
	s_add_i32 s31, s54, s34
	v_add_u32_e32 v158, s30, v163
	v_lshl_add_u64 v[156:157], v[156:157], 0, s[14:15]
	s_mov_b32 m0, s31
	ds_read_b128 v[210:213], v158
	ds_read_b128 v[214:217], v158 offset:1024
	ds_read_b128 v[218:221], v158 offset:2048
	ds_read_b128 v[222:225], v158 offset:3072
	global_load_lds_dwordx4 v[156:157], off
	v_lshl_add_u64 v[156:157], v[160:161], 0, s[14:15]
	s_add_i32 m0, s31, 0x2000
	s_nop 0
	global_load_lds_dwordx4 v[156:157], off
	s_barrier
	s_waitcnt lgkmcnt(0)
	s_setprio 1
	v_mfma_i32_16x16x64_i8 v[128:131], v[210:213], v[178:181], v[128:131]
	v_mfma_i32_16x16x64_i8 v[120:123], v[218:221], v[178:181], v[120:123]
	v_mfma_i32_16x16x64_i8 v[112:115], v[210:213], v[186:189], v[112:115]
	v_mfma_i32_16x16x64_i8 v[104:107], v[218:221], v[186:189], v[104:107]
	v_mfma_i32_16x16x64_i8 v[96:99], v[210:213], v[194:197], v[96:99]
	v_mfma_i32_16x16x64_i8 v[88:91], v[218:221], v[194:197], v[88:91]
	v_mfma_i32_16x16x64_i8 v[80:83], v[210:213], v[202:205], v[80:83]
	v_mfma_i32_16x16x64_i8 v[72:75], v[218:221], v[202:205], v[72:75]
	v_mfma_i32_16x16x64_i8 v[128:131], v[214:217], v[182:185], v[128:131]
	v_mfma_i32_16x16x64_i8 v[120:123], v[222:225], v[182:185], v[120:123]
	v_mfma_i32_16x16x64_i8 v[112:115], v[214:217], v[190:193], v[112:115]
	v_mfma_i32_16x16x64_i8 v[104:107], v[222:225], v[190:193], v[104:107]
	v_mfma_i32_16x16x64_i8 v[96:99], v[214:217], v[198:201], v[96:99]
	v_mfma_i32_16x16x64_i8 v[88:91], v[222:225], v[198:201], v[88:91]
	v_mfma_i32_16x16x64_i8 v[80:83], v[214:217], v[206:209], v[80:83]
	v_mfma_i32_16x16x64_i8 v[72:75], v[222:225], v[206:209], v[72:75]
	s_setprio 0
	s_mov_b32 m0, s41
	v_lshl_add_u64 v[156:157], v[226:227], 0, s[14:15]
	s_barrier
	ds_read_b128 v[178:181], v169 offset:49152
	ds_read_b128 v[182:185], v169 offset:50176
	ds_read_b128 v[186:189], v169 offset:51200
	ds_read_b128 v[190:193], v169 offset:52224
	ds_read_b128 v[194:197], v169 offset:53248
	ds_read_b128 v[198:201], v169 offset:54272
	ds_read_b128 v[202:205], v169 offset:55296
	ds_read_b128 v[206:209], v169 offset:56320
	global_load_lds_dwordx4 v[156:157], off
	v_lshl_add_u64 v[156:157], v[228:229], 0, s[14:15]
	s_mov_b32 m0, s42
	s_nop 0
	global_load_lds_dwordx4 v[156:157], off
	s_barrier
; __device__ __forceinline__ float ld_agent(const float* p) { return __hip_atomic_load(p, __ATOMIC_RELAXED, __HIP_MEMORY_SCOPE_AGENT); }
; #define PG8_STAGE(bufoff, gbase, voff) do { _Pragma("unroll") for (int _i = 0; _i < 2; ++_i) \
;         __builtin_amdgcn_global_load_lds((const unsigned*)((const char*)(gbase) + (voff)[_i]), (LAS unsigned*)(lds + (bufoff) + ldsw + _i * 8192), 16, 0, 0); } while (0)
; #define PG8_MMA(ai, bj, At, Bt) do { __builtin_amdgcn_s_setprio(1); _Pragma("unroll") for (int m = 0; m < 4; ++m) _Pragma("unroll") for (int n = 0; n < 2; ++n) _Pragma("unroll") for (int k = 0; k < 2; ++k) \
;         acc[ai][bj][m][n] = MmaOp<Epi::I8>::run(Bt[n][k], At[m][k], acc[ai][bj][m][n]); __builtin_amdgcn_s_setprio(0); } while (0)
; #define PG8_WAIT_V(n) asm volatile("s_waitcnt vmcnt(" #n ")" ::: "memory")
; #define PG8_WAIT_L(n) asm volatile("s_waitcnt lgkmcnt(" #n ")" ::: "memory")
; #define PG8_BAR __builtin_amdgcn_s_barrier()
; #define PG8_SCHED __builtin_amdgcn_sched_barrier(0)
;     __device__ __forceinline__ void operator()(const i32x4 (&acc)[2][2][4][2], const Unit& u, int wr, int wc, int fr, int fq) const {
;         const int row0 = u.pm * BM + wr * 64 + fr, col0 = u.pn * HALF + wc * 32 + 8 * fq, scol = u.pn * BM + wc * 32 + 8 * fq;
;         float sq[8];
; #pragma unroll
;         for (int g = 0; g < 8; ++g) sq[g] = ld_agent(frs + row0 + (g >> 2) * HALF + (g & 3) * 16);
;         f32x4 sg[2], su[2];
; #pragma unroll
;         for (int n = 0; n < 2; ++n) { sg[n] = *(const f32x4*)(swinv + scol + 4 * n); su[n] = *(const f32x4*)(swinv + scol + HALF + 4 * n); }
; template <class Epi, class Sched>
; __device__ __forceinline__ void gemm_phase(LAS unsigned char* lds, const Gemm g, const Sched& S, const Epi& E) {
;     ...
;             PG8_BAR; PG8_WAIT_L(0); PG8_MMA(1, 0, At, B0); PG8_BAR; PG8_SCHED;
;             PG8_STAGE(PG8_SB(1, 1), b3 + hstepB, voffB);
;             PG8_WAIT_V(6); PG8_BAR; PG8_MMA(1, 1, At, B1); PG8_BAR;
	s_waitcnt lgkmcnt(0)
	s_setprio 1
	v_mfma_i32_16x16x64_i8 v[68:71], v[56:59], v[178:181], v[68:71]
	v_mfma_i32_16x16x64_i8 v[60:63], v[136:139], v[178:181], v[60:63]
	v_mfma_i32_16x16x64_i8 v[48:51], v[56:59], v[186:189], v[48:51]
	v_mfma_i32_16x16x64_i8 v[36:39], v[136:139], v[186:189], v[36:39]
	v_mfma_i32_16x16x64_i8 v[28:31], v[56:59], v[194:197], v[28:31]
	v_mfma_i32_16x16x64_i8 v[20:23], v[136:139], v[194:197], v[20:23]
	v_mfma_i32_16x16x64_i8 v[12:15], v[56:59], v[202:205], v[12:15]
	v_mfma_i32_16x16x64_i8 v[4:7], v[136:139], v[202:205], v[4:7]
	v_mfma_i32_16x16x64_i8 v[68:71], v[64:67], v[182:185], v[68:71]
	v_mfma_i32_16x16x64_i8 v[60:63], v[172:175], v[182:185], v[60:63]
	v_mfma_i32_16x16x64_i8 v[48:51], v[64:67], v[190:193], v[48:51]
	v_mfma_i32_16x16x64_i8 v[36:39], v[172:175], v[190:193], v[36:39]
	v_mfma_i32_16x16x64_i8 v[28:31], v[64:67], v[198:201], v[28:31]
	v_mfma_i32_16x16x64_i8 v[20:23], v[172:175], v[198:201], v[20:23]
	v_mfma_i32_16x16x64_i8 v[12:15], v[64:67], v[206:209], v[12:15]
	v_mfma_i32_16x16x64_i8 v[4:7], v[172:175], v[206:209], v[4:7]
	s_setprio 0
	s_barrier
	s_add_u32 s28, s28, 0x40080
	s_addc_u32 s29, s29, 0
	s_add_i32 s30, s30, s34
	v_lshl_add_u64 v[56:57], s[28:29], 0, v[144:145]
	s_mov_b32 m0, s30
	s_nop 0
	global_load_lds_dwordx4 v[56:57], off
	v_lshl_add_u64 v[56:57], s[28:29], 0, v[140:141]
	s_add_i32 m0, s30, 0x2000
	s_nop 0
	global_load_lds_dwordx4 v[56:57], off
	s_waitcnt vmcnt(6)
	s_barrier
	s_setprio 1
	v_mfma_i32_16x16x64_i8 v[40:43], v[210:213], v[178:181], v[40:43]
	v_mfma_i32_16x16x64_i8 v[64:67], v[214:217], v[182:185], v[40:43]
	v_mfma_i32_16x16x64_i8 v[40:43], v[218:221], v[178:181], v[52:55]
	v_mfma_i32_16x16x64_i8 v[56:59], v[222:225], v[182:185], v[40:43]
	v_mfma_i32_16x16x64_i8 v[40:43], v[210:213], v[186:189], v[44:47]
	v_mfma_i32_16x16x64_i8 v[32:35], v[218:221], v[186:189], v[32:35]
	v_mfma_i32_16x16x64_i8 v[24:27], v[210:213], v[194:197], v[24:27]
	v_mfma_i32_16x16x64_i8 v[16:19], v[218:221], v[194:197], v[16:19]
	v_mfma_i32_16x16x64_i8 v[8:11], v[210:213], v[202:205], v[8:11]
	v_mfma_i32_16x16x64_i8 v[0:3], v[218:221], v[202:205], v[0:3]
	v_mfma_i32_16x16x64_i8 v[44:47], v[214:217], v[190:193], v[40:43]
	v_mfma_i32_16x16x64_i8 v[32:35], v[222:225], v[190:193], v[32:35]
	v_mfma_i32_16x16x64_i8 v[24:27], v[214:217], v[198:201], v[24:27]
	v_mfma_i32_16x16x64_i8 v[16:19], v[222:225], v[198:201], v[16:19]
	v_mfma_i32_16x16x64_i8 v[8:11], v[214:217], v[206:209], v[8:11]
	v_mfma_i32_16x16x64_i8 v[0:3], v[222:225], v[206:209], v[0:3]
	s_setprio 0
	s_add_i32 s53, s53, 2
	s_add_u32 s26, s26, 0x100
	s_addc_u32 s27, s27, 0
	s_add_u32 s50, s50, 0x100
	s_addc_u32 s51, s51, 0
	s_cmp_gt_u32 s53, 13
	s_barrier
	s_cbranch_scc0 .LBB0_115
	v_lshl_add_u32 v156, s24, 8, v159
	v_ashrrev_i32_e32 v157, 31, v156
	v_lshl_add_u64 v[40:41], v[156:157], 2, s[2:3]
	global_load_dword v178, v[40:41], off sc1
	global_load_dword v172, v[40:41], off offset:64 sc1
	global_load_dword v170, v[40:41], off offset:128 sc1
	global_load_dword v168, v[40:41], off offset:192 sc1
	global_load_dword v166, v[40:41], off offset:512 sc1
	global_load_dword v164, v[40:41], off offset:576 sc1
	global_load_dword v162, v[40:41], off offset:640 sc1
	global_load_dword v158, v[40:41], off offset:704 sc1
	v_lshl_or_b32 v40, s47, 8, v165
	v_ashrrev_i32_e32 v41, 31, v40
	v_lshl_add_u64 v[160:161], v[40:41], 2, s[12:13]
	global_load_dwordx4 v[40:43], v[160:161], off offset:16
	global_load_dwordx4 v[52:55], v[160:161], off
	global_load_dwordx4 v[136:139], v[160:161], off offset:528
	global_load_dwordx4 v[180:183], v[160:161], off offset:512
	v_cvt_f32_i32_e32 v161, v132
	v_cvt_f32_i32_e32 v160, v128
	v_cvt_f32_i32_e32 v135, v135
	v_cvt_f32_i32_e32 v125, v125
	v_readlane_b32 s54, v239, 46
	v_lshl_or_b32 v174, s47, 7, v165
	v_readlane_b32 s55, v239, 47
	v_ashrrev_i32_e32 v175, 31, v174
	v_cvt_f32_i32_e32 v117, v117
	v_cvt_f32_i32_e32 v109, v109
	v_cvt_f32_i32_e32 v101, v101
	v_cvt_f32_i32_e32 v93, v93
	v_cvt_f32_i32_e32 v85, v85
	v_cvt_f32_i32_e32 v77, v77
	v_cvt_f32_i32_e32 v69, v69
	v_cvt_f32_i32_e32 v61, v61
	v_cvt_f32_i32_e32 v49, v49
	v_cvt_f32_i32_e32 v37, v37
	v_cvt_f32_i32_e32 v29, v29
	v_cvt_f32_i32_e32 v21, v21
	v_cvt_f32_i32_e32 v13, v13
	v_cvt_f32_i32_e32 v5, v5
	s_and_b64 vcc, exec, s[0:1]
	s_mov_b32 s47, s16
	s_mov_b32 s24, s18
	s_mov_b64 s[28:29], s[22:23]
	s_waitcnt vmcnt(0)
; __device__ __forceinline__ unsigned cvt_pk_bf16(float lo, float hi) { unsigned r; asm volatile("v_cvt_pk_bf16_f32 %0, %1, %2" : "=v"(r) : "v"(lo), "v"(hi)); return r; }
; __device__ __forceinline__ float sigm(float x) { return __builtin_amdgcn_rcpf(1.f + __builtin_amdgcn_exp2f(-LOG2E * x)); }
;     __device__ __forceinline__ void operator()(const i32x4 (&acc)[2][2][4][2], const Unit& u, int wr, int wc, int fr, int fq) const {
;     ...
;         for (int ai = 0; ai < 2; ++ai)
; #pragma unroll
;             for (int m = 0; m < 4; ++m) {
;                 const int r = row0 + ai * HALF + m * 16; const float rs = sq[ai * 4 + m];
;                 float v[8];
; #pragma unroll
;                 for (int n = 0; n < 2; ++n)
; #pragma unroll
;                     for (int j = 0; j < 4; ++j) { const float g = (float)acc[ai][0][m][n][j] * rs * sg[n][j], up = (float)acc[ai][1][m][n][j] * rs * su[n][j]; v[n * 4 + j] = g * sigm(g) * up; }
;                 u32x4 w; w.x = cvt_pk_bf16(v[0], v[1]); w.y = cvt_pk_bf16(v[2], v[3]); w.z = cvt_pk_bf16(v[4], v[5]); w.w = cvt_pk_bf16(v[6], v[7]);
;                 *(u32x4*)(O + (size_t)r * FF + col0) = w;
	v_pk_mul_f32 v[184:185], v[178:179], v[160:161] op_sel_hi:[0,1]
	v_mov_b32_e32 v161, v52
	v_mov_b32_e32 v160, v180
	v_pk_mul_f32 v[184:185], v[184:185], v[160:161]
	s_nop 0
	v_mul_f32_e32 v52, 0xbfb8aa3b, v185
	v_exp_f32_e32 v52, v52
	s_nop 0
	v_add_f32_e32 v52, 1.0, v52
	v_rcp_f32_e32 v52, v52
	s_nop 0
	v_mul_f32_e32 v52, v185, v52
	v_mul_f32_e32 v132, v184, v52
	v_cvt_f32_i32_e32 v185, v133
	v_cvt_f32_i32_e32 v184, v129
	v_mov_b32_e32 v52, v181
	v_pk_mul_f32 v[128:129], v[178:179], v[184:185] op_sel_hi:[0,1]
	v_pk_mul_f32 v[128:129], v[128:129], v[52:53]
	s_nop 0
	v_mul_f32_e32 v133, 0xbfb8aa3b, v129
	v_exp_f32_e32 v133, v133
	s_nop 0
	v_add_f32_e32 v133, 1.0, v133
	v_rcp_f32_e32 v133, v133
	s_nop 0
	v_mul_f32_e32 v129, v129, v133
	v_mul_f32_e32 v133, v128, v129
	v_cvt_f32_i32_e32 v129, v134
	v_cvt_f32_i32_e32 v128, v130
	v_cvt_f32_i32_e32 v134, v131
	v_cvt_pk_bf16_f32 v132, v132, v133
	v_pk_mul_f32 v[180:181], v[178:179], v[128:129] op_sel_hi:[0,1]
	v_mov_b32_e32 v128, v182
	v_mov_b32_e32 v129, v54
	v_pk_mul_f32 v[180:181], v[180:181], v[128:129]
	v_pk_mul_f32 v[130:131], v[178:179], v[134:135] op_sel_hi:[0,1]
	v_mul_f32_e32 v54, 0xbfb8aa3b, v181
	v_exp_f32_e32 v54, v54
	s_nop 0
	v_add_f32_e32 v54, 1.0, v54
	v_rcp_f32_e32 v54, v54
	s_nop 0
	v_mul_f32_e32 v54, v181, v54
	v_mul_f32_e32 v157, v180, v54
	v_mov_b32_e32 v54, v183
	v_pk_mul_f32 v[130:131], v[130:131], v[54:55]
	s_nop 0
	v_mul_f32_e32 v134, 0xbfb8aa3b, v131
	v_exp_f32_e32 v134, v134
	s_nop 0
	v_add_f32_e32 v134, 1.0, v134
	v_rcp_f32_e32 v134, v134
	s_nop 0
	v_mul_f32_e32 v131, v131, v134
	v_mul_f32_e32 v173, v130, v131
	v_cvt_f32_i32_e32 v131, v124
	v_cvt_f32_i32_e32 v130, v120
	v_cvt_f32_i32_e32 v124, v121
	v_cvt_pk_bf16_f32 v133, v157, v173
	v_pk_mul_f32 v[134:135], v[178:179], v[130:131] op_sel_hi:[0,1]
	v_mov_b32_e32 v130, v136
	v_mov_b32_e32 v131, v40
	v_pk_mul_f32 v[134:135], v[134:135], v[130:131]
	v_pk_mul_f32 v[120:121], v[178:179], v[124:125] op_sel_hi:[0,1]
	v_mul_f32_e32 v40, 0xbfb8aa3b, v135
	v_exp_f32_e32 v40, v40
	s_nop 0
	v_add_f32_e32 v40, 1.0, v40
	v_rcp_f32_e32 v40, v40
	s_nop 0
	v_mul_f32_e32 v40, v135, v40
	v_mul_f32_e32 v134, v134, v40
	v_mov_b32_e32 v40, v137
	v_pk_mul_f32 v[120:121], v[120:121], v[40:41]
	s_nop 0
	v_mul_f32_e32 v124, 0xbfb8aa3b, v121
	v_exp_f32_e32 v124, v124
	s_nop 0
	v_add_f32_e32 v124, 1.0, v124
	v_rcp_f32_e32 v124, v124
	s_nop 0
	v_mul_f32_e32 v121, v121, v124
	v_mul_f32_e32 v135, v120, v121
	v_cvt_f32_i32_e32 v121, v126
	v_cvt_f32_i32_e32 v120, v122
	v_cvt_pk_bf16_f32 v134, v134, v135
	v_pk_mul_f32 v[124:125], v[178:179], v[120:121] op_sel_hi:[0,1]
	v_mov_b32_e32 v120, v138
	v_mov_b32_e32 v121, v42
	v_pk_mul_f32 v[124:125], v[124:125], v[120:121]
	s_nop 0
	v_mul_f32_e32 v42, 0xbfb8aa3b, v125
	v_exp_f32_e32 v42, v42
	s_nop 0
	v_add_f32_e32 v42, 1.0, v42
	v_rcp_f32_e32 v42, v42
	s_nop 0
	v_mul_f32_e32 v42, v125, v42
	v_mul_f32_e32 v126, v124, v42
	v_cvt_f32_i32_e32 v125, v127
	v_cvt_f32_i32_e32 v124, v123
	v_mov_b32_e32 v42, v139
	v_pk_mul_f32 v[122:123], v[178:179], v[124:125] op_sel_hi:[0,1]
	v_pk_mul_f32 v[122:123], v[122:123], v[42:43]
	s_nop 0
	v_mul_f32_e32 v124, 0xbfb8aa3b, v123
	v_exp_f32_e32 v124, v124
	s_nop 0
	v_add_f32_e32 v124, 1.0, v124
	v_rcp_f32_e32 v124, v124
	s_nop 0
	v_mul_f32_e32 v123, v123, v124
	v_mul_f32_e32 v122, v122, v123
	v_cvt_pk_bf16_f32 v135, v126, v122
	v_mov_b64_e32 v[122:123], s[54:55]
	v_mad_i64_i32 v[126:127], s[26:27], v156, s46, v[122:123]
	v_lshlrev_b64 v[124:125], 1, v[174:175]
	v_lshl_add_u64 v[126:127], v[126:127], 0, v[124:125]
	global_store_dwordx4 v[126:127], v[132:135], off sc0 sc1
	v_cvt_f32_i32_e32 v127, v116
	v_cvt_f32_i32_e32 v126, v112
	v_cvt_f32_i32_e32 v116, v113
	v_pk_mul_f32 v[126:127], v[172:173], v[126:127] op_sel_hi:[0,1]
	v_pk_mul_f32 v[126:127], v[126:127], v[160:161]
	s_nop 0
	v_mul_f32_e32 v112, 0xbfb8aa3b, v127
	v_exp_f32_e32 v112, v112
	s_nop 0
	v_add_f32_e32 v112, 1.0, v112
	v_rcp_f32_e32 v112, v112
	s_nop 0
	v_mul_f32_e32 v112, v127, v112
	v_mul_f32_e32 v126, v126, v112
	v_pk_mul_f32 v[112:113], v[172:173], v[116:117] op_sel_hi:[0,1]
	v_pk_mul_f32 v[112:113], v[112:113], v[52:53]
	s_nop 0
	v_mul_f32_e32 v116, 0xbfb8aa3b, v113
	v_exp_f32_e32 v116, v116
	s_nop 0
	v_add_f32_e32 v116, 1.0, v116
	v_rcp_f32_e32 v116, v116
	s_nop 0
	v_mul_f32_e32 v113, v113, v116
	v_mul_f32_e32 v116, v112, v113
	v_cvt_f32_i32_e32 v113, v118
	v_cvt_f32_i32_e32 v112, v114
	v_pk_mul_f32 v[112:113], v[172:173], v[112:113] op_sel_hi:[0,1]
	v_pk_mul_f32 v[112:113], v[112:113], v[128:129]
	s_nop 0
	v_mul_f32_e32 v114, 0xbfb8aa3b, v113
	v_exp_f32_e32 v114, v114
	s_nop 0
	v_add_f32_e32 v114, 1.0, v114
	v_rcp_f32_e32 v114, v114
	s_nop 0
	v_mul_f32_e32 v113, v113, v114
	v_mul_f32_e32 v114, v112, v113
	v_cvt_f32_i32_e32 v113, v119
	v_cvt_f32_i32_e32 v112, v115
	v_pk_mul_f32 v[112:113], v[172:173], v[112:113] op_sel_hi:[0,1]
	v_pk_mul_f32 v[112:113], v[112:113], v[54:55]
	s_nop 0
	v_mul_f32_e32 v115, 0xbfb8aa3b, v113
	v_exp_f32_e32 v115, v115
	s_nop 0
	v_add_f32_e32 v115, 1.0, v115
	v_rcp_f32_e32 v115, v115
	s_nop 0
	v_mul_f32_e32 v113, v113, v115
	v_mul_f32_e32 v115, v112, v113
	v_cvt_f32_i32_e32 v113, v108
	v_cvt_f32_i32_e32 v112, v104
	v_cvt_f32_i32_e32 v108, v105
	v_pk_mul_f32 v[112:113], v[172:173], v[112:113] op_sel_hi:[0,1]
	v_pk_mul_f32 v[112:113], v[112:113], v[130:131]
	s_nop 0
	v_mul_f32_e32 v104, 0xbfb8aa3b, v113
	v_exp_f32_e32 v104, v104
	s_nop 0
	v_add_f32_e32 v104, 1.0, v104
	v_rcp_f32_e32 v104, v104
	s_nop 0
	v_mul_f32_e32 v104, v113, v104
	v_mul_f32_e32 v112, v112, v104
	v_pk_mul_f32 v[104:105], v[172:173], v[108:109] op_sel_hi:[0,1]
	v_pk_mul_f32 v[104:105], v[104:105], v[40:41]
; __device__ __forceinline__ unsigned cvt_pk_bf16(float lo, float hi) { unsigned r; asm volatile("v_cvt_pk_bf16_f32 %0, %1, %2" : "=v"(r) : "v"(lo), "v"(hi)); return r; }
; __device__ __forceinline__ float sigm(float x) { return __builtin_amdgcn_rcpf(1.f + __builtin_amdgcn_exp2f(-LOG2E * x)); }
;     __device__ __forceinline__ void operator()(const i32x4 (&acc)[2][2][4][2], const Unit& u, int wr, int wc, int fr, int fq) const {
;     ...
;         for (int ai = 0; ai < 2; ++ai)
; #pragma unroll
;             for (int m = 0; m < 4; ++m) {
;                 const int r = row0 + ai * HALF + m * 16; const float rs = sq[ai * 4 + m];
;                 float v[8];
; #pragma unroll
;                 for (int n = 0; n < 2; ++n)
; #pragma unroll
;                     for (int j = 0; j < 4; ++j) { const float g = (float)acc[ai][0][m][n][j] * rs * sg[n][j], up = (float)acc[ai][1][m][n][j] * rs * su[n][j]; v[n * 4 + j] = g * sigm(g) * up; }
;                 u32x4 w; w.x = cvt_pk_bf16(v[0], v[1]); w.y = cvt_pk_bf16(v[2], v[3]); w.z = cvt_pk_bf16(v[4], v[5]); w.w = cvt_pk_bf16(v[6], v[7]);
;                 *(u32x4*)(O + (size_t)r * FF + col0) = w;
	s_nop 0
	v_mul_f32_e32 v108, 0xbfb8aa3b, v105
	v_exp_f32_e32 v108, v108
	s_nop 0
	v_add_f32_e32 v108, 1.0, v108
	v_rcp_f32_e32 v108, v108
	s_nop 0
	v_mul_f32_e32 v105, v105, v108
	v_mul_f32_e32 v108, v104, v105
	v_cvt_f32_i32_e32 v105, v110
	v_cvt_f32_i32_e32 v104, v106
	v_or_b32_e32 v110, 16, v156
	v_pk_mul_f32 v[104:105], v[172:173], v[104:105] op_sel_hi:[0,1]
	v_pk_mul_f32 v[104:105], v[104:105], v[120:121]
	s_nop 0
	v_mul_f32_e32 v106, 0xbfb8aa3b, v105
	v_exp_f32_e32 v106, v106
	s_nop 0
	v_add_f32_e32 v106, 1.0, v106
	v_rcp_f32_e32 v106, v106
	s_nop 0
	v_mul_f32_e32 v105, v105, v106
	v_mul_f32_e32 v109, v104, v105
	v_cvt_f32_i32_e32 v105, v111
	v_cvt_f32_i32_e32 v104, v107
	v_pk_mul_f32 v[104:105], v[172:173], v[104:105] op_sel_hi:[0,1]
	v_pk_mul_f32 v[104:105], v[104:105], v[42:43]
	s_nop 0
	v_mul_f32_e32 v106, 0xbfb8aa3b, v105
	v_exp_f32_e32 v106, v106
	s_nop 0
	v_add_f32_e32 v106, 1.0, v106
	v_rcp_f32_e32 v106, v106
	s_nop 0
	v_mul_f32_e32 v105, v105, v106
	v_mul_f32_e32 v107, v104, v105
	v_cvt_pk_bf16_f32 v104, v126, v116
	v_cvt_pk_bf16_f32 v105, v114, v115
	v_cvt_pk_bf16_f32 v106, v112, v108
	v_cvt_pk_bf16_f32 v107, v109, v107
	v_mad_i64_i32 v[108:109], s[26:27], v110, s46, v[122:123]
	v_lshl_add_u64 v[108:109], v[108:109], 0, v[124:125]
	global_store_dwordx4 v[108:109], v[104:107], off sc0 sc1
	s_nop 1
	v_cvt_f32_i32_e32 v105, v100
	v_cvt_f32_i32_e32 v104, v96
	v_cvt_f32_i32_e32 v100, v97
	v_pk_mul_f32 v[104:105], v[170:171], v[104:105] op_sel_hi:[0,1]
	v_pk_mul_f32 v[104:105], v[104:105], v[160:161]
	s_nop 0
	v_mul_f32_e32 v96, 0xbfb8aa3b, v105
	v_exp_f32_e32 v96, v96
	s_nop 0
	v_add_f32_e32 v96, 1.0, v96
	v_rcp_f32_e32 v96, v96
	s_nop 0
	v_mul_f32_e32 v96, v105, v96
	v_mul_f32_e32 v104, v104, v96
	v_pk_mul_f32 v[96:97], v[170:171], v[100:101] op_sel_hi:[0,1]
	v_pk_mul_f32 v[96:97], v[96:97], v[52:53]
	s_nop 0
	v_mul_f32_e32 v100, 0xbfb8aa3b, v97
	v_exp_f32_e32 v100, v100
	s_nop 0
	v_add_f32_e32 v100, 1.0, v100
	v_rcp_f32_e32 v100, v100
	s_nop 0
	v_mul_f32_e32 v97, v97, v100
	v_mul_f32_e32 v100, v96, v97
	v_cvt_f32_i32_e32 v97, v102
	v_cvt_f32_i32_e32 v96, v98
	v_pk_mul_f32 v[96:97], v[170:171], v[96:97] op_sel_hi:[0,1]
	v_pk_mul_f32 v[96:97], v[96:97], v[128:129]
	s_nop 0
	v_mul_f32_e32 v98, 0xbfb8aa3b, v97
	v_exp_f32_e32 v98, v98
	s_nop 0
	v_add_f32_e32 v98, 1.0, v98
	v_rcp_f32_e32 v98, v98
	s_nop 0
	v_mul_f32_e32 v97, v97, v98
	v_mul_f32_e32 v98, v96, v97
	v_cvt_f32_i32_e32 v97, v103
	v_cvt_f32_i32_e32 v96, v99
	v_pk_mul_f32 v[96:97], v[170:171], v[96:97] op_sel_hi:[0,1]
	v_pk_mul_f32 v[96:97], v[96:97], v[54:55]
	s_nop 0
	v_mul_f32_e32 v99, 0xbfb8aa3b, v97
	v_exp_f32_e32 v99, v99
	s_nop 0
	v_add_f32_e32 v99, 1.0, v99
	v_rcp_f32_e32 v99, v99
	s_nop 0
	v_mul_f32_e32 v97, v97, v99
	v_mul_f32_e32 v99, v96, v97
	v_cvt_f32_i32_e32 v97, v92
	v_cvt_f32_i32_e32 v96, v88
	v_cvt_f32_i32_e32 v92, v89
	v_pk_mul_f32 v[96:97], v[170:171], v[96:97] op_sel_hi:[0,1]
	v_pk_mul_f32 v[96:97], v[96:97], v[130:131]
	s_nop 0
	v_mul_f32_e32 v88, 0xbfb8aa3b, v97
	v_exp_f32_e32 v88, v88
	s_nop 0
	v_add_f32_e32 v88, 1.0, v88
	v_rcp_f32_e32 v88, v88
	s_nop 0
	v_mul_f32_e32 v88, v97, v88
	v_mul_f32_e32 v96, v96, v88
	v_pk_mul_f32 v[88:89], v[170:171], v[92:93] op_sel_hi:[0,1]
	v_pk_mul_f32 v[88:89], v[88:89], v[40:41]
	s_nop 0
	v_mul_f32_e32 v92, 0xbfb8aa3b, v89
	v_exp_f32_e32 v92, v92
	s_nop 0
	v_add_f32_e32 v92, 1.0, v92
	v_rcp_f32_e32 v92, v92
	s_nop 0
	v_mul_f32_e32 v89, v89, v92
	v_mul_f32_e32 v92, v88, v89
	v_cvt_f32_i32_e32 v89, v94
	v_cvt_f32_i32_e32 v88, v90
	v_or_b32_e32 v94, 32, v156
	v_pk_mul_f32 v[88:89], v[170:171], v[88:89] op_sel_hi:[0,1]
	v_pk_mul_f32 v[88:89], v[88:89], v[120:121]
	s_nop 0
	v_mul_f32_e32 v90, 0xbfb8aa3b, v89
	v_exp_f32_e32 v90, v90
	s_nop 0
	v_add_f32_e32 v90, 1.0, v90
	v_rcp_f32_e32 v90, v90
	s_nop 0
	v_mul_f32_e32 v89, v89, v90
	v_mul_f32_e32 v93, v88, v89
	v_cvt_f32_i32_e32 v89, v95
	v_cvt_f32_i32_e32 v88, v91
	v_pk_mul_f32 v[88:89], v[170:171], v[88:89] op_sel_hi:[0,1]
	v_pk_mul_f32 v[88:89], v[88:89], v[42:43]
	s_nop 0
	v_mul_f32_e32 v90, 0xbfb8aa3b, v89
	v_exp_f32_e32 v90, v90
	s_nop 0
	v_add_f32_e32 v90, 1.0, v90
	v_rcp_f32_e32 v90, v90
	s_nop 0
	v_mul_f32_e32 v89, v89, v90
	v_mul_f32_e32 v91, v88, v89
	v_cvt_pk_bf16_f32 v88, v104, v100
	v_cvt_pk_bf16_f32 v89, v98, v99
	v_cvt_pk_bf16_f32 v90, v96, v92
	v_cvt_pk_bf16_f32 v91, v93, v91
	v_mad_i64_i32 v[92:93], s[26:27], v94, s46, v[122:123]
	v_lshl_add_u64 v[92:93], v[92:93], 0, v[124:125]
	global_store_dwordx4 v[92:93], v[88:91], off sc0 sc1
	s_nop 1
	v_cvt_f32_i32_e32 v89, v84
	v_cvt_f32_i32_e32 v88, v80
	v_cvt_f32_i32_e32 v84, v81
	v_pk_mul_f32 v[88:89], v[168:169], v[88:89] op_sel_hi:[0,1]
	v_pk_mul_f32 v[88:89], v[88:89], v[160:161]
	s_nop 0
	v_mul_f32_e32 v80, 0xbfb8aa3b, v89
	v_exp_f32_e32 v80, v80
	s_nop 0
	v_add_f32_e32 v80, 1.0, v80
	v_rcp_f32_e32 v80, v80
	s_nop 0
	v_mul_f32_e32 v80, v89, v80
	v_mul_f32_e32 v88, v88, v80
	v_pk_mul_f32 v[80:81], v[168:169], v[84:85] op_sel_hi:[0,1]
	v_pk_mul_f32 v[80:81], v[80:81], v[52:53]
	s_nop 0
	v_mul_f32_e32 v84, 0xbfb8aa3b, v81
	v_exp_f32_e32 v84, v84
	s_nop 0
	v_add_f32_e32 v84, 1.0, v84
	v_rcp_f32_e32 v84, v84
	s_nop 0
	v_mul_f32_e32 v81, v81, v84
	v_mul_f32_e32 v84, v80, v81
	v_cvt_f32_i32_e32 v81, v86
	v_cvt_f32_i32_e32 v80, v82
	v_pk_mul_f32 v[80:81], v[168:169], v[80:81] op_sel_hi:[0,1]
	v_pk_mul_f32 v[80:81], v[80:81], v[128:129]
	s_nop 0
	v_mul_f32_e32 v82, 0xbfb8aa3b, v81
	v_exp_f32_e32 v82, v82
	s_nop 0
	v_add_f32_e32 v82, 1.0, v82
	v_rcp_f32_e32 v82, v82
	s_nop 0
	v_mul_f32_e32 v81, v81, v82
	v_mul_f32_e32 v82, v80, v81
	v_cvt_f32_i32_e32 v81, v87
	v_cvt_f32_i32_e32 v80, v83
; __device__ __forceinline__ unsigned cvt_pk_bf16(float lo, float hi) { unsigned r; asm volatile("v_cvt_pk_bf16_f32 %0, %1, %2" : "=v"(r) : "v"(lo), "v"(hi)); return r; }
; __device__ __forceinline__ float sigm(float x) { return __builtin_amdgcn_rcpf(1.f + __builtin_amdgcn_exp2f(-LOG2E * x)); }
;     __device__ __forceinline__ void operator()(const i32x4 (&acc)[2][2][4][2], const Unit& u, int wr, int wc, int fr, int fq) const {
;     ...
;         for (int ai = 0; ai < 2; ++ai)
; #pragma unroll
;             for (int m = 0; m < 4; ++m) {
;                 const int r = row0 + ai * HALF + m * 16; const float rs = sq[ai * 4 + m];
;                 float v[8];
; #pragma unroll
;                 for (int n = 0; n < 2; ++n)
; #pragma unroll
;                     for (int j = 0; j < 4; ++j) { const float g = (float)acc[ai][0][m][n][j] * rs * sg[n][j], up = (float)acc[ai][1][m][n][j] * rs * su[n][j]; v[n * 4 + j] = g * sigm(g) * up; }
;                 u32x4 w; w.x = cvt_pk_bf16(v[0], v[1]); w.y = cvt_pk_bf16(v[2], v[3]); w.z = cvt_pk_bf16(v[4], v[5]); w.w = cvt_pk_bf16(v[6], v[7]);
;                 *(u32x4*)(O + (size_t)r * FF + col0) = w;
	v_pk_mul_f32 v[80:81], v[168:169], v[80:81] op_sel_hi:[0,1]
	v_pk_mul_f32 v[80:81], v[80:81], v[54:55]
	s_nop 0
	v_mul_f32_e32 v83, 0xbfb8aa3b, v81
	v_exp_f32_e32 v83, v83
	s_nop 0
	v_add_f32_e32 v83, 1.0, v83
	v_rcp_f32_e32 v83, v83
	s_nop 0
	v_mul_f32_e32 v81, v81, v83
	v_mul_f32_e32 v83, v80, v81
	v_cvt_f32_i32_e32 v81, v76
	v_cvt_f32_i32_e32 v80, v72
	v_cvt_f32_i32_e32 v76, v73
	v_pk_mul_f32 v[80:81], v[168:169], v[80:81] op_sel_hi:[0,1]
	v_pk_mul_f32 v[80:81], v[80:81], v[130:131]
	s_nop 0
	v_mul_f32_e32 v72, 0xbfb8aa3b, v81
	v_exp_f32_e32 v72, v72
	s_nop 0
	v_add_f32_e32 v72, 1.0, v72
	v_rcp_f32_e32 v72, v72
	s_nop 0
	v_mul_f32_e32 v72, v81, v72
	v_mul_f32_e32 v80, v80, v72
	v_pk_mul_f32 v[72:73], v[168:169], v[76:77] op_sel_hi:[0,1]
	v_pk_mul_f32 v[72:73], v[72:73], v[40:41]
	s_nop 0
	v_mul_f32_e32 v76, 0xbfb8aa3b, v73
	v_exp_f32_e32 v76, v76
	s_nop 0
	v_add_f32_e32 v76, 1.0, v76
	v_rcp_f32_e32 v76, v76
	s_nop 0
	v_mul_f32_e32 v73, v73, v76
	v_mul_f32_e32 v76, v72, v73
	v_cvt_f32_i32_e32 v73, v78
	v_cvt_f32_i32_e32 v72, v74
	v_or_b32_e32 v78, 48, v156
	v_pk_mul_f32 v[72:73], v[168:169], v[72:73] op_sel_hi:[0,1]
	v_pk_mul_f32 v[72:73], v[72:73], v[120:121]
	s_nop 0
	v_mul_f32_e32 v74, 0xbfb8aa3b, v73
	v_exp_f32_e32 v74, v74
	s_nop 0
	v_add_f32_e32 v74, 1.0, v74
	v_rcp_f32_e32 v74, v74
	s_nop 0
	v_mul_f32_e32 v73, v73, v74
	v_mul_f32_e32 v77, v72, v73
	v_cvt_f32_i32_e32 v73, v79
	v_cvt_f32_i32_e32 v72, v75
	v_pk_mul_f32 v[72:73], v[168:169], v[72:73] op_sel_hi:[0,1]
	v_pk_mul_f32 v[72:73], v[72:73], v[42:43]
	s_nop 0
	v_mul_f32_e32 v74, 0xbfb8aa3b, v73
	v_exp_f32_e32 v74, v74
	s_nop 0
	v_add_f32_e32 v74, 1.0, v74
	v_rcp_f32_e32 v74, v74
	s_nop 0
	v_mul_f32_e32 v73, v73, v74
	v_mul_f32_e32 v75, v72, v73
	v_cvt_pk_bf16_f32 v72, v88, v84
	v_cvt_pk_bf16_f32 v73, v82, v83
	v_cvt_pk_bf16_f32 v74, v80, v76
	v_cvt_pk_bf16_f32 v75, v77, v75
	v_mad_i64_i32 v[76:77], s[26:27], v78, s46, v[122:123]
	v_lshl_add_u64 v[76:77], v[76:77], 0, v[124:125]
	global_store_dwordx4 v[76:77], v[72:75], off sc0 sc1
	s_nop 1
	v_cvt_f32_i32_e32 v73, v68
	v_cvt_f32_i32_e32 v72, v64
	v_cvt_f32_i32_e32 v68, v65
	v_add_u32_e32 v74, 0x80, v156
	v_pk_mul_f32 v[72:73], v[166:167], v[72:73] op_sel_hi:[0,1]
	v_pk_mul_f32 v[72:73], v[72:73], v[160:161]
	s_nop 0
	v_mul_f32_e32 v64, 0xbfb8aa3b, v73
	v_exp_f32_e32 v64, v64
	s_nop 0
	v_add_f32_e32 v64, 1.0, v64
	v_rcp_f32_e32 v64, v64
	s_nop 0
	v_mul_f32_e32 v64, v73, v64
	v_mul_f32_e32 v72, v72, v64
	v_pk_mul_f32 v[64:65], v[166:167], v[68:69] op_sel_hi:[0,1]
	v_pk_mul_f32 v[64:65], v[64:65], v[52:53]
	s_nop 0
	v_mul_f32_e32 v68, 0xbfb8aa3b, v65
	v_exp_f32_e32 v68, v68
	s_nop 0
	v_add_f32_e32 v68, 1.0, v68
	v_rcp_f32_e32 v68, v68
	s_nop 0
	v_mul_f32_e32 v65, v65, v68
	v_mul_f32_e32 v68, v64, v65
	v_cvt_f32_i32_e32 v65, v70
	v_cvt_f32_i32_e32 v64, v66
	v_pk_mul_f32 v[64:65], v[166:167], v[64:65] op_sel_hi:[0,1]
	v_pk_mul_f32 v[64:65], v[64:65], v[128:129]
	s_nop 0
	v_mul_f32_e32 v66, 0xbfb8aa3b, v65
	v_exp_f32_e32 v66, v66
	s_nop 0
	v_add_f32_e32 v66, 1.0, v66
	v_rcp_f32_e32 v66, v66
	s_nop 0
	v_mul_f32_e32 v65, v65, v66
	v_mul_f32_e32 v66, v64, v65
	v_cvt_f32_i32_e32 v65, v71
	v_cvt_f32_i32_e32 v64, v67
	v_pk_mul_f32 v[64:65], v[166:167], v[64:65] op_sel_hi:[0,1]
	v_pk_mul_f32 v[64:65], v[64:65], v[54:55]
	s_nop 0
	v_mul_f32_e32 v67, 0xbfb8aa3b, v65
	v_exp_f32_e32 v67, v67
	s_nop 0
	v_add_f32_e32 v67, 1.0, v67
	v_rcp_f32_e32 v67, v67
	s_nop 0
	v_mul_f32_e32 v65, v65, v67
	v_mul_f32_e32 v67, v64, v65
	v_cvt_f32_i32_e32 v65, v60
	v_cvt_f32_i32_e32 v64, v56
	v_cvt_f32_i32_e32 v60, v57
	v_pk_mul_f32 v[64:65], v[166:167], v[64:65] op_sel_hi:[0,1]
	v_pk_mul_f32 v[64:65], v[64:65], v[130:131]
	s_nop 0
	v_mul_f32_e32 v56, 0xbfb8aa3b, v65
	v_exp_f32_e32 v56, v56
	s_nop 0
	v_add_f32_e32 v56, 1.0, v56
	v_rcp_f32_e32 v56, v56
	s_nop 0
	v_mul_f32_e32 v56, v65, v56
	v_mul_f32_e32 v64, v64, v56
	v_pk_mul_f32 v[56:57], v[166:167], v[60:61] op_sel_hi:[0,1]
	v_pk_mul_f32 v[56:57], v[56:57], v[40:41]
	s_nop 0
	v_mul_f32_e32 v60, 0xbfb8aa3b, v57
	v_exp_f32_e32 v60, v60
	s_nop 0
	v_add_f32_e32 v60, 1.0, v60
	v_rcp_f32_e32 v60, v60
	s_nop 0
	v_mul_f32_e32 v57, v57, v60
	v_mul_f32_e32 v60, v56, v57
	v_cvt_f32_i32_e32 v57, v62
	v_cvt_f32_i32_e32 v56, v58
	v_pk_mul_f32 v[56:57], v[166:167], v[56:57] op_sel_hi:[0,1]
	v_pk_mul_f32 v[56:57], v[56:57], v[120:121]
	s_nop 0
	v_mul_f32_e32 v58, 0xbfb8aa3b, v57
	v_exp_f32_e32 v58, v58
	s_nop 0
	v_add_f32_e32 v58, 1.0, v58
	v_rcp_f32_e32 v58, v58
	s_nop 0
	v_mul_f32_e32 v57, v57, v58
	v_mul_f32_e32 v61, v56, v57
	v_cvt_f32_i32_e32 v57, v63
	v_cvt_f32_i32_e32 v56, v59
	v_pk_mul_f32 v[56:57], v[166:167], v[56:57] op_sel_hi:[0,1]
	v_pk_mul_f32 v[56:57], v[56:57], v[42:43]
	s_nop 0
	v_mul_f32_e32 v58, 0xbfb8aa3b, v57
	v_exp_f32_e32 v58, v58
	s_nop 0
	v_add_f32_e32 v58, 1.0, v58
	v_rcp_f32_e32 v58, v58
	s_nop 0
	v_mul_f32_e32 v57, v57, v58
	v_mul_f32_e32 v59, v56, v57
	v_cvt_pk_bf16_f32 v56, v72, v68
	v_cvt_pk_bf16_f32 v57, v66, v67
	v_cvt_pk_bf16_f32 v58, v64, v60
	v_cvt_pk_bf16_f32 v59, v61, v59
	v_mad_i64_i32 v[60:61], s[26:27], v74, s46, v[122:123]
	v_lshl_add_u64 v[60:61], v[60:61], 0, v[124:125]
	global_store_dwordx4 v[60:61], v[56:59], off sc0 sc1
	s_nop 1
	v_cvt_f32_i32_e32 v57, v48
	v_cvt_f32_i32_e32 v56, v44
	v_cvt_f32_i32_e32 v48, v45
	v_pk_mul_f32 v[56:57], v[164:165], v[56:57] op_sel_hi:[0,1]
	v_pk_mul_f32 v[56:57], v[56:57], v[160:161]
	s_nop 0
	v_mul_f32_e32 v44, 0xbfb8aa3b, v57
	v_exp_f32_e32 v44, v44
	s_nop 0
	v_add_f32_e32 v44, 1.0, v44
	v_rcp_f32_e32 v44, v44
	s_nop 0
	v_mul_f32_e32 v44, v57, v44
	v_mul_f32_e32 v56, v56, v44
	v_pk_mul_f32 v[44:45], v[164:165], v[48:49] op_sel_hi:[0,1]
; __device__ __forceinline__ unsigned cvt_pk_bf16(float lo, float hi) { unsigned r; asm volatile("v_cvt_pk_bf16_f32 %0, %1, %2" : "=v"(r) : "v"(lo), "v"(hi)); return r; }
; __device__ __forceinline__ float sigm(float x) { return __builtin_amdgcn_rcpf(1.f + __builtin_amdgcn_exp2f(-LOG2E * x)); }
;     __device__ __forceinline__ void operator()(const i32x4 (&acc)[2][2][4][2], const Unit& u, int wr, int wc, int fr, int fq) const {
;     ...
;         for (int ai = 0; ai < 2; ++ai)
; #pragma unroll
;             for (int m = 0; m < 4; ++m) {
;                 const int r = row0 + ai * HALF + m * 16; const float rs = sq[ai * 4 + m];
;                 float v[8];
; #pragma unroll
;                 for (int n = 0; n < 2; ++n)
; #pragma unroll
;                     for (int j = 0; j < 4; ++j) { const float g = (float)acc[ai][0][m][n][j] * rs * sg[n][j], up = (float)acc[ai][1][m][n][j] * rs * su[n][j]; v[n * 4 + j] = g * sigm(g) * up; }
;                 u32x4 w; w.x = cvt_pk_bf16(v[0], v[1]); w.y = cvt_pk_bf16(v[2], v[3]); w.z = cvt_pk_bf16(v[4], v[5]); w.w = cvt_pk_bf16(v[6], v[7]);
;                 *(u32x4*)(O + (size_t)r * FF + col0) = w;
	v_pk_mul_f32 v[44:45], v[44:45], v[52:53]
	s_nop 0
	v_mul_f32_e32 v48, 0xbfb8aa3b, v45
	v_exp_f32_e32 v48, v48
	s_nop 0
	v_add_f32_e32 v48, 1.0, v48
	v_rcp_f32_e32 v48, v48
	s_nop 0
	v_mul_f32_e32 v45, v45, v48
	v_mul_f32_e32 v48, v44, v45
	v_cvt_f32_i32_e32 v45, v50
	v_cvt_f32_i32_e32 v44, v46
	v_pk_mul_f32 v[44:45], v[164:165], v[44:45] op_sel_hi:[0,1]
	v_pk_mul_f32 v[44:45], v[44:45], v[128:129]
	s_nop 0
	v_mul_f32_e32 v46, 0xbfb8aa3b, v45
	v_exp_f32_e32 v46, v46
	s_nop 0
	v_add_f32_e32 v46, 1.0, v46
	v_rcp_f32_e32 v46, v46
	s_nop 0
	v_mul_f32_e32 v45, v45, v46
	v_mul_f32_e32 v46, v44, v45
	v_cvt_f32_i32_e32 v45, v51
	v_cvt_f32_i32_e32 v44, v47
	v_pk_mul_f32 v[44:45], v[164:165], v[44:45] op_sel_hi:[0,1]
	v_pk_mul_f32 v[44:45], v[44:45], v[54:55]
	s_nop 0
	v_mul_f32_e32 v47, 0xbfb8aa3b, v45
	v_exp_f32_e32 v47, v47
	s_nop 0
	v_add_f32_e32 v47, 1.0, v47
	v_rcp_f32_e32 v47, v47
	s_nop 0
	v_mul_f32_e32 v45, v45, v47
	v_mul_f32_e32 v47, v44, v45
	v_cvt_f32_i32_e32 v45, v36
	v_cvt_f32_i32_e32 v44, v32
	v_cvt_f32_i32_e32 v36, v33
	v_pk_mul_f32 v[44:45], v[164:165], v[44:45] op_sel_hi:[0,1]
	v_pk_mul_f32 v[44:45], v[44:45], v[130:131]
	s_nop 0
	v_mul_f32_e32 v32, 0xbfb8aa3b, v45
	v_exp_f32_e32 v32, v32
	s_nop 0
	v_add_f32_e32 v32, 1.0, v32
	v_rcp_f32_e32 v32, v32
	s_nop 0
	v_mul_f32_e32 v32, v45, v32
	v_mul_f32_e32 v44, v44, v32
	v_pk_mul_f32 v[32:33], v[164:165], v[36:37] op_sel_hi:[0,1]
	v_pk_mul_f32 v[32:33], v[32:33], v[40:41]
	s_nop 0
	v_mul_f32_e32 v36, 0xbfb8aa3b, v33
	v_exp_f32_e32 v36, v36
	s_nop 0
	v_add_f32_e32 v36, 1.0, v36
	v_rcp_f32_e32 v36, v36
	s_nop 0
	v_mul_f32_e32 v33, v33, v36
	v_mul_f32_e32 v36, v32, v33
	v_cvt_f32_i32_e32 v33, v38
	v_cvt_f32_i32_e32 v32, v34
	v_add_u32_e32 v38, 0x90, v156
	v_pk_mul_f32 v[32:33], v[164:165], v[32:33] op_sel_hi:[0,1]
	v_pk_mul_f32 v[32:33], v[32:33], v[120:121]
	s_nop 0
	v_mul_f32_e32 v34, 0xbfb8aa3b, v33
	v_exp_f32_e32 v34, v34
	s_nop 0
	v_add_f32_e32 v34, 1.0, v34
	v_rcp_f32_e32 v34, v34
	s_nop 0
	v_mul_f32_e32 v33, v33, v34
	v_mul_f32_e32 v37, v32, v33
	v_cvt_f32_i32_e32 v33, v39
	v_cvt_f32_i32_e32 v32, v35
	v_pk_mul_f32 v[32:33], v[164:165], v[32:33] op_sel_hi:[0,1]
	v_pk_mul_f32 v[32:33], v[32:33], v[42:43]
	s_nop 0
	v_mul_f32_e32 v34, 0xbfb8aa3b, v33
	v_exp_f32_e32 v34, v34
	s_nop 0
	v_add_f32_e32 v34, 1.0, v34
	v_rcp_f32_e32 v34, v34
	s_nop 0
	v_mul_f32_e32 v33, v33, v34
	v_mul_f32_e32 v35, v32, v33
	v_cvt_pk_bf16_f32 v32, v56, v48
	v_cvt_pk_bf16_f32 v33, v46, v47
	v_cvt_pk_bf16_f32 v34, v44, v36
	v_cvt_pk_bf16_f32 v35, v37, v35
	v_mad_i64_i32 v[36:37], s[26:27], v38, s46, v[122:123]
	v_lshl_add_u64 v[36:37], v[36:37], 0, v[124:125]
	global_store_dwordx4 v[36:37], v[32:35], off sc0 sc1
	s_nop 1
	v_cvt_f32_i32_e32 v33, v28
	v_cvt_f32_i32_e32 v32, v24
	v_cvt_f32_i32_e32 v28, v25
	v_pk_mul_f32 v[32:33], v[162:163], v[32:33] op_sel_hi:[0,1]
	v_pk_mul_f32 v[32:33], v[32:33], v[160:161]
	s_nop 0
	v_mul_f32_e32 v24, 0xbfb8aa3b, v33
	v_exp_f32_e32 v24, v24
	s_nop 0
	v_add_f32_e32 v24, 1.0, v24
	v_rcp_f32_e32 v24, v24
	s_nop 0
	v_mul_f32_e32 v24, v33, v24
	v_mul_f32_e32 v32, v32, v24
	v_pk_mul_f32 v[24:25], v[162:163], v[28:29] op_sel_hi:[0,1]
	v_pk_mul_f32 v[24:25], v[24:25], v[52:53]
	s_nop 0
	v_mul_f32_e32 v28, 0xbfb8aa3b, v25
	v_exp_f32_e32 v28, v28
	s_nop 0
	v_add_f32_e32 v28, 1.0, v28
	v_rcp_f32_e32 v28, v28
	s_nop 0
	v_mul_f32_e32 v25, v25, v28
	v_mul_f32_e32 v28, v24, v25
	v_cvt_f32_i32_e32 v25, v30
	v_cvt_f32_i32_e32 v24, v26
	v_pk_mul_f32 v[24:25], v[162:163], v[24:25] op_sel_hi:[0,1]
	v_pk_mul_f32 v[24:25], v[24:25], v[128:129]
	s_nop 0
	v_mul_f32_e32 v26, 0xbfb8aa3b, v25
	v_exp_f32_e32 v26, v26
	s_nop 0
	v_add_f32_e32 v26, 1.0, v26
	v_rcp_f32_e32 v26, v26
	s_nop 0
	v_mul_f32_e32 v25, v25, v26
	v_mul_f32_e32 v26, v24, v25
	v_cvt_f32_i32_e32 v25, v31
	v_cvt_f32_i32_e32 v24, v27
	v_pk_mul_f32 v[24:25], v[162:163], v[24:25] op_sel_hi:[0,1]
	v_pk_mul_f32 v[24:25], v[24:25], v[54:55]
	s_nop 0
	v_mul_f32_e32 v27, 0xbfb8aa3b, v25
	v_exp_f32_e32 v27, v27
	s_nop 0
	v_add_f32_e32 v27, 1.0, v27
	v_rcp_f32_e32 v27, v27
	s_nop 0
	v_mul_f32_e32 v25, v25, v27
	v_mul_f32_e32 v27, v24, v25
	v_cvt_f32_i32_e32 v25, v20
	v_cvt_f32_i32_e32 v24, v16
	v_cvt_f32_i32_e32 v20, v17
	v_pk_mul_f32 v[24:25], v[162:163], v[24:25] op_sel_hi:[0,1]
	v_pk_mul_f32 v[24:25], v[24:25], v[130:131]
	s_nop 0
	v_mul_f32_e32 v16, 0xbfb8aa3b, v25
	v_exp_f32_e32 v16, v16
	s_nop 0
	v_add_f32_e32 v16, 1.0, v16
	v_rcp_f32_e32 v16, v16
	s_nop 0
	v_mul_f32_e32 v16, v25, v16
; __device__ __forceinline__ unsigned cvt_pk_bf16(float lo, float hi) { unsigned r; asm volatile("v_cvt_pk_bf16_f32 %0, %1, %2" : "=v"(r) : "v"(lo), "v"(hi)); return r; }
; __device__ __forceinline__ float sigm(float x) { return __builtin_amdgcn_rcpf(1.f + __builtin_amdgcn_exp2f(-LOG2E * x)); }
;     __device__ __forceinline__ void operator()(const i32x4 (&acc)[2][2][4][2], const Unit& u, int wr, int wc, int fr, int fq) const {
;     ...
;         for (int ai = 0; ai < 2; ++ai)
; #pragma unroll
;             for (int m = 0; m < 4; ++m) {
;                 const int r = row0 + ai * HALF + m * 16; const float rs = sq[ai * 4 + m];
;                 float v[8];
; #pragma unroll
;                 for (int n = 0; n < 2; ++n)
; #pragma unroll
;                     for (int j = 0; j < 4; ++j) { const float g = (float)acc[ai][0][m][n][j] * rs * sg[n][j], up = (float)acc[ai][1][m][n][j] * rs * su[n][j]; v[n * 4 + j] = g * sigm(g) * up; }
;                 u32x4 w; w.x = cvt_pk_bf16(v[0], v[1]); w.y = cvt_pk_bf16(v[2], v[3]); w.z = cvt_pk_bf16(v[4], v[5]); w.w = cvt_pk_bf16(v[6], v[7]);
;                 *(u32x4*)(O + (size_t)r * FF + col0) = w;
	v_mul_f32_e32 v24, v24, v16
	v_pk_mul_f32 v[16:17], v[162:163], v[20:21] op_sel_hi:[0,1]
	v_pk_mul_f32 v[16:17], v[16:17], v[40:41]
	s_nop 0
	v_mul_f32_e32 v20, 0xbfb8aa3b, v17
	v_exp_f32_e32 v20, v20
	s_nop 0
	v_add_f32_e32 v20, 1.0, v20
	v_rcp_f32_e32 v20, v20
	s_nop 0
	v_mul_f32_e32 v17, v17, v20
	v_mul_f32_e32 v20, v16, v17
	v_cvt_f32_i32_e32 v17, v22
	v_cvt_f32_i32_e32 v16, v18
	v_add_u32_e32 v22, 0xa0, v156
	v_pk_mul_f32 v[16:17], v[162:163], v[16:17] op_sel_hi:[0,1]
	v_pk_mul_f32 v[16:17], v[16:17], v[120:121]
	s_nop 0
	v_mul_f32_e32 v18, 0xbfb8aa3b, v17
	v_exp_f32_e32 v18, v18
	s_nop 0
	v_add_f32_e32 v18, 1.0, v18
	v_rcp_f32_e32 v18, v18
	s_nop 0
	v_mul_f32_e32 v17, v17, v18
	v_mul_f32_e32 v21, v16, v17
	v_cvt_f32_i32_e32 v17, v23
	v_cvt_f32_i32_e32 v16, v19
	v_pk_mul_f32 v[16:17], v[162:163], v[16:17] op_sel_hi:[0,1]
	v_pk_mul_f32 v[16:17], v[16:17], v[42:43]
	s_nop 0
	v_mul_f32_e32 v18, 0xbfb8aa3b, v17
	v_exp_f32_e32 v18, v18
	s_nop 0
	v_add_f32_e32 v18, 1.0, v18
	v_rcp_f32_e32 v18, v18
	s_nop 0
	v_mul_f32_e32 v17, v17, v18
	v_mul_f32_e32 v19, v16, v17
	v_cvt_pk_bf16_f32 v16, v32, v28
	v_cvt_pk_bf16_f32 v17, v26, v27
	v_cvt_pk_bf16_f32 v18, v24, v20
	v_cvt_pk_bf16_f32 v19, v21, v19
	v_mad_i64_i32 v[20:21], s[26:27], v22, s46, v[122:123]
	v_lshl_add_u64 v[20:21], v[20:21], 0, v[124:125]
	global_store_dwordx4 v[20:21], v[16:19], off sc0 sc1
	s_nop 1
	v_cvt_f32_i32_e32 v17, v12
	v_cvt_f32_i32_e32 v16, v8
	v_cvt_f32_i32_e32 v12, v9
	v_pk_mul_f32 v[16:17], v[158:159], v[16:17] op_sel_hi:[0,1]
	v_pk_mul_f32 v[16:17], v[16:17], v[160:161]
	s_nop 0
	v_mul_f32_e32 v8, 0xbfb8aa3b, v17
	v_exp_f32_e32 v8, v8
	s_nop 0
	v_add_f32_e32 v8, 1.0, v8
	v_rcp_f32_e32 v8, v8
	s_nop 0
	v_mul_f32_e32 v8, v17, v8
	v_mul_f32_e32 v16, v16, v8
	v_pk_mul_f32 v[8:9], v[158:159], v[12:13] op_sel_hi:[0,1]
	v_pk_mul_f32 v[8:9], v[8:9], v[52:53]
	s_nop 0
	v_mul_f32_e32 v12, 0xbfb8aa3b, v9
	v_exp_f32_e32 v12, v12
	s_nop 0
	v_add_f32_e32 v12, 1.0, v12
	v_rcp_f32_e32 v12, v12
	s_nop 0
	v_mul_f32_e32 v9, v9, v12
	v_mul_f32_e32 v12, v8, v9
	v_cvt_f32_i32_e32 v9, v14
	v_cvt_f32_i32_e32 v8, v10
	v_pk_mul_f32 v[8:9], v[158:159], v[8:9] op_sel_hi:[0,1]
	v_pk_mul_f32 v[8:9], v[8:9], v[128:129]
	s_nop 0
	v_mul_f32_e32 v10, 0xbfb8aa3b, v9
	v_exp_f32_e32 v10, v10
	s_nop 0
	v_add_f32_e32 v10, 1.0, v10
	v_rcp_f32_e32 v10, v10
	s_nop 0
	v_mul_f32_e32 v9, v9, v10
	v_mul_f32_e32 v10, v8, v9
	v_cvt_f32_i32_e32 v9, v15
	v_cvt_f32_i32_e32 v8, v11
	v_pk_mul_f32 v[8:9], v[158:159], v[8:9] op_sel_hi:[0,1]
	v_pk_mul_f32 v[8:9], v[8:9], v[54:55]
	s_nop 0
	v_mul_f32_e32 v11, 0xbfb8aa3b, v9
	v_exp_f32_e32 v11, v11
	s_nop 0
	v_add_f32_e32 v11, 1.0, v11
	v_rcp_f32_e32 v11, v11
	s_nop 0
	v_mul_f32_e32 v9, v9, v11
	v_mul_f32_e32 v11, v8, v9
	v_cvt_f32_i32_e32 v9, v4
	v_cvt_f32_i32_e32 v8, v0
	v_cvt_f32_i32_e32 v4, v1
	v_pk_mul_f32 v[8:9], v[158:159], v[8:9] op_sel_hi:[0,1]
	v_pk_mul_f32 v[8:9], v[8:9], v[130:131]
	s_nop 0
	v_mul_f32_e32 v0, 0xbfb8aa3b, v9
	v_exp_f32_e32 v0, v0
	s_nop 0
	v_add_f32_e32 v0, 1.0, v0
	v_rcp_f32_e32 v0, v0
	s_nop 0
	v_mul_f32_e32 v0, v9, v0
	v_mul_f32_e32 v8, v8, v0
	v_pk_mul_f32 v[0:1], v[158:159], v[4:5] op_sel_hi:[0,1]
	v_pk_mul_f32 v[0:1], v[0:1], v[40:41]
	s_nop 0
	v_mul_f32_e32 v4, 0xbfb8aa3b, v1
	v_exp_f32_e32 v4, v4
	s_nop 0
	v_add_f32_e32 v4, 1.0, v4
	v_rcp_f32_e32 v4, v4
	s_nop 0
	v_mul_f32_e32 v1, v1, v4
	v_mul_f32_e32 v4, v0, v1
	v_cvt_f32_i32_e32 v1, v6
	v_cvt_f32_i32_e32 v0, v2
	v_add_u32_e32 v6, 0xb0, v156
	v_pk_mul_f32 v[0:1], v[158:159], v[0:1] op_sel_hi:[0,1]
	v_pk_mul_f32 v[0:1], v[0:1], v[120:121]
	s_nop 0
	v_mul_f32_e32 v2, 0xbfb8aa3b, v1
	v_exp_f32_e32 v2, v2
	s_nop 0
	v_add_f32_e32 v2, 1.0, v2
	v_rcp_f32_e32 v2, v2
	s_nop 0
	v_mul_f32_e32 v1, v1, v2
	v_mul_f32_e32 v5, v0, v1
	v_cvt_f32_i32_e32 v1, v7
	v_cvt_f32_i32_e32 v0, v3
	v_pk_mul_f32 v[0:1], v[158:159], v[0:1] op_sel_hi:[0,1]
	v_pk_mul_f32 v[0:1], v[0:1], v[42:43]
	s_nop 0
	v_mul_f32_e32 v2, 0xbfb8aa3b, v1
	v_exp_f32_e32 v2, v2
	s_nop 0
	v_add_f32_e32 v2, 1.0, v2
	v_rcp_f32_e32 v2, v2
	s_nop 0
	v_mul_f32_e32 v1, v1, v2
	v_mul_f32_e32 v3, v0, v1
	v_cvt_pk_bf16_f32 v0, v16, v12
	v_cvt_pk_bf16_f32 v1, v10, v11
	v_cvt_pk_bf16_f32 v2, v8, v4
	v_cvt_pk_bf16_f32 v3, v5, v3
	v_mad_i64_i32 v[4:5], s[26:27], v6, s46, v[122:123]
	v_lshl_add_u64 v[4:5], v[4:5], 0, v[124:125]
	s_mov_b64 s[26:27], s[20:21]
	global_store_dwordx4 v[4:5], v[0:3], off sc0 sc1
	s_cbranch_vccz .LBB0_112
	s_waitcnt vmcnt(0)
	s_cmpk_gt_u32 s33, 0xff
	s_cbranch_scc1 .LBB0_119
	s_barrier

; #define PG8_STAGE(bufoff, gbase, voff) do { _Pragma("unroll") for (int _i = 0; _i < 2; ++_i) \
;         __builtin_amdgcn_global_load_lds((const unsigned*)((const char*)(gbase) + (voff)[_i]), (LAS unsigned*)(lds + (bufoff) + ldsw + _i * 8192), 16, 0, 0); } while (0)
; #define PG8_LDA(dst, b, h) do { _Pragma("unroll") for (int m = 0; m < 4; ++m) _Pragma("unroll") for (int k = 0; k < 2; ++k) dst[m][k] = *(const LAS bf16x8*)(lds + PG8_SA(b, h) + aoff + m * 2048 + k * 1024); } while (0)
; #define PG8_LDB(dst, b, h) do { _Pragma("unroll") for (int n = 0; n < 2; ++n) _Pragma("unroll") for (int k = 0; k < 2; ++k) dst[n][k] = *(const LAS bf16x8*)(lds + PG8_SB(b, h) + boff + n * 2048 + k * 1024); } while (0)
; #define PG8_MMA(ai, bj, At, Bt) do { __builtin_amdgcn_s_setprio(1); _Pragma("unroll") for (int m = 0; m < 4; ++m) _Pragma("unroll") for (int n = 0; n < 2; ++n) _Pragma("unroll") for (int k = 0; k < 2; ++k) \
;         acc[ai][bj][m][n] = MmaOp<Epi::I8>::run(Bt[n][k], At[m][k], acc[ai][bj][m][n]); __builtin_amdgcn_s_setprio(0); } while (0)
; #define PG8_WAIT_L(n) asm volatile("s_waitcnt lgkmcnt(" #n ")" ::: "memory")
; #define PG8_BAR __builtin_amdgcn_s_barrier()
; #define PG8_SCHED __builtin_amdgcn_sched_barrier(0)
; template <class Epi, class Sched>
; __device__ __forceinline__ void gemm_phase(LAS unsigned char* lds, const Gemm g, const Sched& S, const Epi& E) {
;     ...
;             PG8_LDB(B0, 0, 0); PG8_SCHED; PG8_LDA(At, 0, 0); PG8_STAGE(PG8_SA(1, 1), a1 + hstepA, voffA);
;             PG8_WAIT_L(8); PG8_BAR; PG8_WAIT_L(0); PG8_MMA(0, 0, At, B0); PG8_BAR; PG8_SCHED;
;             PG8_LDB(B1, 0, 1); PG8_STAGE(PG8_SB(0, 0), b2, voffB);
;             PG8_BAR; PG8_WAIT_L(0); PG8_MMA(0, 1, At, B1); PG8_BAR;
;             PG8_LDA(At, 0, 1); PG8_STAGE(PG8_SA(0, 0), a2, voffA);
;             PG8_BAR; PG8_WAIT_L(0); PG8_MMA(1, 0, At, B0); PG8_BAR; PG8_SCHED;
.LBB0_238:
	ds_read_b128 v[128:131], v155
	ds_read_b128 v[144:147], v155 offset:1024
	ds_read_b128 v[148:151], v155 offset:2048
	ds_read_b128 v[158:161], v155 offset:3072
	s_add_u32 s18, s16, 0xffea8080
	s_addc_u32 s19, s17, -1
	s_cmpk_eq_i32 s49, 0x52
	s_cselect_b32 s21, s5, s19
	s_cselect_b32 s20, s4, s18
	s_cselect_b32 s19, s7, s48
	s_cselect_b32 s18, s6, s47
	v_lshl_add_u64 v[174:175], s[16:17], 0, v[136:137]
	s_add_i32 m0, s26, 0xc000
	ds_read_b128 v[162:165], v156
	ds_read_b128 v[166:169], v156 offset:1024
	ds_read_b128 v[170:173], v156 offset:2048
	ds_read_b128 v[178:181], v156 offset:3072
	ds_read_b128 v[182:185], v156 offset:4096
	ds_read_b128 v[186:189], v156 offset:5120
	ds_read_b128 v[190:193], v156 offset:6144
	ds_read_b128 v[194:197], v156 offset:7168
	global_load_lds_dwordx4 v[174:175], off
	v_lshl_add_u64 v[174:175], s[16:17], 0, v[138:139]
	s_add_i32 m0, s26, 0xe000
	s_nop 0
	global_load_lds_dwordx4 v[174:175], off
	s_waitcnt lgkmcnt(8)
	s_barrier
	s_waitcnt lgkmcnt(0)
	s_setprio 1
	v_mfma_f32_16x16x32_bf16 v[124:127], v[128:131], v[162:165], v[124:127]
	v_mfma_f32_16x16x32_bf16 v[120:123], v[148:151], v[162:165], v[120:123]
	v_mfma_f32_16x16x32_bf16 v[116:119], v[128:131], v[170:173], v[116:119]
	v_mfma_f32_16x16x32_bf16 v[112:115], v[148:151], v[170:173], v[112:115]
	v_mfma_f32_16x16x32_bf16 v[92:95], v[128:131], v[182:185], v[92:95]
	v_mfma_f32_16x16x32_bf16 v[88:91], v[148:151], v[182:185], v[88:91]
	v_mfma_f32_16x16x32_bf16 v[84:87], v[128:131], v[190:193], v[84:87]
	v_mfma_f32_16x16x32_bf16 v[76:79], v[148:151], v[190:193], v[76:79]
	v_mfma_f32_16x16x32_bf16 v[124:127], v[144:147], v[166:169], v[124:127]
	v_mfma_f32_16x16x32_bf16 v[120:123], v[158:161], v[166:169], v[120:123]
	v_mfma_f32_16x16x32_bf16 v[116:119], v[144:147], v[178:181], v[116:119]
	v_mfma_f32_16x16x32_bf16 v[112:115], v[158:161], v[178:181], v[112:115]
	v_mfma_f32_16x16x32_bf16 v[92:95], v[144:147], v[186:189], v[92:95]
	v_mfma_f32_16x16x32_bf16 v[88:91], v[158:161], v[186:189], v[88:91]
	v_mfma_f32_16x16x32_bf16 v[84:87], v[144:147], v[194:197], v[84:87]
	v_mfma_f32_16x16x32_bf16 v[76:79], v[158:161], v[194:197], v[76:79]
	s_setprio 0
	s_barrier
	s_add_i32 s50, s37, s23
	v_lshl_add_u64 v[174:175], s[18:19], 0, v[134:135]
	s_mov_b32 m0, s50
	ds_read_b128 v[198:201], v157
	ds_read_b128 v[202:205], v157 offset:1024
	ds_read_b128 v[206:209], v157 offset:2048
	ds_read_b128 v[210:213], v157 offset:3072
	global_load_lds_dwordx4 v[174:175], off
	v_lshl_add_u64 v[214:215], s[18:19], 0, v[132:133]
	s_add_i32 m0, s50, 0x2000
	s_nop 0
	global_load_lds_dwordx4 v[214:215], off
	s_barrier
	s_waitcnt lgkmcnt(0)
	s_setprio 1
	v_mfma_f32_16x16x32_bf16 v[108:111], v[198:201], v[162:165], v[108:111]
	v_mfma_f32_16x16x32_bf16 v[104:107], v[206:209], v[162:165], v[104:107]
	v_mfma_f32_16x16x32_bf16 v[100:103], v[198:201], v[170:173], v[100:103]
	v_mfma_f32_16x16x32_bf16 v[96:99], v[206:209], v[170:173], v[96:99]
	v_mfma_f32_16x16x32_bf16 v[80:83], v[198:201], v[182:185], v[80:83]
	v_mfma_f32_16x16x32_bf16 v[72:75], v[206:209], v[182:185], v[72:75]
	v_mfma_f32_16x16x32_bf16 v[68:71], v[198:201], v[190:193], v[68:71]
	v_mfma_f32_16x16x32_bf16 v[64:67], v[206:209], v[190:193], v[64:67]
	v_mfma_f32_16x16x32_bf16 v[108:111], v[202:205], v[166:169], v[108:111]
	v_mfma_f32_16x16x32_bf16 v[104:107], v[210:213], v[166:169], v[104:107]
	v_mfma_f32_16x16x32_bf16 v[100:103], v[202:205], v[178:181], v[100:103]
	v_mfma_f32_16x16x32_bf16 v[96:99], v[210:213], v[178:181], v[96:99]
	v_mfma_f32_16x16x32_bf16 v[80:83], v[202:205], v[186:189], v[80:83]
	v_mfma_f32_16x16x32_bf16 v[72:75], v[210:213], v[186:189], v[72:75]
	v_mfma_f32_16x16x32_bf16 v[68:71], v[202:205], v[194:197], v[68:71]
	v_mfma_f32_16x16x32_bf16 v[64:67], v[210:213], v[194:197], v[64:67]
	s_setprio 0
	s_mov_b32 m0, s26
	v_lshl_add_u64 v[216:217], s[20:21], 0, v[134:135]
	s_barrier
	ds_read_b128 v[162:165], v156 offset:16384
	ds_read_b128 v[166:169], v156 offset:17408
	ds_read_b128 v[170:173], v156 offset:18432
	ds_read_b128 v[178:181], v156 offset:19456
	ds_read_b128 v[182:185], v156 offset:20480
	ds_read_b128 v[186:189], v156 offset:21504
	ds_read_b128 v[190:193], v156 offset:22528
	ds_read_b128 v[194:197], v156 offset:23552
	global_load_lds_dwordx4 v[216:217], off
	v_lshl_add_u64 v[218:219], s[20:21], 0, v[132:133]
	s_mov_b32 m0, s27
	s_nop 0
	global_load_lds_dwordx4 v[218:219], off
	s_barrier
	s_waitcnt lgkmcnt(0)
	s_setprio 1
	v_mfma_f32_16x16x32_bf16 v[60:63], v[128:131], v[162:165], v[60:63]
	v_mfma_f32_16x16x32_bf16 v[56:59], v[148:151], v[162:165], v[56:59]
	v_mfma_f32_16x16x32_bf16 v[52:55], v[128:131], v[170:173], v[52:55]
	v_mfma_f32_16x16x32_bf16 v[44:47], v[148:151], v[170:173], v[44:47]
	v_mfma_f32_16x16x32_bf16 v[28:31], v[128:131], v[182:185], v[28:31]
	v_mfma_f32_16x16x32_bf16 v[24:27], v[148:151], v[182:185], v[24:27]
	v_mfma_f32_16x16x32_bf16 v[20:23], v[128:131], v[190:193], v[20:23]
	v_mfma_f32_16x16x32_bf16 v[12:15], v[148:151], v[190:193], v[12:15]
	v_mfma_f32_16x16x32_bf16 v[60:63], v[144:147], v[166:169], v[60:63]
	v_mfma_f32_16x16x32_bf16 v[56:59], v[158:161], v[166:169], v[56:59]
	v_mfma_f32_16x16x32_bf16 v[52:55], v[144:147], v[178:181], v[52:55]
	v_mfma_f32_16x16x32_bf16 v[44:47], v[158:161], v[178:181], v[44:47]
	v_mfma_f32_16x16x32_bf16 v[28:31], v[144:147], v[186:189], v[28:31]
	v_mfma_f32_16x16x32_bf16 v[24:27], v[158:161], v[186:189], v[24:27]
	v_mfma_f32_16x16x32_bf16 v[20:23], v[144:147], v[194:197], v[20:23]
	v_mfma_f32_16x16x32_bf16 v[12:15], v[158:161], v[194:197], v[12:15]
	s_setprio 0
	s_barrier
; #define PG8_STAGE(bufoff, gbase, voff) do { _Pragma("unroll") for (int _i = 0; _i < 2; ++_i) \
;         __builtin_amdgcn_global_load_lds((const unsigned*)((const char*)(gbase) + (voff)[_i]), (LAS unsigned*)(lds + (bufoff) + ldsw + _i * 8192), 16, 0, 0); } while (0)
; #define PG8_LDA(dst, b, h) do { _Pragma("unroll") for (int m = 0; m < 4; ++m) _Pragma("unroll") for (int k = 0; k < 2; ++k) dst[m][k] = *(const LAS bf16x8*)(lds + PG8_SA(b, h) + aoff + m * 2048 + k * 1024); } while (0)
; #define PG8_LDB(dst, b, h) do { _Pragma("unroll") for (int n = 0; n < 2; ++n) _Pragma("unroll") for (int k = 0; k < 2; ++k) dst[n][k] = *(const LAS bf16x8*)(lds + PG8_SB(b, h) + boff + n * 2048 + k * 1024); } while (0)
; #define PG8_MMA(ai, bj, At, Bt) do { __builtin_amdgcn_s_setprio(1); _Pragma("unroll") for (int m = 0; m < 4; ++m) _Pragma("unroll") for (int n = 0; n < 2; ++n) _Pragma("unroll") for (int k = 0; k < 2; ++k) \
;         acc[ai][bj][m][n] = MmaOp<Epi::I8>::run(Bt[n][k], At[m][k], acc[ai][bj][m][n]); __builtin_amdgcn_s_setprio(0); } while (0)
; #define PG8_WAIT_V(n) asm volatile("s_waitcnt vmcnt(" #n ")" ::: "memory")
; #define PG8_WAIT_L(n) asm volatile("s_waitcnt lgkmcnt(" #n ")" ::: "memory")
; #define PG8_BAR __builtin_amdgcn_s_barrier()
; #define PG8_SCHED __builtin_amdgcn_sched_barrier(0)
; template <class Epi, class Sched>
; __device__ __forceinline__ void gemm_phase(LAS unsigned char* lds, const Gemm g, const Sched& S, const Epi& E) {
;     ...
;             PG8_STAGE(PG8_SB(0, 1), b2 + hstepB, voffB);
;             PG8_WAIT_V(6); PG8_BAR; PG8_MMA(1, 1, At, B1); PG8_BAR;
;             PG8_LDB(B0, 1, 0); PG8_SCHED; PG8_LDA(At, 1, 0); PG8_STAGE(PG8_SA(0, 1), a2 + hstepA, voffA);
;             PG8_WAIT_L(8); PG8_BAR; PG8_WAIT_L(0); PG8_MMA(0, 0, At, B0); PG8_BAR; PG8_SCHED;
;             PG8_LDB(B1, 1, 1); PG8_STAGE(PG8_SB(1, 0), b3, voffB);
;             PG8_BAR; PG8_WAIT_L(0); PG8_MMA(0, 1, At, B1); PG8_BAR;
;             PG8_LDA(At, 1, 1); PG8_STAGE(PG8_SA(1, 0), a3, voffA);
;             PG8_BAR; PG8_WAIT_L(0); PG8_MMA(1, 0, At, B0); PG8_BAR; PG8_SCHED;
	s_add_u32 s50, s18, 0x158000
	s_addc_u32 s51, s19, 0
	s_add_i32 s53, s38, s23
	v_lshl_add_u64 v[128:129], s[50:51], 0, v[134:135]
	s_mov_b32 m0, s53
	s_nop 0
	global_load_lds_dwordx4 v[128:129], off
	v_lshl_add_u64 v[128:129], s[50:51], 0, v[132:133]
	s_add_i32 m0, s53, 0x2000
	s_nop 0
	global_load_lds_dwordx4 v[128:129], off
	s_waitcnt vmcnt(6)
	s_barrier
	s_setprio 1
	v_mfma_f32_16x16x32_bf16 v[48:51], v[198:201], v[162:165], v[48:51]
	v_mfma_f32_16x16x32_bf16 v[40:43], v[206:209], v[162:165], v[40:43]
	v_mfma_f32_16x16x32_bf16 v[36:39], v[198:201], v[170:173], v[36:39]
	v_mfma_f32_16x16x32_bf16 v[32:35], v[206:209], v[170:173], v[32:35]
	v_mfma_f32_16x16x32_bf16 v[16:19], v[198:201], v[182:185], v[16:19]
	v_mfma_f32_16x16x32_bf16 v[8:11], v[206:209], v[182:185], v[8:11]
	v_mfma_f32_16x16x32_bf16 v[4:7], v[198:201], v[190:193], v[4:7]
	v_mfma_f32_16x16x32_bf16 v[0:3], v[206:209], v[190:193], v[0:3]
	v_mfma_f32_16x16x32_bf16 v[48:51], v[202:205], v[166:169], v[48:51]
	v_mfma_f32_16x16x32_bf16 v[40:43], v[210:213], v[166:169], v[40:43]
	v_mfma_f32_16x16x32_bf16 v[36:39], v[202:205], v[178:181], v[36:39]
	v_mfma_f32_16x16x32_bf16 v[32:35], v[210:213], v[178:181], v[32:35]
	v_mfma_f32_16x16x32_bf16 v[16:19], v[202:205], v[186:189], v[16:19]
	v_mfma_f32_16x16x32_bf16 v[8:11], v[210:213], v[186:189], v[8:11]
	v_mfma_f32_16x16x32_bf16 v[4:7], v[202:205], v[194:197], v[4:7]
	v_mfma_f32_16x16x32_bf16 v[0:3], v[210:213], v[194:197], v[0:3]
	s_setprio 0
	s_add_i32 s50, 0, 0x18000
	v_add_u32_e32 v158, s50, v153
	s_barrier
	ds_read_b128 v[128:131], v158
	ds_read_b128 v[144:147], v158 offset:1024
	ds_read_b128 v[148:151], v158 offset:2048
	ds_read_b128 v[158:161], v158 offset:3072
	s_add_u32 s20, s20, 0x158000
	s_addc_u32 s21, s21, 0
	s_mov_b32 m0, s28
	v_lshl_add_u64 v[198:199], s[20:21], 0, v[134:135]
	ds_read_b128 v[162:165], v156 offset:32768
	ds_read_b128 v[166:169], v156 offset:33792
	ds_read_b128 v[170:173], v156 offset:34816
	ds_read_b128 v[178:181], v156 offset:35840
	ds_read_b128 v[182:185], v156 offset:36864
	ds_read_b128 v[186:189], v156 offset:37888
	ds_read_b128 v[190:193], v156 offset:38912
	ds_read_b128 v[194:197], v156 offset:39936
	global_load_lds_dwordx4 v[198:199], off
	v_lshl_add_u64 v[198:199], s[20:21], 0, v[132:133]
	s_mov_b32 m0, s29
	s_nop 0
	global_load_lds_dwordx4 v[198:199], off
	s_waitcnt lgkmcnt(8)
	s_barrier
	s_waitcnt lgkmcnt(0)
	s_setprio 1
	v_mfma_f32_16x16x32_bf16 v[124:127], v[128:131], v[162:165], v[124:127]
	v_mfma_f32_16x16x32_bf16 v[120:123], v[148:151], v[162:165], v[120:123]
	v_mfma_f32_16x16x32_bf16 v[116:119], v[128:131], v[170:173], v[116:119]
	v_mfma_f32_16x16x32_bf16 v[112:115], v[148:151], v[170:173], v[112:115]
	v_mfma_f32_16x16x32_bf16 v[92:95], v[128:131], v[182:185], v[92:95]
	v_mfma_f32_16x16x32_bf16 v[88:91], v[148:151], v[182:185], v[88:91]
	v_mfma_f32_16x16x32_bf16 v[84:87], v[128:131], v[190:193], v[84:87]
	v_mfma_f32_16x16x32_bf16 v[76:79], v[148:151], v[190:193], v[76:79]
	v_mfma_f32_16x16x32_bf16 v[124:127], v[144:147], v[166:169], v[124:127]
	v_mfma_f32_16x16x32_bf16 v[120:123], v[158:161], v[166:169], v[120:123]
	v_mfma_f32_16x16x32_bf16 v[116:119], v[144:147], v[178:181], v[116:119]
	v_mfma_f32_16x16x32_bf16 v[112:115], v[158:161], v[178:181], v[112:115]
	v_mfma_f32_16x16x32_bf16 v[92:95], v[144:147], v[186:189], v[92:95]
	v_mfma_f32_16x16x32_bf16 v[88:91], v[158:161], v[186:189], v[88:91]
	v_mfma_f32_16x16x32_bf16 v[84:87], v[144:147], v[194:197], v[84:87]
	v_mfma_f32_16x16x32_bf16 v[76:79], v[158:161], v[194:197], v[76:79]
	s_setprio 0
	s_barrier
	s_add_i32 s20, 0, 0x1c000
	s_add_i32 s21, s50, s23
	v_add_u32_e32 v210, s20, v153
	v_lshl_add_u64 v[174:175], v[174:175], 0, s[12:13]
	s_mov_b32 m0, s21
	ds_read_b128 v[198:201], v210
	ds_read_b128 v[202:205], v210 offset:1024
	ds_read_b128 v[206:209], v210 offset:2048
	ds_read_b128 v[210:213], v210 offset:3072
	global_load_lds_dwordx4 v[174:175], off
	v_lshl_add_u64 v[174:175], v[214:215], 0, s[12:13]
	s_add_i32 m0, s21, 0x2000
	s_nop 0
	global_load_lds_dwordx4 v[174:175], off
	s_barrier
	s_waitcnt lgkmcnt(0)
	s_setprio 1
	v_mfma_f32_16x16x32_bf16 v[108:111], v[198:201], v[162:165], v[108:111]
	v_mfma_f32_16x16x32_bf16 v[104:107], v[206:209], v[162:165], v[104:107]
	v_mfma_f32_16x16x32_bf16 v[100:103], v[198:201], v[170:173], v[100:103]
	v_mfma_f32_16x16x32_bf16 v[96:99], v[206:209], v[170:173], v[96:99]
	v_mfma_f32_16x16x32_bf16 v[80:83], v[198:201], v[182:185], v[80:83]
	v_mfma_f32_16x16x32_bf16 v[72:75], v[206:209], v[182:185], v[72:75]
	v_mfma_f32_16x16x32_bf16 v[68:71], v[198:201], v[190:193], v[68:71]
	v_mfma_f32_16x16x32_bf16 v[64:67], v[206:209], v[190:193], v[64:67]
	v_mfma_f32_16x16x32_bf16 v[108:111], v[202:205], v[166:169], v[108:111]
	v_mfma_f32_16x16x32_bf16 v[104:107], v[210:213], v[166:169], v[104:107]
	v_mfma_f32_16x16x32_bf16 v[100:103], v[202:205], v[178:181], v[100:103]
	v_mfma_f32_16x16x32_bf16 v[96:99], v[210:213], v[178:181], v[96:99]
	v_mfma_f32_16x16x32_bf16 v[80:83], v[202:205], v[186:189], v[80:83]
	v_mfma_f32_16x16x32_bf16 v[72:75], v[210:213], v[186:189], v[72:75]
	v_mfma_f32_16x16x32_bf16 v[68:71], v[202:205], v[194:197], v[68:71]
	v_mfma_f32_16x16x32_bf16 v[64:67], v[210:213], v[194:197], v[64:67]
	s_setprio 0
	s_mov_b32 m0, s31
	v_lshl_add_u64 v[174:175], v[216:217], 0, s[12:13]
	s_barrier
	ds_read_b128 v[162:165], v156 offset:49152
	ds_read_b128 v[166:169], v156 offset:50176
	ds_read_b128 v[170:173], v156 offset:51200
	ds_read_b128 v[178:181], v156 offset:52224
	ds_read_b128 v[182:185], v156 offset:53248
	ds_read_b128 v[186:189], v156 offset:54272
	ds_read_b128 v[190:193], v156 offset:55296
	ds_read_b128 v[194:197], v156 offset:56320
	global_load_lds_dwordx4 v[174:175], off
	v_lshl_add_u64 v[174:175], v[218:219], 0, s[12:13]
	s_mov_b32 m0, s33
	s_nop 0
	global_load_lds_dwordx4 v[174:175], off
	s_barrier
; #define PG8_STAGE(bufoff, gbase, voff) do { _Pragma("unroll") for (int _i = 0; _i < 2; ++_i) \
;         __builtin_amdgcn_global_load_lds((const unsigned*)((const char*)(gbase) + (voff)[_i]), (LAS unsigned*)(lds + (bufoff) + ldsw + _i * 8192), 16, 0, 0); } while (0)
; #define PG8_MMA(ai, bj, At, Bt) do { __builtin_amdgcn_s_setprio(1); _Pragma("unroll") for (int m = 0; m < 4; ++m) _Pragma("unroll") for (int n = 0; n < 2; ++n) _Pragma("unroll") for (int k = 0; k < 2; ++k) \
;         acc[ai][bj][m][n] = MmaOp<Epi::I8>::run(Bt[n][k], At[m][k], acc[ai][bj][m][n]); __builtin_amdgcn_s_setprio(0); } while (0)
; #define PG8_WAIT_V(n) asm volatile("s_waitcnt vmcnt(" #n ")" ::: "memory")
; #define PG8_WAIT_L(n) asm volatile("s_waitcnt lgkmcnt(" #n ")" ::: "memory")
; #define PG8_BAR __builtin_amdgcn_s_barrier()
; #define PG8_SCHED __builtin_amdgcn_sched_barrier(0)
;     __device__ __forceinline__ void operator()(const f32x4 (&acc)[2][2][4][2], const Unit& u, int wr, int wc, int fr, int fq) const {
;         const int row0 = u.pm * BM + wr * 64 + fr, col0 = u.pn * BM + wc * 32 + 4 * fq;
;         const float* base = ((u.pm < MP / BM) ? base_lo : base_hi - (size_t)MP * DM) + (size_t)row0 * DM + col0;
;         f32x4 b[2][2], nb[2][2];
; #pragma unroll
;         for (int bj = 0; bj < 2; ++bj)
; #pragma unroll
;             for (int n = 0; n < 2; ++n) b[bj][n] = *(const f32x4*)(base + bj * HALF + n * 16);
; #pragma unroll
;         for (int g = 0; g < 8; ++g) {
;             const int ai = g >> 2, m = g & 3;
;             const int r = row0 + ai * HALF + m * 16; const size_t off = (size_t)r * DM + col0; float s = 0.f;
;             if (g < 7) { const float* nrow = base + (size_t)(((g + 1) >> 2) * HALF + ((g + 1) & 3) * 16) * DM;
; #pragma unroll
;                 for (int bj = 0; bj < 2; ++bj)
; #pragma unroll
;                     for (int n = 0; n < 2; ++n) nb[bj][n] = *(const f32x4*)(nrow + bj * HALF + n * 16); }
; template <class Epi, class Sched>
; __device__ __forceinline__ void gemm_phase(LAS unsigned char* lds, const Gemm g, const Sched& S, const Epi& E) {
;     ...
;             PG8_BAR; PG8_WAIT_L(0); PG8_MMA(1, 0, At, B0); PG8_BAR; PG8_SCHED;
;             PG8_STAGE(PG8_SB(1, 1), b3 + hstepB, voffB);
;             PG8_WAIT_V(6); PG8_BAR; PG8_MMA(1, 1, At, B1); PG8_BAR;
;         }
	s_waitcnt lgkmcnt(0)
	s_setprio 1
	v_mfma_f32_16x16x32_bf16 v[60:63], v[128:131], v[162:165], v[60:63]
	v_mfma_f32_16x16x32_bf16 v[56:59], v[148:151], v[162:165], v[56:59]
	v_mfma_f32_16x16x32_bf16 v[52:55], v[128:131], v[170:173], v[52:55]
	v_mfma_f32_16x16x32_bf16 v[44:47], v[148:151], v[170:173], v[44:47]
	v_mfma_f32_16x16x32_bf16 v[28:31], v[128:131], v[182:185], v[28:31]
	v_mfma_f32_16x16x32_bf16 v[24:27], v[148:151], v[182:185], v[24:27]
	v_mfma_f32_16x16x32_bf16 v[20:23], v[128:131], v[190:193], v[20:23]
	v_mfma_f32_16x16x32_bf16 v[12:15], v[148:151], v[190:193], v[12:15]
	v_mfma_f32_16x16x32_bf16 v[60:63], v[144:147], v[166:169], v[60:63]
	v_mfma_f32_16x16x32_bf16 v[56:59], v[158:161], v[166:169], v[56:59]
	v_mfma_f32_16x16x32_bf16 v[52:55], v[144:147], v[178:181], v[52:55]
	v_mfma_f32_16x16x32_bf16 v[44:47], v[158:161], v[178:181], v[44:47]
	v_mfma_f32_16x16x32_bf16 v[28:31], v[144:147], v[186:189], v[28:31]
	v_mfma_f32_16x16x32_bf16 v[24:27], v[158:161], v[186:189], v[24:27]
	v_mfma_f32_16x16x32_bf16 v[20:23], v[144:147], v[194:197], v[20:23]
	v_mfma_f32_16x16x32_bf16 v[12:15], v[158:161], v[194:197], v[12:15]
	s_setprio 0
	s_barrier
	s_add_u32 s18, s18, 0x158080
	s_addc_u32 s19, s19, 0
	s_add_i32 s20, s20, s23
	v_lshl_add_u64 v[128:129], s[18:19], 0, v[134:135]
	s_mov_b32 m0, s20
	s_nop 0
	global_load_lds_dwordx4 v[128:129], off
	v_lshl_add_u64 v[128:129], s[18:19], 0, v[132:133]
	s_add_i32 m0, s20, 0x2000
	s_nop 0
	global_load_lds_dwordx4 v[128:129], off
	s_waitcnt vmcnt(6)
	s_barrier
	s_setprio 1
	v_mfma_f32_16x16x32_bf16 v[48:51], v[198:201], v[162:165], v[48:51]
	v_mfma_f32_16x16x32_bf16 v[40:43], v[206:209], v[162:165], v[40:43]
	v_mfma_f32_16x16x32_bf16 v[36:39], v[198:201], v[170:173], v[36:39]
	v_mfma_f32_16x16x32_bf16 v[32:35], v[206:209], v[170:173], v[32:35]
	v_mfma_f32_16x16x32_bf16 v[16:19], v[198:201], v[182:185], v[16:19]
	v_mfma_f32_16x16x32_bf16 v[8:11], v[206:209], v[182:185], v[8:11]
	v_mfma_f32_16x16x32_bf16 v[4:7], v[198:201], v[190:193], v[4:7]
	v_mfma_f32_16x16x32_bf16 v[0:3], v[206:209], v[190:193], v[0:3]
	v_mfma_f32_16x16x32_bf16 v[48:51], v[202:205], v[166:169], v[48:51]
	v_mfma_f32_16x16x32_bf16 v[40:43], v[210:213], v[166:169], v[40:43]
	v_mfma_f32_16x16x32_bf16 v[36:39], v[202:205], v[178:181], v[36:39]
	v_mfma_f32_16x16x32_bf16 v[32:35], v[210:213], v[178:181], v[32:35]
	v_mfma_f32_16x16x32_bf16 v[16:19], v[202:205], v[186:189], v[16:19]
	v_mfma_f32_16x16x32_bf16 v[8:11], v[210:213], v[186:189], v[8:11]
	v_mfma_f32_16x16x32_bf16 v[4:7], v[202:205], v[194:197], v[4:7]
	v_mfma_f32_16x16x32_bf16 v[0:3], v[210:213], v[194:197], v[0:3]
	s_setprio 0
	s_add_i32 s49, s49, 2
	s_add_u32 s16, s16, 0x100
	s_addc_u32 s17, s17, 0
	s_add_u32 s47, s47, 0x100
	s_addc_u32 s48, s48, 0
	s_cmpk_gt_u32 s49, 0x53
	s_barrier
	s_cbranch_scc0 .LBB0_238
	v_readlane_b32 s56, v239, 2
	v_lshl_add_u32 v146, s45, 8, v152
	v_readlane_b32 s57, v239, 3
	s_cmp_lt_i32 s45, 32
	s_mov_b64 s[48:49], s[56:57]
	v_ashrrev_i32_e32 v147, 31, v146
	v_lshl_or_b32 v144, s46, 8, v154
	s_cselect_b32 s17, s49, s36
	s_cselect_b32 s16, s48, s35
	v_lshlrev_b64 v[128:129], 13, v[146:147]
	v_lshl_add_u64 v[128:129], s[16:17], 0, v[128:129]
	v_ashrrev_i32_e32 v145, 31, v144
	v_lshl_add_u64 v[148:149], v[144:145], 2, v[128:129]
	global_load_dwordx4 v[158:161], v[148:149], off
	global_load_dwordx4 v[162:165], v[148:149], off offset:64
	global_load_dwordx4 v[166:169], v[148:149], off offset:512
	global_load_dwordx4 v[170:173], v[148:149], off offset:576
	s_mov_b32 s16, 0x20000
	v_add_co_u32_e32 v128, vcc, s16, v148
	v_lshlrev_b64 v[150:151], 11, v[146:147]
	s_nop 0
	v_addc_co_u32_e32 v129, vcc, 0, v149, vcc
	global_load_dwordx4 v[178:181], v[128:129], off
	global_load_dwordx4 v[182:185], v[128:129], off offset:64
	global_load_dwordx4 v[186:189], v[128:129], off offset:512
	s_nop 0
	global_load_dwordx4 v[128:131], v[128:129], off offset:576
	v_readlane_b32 s88, v239, 27
	v_lshl_add_u64 v[150:151], v[150:151], 0, v[144:145]
	v_readlane_b32 s92, v239, 31
	v_readlane_b32 s93, v239, 32
	v_readlane_b32 s18, v239, 25
	v_readlane_b32 s19, v239, 26
	v_lshl_add_u64 v[190:191], v[150:151], 2, s[92:93]
	s_mov_b32 s16, 0x40000
	v_lshl_add_u64 v[192:193], v[150:151], 1, s[18:19]
	v_add_co_u32_e32 v194, vcc, s16, v148
	v_or_b32_e32 v174, 16, v146
	s_nop 0
	v_addc_co_u32_e32 v195, vcc, 0, v149, vcc
	v_ashrrev_i32_e32 v175, 31, v174
	v_lshlrev_b64 v[174:175], 11, v[174:175]
	v_lshl_add_u64 v[174:175], v[174:175], 0, v[144:145]
	v_lshl_add_u64 v[196:197], v[174:175], 2, s[92:93]
	v_lshl_add_u64 v[174:175], v[174:175], 1, s[18:19]
	s_mov_b32 s17, 0x60000
	v_add_co_u32_e32 v198, vcc, s17, v148
	s_mov_b32 s46, s43
	s_nop 0
	v_addc_co_u32_e32 v199, vcc, 0, v149, vcc
	s_mov_b32 s45, s44
	s_mov_b64 s[16:17], s[4:5]
	v_readlane_b32 s58, v239, 4
	v_readlane_b32 s59, v239, 5
	v_readlane_b32 s60, v239, 6
	v_readlane_b32 s61, v239, 7
	v_readlane_b32 s62, v239, 8
	v_readlane_b32 s63, v239, 9
	v_readlane_b32 s64, v239, 10
	v_readlane_b32 s65, v239, 11
	v_readlane_b32 s66, v239, 12
	v_readlane_b32 s67, v239, 13
	v_readlane_b32 s68, v239, 14
	v_readlane_b32 s69, v239, 15
	v_readlane_b32 s70, v239, 16
	v_readlane_b32 s71, v239, 17
	v_readlane_b32 s89, v239, 28
	v_readlane_b32 s90, v239, 29
	v_readlane_b32 s91, v239, 30
	v_readlane_b32 s94, v239, 33
	v_readlane_b32 s95, v239, 34
	s_waitcnt vmcnt(0)
; __device__ __forceinline__ unsigned cvt_pk_bf16(float lo, float hi) { unsigned r; asm volatile("v_cvt_pk_bf16_f32 %0, %1, %2" : "=v"(r) : "v"(lo), "v"(hi)); return r; }
;     __device__ __forceinline__ void operator()(const f32x4 (&acc)[2][2][4][2], const Unit& u, int wr, int wc, int fr, int fq) const {
;     ...
;         for (int g = 0; g < 8; ++g) {
;             const int ai = g >> 2, m = g & 3;
;             const int r = row0 + ai * HALF + m * 16; const size_t off = (size_t)r * DM + col0; float s = 0.f;
;             if (g < 7) { const float* nrow = base + (size_t)(((g + 1) >> 2) * HALF + ((g + 1) & 3) * 16) * DM;
; #pragma unroll
;                 for (int bj = 0; bj < 2; ++bj)
; #pragma unroll
;                     for (int n = 0; n < 2; ++n) nb[bj][n] = *(const f32x4*)(nrow + bj * HALF + n * 16); }
; #pragma unroll
;             for (int bj = 0; bj < 2; ++bj)
; #pragma unroll
;                 for (int n = 0; n < 2; ++n) {
;                     const f32x4 o = b[bj][n] + acc[ai][bj][m][n] * alpha;
;                     *(f32x4*)(out + off + bj * HALF + n * 16) = o;
;                     if (WITH_SSQ) s += (o[0] * o[0] + o[1] * o[1]) + (o[2] * o[2] + o[3] * o[3]);
;                     if (WITH_HB) { u32x2 w; w.x = cvt_pk_bf16(o[0], o[1]); w.y = cvt_pk_bf16(o[2], o[3]); *(u32x2*)(hb + off + bj * HALF + n * 16) = w; }
;                 }
;             if (WITH_SSQ) { s += __shfl_xor(s, 16); s += __shfl_xor(s, 32); if (fq == 0) atomicAdd(ssq + r, s); }
;             asm volatile("" ::: "memory");
; #pragma unroll
;             for (int bj = 0; bj < 2; ++bj)
; #pragma unroll
;                 for (int n = 0; n < 2; ++n) b[bj][n] = nb[bj][n];
	v_pk_fma_f32 v[126:127], v[126:127], 0.5, v[160:161] op_sel_hi:[1,0,1]
	v_pk_fma_f32 v[124:125], v[124:125], 0.5, v[158:159] op_sel_hi:[1,0,1]
	v_pk_fma_f32 v[120:121], v[120:121], 0.5, v[162:163] op_sel_hi:[1,0,1]
	global_store_dwordx4 v[190:191], v[124:127], off sc0 sc1
	v_pk_fma_f32 v[122:123], v[122:123], 0.5, v[164:165] op_sel_hi:[1,0,1]
	v_pk_fma_f32 v[108:109], v[108:109], 0.5, v[166:167] op_sel_hi:[1,0,1]
	v_cvt_pk_bf16_f32 v124, v124, v125
	v_cvt_pk_bf16_f32 v125, v126, v127
	global_store_dwordx2 v[192:193], v[124:125], off sc0 sc1
	global_store_dwordx4 v[190:191], v[120:123], off offset:64 sc0 sc1
	v_pk_fma_f32 v[110:111], v[110:111], 0.5, v[168:169] op_sel_hi:[1,0,1]
	v_pk_fma_f32 v[104:105], v[104:105], 0.5, v[170:171] op_sel_hi:[1,0,1]
	v_cvt_pk_bf16_f32 v120, v120, v121
	v_cvt_pk_bf16_f32 v121, v122, v123
	global_store_dwordx2 v[192:193], v[120:121], off offset:32 sc0 sc1
	global_store_dwordx4 v[190:191], v[108:111], off offset:512 sc0 sc1
	v_pk_fma_f32 v[106:107], v[106:107], 0.5, v[172:173] op_sel_hi:[1,0,1]
	v_pk_fma_f32 v[118:119], v[118:119], 0.5, v[180:181] op_sel_hi:[1,0,1]
	v_cvt_pk_bf16_f32 v108, v108, v109
	v_cvt_pk_bf16_f32 v109, v110, v111
	global_store_dwordx2 v[192:193], v[108:109], off offset:256 sc0 sc1
	global_store_dwordx4 v[190:191], v[104:107], off offset:576 sc0 sc1
	v_pk_fma_f32 v[116:117], v[116:117], 0.5, v[178:179] op_sel_hi:[1,0,1]
	v_pk_fma_f32 v[112:113], v[112:113], 0.5, v[182:183] op_sel_hi:[1,0,1]
	v_cvt_pk_bf16_f32 v104, v104, v105
	v_cvt_pk_bf16_f32 v105, v106, v107
	global_store_dwordx2 v[192:193], v[104:105], off offset:288 sc0 sc1
	global_load_dwordx4 v[104:107], v[194:195], off
	global_load_dwordx4 v[108:111], v[194:195], off offset:64
	global_load_dwordx4 v[120:123], v[194:195], off offset:512
	global_load_dwordx4 v[124:127], v[194:195], off offset:576
	v_pk_fma_f32 v[114:115], v[114:115], 0.5, v[184:185] op_sel_hi:[1,0,1]
	global_store_dwordx4 v[196:197], v[116:119], off sc0 sc1
	v_pk_fma_f32 v[100:101], v[100:101], 0.5, v[186:187] op_sel_hi:[1,0,1]
	v_pk_fma_f32 v[102:103], v[102:103], 0.5, v[188:189] op_sel_hi:[1,0,1]
	v_cvt_pk_bf16_f32 v116, v116, v117
	v_cvt_pk_bf16_f32 v117, v118, v119
	global_store_dwordx2 v[174:175], v[116:117], off sc0 sc1
	global_store_dwordx4 v[196:197], v[112:115], off offset:64 sc0 sc1
	v_pk_fma_f32 v[96:97], v[96:97], 0.5, v[128:129] op_sel_hi:[1,0,1]
	v_pk_fma_f32 v[98:99], v[98:99], 0.5, v[130:131] op_sel_hi:[1,0,1]
	v_cvt_pk_bf16_f32 v112, v112, v113
	v_cvt_pk_bf16_f32 v113, v114, v115
	global_store_dwordx2 v[174:175], v[112:113], off offset:32 sc0 sc1
	global_store_dwordx4 v[196:197], v[100:103], off offset:512 sc0 sc1
	v_or_b32_e32 v128, 32, v146
	v_ashrrev_i32_e32 v129, 31, v128
	v_cvt_pk_bf16_f32 v100, v100, v101
	v_cvt_pk_bf16_f32 v101, v102, v103
	global_store_dwordx2 v[174:175], v[100:101], off offset:256 sc0 sc1
	global_store_dwordx4 v[196:197], v[96:99], off offset:576 sc0 sc1
	v_lshlrev_b64 v[128:129], 11, v[128:129]
	v_lshl_add_u64 v[128:129], v[128:129], 0, v[144:145]
	v_cvt_pk_bf16_f32 v96, v96, v97
	v_cvt_pk_bf16_f32 v97, v98, v99
	global_store_dwordx2 v[174:175], v[96:97], off offset:288 sc0 sc1
	global_load_dwordx4 v[96:99], v[198:199], off
	global_load_dwordx4 v[100:103], v[198:199], off offset:64
	global_load_dwordx4 v[112:115], v[198:199], off offset:512
	global_load_dwordx4 v[116:119], v[198:199], off offset:576
	v_lshl_add_u64 v[158:159], v[128:129], 2, s[92:93]
	v_lshl_add_u64 v[128:129], v[128:129], 1, s[18:19]
	v_add_co_u32_e32 v160, vcc, s39, v148
	v_or_b32_e32 v130, 48, v146
	s_nop 0
	v_addc_co_u32_e32 v161, vcc, 0, v149, vcc
	v_ashrrev_i32_e32 v131, 31, v130
	v_lshlrev_b64 v[130:131], 11, v[130:131]
	v_lshl_add_u64 v[130:131], v[130:131], 0, v[144:145]
	v_lshl_add_u64 v[162:163], v[130:131], 2, s[92:93]
	v_lshl_add_u64 v[130:131], v[130:131], 1, s[18:19]
	v_add_co_u32_e32 v164, vcc, s40, v148
	s_waitcnt vmcnt(0)
	v_pk_fma_f32 v[94:95], v[94:95], 0.5, v[106:107] op_sel_hi:[1,0,1]
	v_pk_fma_f32 v[92:93], v[92:93], 0.5, v[104:105] op_sel_hi:[1,0,1]
	v_pk_fma_f32 v[88:89], v[88:89], 0.5, v[108:109] op_sel_hi:[1,0,1]
	global_store_dwordx4 v[158:159], v[92:95], off sc0 sc1
	v_pk_fma_f32 v[90:91], v[90:91], 0.5, v[110:111] op_sel_hi:[1,0,1]
	v_pk_fma_f32 v[80:81], v[80:81], 0.5, v[120:121] op_sel_hi:[1,0,1]
	v_cvt_pk_bf16_f32 v92, v92, v93
	v_cvt_pk_bf16_f32 v93, v94, v95
	global_store_dwordx2 v[128:129], v[92:93], off sc0 sc1
	global_store_dwordx4 v[158:159], v[88:91], off offset:64 sc0 sc1
	v_pk_fma_f32 v[82:83], v[82:83], 0.5, v[122:123] op_sel_hi:[1,0,1]
	v_pk_fma_f32 v[72:73], v[72:73], 0.5, v[124:125] op_sel_hi:[1,0,1]
	v_cvt_pk_bf16_f32 v88, v88, v89
	v_cvt_pk_bf16_f32 v89, v90, v91
	global_store_dwordx2 v[128:129], v[88:89], off offset:32 sc0 sc1
	global_store_dwordx4 v[158:159], v[80:83], off offset:512 sc0 sc1
	v_pk_fma_f32 v[74:75], v[74:75], 0.5, v[126:127] op_sel_hi:[1,0,1]
	v_addc_co_u32_e32 v165, vcc, 0, v149, vcc
	v_cvt_pk_bf16_f32 v80, v80, v81
	v_cvt_pk_bf16_f32 v81, v82, v83
	global_store_dwordx2 v[128:129], v[80:81], off offset:256 sc0 sc1
	global_store_dwordx4 v[158:159], v[72:75], off offset:576 sc0 sc1
	v_pk_fma_f32 v[78:79], v[78:79], 0.5, v[102:103] op_sel_hi:[1,0,1]
	s_nop 0
	v_cvt_pk_bf16_f32 v72, v72, v73
	v_cvt_pk_bf16_f32 v73, v74, v75
	global_store_dwordx2 v[128:129], v[72:73], off offset:288 sc0 sc1
	global_load_dwordx4 v[80:83], v[160:161], off
	v_pk_fma_f32 v[74:75], v[86:87], 0.5, v[98:99] op_sel_hi:[1,0,1]
	v_pk_fma_f32 v[72:73], v[84:85], 0.5, v[96:97] op_sel_hi:[1,0,1]
	global_load_dwordx4 v[84:87], v[160:161], off offset:64
	global_load_dwordx4 v[88:91], v[160:161], off offset:512
; __device__ __forceinline__ unsigned cvt_pk_bf16(float lo, float hi) { unsigned r; asm volatile("v_cvt_pk_bf16_f32 %0, %1, %2" : "=v"(r) : "v"(lo), "v"(hi)); return r; }
;     __device__ __forceinline__ void operator()(const f32x4 (&acc)[2][2][4][2], const Unit& u, int wr, int wc, int fr, int fq) const {
;     ...
;         for (int g = 0; g < 8; ++g) {
;             const int ai = g >> 2, m = g & 3;
;             const int r = row0 + ai * HALF + m * 16; const size_t off = (size_t)r * DM + col0; float s = 0.f;
;             if (g < 7) { const float* nrow = base + (size_t)(((g + 1) >> 2) * HALF + ((g + 1) & 3) * 16) * DM;
; #pragma unroll
;                 for (int bj = 0; bj < 2; ++bj)
; #pragma unroll
;                     for (int n = 0; n < 2; ++n) nb[bj][n] = *(const f32x4*)(nrow + bj * HALF + n * 16); }
; #pragma unroll
;             for (int bj = 0; bj < 2; ++bj)
; #pragma unroll
;                 for (int n = 0; n < 2; ++n) {
;                     const f32x4 o = b[bj][n] + acc[ai][bj][m][n] * alpha;
;                     *(f32x4*)(out + off + bj * HALF + n * 16) = o;
;                     if (WITH_SSQ) s += (o[0] * o[0] + o[1] * o[1]) + (o[2] * o[2] + o[3] * o[3]);
;                     if (WITH_HB) { u32x2 w; w.x = cvt_pk_bf16(o[0], o[1]); w.y = cvt_pk_bf16(o[2], o[3]); *(u32x2*)(hb + off + bj * HALF + n * 16) = w; }
;                 }
;             if (WITH_SSQ) { s += __shfl_xor(s, 16); s += __shfl_xor(s, 32); if (fq == 0) atomicAdd(ssq + r, s); }
;             asm volatile("" ::: "memory");
; #pragma unroll
;             for (int bj = 0; bj < 2; ++bj)
; #pragma unroll
;                 for (int n = 0; n < 2; ++n) b[bj][n] = nb[bj][n];
	global_load_dwordx4 v[92:95], v[160:161], off offset:576
	v_pk_fma_f32 v[76:77], v[76:77], 0.5, v[100:101] op_sel_hi:[1,0,1]
	global_store_dwordx4 v[162:163], v[72:75], off sc0 sc1
	v_pk_fma_f32 v[68:69], v[68:69], 0.5, v[112:113] op_sel_hi:[1,0,1]
	v_pk_fma_f32 v[70:71], v[70:71], 0.5, v[114:115] op_sel_hi:[1,0,1]
	v_cvt_pk_bf16_f32 v72, v72, v73
	v_cvt_pk_bf16_f32 v73, v74, v75
	global_store_dwordx2 v[130:131], v[72:73], off sc0 sc1
	global_store_dwordx4 v[162:163], v[76:79], off offset:64 sc0 sc1
	v_cvt_pk_bf16_f32 v72, v76, v77
	v_cvt_pk_bf16_f32 v73, v78, v79
	v_pk_fma_f32 v[64:65], v[64:65], 0.5, v[116:117] op_sel_hi:[1,0,1]
	global_store_dwordx2 v[130:131], v[72:73], off offset:32 sc0 sc1
	global_store_dwordx4 v[162:163], v[68:71], off offset:512 sc0 sc1
	v_pk_fma_f32 v[66:67], v[66:67], 0.5, v[118:119] op_sel_hi:[1,0,1]
	v_lshl_add_u64 v[98:99], v[150:151], 0, s[14:15]
	v_cvt_pk_bf16_f32 v68, v68, v69
	v_cvt_pk_bf16_f32 v69, v70, v71
	global_store_dwordx2 v[130:131], v[68:69], off offset:256 sc0 sc1
	global_store_dwordx4 v[162:163], v[64:67], off offset:576 sc0 sc1
	v_lshl_add_u64 v[100:101], v[98:99], 2, s[92:93]
	v_lshl_add_u64 v[98:99], v[98:99], 1, s[18:19]
	v_cvt_pk_bf16_f32 v64, v64, v65
	v_cvt_pk_bf16_f32 v65, v66, v67
	global_store_dwordx2 v[130:131], v[64:65], off offset:288 sc0 sc1
	global_load_dwordx4 v[64:67], v[164:165], off
	global_load_dwordx4 v[68:71], v[164:165], off offset:64
	global_load_dwordx4 v[72:75], v[164:165], off offset:512
	global_load_dwordx4 v[76:79], v[164:165], off offset:576
	v_add_u32_e32 v96, 0x90, v146
	v_add_co_u32_e32 v102, vcc, s41, v148
	v_ashrrev_i32_e32 v97, 31, v96
	s_nop 0
	v_addc_co_u32_e32 v103, vcc, 0, v149, vcc
	v_lshlrev_b64 v[96:97], 11, v[96:97]
	v_lshl_add_u64 v[96:97], v[96:97], 0, v[144:145]
	v_lshl_add_u64 v[104:105], v[96:97], 2, s[92:93]
	v_lshl_add_u64 v[96:97], v[96:97], 1, s[18:19]
	v_add_co_u32_e32 v106, vcc, s42, v148
	s_waitcnt vmcnt(0)
	v_pk_fma_f32 v[62:63], v[62:63], 0.5, v[82:83] op_sel_hi:[1,0,1]
	v_pk_fma_f32 v[60:61], v[60:61], 0.5, v[80:81] op_sel_hi:[1,0,1]
	global_store_dwordx4 v[100:101], v[60:63], off sc0 sc1
	v_pk_fma_f32 v[56:57], v[56:57], 0.5, v[84:85] op_sel_hi:[1,0,1]
	v_pk_fma_f32 v[58:59], v[58:59], 0.5, v[86:87] op_sel_hi:[1,0,1]
	v_cvt_pk_bf16_f32 v60, v60, v61
	v_cvt_pk_bf16_f32 v61, v62, v63
	v_pk_fma_f32 v[48:49], v[48:49], 0.5, v[88:89] op_sel_hi:[1,0,1]
	global_store_dwordx2 v[98:99], v[60:61], off sc0 sc1
	global_store_dwordx4 v[100:101], v[56:59], off offset:64 sc0 sc1
	v_pk_fma_f32 v[50:51], v[50:51], 0.5, v[90:91] op_sel_hi:[1,0,1]
	v_pk_fma_f32 v[40:41], v[40:41], 0.5, v[92:93] op_sel_hi:[1,0,1]
	v_cvt_pk_bf16_f32 v56, v56, v57
	v_cvt_pk_bf16_f32 v57, v58, v59
	global_store_dwordx2 v[98:99], v[56:57], off offset:32 sc0 sc1
	global_store_dwordx4 v[100:101], v[48:51], off offset:512 sc0 sc1
	v_pk_fma_f32 v[42:43], v[42:43], 0.5, v[94:95] op_sel_hi:[1,0,1]
	v_addc_co_u32_e32 v107, vcc, 0, v149, vcc
	v_cvt_pk_bf16_f32 v48, v48, v49
	v_cvt_pk_bf16_f32 v49, v50, v51
	global_store_dwordx2 v[98:99], v[48:49], off offset:256 sc0 sc1
	global_store_dwordx4 v[100:101], v[40:43], off offset:576 sc0 sc1
	s_and_b64 vcc, exec, s[0:1]
	v_pk_fma_f32 v[46:47], v[46:47], 0.5, v[70:71] op_sel_hi:[1,0,1]
	v_cvt_pk_bf16_f32 v40, v40, v41
	v_cvt_pk_bf16_f32 v41, v42, v43
	global_store_dwordx2 v[98:99], v[40:41], off offset:288 sc0 sc1
	global_load_dwordx4 v[48:51], v[102:103], off
	v_pk_fma_f32 v[42:43], v[54:55], 0.5, v[66:67] op_sel_hi:[1,0,1]
	v_pk_fma_f32 v[40:41], v[52:53], 0.5, v[64:65] op_sel_hi:[1,0,1]
	global_load_dwordx4 v[52:55], v[102:103], off offset:64
	global_load_dwordx4 v[56:59], v[102:103], off offset:512
	global_load_dwordx4 v[60:63], v[102:103], off offset:576
	v_pk_fma_f32 v[44:45], v[44:45], 0.5, v[68:69] op_sel_hi:[1,0,1]
	global_store_dwordx4 v[104:105], v[40:43], off sc0 sc1
	v_pk_fma_f32 v[36:37], v[36:37], 0.5, v[72:73] op_sel_hi:[1,0,1]
	v_pk_fma_f32 v[38:39], v[38:39], 0.5, v[74:75] op_sel_hi:[1,0,1]
	v_cvt_pk_bf16_f32 v40, v40, v41
	v_cvt_pk_bf16_f32 v41, v42, v43
	global_store_dwordx2 v[96:97], v[40:41], off sc0 sc1
	global_store_dwordx4 v[104:105], v[44:47], off offset:64 sc0 sc1
	v_cvt_pk_bf16_f32 v40, v44, v45
	v_cvt_pk_bf16_f32 v41, v46, v47
	v_pk_fma_f32 v[32:33], v[32:33], 0.5, v[76:77] op_sel_hi:[1,0,1]
	global_store_dwordx2 v[96:97], v[40:41], off offset:32 sc0 sc1
	global_store_dwordx4 v[104:105], v[36:39], off offset:512 sc0 sc1
	v_pk_fma_f32 v[34:35], v[34:35], 0.5, v[78:79] op_sel_hi:[1,0,1]
	v_add_u32_e32 v64, 0xa0, v146
	v_cvt_pk_bf16_f32 v36, v36, v37
	v_cvt_pk_bf16_f32 v37, v38, v39
	global_store_dwordx2 v[96:97], v[36:37], off offset:256 sc0 sc1
	global_store_dwordx4 v[104:105], v[32:35], off offset:576 sc0 sc1
	v_ashrrev_i32_e32 v65, 31, v64
	v_lshlrev_b64 v[64:65], 11, v[64:65]
	v_cvt_pk_bf16_f32 v32, v32, v33
	v_cvt_pk_bf16_f32 v33, v34, v35
	global_store_dwordx2 v[96:97], v[32:33], off offset:288 sc0 sc1
	global_load_dwordx4 v[32:35], v[106:107], off
	global_load_dwordx4 v[36:39], v[106:107], off offset:64
	global_load_dwordx4 v[40:43], v[106:107], off offset:512
	global_load_dwordx4 v[44:47], v[106:107], off offset:576
	v_lshl_add_u64 v[64:65], v[64:65], 0, v[144:145]
	v_lshl_add_u64 v[68:69], v[64:65], 2, s[92:93]
	v_add_u32_e32 v66, 0xb0, v146
	v_lshl_add_u64 v[64:65], v[64:65], 1, s[18:19]
	v_ashrrev_i32_e32 v67, 31, v66
	v_lshlrev_b64 v[66:67], 11, v[66:67]
	v_lshl_add_u64 v[66:67], v[66:67], 0, v[144:145]
	v_lshl_add_u64 v[70:71], v[66:67], 2, s[92:93]
	v_lshl_add_u64 v[66:67], v[66:67], 1, s[18:19]
	s_mov_b64 s[18:19], s[6:7]
	s_waitcnt vmcnt(0)
; __device__ __forceinline__ unsigned cvt_pk_bf16(float lo, float hi) { unsigned r; asm volatile("v_cvt_pk_bf16_f32 %0, %1, %2" : "=v"(r) : "v"(lo), "v"(hi)); return r; }
; #define PG8_WAIT_V(n) asm volatile("s_waitcnt vmcnt(" #n ")" ::: "memory")
; #define PG8_BAR __builtin_amdgcn_s_barrier()
;     __device__ __forceinline__ void operator()(const f32x4 (&acc)[2][2][4][2], const Unit& u, int wr, int wc, int fr, int fq) const {
;     ...
;         for (int g = 0; g < 8; ++g) {
;             const int ai = g >> 2, m = g & 3;
;             const int r = row0 + ai * HALF + m * 16; const size_t off = (size_t)r * DM + col0; float s = 0.f;
;             if (g < 7) { const float* nrow = base + (size_t)(((g + 1) >> 2) * HALF + ((g + 1) & 3) * 16) * DM;
; #pragma unroll
;                 for (int bj = 0; bj < 2; ++bj)
; #pragma unroll
;                     for (int n = 0; n < 2; ++n) nb[bj][n] = *(const f32x4*)(nrow + bj * HALF + n * 16); }
; #pragma unroll
;             for (int bj = 0; bj < 2; ++bj)
; #pragma unroll
;                 for (int n = 0; n < 2; ++n) {
;                     const f32x4 o = b[bj][n] + acc[ai][bj][m][n] * alpha;
;                     *(f32x4*)(out + off + bj * HALF + n * 16) = o;
;                     if (WITH_SSQ) s += (o[0] * o[0] + o[1] * o[1]) + (o[2] * o[2] + o[3] * o[3]);
;                     if (WITH_HB) { u32x2 w; w.x = cvt_pk_bf16(o[0], o[1]); w.y = cvt_pk_bf16(o[2], o[3]); *(u32x2*)(hb + off + bj * HALF + n * 16) = w; }
;                 }
;             if (WITH_SSQ) { s += __shfl_xor(s, 16); s += __shfl_xor(s, 32); if (fq == 0) atomicAdd(ssq + r, s); }
;             asm volatile("" ::: "memory");
; #pragma unroll
;             for (int bj = 0; bj < 2; ++bj)
; #pragma unroll
;                 for (int n = 0; n < 2; ++n) b[bj][n] = nb[bj][n];
;         }
; template <class Epi, class Sched>
; __device__ __forceinline__ void gemm_phase(LAS unsigned char* lds, const Gemm g, const Sched& S, const Epi& E) {
;     ...
;         if (!has_next) break;
; #pragma unroll
;         for (int a = 0; a < 2; ++a)
; #pragma unroll
;             for (int b = 0; b < 2; ++b)
; #pragma unroll
;                 for (int m = 0; m < 4; ++m)
; #pragma unroll
;                     for (int n = 0; n < 2; ++n) acc[a][b][m][n] = (acc_t){0, 0, 0, 0};
;         cur = nxt; cA = nA; cB = nB; ++ui;
;     }
;     PG8_WAIT_V(0);
;     if (wr == 0) PG8_BAR;
;     PG8_BAR;
	v_pk_fma_f32 v[30:31], v[30:31], 0.5, v[50:51] op_sel_hi:[1,0,1]
	v_pk_fma_f32 v[28:29], v[28:29], 0.5, v[48:49] op_sel_hi:[1,0,1]
	global_store_dwordx4 v[68:69], v[28:31], off sc0 sc1
	v_pk_fma_f32 v[24:25], v[24:25], 0.5, v[52:53] op_sel_hi:[1,0,1]
	v_pk_fma_f32 v[26:27], v[26:27], 0.5, v[54:55] op_sel_hi:[1,0,1]
	v_cvt_pk_bf16_f32 v28, v28, v29
	v_cvt_pk_bf16_f32 v29, v30, v31
	v_pk_fma_f32 v[16:17], v[16:17], 0.5, v[56:57] op_sel_hi:[1,0,1]
	global_store_dwordx2 v[64:65], v[28:29], off sc0 sc1
	global_store_dwordx4 v[68:69], v[24:27], off offset:64 sc0 sc1
	v_pk_fma_f32 v[18:19], v[18:19], 0.5, v[58:59] op_sel_hi:[1,0,1]
	v_pk_fma_f32 v[8:9], v[8:9], 0.5, v[60:61] op_sel_hi:[1,0,1]
	v_cvt_pk_bf16_f32 v24, v24, v25
	v_cvt_pk_bf16_f32 v25, v26, v27
	global_store_dwordx2 v[64:65], v[24:25], off offset:32 sc0 sc1
	global_store_dwordx4 v[68:69], v[16:19], off offset:512 sc0 sc1
	v_pk_fma_f32 v[10:11], v[10:11], 0.5, v[62:63] op_sel_hi:[1,0,1]
	v_pk_fma_f32 v[14:15], v[14:15], 0.5, v[38:39] op_sel_hi:[1,0,1]
	v_cvt_pk_bf16_f32 v16, v16, v17
	v_cvt_pk_bf16_f32 v17, v18, v19
	global_store_dwordx2 v[64:65], v[16:17], off offset:256 sc0 sc1
	global_store_dwordx4 v[68:69], v[8:11], off offset:576 sc0 sc1
	v_pk_fma_f32 v[12:13], v[12:13], 0.5, v[36:37] op_sel_hi:[1,0,1]
	v_pk_fma_f32 v[4:5], v[4:5], 0.5, v[40:41] op_sel_hi:[1,0,1]
	v_cvt_pk_bf16_f32 v8, v8, v9
	v_cvt_pk_bf16_f32 v9, v10, v11
	global_store_dwordx2 v[64:65], v[8:9], off offset:288 sc0 sc1
	v_pk_fma_f32 v[10:11], v[22:23], 0.5, v[34:35] op_sel_hi:[1,0,1]
	v_pk_fma_f32 v[8:9], v[20:21], 0.5, v[32:33] op_sel_hi:[1,0,1]
	global_store_dwordx4 v[70:71], v[8:11], off sc0 sc1
	v_pk_fma_f32 v[6:7], v[6:7], 0.5, v[42:43] op_sel_hi:[1,0,1]
	v_pk_fma_f32 v[0:1], v[0:1], 0.5, v[44:45] op_sel_hi:[1,0,1]
	v_cvt_pk_bf16_f32 v8, v8, v9
	v_cvt_pk_bf16_f32 v9, v10, v11
	global_store_dwordx2 v[66:67], v[8:9], off sc0 sc1
	global_store_dwordx4 v[70:71], v[12:15], off offset:64 sc0 sc1
	v_cvt_pk_bf16_f32 v8, v12, v13
	v_cvt_pk_bf16_f32 v9, v14, v15
	global_store_dwordx2 v[66:67], v[8:9], off offset:32 sc0 sc1
	global_store_dwordx4 v[70:71], v[4:7], off offset:512 sc0 sc1
	v_pk_fma_f32 v[2:3], v[2:3], 0.5, v[46:47] op_sel_hi:[1,0,1]
	s_nop 0
	v_cvt_pk_bf16_f32 v4, v4, v5
	v_cvt_pk_bf16_f32 v5, v6, v7
	global_store_dwordx2 v[66:67], v[4:5], off offset:256 sc0 sc1
	global_store_dwordx4 v[70:71], v[0:3], off offset:576 sc0 sc1
	s_nop 1
	v_cvt_pk_bf16_f32 v0, v0, v1
	v_cvt_pk_bf16_f32 v1, v2, v3
	global_store_dwordx2 v[66:67], v[0:1], off offset:288 sc0 sc1
	s_cbranch_vccz .LBB0_231
	s_waitcnt vmcnt(0)
	s_cmpk_gt_u32 s22, 0xff
	s_mov_b32 s61, s78
	s_mov_b32 s63, s79
	s_cbranch_scc1 .LBB0_242
	s_barrier

; #define PG8_STAGE(bufoff, gbase, voff) do { _Pragma("unroll") for (int _i = 0; _i < 2; ++_i) \
;         __builtin_amdgcn_global_load_lds((const unsigned*)((const char*)(gbase) + (voff)[_i]), (LAS unsigned*)(lds + (bufoff) + ldsw + _i * 8192), 16, 0, 0); } while (0)
; #define PG8_LDA(dst, b, h) do { _Pragma("unroll") for (int m = 0; m < 4; ++m) _Pragma("unroll") for (int k = 0; k < 2; ++k) dst[m][k] = *(const LAS bf16x8*)(lds + PG8_SA(b, h) + aoff + m * 2048 + k * 1024); } while (0)
; #define PG8_LDB(dst, b, h) do { _Pragma("unroll") for (int n = 0; n < 2; ++n) _Pragma("unroll") for (int k = 0; k < 2; ++k) dst[n][k] = *(const LAS bf16x8*)(lds + PG8_SB(b, h) + boff + n * 2048 + k * 1024); } while (0)
; #define PG8_MMA(ai, bj, At, Bt) do { __builtin_amdgcn_s_setprio(1); _Pragma("unroll") for (int m = 0; m < 4; ++m) _Pragma("unroll") for (int n = 0; n < 2; ++n) _Pragma("unroll") for (int k = 0; k < 2; ++k) \
;         acc[ai][bj][m][n] = MmaOp<Epi::I8>::run(Bt[n][k], At[m][k], acc[ai][bj][m][n]); __builtin_amdgcn_s_setprio(0); } while (0)
; #define PG8_WAIT_V(n) asm volatile("s_waitcnt vmcnt(" #n ")" ::: "memory")
; #define PG8_WAIT_L(n) asm volatile("s_waitcnt lgkmcnt(" #n ")" ::: "memory")
; #define PG8_BAR __builtin_amdgcn_s_barrier()
; #define PG8_SCHED __builtin_amdgcn_sched_barrier(0)
; template <class Epi, class Sched>
; __device__ __forceinline__ void gemm_phase(LAS unsigned char* lds, const Gemm g, const Sched& S, const Epi& E) {
;     ...
;             PG8_LDB(B0, 0, 0); PG8_SCHED; PG8_LDA(At, 0, 0); PG8_STAGE(PG8_SA(1, 1), a1 + hstepA, voffA);
;             PG8_WAIT_L(8); PG8_BAR; PG8_WAIT_L(0); PG8_MMA(0, 0, At, B0); PG8_BAR; PG8_SCHED;
;             PG8_LDB(B1, 0, 1); PG8_STAGE(PG8_SB(0, 0), b2, voffB);
;             PG8_BAR; PG8_WAIT_L(0); PG8_MMA(0, 1, At, B1); PG8_BAR;
;             PG8_LDA(At, 0, 1); PG8_STAGE(PG8_SA(0, 0), a2, voffA);
;             PG8_BAR; PG8_WAIT_L(0); PG8_MMA(1, 0, At, B0); PG8_BAR; PG8_SCHED;
;             PG8_STAGE(PG8_SB(0, 1), b2 + hstepB, voffB);
;             PG8_WAIT_V(6); PG8_BAR; PG8_MMA(1, 1, At, B1); PG8_BAR;
.LBB0_386:
	ds_read_b128 v[104:107], v169
	ds_read_b128 v[108:111], v169 offset:1024
	ds_read_b128 v[112:115], v169 offset:2048
	ds_read_b128 v[116:119], v169 offset:3072
	s_add_u32 s24, s22, 0xfff80080
	s_addc_u32 s25, s23, -1
	s_cmp_eq_u32 s48, 12
	s_cselect_b32 s27, s15, s25
	s_cselect_b32 s26, s44, s24
	s_cselect_b32 s25, s13, s47
	s_cselect_b32 s24, s45, s46
	v_lshl_add_u64 v[164:165], s[22:23], 0, v[152:153]
	s_add_i32 m0, s21, 0xc000
	ds_read_b128 v[160:163], v170
	ds_read_b128 v[172:175], v170 offset:1024
	ds_read_b128 v[178:181], v170 offset:2048
	ds_read_b128 v[182:185], v170 offset:3072
	ds_read_b128 v[186:189], v170 offset:4096
	ds_read_b128 v[190:193], v170 offset:5120
	ds_read_b128 v[194:197], v170 offset:6144
	ds_read_b128 v[198:201], v170 offset:7168
	global_load_lds_dwordx4 v[164:165], off
	v_lshl_add_u64 v[164:165], s[22:23], 0, v[154:155]
	s_add_i32 m0, s21, 0xe000
	s_nop 0
	global_load_lds_dwordx4 v[164:165], off
	s_waitcnt lgkmcnt(8)
	s_barrier
	s_waitcnt lgkmcnt(0)
	s_setprio 1
	v_mfma_i32_16x16x64_i8 v[140:143], v[104:107], v[160:163], v[140:143]
	v_mfma_i32_16x16x64_i8 v[136:139], v[112:115], v[160:163], v[136:139]
	v_mfma_i32_16x16x64_i8 v[124:127], v[104:107], v[178:181], v[124:127]
	v_mfma_i32_16x16x64_i8 v[120:123], v[112:115], v[178:181], v[120:123]
	v_mfma_i32_16x16x64_i8 v[92:95], v[104:107], v[186:189], v[92:95]
	v_mfma_i32_16x16x64_i8 v[88:91], v[112:115], v[186:189], v[88:91]
	v_mfma_i32_16x16x64_i8 v[76:79], v[104:107], v[194:197], v[76:79]
	v_mfma_i32_16x16x64_i8 v[72:75], v[112:115], v[194:197], v[72:75]
	v_mfma_i32_16x16x64_i8 v[140:143], v[108:111], v[172:175], v[140:143]
	v_mfma_i32_16x16x64_i8 v[136:139], v[116:119], v[172:175], v[136:139]
	v_mfma_i32_16x16x64_i8 v[124:127], v[108:111], v[182:185], v[124:127]
	v_mfma_i32_16x16x64_i8 v[120:123], v[116:119], v[182:185], v[120:123]
	v_mfma_i32_16x16x64_i8 v[92:95], v[108:111], v[190:193], v[92:95]
	v_mfma_i32_16x16x64_i8 v[88:91], v[116:119], v[190:193], v[88:91]
	v_mfma_i32_16x16x64_i8 v[76:79], v[108:111], v[198:201], v[76:79]
	v_mfma_i32_16x16x64_i8 v[72:75], v[116:119], v[198:201], v[72:75]
	s_setprio 0
	s_barrier
	s_add_i32 s49, s40, s29
	v_lshl_add_u64 v[164:165], s[24:25], 0, v[148:149]
	s_mov_b32 m0, s49
	ds_read_b128 v[202:205], v171
	ds_read_b128 v[206:209], v171 offset:1024
	ds_read_b128 v[210:213], v171 offset:2048
	ds_read_b128 v[214:217], v171 offset:3072
	global_load_lds_dwordx4 v[164:165], off
	v_lshl_add_u64 v[218:219], s[24:25], 0, v[144:145]
	s_add_i32 m0, s49, 0x2000
	s_nop 0
	global_load_lds_dwordx4 v[218:219], off
	s_barrier
	s_waitcnt lgkmcnt(0)
	s_setprio 1
	v_mfma_i32_16x16x64_i8 v[132:135], v[202:205], v[160:163], v[132:135]
	v_mfma_i32_16x16x64_i8 v[128:131], v[210:213], v[160:163], v[128:131]
	v_mfma_i32_16x16x64_i8 v[100:103], v[202:205], v[178:181], v[100:103]
	v_mfma_i32_16x16x64_i8 v[96:99], v[210:213], v[178:181], v[96:99]
	v_mfma_i32_16x16x64_i8 v[84:87], v[202:205], v[186:189], v[84:87]
	v_mfma_i32_16x16x64_i8 v[80:83], v[210:213], v[186:189], v[80:83]
	v_mfma_i32_16x16x64_i8 v[68:71], v[202:205], v[194:197], v[68:71]
	v_mfma_i32_16x16x64_i8 v[64:67], v[210:213], v[194:197], v[64:67]
	v_mfma_i32_16x16x64_i8 v[132:135], v[206:209], v[172:175], v[132:135]
	v_mfma_i32_16x16x64_i8 v[128:131], v[214:217], v[172:175], v[128:131]
	v_mfma_i32_16x16x64_i8 v[100:103], v[206:209], v[182:185], v[100:103]
	v_mfma_i32_16x16x64_i8 v[96:99], v[214:217], v[182:185], v[96:99]
	v_mfma_i32_16x16x64_i8 v[84:87], v[206:209], v[190:193], v[84:87]
	v_mfma_i32_16x16x64_i8 v[80:83], v[214:217], v[190:193], v[80:83]
	v_mfma_i32_16x16x64_i8 v[68:71], v[206:209], v[198:201], v[68:71]
	v_mfma_i32_16x16x64_i8 v[64:67], v[214:217], v[198:201], v[64:67]
	s_setprio 0
	s_mov_b32 m0, s21
	v_lshl_add_u64 v[220:221], s[26:27], 0, v[150:151]
	s_barrier
	ds_read_b128 v[160:163], v170 offset:16384
	ds_read_b128 v[172:175], v170 offset:17408
	ds_read_b128 v[178:181], v170 offset:18432
	ds_read_b128 v[182:185], v170 offset:19456
	ds_read_b128 v[186:189], v170 offset:20480
	ds_read_b128 v[190:193], v170 offset:21504
	ds_read_b128 v[194:197], v170 offset:22528
	ds_read_b128 v[198:201], v170 offset:23552
	global_load_lds_dwordx4 v[220:221], off
	v_lshl_add_u64 v[222:223], s[26:27], 0, v[146:147]
	s_mov_b32 m0, s33
	s_nop 0
	global_load_lds_dwordx4 v[222:223], off
	s_barrier
	s_waitcnt lgkmcnt(0)
	s_setprio 1
	v_mfma_i32_16x16x64_i8 v[60:63], v[104:107], v[160:163], v[60:63]
	v_mfma_i32_16x16x64_i8 v[56:59], v[112:115], v[160:163], v[56:59]
	v_mfma_i32_16x16x64_i8 v[44:47], v[104:107], v[178:181], v[44:47]
	v_mfma_i32_16x16x64_i8 v[40:43], v[112:115], v[178:181], v[40:43]
	v_mfma_i32_16x16x64_i8 v[28:31], v[104:107], v[186:189], v[28:31]
	v_mfma_i32_16x16x64_i8 v[24:27], v[112:115], v[186:189], v[24:27]
	v_mfma_i32_16x16x64_i8 v[12:15], v[104:107], v[194:197], v[12:15]
	v_mfma_i32_16x16x64_i8 v[8:11], v[112:115], v[194:197], v[8:11]
	v_mfma_i32_16x16x64_i8 v[60:63], v[108:111], v[172:175], v[60:63]
	v_mfma_i32_16x16x64_i8 v[56:59], v[116:119], v[172:175], v[56:59]
	v_mfma_i32_16x16x64_i8 v[44:47], v[108:111], v[182:185], v[44:47]
	v_mfma_i32_16x16x64_i8 v[40:43], v[116:119], v[182:185], v[40:43]
	v_mfma_i32_16x16x64_i8 v[28:31], v[108:111], v[190:193], v[28:31]
	v_mfma_i32_16x16x64_i8 v[24:27], v[116:119], v[190:193], v[24:27]
	v_mfma_i32_16x16x64_i8 v[12:15], v[108:111], v[198:201], v[12:15]
	v_mfma_i32_16x16x64_i8 v[8:11], v[116:119], v[198:201], v[8:11]
	s_setprio 0
	s_barrier
	s_add_u32 s50, s24, 0x40000
	s_addc_u32 s51, s25, 0
	s_add_i32 s49, s41, s29
	v_lshl_add_u64 v[104:105], s[50:51], 0, v[148:149]
	s_mov_b32 m0, s49
	s_nop 0
	global_load_lds_dwordx4 v[104:105], off
	v_lshl_add_u64 v[104:105], s[50:51], 0, v[144:145]
	s_add_i32 m0, s49, 0x2000
	s_nop 0
	global_load_lds_dwordx4 v[104:105], off
	s_waitcnt vmcnt(6)
	s_barrier
; #define PG8_STAGE(bufoff, gbase, voff) do { _Pragma("unroll") for (int _i = 0; _i < 2; ++_i) \
;         __builtin_amdgcn_global_load_lds((const unsigned*)((const char*)(gbase) + (voff)[_i]), (LAS unsigned*)(lds + (bufoff) + ldsw + _i * 8192), 16, 0, 0); } while (0)
; #define PG8_LDA(dst, b, h) do { _Pragma("unroll") for (int m = 0; m < 4; ++m) _Pragma("unroll") for (int k = 0; k < 2; ++k) dst[m][k] = *(const LAS bf16x8*)(lds + PG8_SA(b, h) + aoff + m * 2048 + k * 1024); } while (0)
; #define PG8_LDB(dst, b, h) do { _Pragma("unroll") for (int n = 0; n < 2; ++n) _Pragma("unroll") for (int k = 0; k < 2; ++k) dst[n][k] = *(const LAS bf16x8*)(lds + PG8_SB(b, h) + boff + n * 2048 + k * 1024); } while (0)
; #define PG8_MMA(ai, bj, At, Bt) do { __builtin_amdgcn_s_setprio(1); _Pragma("unroll") for (int m = 0; m < 4; ++m) _Pragma("unroll") for (int n = 0; n < 2; ++n) _Pragma("unroll") for (int k = 0; k < 2; ++k) \
;         acc[ai][bj][m][n] = MmaOp<Epi::I8>::run(Bt[n][k], At[m][k], acc[ai][bj][m][n]); __builtin_amdgcn_s_setprio(0); } while (0)
; #define PG8_WAIT_V(n) asm volatile("s_waitcnt vmcnt(" #n ")" ::: "memory")
; #define PG8_WAIT_L(n) asm volatile("s_waitcnt lgkmcnt(" #n ")" ::: "memory")
; #define PG8_BAR __builtin_amdgcn_s_barrier()
; #define PG8_SCHED __builtin_amdgcn_sched_barrier(0)
; template <class Epi, class Sched>
; __device__ __forceinline__ void gemm_phase(LAS unsigned char* lds, const Gemm g, const Sched& S, const Epi& E) {
;     ...
;             PG8_WAIT_V(6); PG8_BAR; PG8_MMA(1, 1, At, B1); PG8_BAR;
;             PG8_LDB(B0, 1, 0); PG8_SCHED; PG8_LDA(At, 1, 0); PG8_STAGE(PG8_SA(0, 1), a2 + hstepA, voffA);
;             PG8_WAIT_L(8); PG8_BAR; PG8_WAIT_L(0); PG8_MMA(0, 0, At, B0); PG8_BAR; PG8_SCHED;
;             PG8_LDB(B1, 1, 1); PG8_STAGE(PG8_SB(1, 0), b3, voffB);
;             PG8_BAR; PG8_WAIT_L(0); PG8_MMA(0, 1, At, B1); PG8_BAR;
;             PG8_LDA(At, 1, 1); PG8_STAGE(PG8_SA(1, 0), a3, voffA);
;             PG8_BAR; PG8_WAIT_L(0); PG8_MMA(1, 0, At, B0); PG8_BAR; PG8_SCHED;
	s_setprio 1
	v_mfma_i32_16x16x64_i8 v[52:55], v[202:205], v[160:163], v[52:55]
	v_mfma_i32_16x16x64_i8 v[48:51], v[210:213], v[160:163], v[48:51]
	v_mfma_i32_16x16x64_i8 v[36:39], v[202:205], v[178:181], v[36:39]
	v_mfma_i32_16x16x64_i8 v[32:35], v[210:213], v[178:181], v[32:35]
	v_mfma_i32_16x16x64_i8 v[20:23], v[202:205], v[186:189], v[20:23]
	v_mfma_i32_16x16x64_i8 v[16:19], v[210:213], v[186:189], v[16:19]
	v_mfma_i32_16x16x64_i8 v[4:7], v[202:205], v[194:197], v[4:7]
	v_mfma_i32_16x16x64_i8 v[0:3], v[210:213], v[194:197], v[0:3]
	v_mfma_i32_16x16x64_i8 v[52:55], v[206:209], v[172:175], v[52:55]
	v_mfma_i32_16x16x64_i8 v[48:51], v[214:217], v[172:175], v[48:51]
	v_mfma_i32_16x16x64_i8 v[36:39], v[206:209], v[182:185], v[36:39]
	v_mfma_i32_16x16x64_i8 v[32:35], v[214:217], v[182:185], v[32:35]
	v_mfma_i32_16x16x64_i8 v[20:23], v[206:209], v[190:193], v[20:23]
	v_mfma_i32_16x16x64_i8 v[16:19], v[214:217], v[190:193], v[16:19]
	v_mfma_i32_16x16x64_i8 v[4:7], v[206:209], v[198:201], v[4:7]
	v_mfma_i32_16x16x64_i8 v[0:3], v[214:217], v[198:201], v[0:3]
	s_setprio 0
	s_add_i32 s49, 0, 0x18000
	v_add_u32_e32 v116, s49, v167
	s_barrier
	ds_read_b128 v[104:107], v116
	ds_read_b128 v[108:111], v116 offset:1024
	ds_read_b128 v[112:115], v116 offset:2048
	ds_read_b128 v[116:119], v116 offset:3072
	s_add_u32 s26, s26, 0x80000
	s_addc_u32 s27, s27, 0
	s_mov_b32 m0, s34
	v_lshl_add_u64 v[202:203], s[26:27], 0, v[150:151]
	ds_read_b128 v[160:163], v170 offset:32768
	ds_read_b128 v[172:175], v170 offset:33792
	ds_read_b128 v[178:181], v170 offset:34816
	ds_read_b128 v[182:185], v170 offset:35840
	ds_read_b128 v[186:189], v170 offset:36864
	ds_read_b128 v[190:193], v170 offset:37888
	ds_read_b128 v[194:197], v170 offset:38912
	ds_read_b128 v[198:201], v170 offset:39936
	global_load_lds_dwordx4 v[202:203], off
	v_lshl_add_u64 v[202:203], s[26:27], 0, v[146:147]
	s_mov_b32 m0, s35
	s_nop 0
	global_load_lds_dwordx4 v[202:203], off
	s_waitcnt lgkmcnt(8)
	s_barrier
	s_waitcnt lgkmcnt(0)
	s_setprio 1
	v_mfma_i32_16x16x64_i8 v[140:143], v[104:107], v[160:163], v[140:143]
	v_mfma_i32_16x16x64_i8 v[136:139], v[112:115], v[160:163], v[136:139]
	v_mfma_i32_16x16x64_i8 v[124:127], v[104:107], v[178:181], v[124:127]
	v_mfma_i32_16x16x64_i8 v[120:123], v[112:115], v[178:181], v[120:123]
	v_mfma_i32_16x16x64_i8 v[92:95], v[104:107], v[186:189], v[92:95]
	v_mfma_i32_16x16x64_i8 v[88:91], v[112:115], v[186:189], v[88:91]
	v_mfma_i32_16x16x64_i8 v[76:79], v[104:107], v[194:197], v[76:79]
	v_mfma_i32_16x16x64_i8 v[72:75], v[112:115], v[194:197], v[72:75]
	v_mfma_i32_16x16x64_i8 v[140:143], v[108:111], v[172:175], v[140:143]
	v_mfma_i32_16x16x64_i8 v[136:139], v[116:119], v[172:175], v[136:139]
	v_mfma_i32_16x16x64_i8 v[124:127], v[108:111], v[182:185], v[124:127]
	v_mfma_i32_16x16x64_i8 v[120:123], v[116:119], v[182:185], v[120:123]
	v_mfma_i32_16x16x64_i8 v[92:95], v[108:111], v[190:193], v[92:95]
	v_mfma_i32_16x16x64_i8 v[88:91], v[116:119], v[190:193], v[88:91]
	v_mfma_i32_16x16x64_i8 v[76:79], v[108:111], v[198:201], v[76:79]
	v_mfma_i32_16x16x64_i8 v[72:75], v[116:119], v[198:201], v[72:75]
	s_setprio 0
	s_barrier
	s_add_i32 s26, 0, 0x1c000
	s_add_i32 s27, s49, s29
	v_add_u32_e32 v214, s26, v167
	v_lshl_add_u64 v[164:165], v[164:165], 0, s[6:7]
	s_mov_b32 m0, s27
	ds_read_b128 v[202:205], v214
	ds_read_b128 v[206:209], v214 offset:1024
	ds_read_b128 v[210:213], v214 offset:2048
	ds_read_b128 v[214:217], v214 offset:3072
	global_load_lds_dwordx4 v[164:165], off
	v_lshl_add_u64 v[164:165], v[218:219], 0, s[6:7]
	s_add_i32 m0, s27, 0x2000
	s_nop 0
	global_load_lds_dwordx4 v[164:165], off
	s_barrier
	s_waitcnt lgkmcnt(0)
	s_setprio 1
	v_mfma_i32_16x16x64_i8 v[132:135], v[202:205], v[160:163], v[132:135]
	v_mfma_i32_16x16x64_i8 v[128:131], v[210:213], v[160:163], v[128:131]
	v_mfma_i32_16x16x64_i8 v[100:103], v[202:205], v[178:181], v[100:103]
	v_mfma_i32_16x16x64_i8 v[96:99], v[210:213], v[178:181], v[96:99]
	v_mfma_i32_16x16x64_i8 v[84:87], v[202:205], v[186:189], v[84:87]
	v_mfma_i32_16x16x64_i8 v[80:83], v[210:213], v[186:189], v[80:83]
	v_mfma_i32_16x16x64_i8 v[68:71], v[202:205], v[194:197], v[68:71]
	v_mfma_i32_16x16x64_i8 v[64:67], v[210:213], v[194:197], v[64:67]
	v_mfma_i32_16x16x64_i8 v[132:135], v[206:209], v[172:175], v[132:135]
	v_mfma_i32_16x16x64_i8 v[128:131], v[214:217], v[172:175], v[128:131]
	v_mfma_i32_16x16x64_i8 v[100:103], v[206:209], v[182:185], v[100:103]
	v_mfma_i32_16x16x64_i8 v[96:99], v[214:217], v[182:185], v[96:99]
	v_mfma_i32_16x16x64_i8 v[84:87], v[206:209], v[190:193], v[84:87]
	v_mfma_i32_16x16x64_i8 v[80:83], v[214:217], v[190:193], v[80:83]
	v_mfma_i32_16x16x64_i8 v[68:71], v[206:209], v[198:201], v[68:71]
	v_mfma_i32_16x16x64_i8 v[64:67], v[214:217], v[198:201], v[64:67]
	s_setprio 0
	s_mov_b32 m0, s37
	v_lshl_add_u64 v[164:165], v[220:221], 0, s[6:7]
	s_barrier
	ds_read_b128 v[160:163], v170 offset:49152
	ds_read_b128 v[172:175], v170 offset:50176
	ds_read_b128 v[178:181], v170 offset:51200
	ds_read_b128 v[182:185], v170 offset:52224
	ds_read_b128 v[186:189], v170 offset:53248
	ds_read_b128 v[190:193], v170 offset:54272
	ds_read_b128 v[194:197], v170 offset:55296
	ds_read_b128 v[198:201], v170 offset:56320
	global_load_lds_dwordx4 v[164:165], off
	v_lshl_add_u64 v[164:165], v[222:223], 0, s[6:7]
	s_mov_b32 m0, s38
	s_nop 0
	global_load_lds_dwordx4 v[164:165], off
	s_barrier
; __device__ __forceinline__ float ld_agent(const float* p) { return __hip_atomic_load(p, __ATOMIC_RELAXED, __HIP_MEMORY_SCOPE_AGENT); }
; #define PG8_STAGE(bufoff, gbase, voff) do { _Pragma("unroll") for (int _i = 0; _i < 2; ++_i) \
;         __builtin_amdgcn_global_load_lds((const unsigned*)((const char*)(gbase) + (voff)[_i]), (LAS unsigned*)(lds + (bufoff) + ldsw + _i * 8192), 16, 0, 0); } while (0)
; #define PG8_MMA(ai, bj, At, Bt) do { __builtin_amdgcn_s_setprio(1); _Pragma("unroll") for (int m = 0; m < 4; ++m) _Pragma("unroll") for (int n = 0; n < 2; ++n) _Pragma("unroll") for (int k = 0; k < 2; ++k) \
;         acc[ai][bj][m][n] = MmaOp<Epi::I8>::run(Bt[n][k], At[m][k], acc[ai][bj][m][n]); __builtin_amdgcn_s_setprio(0); } while (0)
; #define PG8_WAIT_V(n) asm volatile("s_waitcnt vmcnt(" #n ")" ::: "memory")
; #define PG8_WAIT_L(n) asm volatile("s_waitcnt lgkmcnt(" #n ")" ::: "memory")
; #define PG8_BAR __builtin_amdgcn_s_barrier()
; #define PG8_SCHED __builtin_amdgcn_sched_barrier(0)
;     __device__ __forceinline__ void operator()(const i32x4 (&acc)[2][2][4][2], const Unit& u, int wr, int wc, int fr_, int fq) const {
;         const int row0 = u.pm * BM + wr * 64 + fr_, col0 = u.pn * BM + wc * 32 + 8 * fq;
;         f32x4 sw[2][2], bv[2][2];
; #pragma unroll
;         for (int bj = 0; bj < 2; ++bj)
; #pragma unroll
;             for (int n = 0; n < 2; ++n) { sw[bj][n] = *(const f32x4*)(swinv + col0 + bj * HALF + 4 * n);
;                 bv[bj][n] = MODE == 1 ? *(const f32x4*)(bias + col0 + bj * HALF + 4 * n) : (f32x4){0.f, 0.f, 0.f, 0.f}; }
; #pragma unroll
;         for (int ai = 0; ai < 2; ++ai)
; #pragma unroll
;             for (int m = 0; m < 4; ++m) {
;                 asm volatile("" ::: "memory");
;                 const int r = row0 + ai * HALF + m * 16; const float rs = ld_agent(fr + r);
; template <class Epi, class Sched>
; __device__ __forceinline__ void gemm_phase(LAS unsigned char* lds, const Gemm g, const Sched& S, const Epi& E) {
;     ...
;             PG8_BAR; PG8_WAIT_L(0); PG8_MMA(1, 0, At, B0); PG8_BAR; PG8_SCHED;
;             PG8_STAGE(PG8_SB(1, 1), b3 + hstepB, voffB);
;             PG8_WAIT_V(6); PG8_BAR; PG8_MMA(1, 1, At, B1); PG8_BAR;
;         }
	s_waitcnt lgkmcnt(0)
	s_setprio 1
	v_mfma_i32_16x16x64_i8 v[60:63], v[104:107], v[160:163], v[60:63]
	v_mfma_i32_16x16x64_i8 v[56:59], v[112:115], v[160:163], v[56:59]
	v_mfma_i32_16x16x64_i8 v[44:47], v[104:107], v[178:181], v[44:47]
	v_mfma_i32_16x16x64_i8 v[40:43], v[112:115], v[178:181], v[40:43]
	v_mfma_i32_16x16x64_i8 v[28:31], v[104:107], v[186:189], v[28:31]
	v_mfma_i32_16x16x64_i8 v[24:27], v[112:115], v[186:189], v[24:27]
	v_mfma_i32_16x16x64_i8 v[12:15], v[104:107], v[194:197], v[12:15]
	v_mfma_i32_16x16x64_i8 v[8:11], v[112:115], v[194:197], v[8:11]
	v_mfma_i32_16x16x64_i8 v[60:63], v[108:111], v[172:175], v[60:63]
	v_mfma_i32_16x16x64_i8 v[56:59], v[116:119], v[172:175], v[56:59]
	v_mfma_i32_16x16x64_i8 v[44:47], v[108:111], v[182:185], v[44:47]
	v_mfma_i32_16x16x64_i8 v[40:43], v[116:119], v[182:185], v[40:43]
	v_mfma_i32_16x16x64_i8 v[28:31], v[108:111], v[190:193], v[28:31]
	v_mfma_i32_16x16x64_i8 v[24:27], v[116:119], v[190:193], v[24:27]
	v_mfma_i32_16x16x64_i8 v[12:15], v[108:111], v[198:201], v[12:15]
	v_mfma_i32_16x16x64_i8 v[8:11], v[116:119], v[198:201], v[8:11]
	s_setprio 0
	s_barrier
	s_add_u32 s24, s24, 0x40080
	s_addc_u32 s25, s25, 0
	s_add_i32 s26, s26, s29
	v_lshl_add_u64 v[104:105], s[24:25], 0, v[148:149]
	s_mov_b32 m0, s26
	s_nop 0
	global_load_lds_dwordx4 v[104:105], off
	v_lshl_add_u64 v[104:105], s[24:25], 0, v[144:145]
	s_add_i32 m0, s26, 0x2000
	s_nop 0
	global_load_lds_dwordx4 v[104:105], off
	s_waitcnt vmcnt(6)
	s_barrier
	s_setprio 1
	v_mfma_i32_16x16x64_i8 v[52:55], v[202:205], v[160:163], v[52:55]
	v_mfma_i32_16x16x64_i8 v[48:51], v[210:213], v[160:163], v[48:51]
	v_mfma_i32_16x16x64_i8 v[36:39], v[202:205], v[178:181], v[36:39]
	v_mfma_i32_16x16x64_i8 v[32:35], v[210:213], v[178:181], v[32:35]
	v_mfma_i32_16x16x64_i8 v[20:23], v[202:205], v[186:189], v[20:23]
	v_mfma_i32_16x16x64_i8 v[16:19], v[210:213], v[186:189], v[16:19]
	v_mfma_i32_16x16x64_i8 v[4:7], v[202:205], v[194:197], v[4:7]
	v_mfma_i32_16x16x64_i8 v[0:3], v[210:213], v[194:197], v[0:3]
	v_mfma_i32_16x16x64_i8 v[52:55], v[206:209], v[172:175], v[52:55]
	v_mfma_i32_16x16x64_i8 v[48:51], v[214:217], v[172:175], v[48:51]
	v_mfma_i32_16x16x64_i8 v[36:39], v[206:209], v[182:185], v[36:39]
	v_mfma_i32_16x16x64_i8 v[32:35], v[214:217], v[182:185], v[32:35]
	v_mfma_i32_16x16x64_i8 v[20:23], v[206:209], v[190:193], v[20:23]
	v_mfma_i32_16x16x64_i8 v[16:19], v[214:217], v[190:193], v[16:19]
	v_mfma_i32_16x16x64_i8 v[4:7], v[206:209], v[198:201], v[4:7]
	v_mfma_i32_16x16x64_i8 v[0:3], v[214:217], v[198:201], v[0:3]
	s_setprio 0
	s_add_i32 s48, s48, 2
	s_add_u32 s22, s22, 0x100
	s_addc_u32 s23, s23, 0
	s_add_u32 s46, s46, 0x100
	s_addc_u32 s47, s47, 0
	s_cmp_gt_u32 s48, 13
	s_barrier
	s_cbranch_scc0 .LBB0_386
	v_lshl_or_b32 v172, s43, 8, v168
	v_ashrrev_i32_e32 v173, 31, v172
	v_lshl_add_u32 v160, s20, 8, v166
	v_lshl_add_u64 v[108:109], v[172:173], 2, s[8:9]
	v_ashrrev_i32_e32 v161, 31, v160
	global_load_dwordx4 v[112:115], v[108:109], off offset:16
	global_load_dwordx4 v[116:119], v[108:109], off
	global_load_dwordx4 v[104:107], v[108:109], off offset:528
	s_nop 0
	global_load_dwordx4 v[108:111], v[108:109], off offset:512
	v_lshl_add_u64 v[164:165], v[160:161], 2, s[2:3]
	global_load_dword v161, v[164:165], off sc1
	global_load_dword v190, v[164:165], off offset:64 sc1
	global_load_dword v191, v[164:165], off offset:128 sc1
	global_load_dword v192, v[164:165], off offset:192 sc1
	global_load_dword v193, v[164:165], off offset:512 sc1
	global_load_dword v194, v[164:165], off offset:576 sc1
	global_load_dword v195, v[164:165], off offset:640 sc1
	global_load_dword v196, v[164:165], off offset:704 sc1
	v_cvt_f32_i32_e32 v140, v140
	v_cvt_f32_i32_e32 v174, v136
	v_cvt_f32_i32_e32 v141, v141
	v_cvt_f32_i32_e32 v175, v137
	v_cvt_f32_i32_e32 v142, v142
	v_cvt_f32_i32_e32 v178, v138
	v_cvt_f32_i32_e32 v143, v143
	v_cvt_f32_i32_e32 v179, v139
	v_cvt_f32_i32_e32 v132, v132
	v_cvt_f32_i32_e32 v180, v128
	v_cvt_f32_i32_e32 v133, v133
	v_mov_b64_e32 v[162:163], s[54:55]
	v_cvt_f32_i32_e32 v181, v129
	v_cvt_f32_i32_e32 v182, v134
	v_cvt_f32_i32_e32 v183, v130
	v_cvt_f32_i32_e32 v184, v135
	v_cvt_f32_i32_e32 v185, v131
	v_or_b32_e32 v134, 16, v160
	v_mad_i64_i32 v[130:131], s[22:23], v160, s42, v[162:163]
	v_lshlrev_b64 v[128:129], 1, v[172:173]
	v_ashrrev_i32_e32 v135, 31, v134
	v_lshl_add_u64 v[136:137], v[130:131], 0, v[128:129]
	v_lshl_add_u64 v[138:139], v[134:135], 2, s[2:3]
	v_cvt_f32_i32_e32 v124, v124
	v_cvt_f32_i32_e32 v125, v125
	v_cvt_f32_i32_e32 v126, v126
	v_cvt_f32_i32_e32 v122, v122
	v_cvt_f32_i32_e32 v127, v127
	v_cvt_f32_i32_e32 v123, v123
	v_cvt_f32_i32_e32 v98, v98
	v_cvt_f32_i32_e32 v99, v99
	v_cvt_f32_i32_e32 v92, v92
	v_cvt_f32_i32_e32 v93, v93
	v_cvt_f32_i32_e32 v94, v94
	v_cvt_f32_i32_e32 v90, v90
	v_cvt_f32_i32_e32 v95, v95
	v_cvt_f32_i32_e32 v91, v91
	v_cvt_f32_i32_e32 v82, v82
	v_cvt_f32_i32_e32 v83, v83
	v_cvt_f32_i32_e32 v76, v76
	v_cvt_f32_i32_e32 v72, v72
	v_cvt_f32_i32_e32 v77, v77
	v_cvt_f32_i32_e32 v73, v73
	v_cvt_f32_i32_e32 v78, v78
	v_cvt_f32_i32_e32 v74, v74
	v_cvt_f32_i32_e32 v79, v79
	v_cvt_f32_i32_e32 v75, v75
	v_cvt_f32_i32_e32 v70, v70
	v_cvt_f32_i32_e32 v66, v66
	v_cvt_f32_i32_e32 v71, v71
	v_cvt_f32_i32_e32 v67, v67
	v_cvt_f32_i32_e32 v60, v60
	v_cvt_f32_i32_e32 v56, v56
	v_cvt_f32_i32_e32 v61, v61
	v_cvt_f32_i32_e32 v57, v57
	v_cvt_f32_i32_e32 v62, v62
	v_cvt_f32_i32_e32 v58, v58
	v_cvt_f32_i32_e32 v63, v63
	v_cvt_f32_i32_e32 v59, v59
	v_cvt_f32_i32_e32 v54, v54
	v_cvt_f32_i32_e32 v50, v50
	v_cvt_f32_i32_e32 v55, v55
	v_cvt_f32_i32_e32 v51, v51
	v_cvt_f32_i32_e32 v44, v44
	v_cvt_f32_i32_e32 v40, v40
	v_cvt_f32_i32_e32 v45, v45
	v_cvt_f32_i32_e32 v41, v41
	v_cvt_f32_i32_e32 v46, v46
	v_cvt_f32_i32_e32 v42, v42
	v_cvt_f32_i32_e32 v47, v47
	v_cvt_f32_i32_e32 v43, v43
	v_cvt_f32_i32_e32 v38, v38
	v_cvt_f32_i32_e32 v34, v34
	v_cvt_f32_i32_e32 v39, v39
	v_cvt_f32_i32_e32 v35, v35
	v_cvt_f32_i32_e32 v28, v28
	v_cvt_f32_i32_e32 v24, v24
	v_cvt_f32_i32_e32 v29, v29
	s_waitcnt vmcnt(0)
; __device__ __forceinline__ unsigned cvt_pk_bf16(float lo, float hi) { unsigned r; asm volatile("v_cvt_pk_bf16_f32 %0, %1, %2" : "=v"(r) : "v"(lo), "v"(hi)); return r; }
; __device__ __forceinline__ float ld_agent(const float* p) { return __hip_atomic_load(p, __ATOMIC_RELAXED, __HIP_MEMORY_SCOPE_AGENT); }
; __device__ __forceinline__ float sigm(float x) { return __builtin_amdgcn_rcpf(1.f + __builtin_amdgcn_exp2f(-LOG2E * x)); }
;     __device__ __forceinline__ void operator()(const i32x4 (&acc)[2][2][4][2], const Unit& u, int wr, int wc, int fr_, int fq) const {
;     ...
;         for (int ai = 0; ai < 2; ++ai)
; #pragma unroll
;             for (int m = 0; m < 4; ++m) {
;                 asm volatile("" ::: "memory");
;                 const int r = row0 + ai * HALF + m * 16; const float rs = ld_agent(fr + r);
;                 bf16_t* rowp = O + (size_t)r * ldc + col0;
; #pragma unroll
;                 for (int bj = 0; bj < 2; ++bj) {
;                     f32x4 v0, v1;
; #pragma unroll
;                     for (int j = 0; j < 4; ++j) { v0[j] = (float)acc[ai][bj][m][0][j] * rs * sw[bj][0][j] + bv[bj][0][j]; v1[j] = (float)acc[ai][bj][m][1][j] * rs * sw[bj][1][j] + bv[bj][1][j]; }
;                     if (MODE == 1) {
; #pragma unroll
;                         for (int j = 0; j < 4; ++j) { v0[j] = sigm(v0[j]); v1[j] = sigm(v1[j]); } }
;                     u32x4 w; w.x = cvt_pk_bf16(v0[0], v0[1]); w.y = cvt_pk_bf16(v0[2], v0[3]); w.z = cvt_pk_bf16(v1[0], v1[1]); w.w = cvt_pk_bf16(v1[2], v1[3]);
;                     *(u32x4*)(rowp + bj * HALF) = w;
;                 }
;             }
	v_mul_f32_e32 v130, v140, v161
	v_mul_f32_e32 v131, v174, v161
	v_mul_f32_e32 v135, v141, v161
	v_mul_f32_e32 v140, v175, v161
	v_mul_f32_e32 v141, v142, v161
	v_mul_f32_e32 v142, v178, v161
	v_mul_f32_e32 v143, v143, v161
	v_mul_f32_e32 v172, v179, v161
	v_mul_f32_e32 v132, v132, v161
	v_mul_f32_e32 v173, v180, v161
	v_mul_f32_e32 v133, v133, v161
	v_fma_f32 v130, v116, v130, 0
	v_fma_f32 v180, v112, v131, 0
	v_fma_f32 v131, v117, v135, 0
	v_mul_f32_e32 v174, v181, v161
	v_mul_f32_e32 v175, v182, v161
	v_mul_f32_e32 v178, v183, v161
	v_mul_f32_e32 v179, v184, v161
	v_mul_f32_e32 v161, v185, v161
	v_fma_f32 v135, v113, v140, 0
	v_fma_f32 v140, v118, v141, 0
	v_fma_f32 v141, v114, v142, 0
	v_fma_f32 v142, v119, v143, 0
	v_fma_f32 v143, v115, v172, 0
	v_fma_f32 v172, v108, v132, 0
	v_fma_f32 v181, v109, v133, 0
	v_cvt_pk_bf16_f32 v130, v130, v131
	v_cvt_pk_bf16_f32 v131, v140, v142
	v_cvt_pk_bf16_f32 v132, v180, v135
	v_cvt_pk_bf16_f32 v133, v141, v143
	v_fma_f32 v173, v104, v173, 0
	v_fma_f32 v174, v105, v174, 0
	v_fma_f32 v175, v110, v175, 0
	v_fma_f32 v178, v106, v178, 0
	v_fma_f32 v179, v111, v179, 0
	v_fma_f32 v161, v107, v161, 0
	global_store_dwordx4 v[136:137], v[130:133], off sc0 sc1
	v_cvt_f32_i32_e32 v135, v96
	v_cvt_f32_i32_e32 v25, v25
	v_cvt_pk_bf16_f32 v130, v172, v181
	v_cvt_pk_bf16_f32 v131, v175, v179
	v_cvt_pk_bf16_f32 v132, v173, v174
	v_cvt_pk_bf16_f32 v133, v178, v161
	global_store_dwordx4 v[136:137], v[130:133], off offset:256 sc0 sc1
	s_nop 1
	v_mov_b32_e32 v130, v190
	v_cvt_f32_i32_e32 v136, v101
	v_cvt_f32_i32_e32 v131, v120
	v_cvt_f32_i32_e32 v132, v121
	v_cvt_f32_i32_e32 v133, v100
	v_cvt_f32_i32_e32 v137, v97
	v_cvt_f32_i32_e32 v138, v102
	v_cvt_f32_i32_e32 v139, v103
	v_or_b32_e32 v100, 32, v160
	v_mad_i64_i32 v[96:97], s[22:23], v134, s42, v[162:163]
	v_ashrrev_i32_e32 v101, 31, v100
	v_lshl_add_u64 v[102:103], v[96:97], 0, v[128:129]
	v_lshl_add_u64 v[120:121], v[100:101], 2, s[2:3]
	v_cvt_f32_i32_e32 v30, v30
	v_cvt_f32_i32_e32 v26, v26
	v_cvt_f32_i32_e32 v31, v31
	v_cvt_f32_i32_e32 v27, v27
	v_cvt_f32_i32_e32 v22, v22
	v_cvt_f32_i32_e32 v18, v18
	v_cvt_f32_i32_e32 v23, v23
	v_cvt_f32_i32_e32 v19, v19
	v_cvt_f32_i32_e32 v12, v12
	v_cvt_f32_i32_e32 v8, v8
	v_cvt_f32_i32_e32 v13, v13
	v_cvt_f32_i32_e32 v9, v9
	v_cvt_f32_i32_e32 v14, v14
	v_cvt_f32_i32_e32 v10, v10
	v_cvt_f32_i32_e32 v15, v15
	v_cvt_f32_i32_e32 v11, v11
	v_cvt_f32_i32_e32 v6, v6
	v_cvt_f32_i32_e32 v2, v2
	v_cvt_f32_i32_e32 v7, v7
	v_cvt_f32_i32_e32 v3, v3
	s_and_b64 vcc, exec, s[0:1]
	s_mov_b32 s43, s12
	s_mov_b32 s20, s14
	s_mov_b64 s[24:25], s[18:19]
	v_mul_f32_e32 v96, v124, v130
	v_mul_f32_e32 v97, v131, v130
	v_mul_f32_e32 v101, v125, v130
	v_mul_f32_e32 v124, v132, v130
	v_mul_f32_e32 v125, v126, v130
	v_mul_f32_e32 v122, v122, v130
	v_mul_f32_e32 v126, v127, v130
	v_mul_f32_e32 v123, v123, v130
	v_mul_f32_e32 v127, v133, v130
	v_mul_f32_e32 v131, v135, v130
	v_mul_f32_e32 v132, v136, v130
	v_mul_f32_e32 v133, v137, v130
	v_mul_f32_e32 v134, v138, v130
	v_mul_f32_e32 v98, v98, v130
	v_mul_f32_e32 v135, v139, v130
	v_mul_f32_e32 v99, v99, v130
	v_fma_f32 v96, v116, v96, 0
	v_fma_f32 v130, v112, v97, 0
	v_fma_f32 v97, v117, v101, 0
	v_fma_f32 v101, v113, v124, 0
	v_fma_f32 v124, v118, v125, 0
	v_fma_f32 v122, v114, v122, 0
	v_fma_f32 v125, v119, v126, 0
	v_fma_f32 v123, v115, v123, 0
	v_fma_f32 v126, v108, v127, 0
	v_fma_f32 v127, v104, v131, 0
	v_fma_f32 v131, v109, v132, 0
	v_fma_f32 v132, v105, v133, 0
	v_fma_f32 v133, v110, v134, 0
	v_fma_f32 v134, v106, v98, 0
	v_fma_f32 v136, v107, v99, 0
	v_cvt_pk_bf16_f32 v96, v96, v97
	v_cvt_pk_bf16_f32 v97, v124, v125
	v_cvt_pk_bf16_f32 v98, v130, v101
	v_cvt_pk_bf16_f32 v99, v122, v123
	v_fma_f32 v135, v111, v135, 0
	global_store_dwordx4 v[102:103], v[96:99], off sc0 sc1
	v_cvt_f32_i32_e32 v101, v80
	s_nop 0
	v_cvt_pk_bf16_f32 v96, v126, v131
	v_cvt_pk_bf16_f32 v97, v133, v135
	v_cvt_pk_bf16_f32 v98, v127, v132
	v_cvt_pk_bf16_f32 v99, v134, v136
	global_store_dwordx4 v[102:103], v[96:99], off offset:256 sc0 sc1
	s_nop 1
	v_mov_b32_e32 v96, v191
	v_cvt_f32_i32_e32 v102, v85
	v_cvt_f32_i32_e32 v97, v88
	v_cvt_f32_i32_e32 v98, v89
	v_cvt_f32_i32_e32 v99, v84
	v_cvt_f32_i32_e32 v103, v81
	v_cvt_f32_i32_e32 v120, v86
	v_cvt_f32_i32_e32 v121, v87
	v_or_b32_e32 v84, 48, v160
	v_mad_i64_i32 v[80:81], s[22:23], v100, s42, v[162:163]
	v_ashrrev_i32_e32 v85, 31, v84
	v_lshl_add_u64 v[86:87], v[80:81], 0, v[128:129]
	v_lshl_add_u64 v[88:89], v[84:85], 2, s[2:3]
	v_mul_f32_e32 v80, v92, v96
	v_mul_f32_e32 v81, v97, v96
	v_mul_f32_e32 v85, v93, v96
	v_mul_f32_e32 v92, v98, v96
	v_mul_f32_e32 v93, v94, v96
	v_mul_f32_e32 v90, v90, v96
	v_mul_f32_e32 v94, v95, v96
	v_mul_f32_e32 v91, v91, v96
	v_mul_f32_e32 v95, v99, v96
	v_mul_f32_e32 v97, v101, v96
	v_mul_f32_e32 v98, v102, v96
	v_mul_f32_e32 v99, v103, v96
	v_mul_f32_e32 v100, v120, v96
	v_mul_f32_e32 v82, v82, v96
	v_mul_f32_e32 v101, v121, v96
	v_mul_f32_e32 v83, v83, v96
	v_fma_f32 v80, v116, v80, 0
	v_fma_f32 v96, v112, v81, 0
	v_fma_f32 v81, v117, v85, 0
	v_fma_f32 v85, v113, v92, 0
	v_fma_f32 v92, v118, v93, 0
	v_fma_f32 v90, v114, v90, 0
	v_fma_f32 v93, v119, v94, 0
	v_fma_f32 v91, v115, v91, 0
	v_fma_f32 v94, v108, v95, 0
	v_fma_f32 v95, v104, v97, 0
	v_fma_f32 v97, v109, v98, 0
	v_fma_f32 v98, v105, v99, 0
	v_fma_f32 v99, v110, v100, 0
	v_fma_f32 v100, v106, v82, 0
	v_fma_f32 v102, v107, v83, 0
	v_cvt_pk_bf16_f32 v80, v80, v81
	v_cvt_pk_bf16_f32 v81, v92, v93
	v_cvt_pk_bf16_f32 v82, v96, v85
	v_cvt_pk_bf16_f32 v83, v90, v91
	v_fma_f32 v101, v111, v101, 0
	global_store_dwordx4 v[86:87], v[80:83], off sc0 sc1
	v_cvt_f32_i32_e32 v85, v65
	s_nop 0
; __device__ __forceinline__ unsigned cvt_pk_bf16(float lo, float hi) { unsigned r; asm volatile("v_cvt_pk_bf16_f32 %0, %1, %2" : "=v"(r) : "v"(lo), "v"(hi)); return r; }
; __device__ __forceinline__ float ld_agent(const float* p) { return __hip_atomic_load(p, __ATOMIC_RELAXED, __HIP_MEMORY_SCOPE_AGENT); }
; __device__ __forceinline__ float sigm(float x) { return __builtin_amdgcn_rcpf(1.f + __builtin_amdgcn_exp2f(-LOG2E * x)); }
;     __device__ __forceinline__ void operator()(const i32x4 (&acc)[2][2][4][2], const Unit& u, int wr, int wc, int fr_, int fq) const {
;     ...
;         for (int ai = 0; ai < 2; ++ai)
; #pragma unroll
;             for (int m = 0; m < 4; ++m) {
;                 asm volatile("" ::: "memory");
;                 const int r = row0 + ai * HALF + m * 16; const float rs = ld_agent(fr + r);
;                 bf16_t* rowp = O + (size_t)r * ldc + col0;
; #pragma unroll
;                 for (int bj = 0; bj < 2; ++bj) {
;                     f32x4 v0, v1;
; #pragma unroll
;                     for (int j = 0; j < 4; ++j) { v0[j] = (float)acc[ai][bj][m][0][j] * rs * sw[bj][0][j] + bv[bj][0][j]; v1[j] = (float)acc[ai][bj][m][1][j] * rs * sw[bj][1][j] + bv[bj][1][j]; }
;                     if (MODE == 1) {
; #pragma unroll
;                         for (int j = 0; j < 4; ++j) { v0[j] = sigm(v0[j]); v1[j] = sigm(v1[j]); } }
;                     u32x4 w; w.x = cvt_pk_bf16(v0[0], v0[1]); w.y = cvt_pk_bf16(v0[2], v0[3]); w.z = cvt_pk_bf16(v1[0], v1[1]); w.w = cvt_pk_bf16(v1[2], v1[3]);
;                     *(u32x4*)(rowp + bj * HALF) = w;
;                 }
;             }
	v_cvt_pk_bf16_f32 v80, v94, v97
	v_cvt_pk_bf16_f32 v81, v99, v101
	v_cvt_pk_bf16_f32 v82, v95, v98
	v_cvt_pk_bf16_f32 v83, v100, v102
	global_store_dwordx4 v[86:87], v[80:83], off offset:256 sc0 sc1
	s_nop 1
	v_mov_b32_e32 v80, v192
	v_mul_f32_e32 v73, v73, v80
	v_cvt_f32_i32_e32 v81, v68
	v_cvt_f32_i32_e32 v82, v64
	v_cvt_f32_i32_e32 v83, v69
	v_mad_i64_i32 v[64:65], s[22:23], v84, s42, v[162:163]
	v_lshl_add_u64 v[68:69], v[64:65], 0, v[128:129]
	v_mul_f32_e32 v64, v76, v80
	v_mul_f32_e32 v65, v72, v80
	v_mul_f32_e32 v72, v77, v80
	v_mul_f32_e32 v76, v78, v80
	v_mul_f32_e32 v74, v74, v80
	v_mul_f32_e32 v77, v79, v80
	v_mul_f32_e32 v75, v75, v80
	v_mul_f32_e32 v78, v81, v80
	v_mul_f32_e32 v79, v82, v80
	v_mul_f32_e32 v81, v83, v80
	v_mul_f32_e32 v82, v85, v80
	v_mul_f32_e32 v70, v70, v80
	v_mul_f32_e32 v66, v66, v80
	v_mul_f32_e32 v71, v71, v80
	v_mul_f32_e32 v67, v67, v80
	v_fma_f32 v64, v116, v64, 0
	v_fma_f32 v80, v112, v65, 0
	v_fma_f32 v65, v117, v72, 0
	v_fma_f32 v72, v113, v73, 0
	v_fma_f32 v73, v118, v76, 0
	v_fma_f32 v74, v114, v74, 0
	v_fma_f32 v76, v119, v77, 0
	v_fma_f32 v75, v115, v75, 0
	v_fma_f32 v77, v108, v78, 0
	v_fma_f32 v78, v104, v79, 0
	v_fma_f32 v79, v109, v81, 0
	v_fma_f32 v81, v105, v82, 0
	v_fma_f32 v82, v106, v66, 0
	v_fma_f32 v83, v107, v67, 0
	v_cvt_pk_bf16_f32 v64, v64, v65
	v_cvt_pk_bf16_f32 v65, v73, v76
	v_cvt_pk_bf16_f32 v66, v80, v72
	v_cvt_pk_bf16_f32 v67, v74, v75
	v_fma_f32 v70, v110, v70, 0
	v_fma_f32 v71, v111, v71, 0
	global_store_dwordx4 v[68:69], v[64:67], off sc0 sc1
	s_nop 1
	v_cvt_pk_bf16_f32 v64, v77, v79
	v_cvt_pk_bf16_f32 v65, v70, v71
	v_cvt_pk_bf16_f32 v66, v78, v81
	v_cvt_pk_bf16_f32 v67, v82, v83
	global_store_dwordx4 v[68:69], v[64:67], off offset:256 sc0 sc1
	s_nop 1
	v_mov_b32_e32 v64, v193
	v_cvt_f32_i32_e32 v68, v49
	v_cvt_f32_i32_e32 v65, v52
	v_cvt_f32_i32_e32 v66, v48
	v_cvt_f32_i32_e32 v67, v53
	v_add_u32_e32 v48, 0x80, v160
	v_mad_i64_i32 v[48:49], s[22:23], v48, s42, v[162:163]
	v_lshl_add_u64 v[52:53], v[48:49], 0, v[128:129]
	v_mul_f32_e32 v48, v60, v64
	v_mul_f32_e32 v49, v56, v64
	v_mul_f32_e32 v56, v61, v64
	v_mul_f32_e32 v57, v57, v64
	v_mul_f32_e32 v60, v62, v64
	v_mul_f32_e32 v58, v58, v64
	v_mul_f32_e32 v61, v63, v64
	v_mul_f32_e32 v59, v59, v64
	v_mul_f32_e32 v62, v65, v64
	v_mul_f32_e32 v63, v66, v64
	v_mul_f32_e32 v65, v67, v64
	v_mul_f32_e32 v66, v68, v64
	v_mul_f32_e32 v54, v54, v64
	v_mul_f32_e32 v50, v50, v64
	v_mul_f32_e32 v55, v55, v64
	v_mul_f32_e32 v51, v51, v64
	v_fma_f32 v48, v116, v48, 0
	v_fma_f32 v64, v112, v49, 0
	v_fma_f32 v49, v117, v56, 0
	v_fma_f32 v56, v113, v57, 0
	v_fma_f32 v57, v118, v60, 0
	v_fma_f32 v58, v114, v58, 0
	v_fma_f32 v60, v119, v61, 0
	v_fma_f32 v59, v115, v59, 0
	v_fma_f32 v61, v108, v62, 0
	v_fma_f32 v62, v104, v63, 0
	v_fma_f32 v63, v109, v65, 0
	v_fma_f32 v65, v105, v66, 0
	v_fma_f32 v66, v106, v50, 0
	v_fma_f32 v67, v107, v51, 0
	v_cvt_pk_bf16_f32 v48, v48, v49
	v_cvt_pk_bf16_f32 v49, v57, v60
	v_cvt_pk_bf16_f32 v50, v64, v56
	v_cvt_pk_bf16_f32 v51, v58, v59
	v_fma_f32 v54, v110, v54, 0
	v_fma_f32 v55, v111, v55, 0
	global_store_dwordx4 v[52:53], v[48:51], off sc0 sc1
	s_nop 1
	v_cvt_pk_bf16_f32 v48, v61, v63
	v_cvt_pk_bf16_f32 v49, v54, v55
	v_cvt_pk_bf16_f32 v50, v62, v65
	v_cvt_pk_bf16_f32 v51, v66, v67
	global_store_dwordx4 v[52:53], v[48:51], off offset:256 sc0 sc1
	s_nop 1
	v_mov_b32_e32 v48, v194
	v_cvt_f32_i32_e32 v52, v33
	v_cvt_f32_i32_e32 v49, v36
	v_cvt_f32_i32_e32 v50, v32
	v_cvt_f32_i32_e32 v51, v37
	v_add_u32_e32 v32, 0x90, v160
	v_mad_i64_i32 v[32:33], s[22:23], v32, s42, v[162:163]
	v_lshl_add_u64 v[36:37], v[32:33], 0, v[128:129]
	v_mul_f32_e32 v32, v44, v48
	v_mul_f32_e32 v33, v40, v48
	v_mul_f32_e32 v40, v45, v48
	v_mul_f32_e32 v41, v41, v48
	v_mul_f32_e32 v44, v46, v48
	v_mul_f32_e32 v42, v42, v48
	v_mul_f32_e32 v45, v47, v48
	v_mul_f32_e32 v43, v43, v48
	v_mul_f32_e32 v46, v49, v48
	v_mul_f32_e32 v47, v50, v48
	v_mul_f32_e32 v49, v51, v48
	v_mul_f32_e32 v50, v52, v48
	v_mul_f32_e32 v38, v38, v48
	v_mul_f32_e32 v34, v34, v48
	v_mul_f32_e32 v39, v39, v48
	v_mul_f32_e32 v35, v35, v48
	v_fma_f32 v32, v116, v32, 0
; __device__ __forceinline__ unsigned cvt_pk_bf16(float lo, float hi) { unsigned r; asm volatile("v_cvt_pk_bf16_f32 %0, %1, %2" : "=v"(r) : "v"(lo), "v"(hi)); return r; }
; __device__ __forceinline__ float ld_agent(const float* p) { return __hip_atomic_load(p, __ATOMIC_RELAXED, __HIP_MEMORY_SCOPE_AGENT); }
; __device__ __forceinline__ float sigm(float x) { return __builtin_amdgcn_rcpf(1.f + __builtin_amdgcn_exp2f(-LOG2E * x)); }
; #define PG8_WAIT_V(n) asm volatile("s_waitcnt vmcnt(" #n ")" ::: "memory")
; #define PG8_BAR __builtin_amdgcn_s_barrier()
;     __device__ __forceinline__ void operator()(const i32x4 (&acc)[2][2][4][2], const Unit& u, int wr, int wc, int fr_, int fq) const {
;     ...
;         for (int ai = 0; ai < 2; ++ai)
; #pragma unroll
;             for (int m = 0; m < 4; ++m) {
;                 asm volatile("" ::: "memory");
;                 const int r = row0 + ai * HALF + m * 16; const float rs = ld_agent(fr + r);
;                 bf16_t* rowp = O + (size_t)r * ldc + col0;
; #pragma unroll
;                 for (int bj = 0; bj < 2; ++bj) {
;                     f32x4 v0, v1;
; #pragma unroll
;                     for (int j = 0; j < 4; ++j) { v0[j] = (float)acc[ai][bj][m][0][j] * rs * sw[bj][0][j] + bv[bj][0][j]; v1[j] = (float)acc[ai][bj][m][1][j] * rs * sw[bj][1][j] + bv[bj][1][j]; }
;                     if (MODE == 1) {
; #pragma unroll
;                         for (int j = 0; j < 4; ++j) { v0[j] = sigm(v0[j]); v1[j] = sigm(v1[j]); } }
;                     u32x4 w; w.x = cvt_pk_bf16(v0[0], v0[1]); w.y = cvt_pk_bf16(v0[2], v0[3]); w.z = cvt_pk_bf16(v1[0], v1[1]); w.w = cvt_pk_bf16(v1[2], v1[3]);
;                     *(u32x4*)(rowp + bj * HALF) = w;
;                 }
;             }
; template <class Epi, class Sched>
; __device__ __forceinline__ void gemm_phase(LAS unsigned char* lds, const Gemm g, const Sched& S, const Epi& E) {
;     ...
;         if (!has_next) break;
; #pragma unroll
;         for (int a = 0; a < 2; ++a)
; #pragma unroll
;             for (int b = 0; b < 2; ++b)
; #pragma unroll
;                 for (int m = 0; m < 4; ++m)
; #pragma unroll
;                     for (int n = 0; n < 2; ++n) acc[a][b][m][n] = (acc_t){0, 0, 0, 0};
;         cur = nxt; cA = nA; cB = nB; ++ui;
;     }
;     PG8_WAIT_V(0);
;     if (wr == 0) PG8_BAR;
;     PG8_BAR;
	v_fma_f32 v48, v112, v33, 0
	v_fma_f32 v33, v117, v40, 0
	v_fma_f32 v40, v113, v41, 0
	v_fma_f32 v41, v118, v44, 0
	v_fma_f32 v42, v114, v42, 0
	v_fma_f32 v44, v119, v45, 0
	v_fma_f32 v43, v115, v43, 0
	v_fma_f32 v45, v108, v46, 0
	v_fma_f32 v46, v104, v47, 0
	v_fma_f32 v47, v109, v49, 0
	v_fma_f32 v49, v105, v50, 0
	v_fma_f32 v50, v106, v34, 0
	v_fma_f32 v51, v107, v35, 0
	v_cvt_pk_bf16_f32 v32, v32, v33
	v_cvt_pk_bf16_f32 v33, v41, v44
	v_cvt_pk_bf16_f32 v34, v48, v40
	v_cvt_pk_bf16_f32 v35, v42, v43
	v_fma_f32 v38, v110, v38, 0
	v_fma_f32 v39, v111, v39, 0
	global_store_dwordx4 v[36:37], v[32:35], off sc0 sc1
	s_nop 1
	v_cvt_pk_bf16_f32 v32, v45, v47
	v_cvt_pk_bf16_f32 v33, v38, v39
	v_cvt_pk_bf16_f32 v34, v46, v49
	v_cvt_pk_bf16_f32 v35, v50, v51
	global_store_dwordx4 v[36:37], v[32:35], off offset:256 sc0 sc1
	s_nop 1
	v_mov_b32_e32 v32, v195
	v_cvt_f32_i32_e32 v36, v17
	v_cvt_f32_i32_e32 v33, v20
	v_cvt_f32_i32_e32 v34, v16
	v_cvt_f32_i32_e32 v35, v21
	v_add_u32_e32 v16, 0xa0, v160
	v_mad_i64_i32 v[16:17], s[22:23], v16, s42, v[162:163]
	v_lshl_add_u64 v[20:21], v[16:17], 0, v[128:129]
	s_mov_b64 s[22:23], s[16:17]
	v_mul_f32_e32 v16, v28, v32
	v_mul_f32_e32 v17, v24, v32
	v_mul_f32_e32 v24, v29, v32
	v_mul_f32_e32 v25, v25, v32
	v_mul_f32_e32 v28, v30, v32
	v_mul_f32_e32 v26, v26, v32
	v_mul_f32_e32 v29, v31, v32
	v_mul_f32_e32 v27, v27, v32
	v_mul_f32_e32 v30, v33, v32
	v_mul_f32_e32 v31, v34, v32
	v_mul_f32_e32 v33, v35, v32
	v_mul_f32_e32 v34, v36, v32
	v_mul_f32_e32 v22, v22, v32
	v_mul_f32_e32 v18, v18, v32
	v_mul_f32_e32 v23, v23, v32
	v_mul_f32_e32 v19, v19, v32
	v_fma_f32 v16, v116, v16, 0
	v_fma_f32 v32, v112, v17, 0
	v_fma_f32 v17, v117, v24, 0
	v_fma_f32 v24, v113, v25, 0
	v_fma_f32 v25, v118, v28, 0
	v_fma_f32 v26, v114, v26, 0
	v_fma_f32 v28, v119, v29, 0
	v_fma_f32 v27, v115, v27, 0
	v_fma_f32 v29, v108, v30, 0
	v_fma_f32 v30, v104, v31, 0
	v_fma_f32 v31, v109, v33, 0
	v_fma_f32 v33, v105, v34, 0
	v_fma_f32 v34, v106, v18, 0
	v_fma_f32 v35, v107, v19, 0
	v_cvt_pk_bf16_f32 v16, v16, v17
	v_cvt_pk_bf16_f32 v17, v25, v28
	v_cvt_pk_bf16_f32 v18, v32, v24
	v_cvt_pk_bf16_f32 v19, v26, v27
	v_fma_f32 v22, v110, v22, 0
	v_fma_f32 v23, v111, v23, 0
	global_store_dwordx4 v[20:21], v[16:19], off sc0 sc1
	s_nop 1
	v_cvt_pk_bf16_f32 v16, v29, v31
	v_cvt_pk_bf16_f32 v17, v22, v23
	v_cvt_pk_bf16_f32 v18, v30, v33
	v_cvt_pk_bf16_f32 v19, v34, v35
	global_store_dwordx4 v[20:21], v[16:19], off offset:256 sc0 sc1
	s_nop 1
	v_mov_b32_e32 v16, v196
	v_cvt_f32_i32_e32 v20, v1
	v_cvt_f32_i32_e32 v17, v4
	v_cvt_f32_i32_e32 v18, v0
	v_cvt_f32_i32_e32 v19, v5
	v_add_u32_e32 v0, 0xb0, v160
	v_mad_i64_i32 v[0:1], s[0:1], v0, s42, v[162:163]
	v_lshl_add_u64 v[4:5], v[0:1], 0, v[128:129]
	v_mul_f32_e32 v0, v12, v16
	v_mul_f32_e32 v1, v8, v16
	v_mul_f32_e32 v8, v13, v16
	v_mul_f32_e32 v9, v9, v16
	v_mul_f32_e32 v12, v14, v16
	v_mul_f32_e32 v10, v10, v16
	v_mul_f32_e32 v13, v15, v16
	v_mul_f32_e32 v11, v11, v16
	v_mul_f32_e32 v14, v17, v16
	v_mul_f32_e32 v15, v18, v16
	v_mul_f32_e32 v17, v19, v16
	v_mul_f32_e32 v18, v20, v16
	v_mul_f32_e32 v6, v6, v16
	v_mul_f32_e32 v2, v2, v16
	v_mul_f32_e32 v7, v7, v16
	v_mul_f32_e32 v3, v3, v16
	v_fma_f32 v0, v116, v0, 0
	v_fma_f32 v16, v112, v1, 0
	v_fma_f32 v1, v117, v8, 0
	v_fma_f32 v8, v113, v9, 0
	v_fma_f32 v9, v118, v12, 0
	v_fma_f32 v10, v114, v10, 0
	v_fma_f32 v12, v119, v13, 0
	v_fma_f32 v11, v115, v11, 0
	v_fma_f32 v13, v108, v14, 0
	v_fma_f32 v14, v104, v15, 0
	v_fma_f32 v15, v109, v17, 0
	v_fma_f32 v17, v105, v18, 0
	v_fma_f32 v18, v106, v2, 0
	v_fma_f32 v19, v107, v3, 0
	v_cvt_pk_bf16_f32 v0, v0, v1
	v_cvt_pk_bf16_f32 v1, v9, v12
	v_cvt_pk_bf16_f32 v2, v16, v8
	v_cvt_pk_bf16_f32 v3, v10, v11
	v_fma_f32 v6, v110, v6, 0
	v_fma_f32 v7, v111, v7, 0
	global_store_dwordx4 v[4:5], v[0:3], off sc0 sc1
	s_nop 1
	v_cvt_pk_bf16_f32 v0, v13, v15
	v_cvt_pk_bf16_f32 v1, v6, v7
	v_cvt_pk_bf16_f32 v2, v14, v17
	v_cvt_pk_bf16_f32 v3, v18, v19
	global_store_dwordx4 v[4:5], v[0:3], off offset:256 sc0 sc1
	s_cbranch_vccz .LBB0_383
	s_waitcnt vmcnt(0)
	s_cmpk_gt_u32 s28, 0xff
	s_cbranch_scc1 .LBB0_390
	s_barrier

; #define PG8_STAGE(bufoff, gbase, voff) do { _Pragma("unroll") for (int _i = 0; _i < 2; ++_i) \
;         __builtin_amdgcn_global_load_lds((const unsigned*)((const char*)(gbase) + (voff)[_i]), (LAS unsigned*)(lds + (bufoff) + ldsw + _i * 8192), 16, 0, 0); } while (0)
; #define PG8_LDA(dst, b, h) do { _Pragma("unroll") for (int m = 0; m < 4; ++m) _Pragma("unroll") for (int k = 0; k < 2; ++k) dst[m][k] = *(const LAS bf16x8*)(lds + PG8_SA(b, h) + aoff + m * 2048 + k * 1024); } while (0)
; #define PG8_LDB(dst, b, h) do { _Pragma("unroll") for (int n = 0; n < 2; ++n) _Pragma("unroll") for (int k = 0; k < 2; ++k) dst[n][k] = *(const LAS bf16x8*)(lds + PG8_SB(b, h) + boff + n * 2048 + k * 1024); } while (0)
; #define PG8_MMA(ai, bj, At, Bt) do { __builtin_amdgcn_s_setprio(1); _Pragma("unroll") for (int m = 0; m < 4; ++m) _Pragma("unroll") for (int n = 0; n < 2; ++n) _Pragma("unroll") for (int k = 0; k < 2; ++k) \
;         acc[ai][bj][m][n] = MmaOp<Epi::I8>::run(Bt[n][k], At[m][k], acc[ai][bj][m][n]); __builtin_amdgcn_s_setprio(0); } while (0)
; #define PG8_WAIT_V(n) asm volatile("s_waitcnt vmcnt(" #n ")" ::: "memory")
; #define PG8_WAIT_L(n) asm volatile("s_waitcnt lgkmcnt(" #n ")" ::: "memory")
; #define PG8_BAR __builtin_amdgcn_s_barrier()
; #define PG8_SCHED __builtin_amdgcn_sched_barrier(0)
; template <class Epi, class Sched>
; __device__ __forceinline__ void gemm_phase(LAS unsigned char* lds, const Gemm g, const Sched& S, const Epi& E) {
;     ...
;             PG8_LDB(B0, 0, 0); PG8_SCHED; PG8_LDA(At, 0, 0); PG8_STAGE(PG8_SA(1, 1), a1 + hstepA, voffA);
;             PG8_WAIT_L(8); PG8_BAR; PG8_WAIT_L(0); PG8_MMA(0, 0, At, B0); PG8_BAR; PG8_SCHED;
;             PG8_LDB(B1, 0, 1); PG8_STAGE(PG8_SB(0, 0), b2, voffB);
;             PG8_BAR; PG8_WAIT_L(0); PG8_MMA(0, 1, At, B1); PG8_BAR;
;             PG8_LDA(At, 0, 1); PG8_STAGE(PG8_SA(0, 0), a2, voffA);
;             PG8_BAR; PG8_WAIT_L(0); PG8_MMA(1, 0, At, B0); PG8_BAR; PG8_SCHED;
;             PG8_STAGE(PG8_SB(0, 1), b2 + hstepB, voffB);
;             PG8_WAIT_V(6); PG8_BAR; PG8_MMA(1, 1, At, B1); PG8_BAR;
.LBB0_635:
	ds_read_b128 v[56:59], v169
	ds_read_b128 v[60:63], v169 offset:1024
	ds_read_b128 v[72:75], v169 offset:2048
	ds_read_b128 v[76:79], v169 offset:3072
	s_add_u32 s30, s28, 0xfff80080
	s_addc_u32 s31, s29, -1
	s_cmp_eq_u32 s59, 12
	s_cselect_b32 s35, s21, s31
	s_cselect_b32 s34, s55, s30
	s_cselect_b32 s31, s19, s58
	s_cselect_b32 s30, s56, s57
	v_lshl_add_u64 v[164:165], s[28:29], 0, v[152:153]
	s_add_i32 m0, s27, 0xc000
	ds_read_b128 v[160:163], v170
	ds_read_b128 v[178:181], v170 offset:1024
	ds_read_b128 v[182:185], v170 offset:2048
	ds_read_b128 v[186:189], v170 offset:3072
	ds_read_b128 v[190:193], v170 offset:4096
	ds_read_b128 v[194:197], v170 offset:5120
	ds_read_b128 v[198:201], v170 offset:6144
	ds_read_b128 v[202:205], v170 offset:7168
	global_load_lds_dwordx4 v[164:165], off
	v_lshl_add_u64 v[164:165], s[28:29], 0, v[154:155]
	s_add_i32 m0, s27, 0xe000
	s_nop 0
	global_load_lds_dwordx4 v[164:165], off
	s_waitcnt lgkmcnt(8)
	s_barrier
	s_waitcnt lgkmcnt(0)
	s_setprio 1
	v_mfma_i32_16x16x64_i8 v[140:143], v[56:59], v[160:163], v[140:143]
	v_mfma_i32_16x16x64_i8 v[136:139], v[72:75], v[160:163], v[136:139]
	v_mfma_i32_16x16x64_i8 v[124:127], v[56:59], v[182:185], v[124:127]
	v_mfma_i32_16x16x64_i8 v[120:123], v[72:75], v[182:185], v[120:123]
	v_mfma_i32_16x16x64_i8 v[108:111], v[56:59], v[190:193], v[108:111]
	v_mfma_i32_16x16x64_i8 v[104:107], v[72:75], v[190:193], v[104:107]
	v_mfma_i32_16x16x64_i8 v[92:95], v[56:59], v[198:201], v[92:95]
	v_mfma_i32_16x16x64_i8 v[88:91], v[72:75], v[198:201], v[88:91]
	v_mfma_i32_16x16x64_i8 v[140:143], v[60:63], v[178:181], v[140:143]
	v_mfma_i32_16x16x64_i8 v[136:139], v[76:79], v[178:181], v[136:139]
	v_mfma_i32_16x16x64_i8 v[124:127], v[60:63], v[186:189], v[124:127]
	v_mfma_i32_16x16x64_i8 v[120:123], v[76:79], v[186:189], v[120:123]
	v_mfma_i32_16x16x64_i8 v[108:111], v[60:63], v[194:197], v[108:111]
	v_mfma_i32_16x16x64_i8 v[104:107], v[76:79], v[194:197], v[104:107]
	v_mfma_i32_16x16x64_i8 v[92:95], v[60:63], v[202:205], v[92:95]
	v_mfma_i32_16x16x64_i8 v[88:91], v[76:79], v[202:205], v[88:91]
	s_setprio 0
	s_barrier
	s_add_i32 s60, s48, s38
	v_lshl_add_u64 v[164:165], s[30:31], 0, v[148:149]
	s_mov_b32 m0, s60
	ds_read_b128 v[206:209], v171
	ds_read_b128 v[210:213], v171 offset:1024
	ds_read_b128 v[214:217], v171 offset:2048
	ds_read_b128 v[218:221], v171 offset:3072
	global_load_lds_dwordx4 v[164:165], off
	v_lshl_add_u64 v[174:175], s[30:31], 0, v[144:145]
	s_add_i32 m0, s60, 0x2000
	s_nop 0
	global_load_lds_dwordx4 v[174:175], off
	s_barrier
	s_waitcnt lgkmcnt(0)
	s_setprio 1
	v_mfma_i32_16x16x64_i8 v[132:135], v[206:209], v[160:163], v[132:135]
	v_mfma_i32_16x16x64_i8 v[128:131], v[214:217], v[160:163], v[128:131]
	v_mfma_i32_16x16x64_i8 v[116:119], v[206:209], v[182:185], v[116:119]
	v_mfma_i32_16x16x64_i8 v[112:115], v[214:217], v[182:185], v[112:115]
	v_mfma_i32_16x16x64_i8 v[100:103], v[206:209], v[190:193], v[100:103]
	v_mfma_i32_16x16x64_i8 v[96:99], v[214:217], v[190:193], v[96:99]
	v_mfma_i32_16x16x64_i8 v[84:87], v[206:209], v[198:201], v[84:87]
	v_mfma_i32_16x16x64_i8 v[80:83], v[214:217], v[198:201], v[80:83]
	v_mfma_i32_16x16x64_i8 v[132:135], v[210:213], v[178:181], v[132:135]
	v_mfma_i32_16x16x64_i8 v[128:131], v[218:221], v[178:181], v[128:131]
	v_mfma_i32_16x16x64_i8 v[116:119], v[210:213], v[186:189], v[116:119]
	v_mfma_i32_16x16x64_i8 v[112:115], v[218:221], v[186:189], v[112:115]
	v_mfma_i32_16x16x64_i8 v[100:103], v[210:213], v[194:197], v[100:103]
	v_mfma_i32_16x16x64_i8 v[96:99], v[218:221], v[194:197], v[96:99]
	v_mfma_i32_16x16x64_i8 v[84:87], v[210:213], v[202:205], v[84:87]
	v_mfma_i32_16x16x64_i8 v[80:83], v[218:221], v[202:205], v[80:83]
	s_setprio 0
	s_mov_b32 m0, s27
	v_lshl_add_u64 v[222:223], s[34:35], 0, v[150:151]
	s_barrier
	ds_read_b128 v[160:163], v170 offset:16384
	ds_read_b128 v[178:181], v170 offset:17408
	ds_read_b128 v[182:185], v170 offset:18432
	ds_read_b128 v[186:189], v170 offset:19456
	ds_read_b128 v[190:193], v170 offset:20480
	ds_read_b128 v[194:197], v170 offset:21504
	ds_read_b128 v[198:201], v170 offset:22528
	ds_read_b128 v[202:205], v170 offset:23552
	global_load_lds_dwordx4 v[222:223], off
	v_lshl_add_u64 v[224:225], s[34:35], 0, v[146:147]
	s_mov_b32 m0, s41
	s_nop 0
	global_load_lds_dwordx4 v[224:225], off
	s_barrier
	s_waitcnt lgkmcnt(0)
	s_setprio 1
	v_mfma_i32_16x16x64_i8 v[68:71], v[56:59], v[160:163], v[68:71]
	v_mfma_i32_16x16x64_i8 v[64:67], v[72:75], v[160:163], v[64:67]
	v_mfma_i32_16x16x64_i8 v[44:47], v[56:59], v[182:185], v[44:47]
	v_mfma_i32_16x16x64_i8 v[40:43], v[72:75], v[182:185], v[40:43]
	v_mfma_i32_16x16x64_i8 v[28:31], v[56:59], v[190:193], v[28:31]
	v_mfma_i32_16x16x64_i8 v[24:27], v[72:75], v[190:193], v[24:27]
	v_mfma_i32_16x16x64_i8 v[12:15], v[56:59], v[198:201], v[12:15]
	v_mfma_i32_16x16x64_i8 v[8:11], v[72:75], v[198:201], v[8:11]
	v_mfma_i32_16x16x64_i8 v[68:71], v[60:63], v[178:181], v[68:71]
	v_mfma_i32_16x16x64_i8 v[64:67], v[76:79], v[178:181], v[64:67]
	v_mfma_i32_16x16x64_i8 v[44:47], v[60:63], v[186:189], v[44:47]
	v_mfma_i32_16x16x64_i8 v[40:43], v[76:79], v[186:189], v[40:43]
	v_mfma_i32_16x16x64_i8 v[28:31], v[60:63], v[194:197], v[28:31]
	v_mfma_i32_16x16x64_i8 v[24:27], v[76:79], v[194:197], v[24:27]
	v_mfma_i32_16x16x64_i8 v[12:15], v[60:63], v[202:205], v[12:15]
	v_mfma_i32_16x16x64_i8 v[8:11], v[76:79], v[202:205], v[8:11]
	s_setprio 0
	s_barrier
	s_add_u32 s60, s30, 0x40000
	s_addc_u32 s61, s31, 0
	s_add_i32 s62, s49, s38
	v_lshl_add_u64 v[56:57], s[60:61], 0, v[148:149]
	s_mov_b32 m0, s62
	s_nop 0
	global_load_lds_dwordx4 v[56:57], off
	v_lshl_add_u64 v[56:57], s[60:61], 0, v[144:145]
	s_add_i32 m0, s62, 0x2000
	s_nop 0
	global_load_lds_dwordx4 v[56:57], off
	s_waitcnt vmcnt(6)
	s_barrier
; #define PG8_STAGE(bufoff, gbase, voff) do { _Pragma("unroll") for (int _i = 0; _i < 2; ++_i) \
;         __builtin_amdgcn_global_load_lds((const unsigned*)((const char*)(gbase) + (voff)[_i]), (LAS unsigned*)(lds + (bufoff) + ldsw + _i * 8192), 16, 0, 0); } while (0)
; #define PG8_LDA(dst, b, h) do { _Pragma("unroll") for (int m = 0; m < 4; ++m) _Pragma("unroll") for (int k = 0; k < 2; ++k) dst[m][k] = *(const LAS bf16x8*)(lds + PG8_SA(b, h) + aoff + m * 2048 + k * 1024); } while (0)
; #define PG8_LDB(dst, b, h) do { _Pragma("unroll") for (int n = 0; n < 2; ++n) _Pragma("unroll") for (int k = 0; k < 2; ++k) dst[n][k] = *(const LAS bf16x8*)(lds + PG8_SB(b, h) + boff + n * 2048 + k * 1024); } while (0)
; #define PG8_MMA(ai, bj, At, Bt) do { __builtin_amdgcn_s_setprio(1); _Pragma("unroll") for (int m = 0; m < 4; ++m) _Pragma("unroll") for (int n = 0; n < 2; ++n) _Pragma("unroll") for (int k = 0; k < 2; ++k) \
;         acc[ai][bj][m][n] = MmaOp<Epi::I8>::run(Bt[n][k], At[m][k], acc[ai][bj][m][n]); __builtin_amdgcn_s_setprio(0); } while (0)
; #define PG8_WAIT_V(n) asm volatile("s_waitcnt vmcnt(" #n ")" ::: "memory")
; #define PG8_WAIT_L(n) asm volatile("s_waitcnt lgkmcnt(" #n ")" ::: "memory")
; #define PG8_BAR __builtin_amdgcn_s_barrier()
; #define PG8_SCHED __builtin_amdgcn_sched_barrier(0)
; template <class Epi, class Sched>
; __device__ __forceinline__ void gemm_phase(LAS unsigned char* lds, const Gemm g, const Sched& S, const Epi& E) {
;     ...
;             PG8_WAIT_V(6); PG8_BAR; PG8_MMA(1, 1, At, B1); PG8_BAR;
;             PG8_LDB(B0, 1, 0); PG8_SCHED; PG8_LDA(At, 1, 0); PG8_STAGE(PG8_SA(0, 1), a2 + hstepA, voffA);
;             PG8_WAIT_L(8); PG8_BAR; PG8_WAIT_L(0); PG8_MMA(0, 0, At, B0); PG8_BAR; PG8_SCHED;
;             PG8_LDB(B1, 1, 1); PG8_STAGE(PG8_SB(1, 0), b3, voffB);
;             PG8_BAR; PG8_WAIT_L(0); PG8_MMA(0, 1, At, B1); PG8_BAR;
;             PG8_LDA(At, 1, 1); PG8_STAGE(PG8_SA(1, 0), a3, voffA);
;             PG8_BAR; PG8_WAIT_L(0); PG8_MMA(1, 0, At, B0); PG8_BAR; PG8_SCHED;
	s_setprio 1
	v_mfma_i32_16x16x64_i8 v[52:55], v[206:209], v[160:163], v[52:55]
	v_mfma_i32_16x16x64_i8 v[48:51], v[214:217], v[160:163], v[48:51]
	v_mfma_i32_16x16x64_i8 v[36:39], v[206:209], v[182:185], v[36:39]
	v_mfma_i32_16x16x64_i8 v[32:35], v[214:217], v[182:185], v[32:35]
	v_mfma_i32_16x16x64_i8 v[20:23], v[206:209], v[190:193], v[20:23]
	v_mfma_i32_16x16x64_i8 v[16:19], v[214:217], v[190:193], v[16:19]
	v_mfma_i32_16x16x64_i8 v[4:7], v[206:209], v[198:201], v[4:7]
	v_mfma_i32_16x16x64_i8 v[0:3], v[214:217], v[198:201], v[0:3]
	v_mfma_i32_16x16x64_i8 v[52:55], v[210:213], v[178:181], v[52:55]
	v_mfma_i32_16x16x64_i8 v[48:51], v[218:221], v[178:181], v[48:51]
	v_mfma_i32_16x16x64_i8 v[36:39], v[210:213], v[186:189], v[36:39]
	v_mfma_i32_16x16x64_i8 v[32:35], v[218:221], v[186:189], v[32:35]
	v_mfma_i32_16x16x64_i8 v[20:23], v[210:213], v[194:197], v[20:23]
	v_mfma_i32_16x16x64_i8 v[16:19], v[218:221], v[194:197], v[16:19]
	v_mfma_i32_16x16x64_i8 v[4:7], v[210:213], v[202:205], v[4:7]
	v_mfma_i32_16x16x64_i8 v[0:3], v[218:221], v[202:205], v[0:3]
	s_setprio 0
	s_add_i32 s60, 0, 0x18000
	v_add_u32_e32 v76, s60, v167
	s_barrier
	ds_read_b128 v[56:59], v76
	ds_read_b128 v[60:63], v76 offset:1024
	ds_read_b128 v[72:75], v76 offset:2048
	ds_read_b128 v[76:79], v76 offset:3072
	s_add_u32 s34, s34, 0x80000
	s_addc_u32 s35, s35, 0
	s_mov_b32 m0, s42
	v_lshl_add_u64 v[206:207], s[34:35], 0, v[150:151]
	ds_read_b128 v[160:163], v170 offset:32768
	ds_read_b128 v[178:181], v170 offset:33792
	ds_read_b128 v[182:185], v170 offset:34816
	ds_read_b128 v[186:189], v170 offset:35840
	ds_read_b128 v[190:193], v170 offset:36864
	ds_read_b128 v[194:197], v170 offset:37888
	ds_read_b128 v[198:201], v170 offset:38912
	ds_read_b128 v[202:205], v170 offset:39936
	global_load_lds_dwordx4 v[206:207], off
	v_lshl_add_u64 v[206:207], s[34:35], 0, v[146:147]
	s_mov_b32 m0, s43
	s_nop 0
	global_load_lds_dwordx4 v[206:207], off
	s_waitcnt lgkmcnt(8)
	s_barrier
	s_waitcnt lgkmcnt(0)
	s_setprio 1
	v_mfma_i32_16x16x64_i8 v[140:143], v[56:59], v[160:163], v[140:143]
	v_mfma_i32_16x16x64_i8 v[136:139], v[72:75], v[160:163], v[136:139]
	v_mfma_i32_16x16x64_i8 v[124:127], v[56:59], v[182:185], v[124:127]
	v_mfma_i32_16x16x64_i8 v[120:123], v[72:75], v[182:185], v[120:123]
	v_mfma_i32_16x16x64_i8 v[108:111], v[56:59], v[190:193], v[108:111]
	v_mfma_i32_16x16x64_i8 v[104:107], v[72:75], v[190:193], v[104:107]
	v_mfma_i32_16x16x64_i8 v[92:95], v[56:59], v[198:201], v[92:95]
	v_mfma_i32_16x16x64_i8 v[88:91], v[72:75], v[198:201], v[88:91]
	v_mfma_i32_16x16x64_i8 v[140:143], v[60:63], v[178:181], v[140:143]
	v_mfma_i32_16x16x64_i8 v[136:139], v[76:79], v[178:181], v[136:139]
	v_mfma_i32_16x16x64_i8 v[124:127], v[60:63], v[186:189], v[124:127]
	v_mfma_i32_16x16x64_i8 v[120:123], v[76:79], v[186:189], v[120:123]
	v_mfma_i32_16x16x64_i8 v[108:111], v[60:63], v[194:197], v[108:111]
	v_mfma_i32_16x16x64_i8 v[104:107], v[76:79], v[194:197], v[104:107]
	v_mfma_i32_16x16x64_i8 v[92:95], v[60:63], v[202:205], v[92:95]
	v_mfma_i32_16x16x64_i8 v[88:91], v[76:79], v[202:205], v[88:91]
	s_setprio 0
	s_barrier
	s_add_i32 s34, 0, 0x1c000
	s_add_i32 s35, s60, s38
	v_add_u32_e32 v173, s34, v167
	v_lshl_add_u64 v[164:165], v[164:165], 0, s[8:9]
	s_mov_b32 m0, s35
	ds_read_b128 v[206:209], v173
	ds_read_b128 v[210:213], v173 offset:1024
	ds_read_b128 v[214:217], v173 offset:2048
	ds_read_b128 v[218:221], v173 offset:3072
	global_load_lds_dwordx4 v[164:165], off
	v_lshl_add_u64 v[164:165], v[174:175], 0, s[8:9]
	s_add_i32 m0, s35, 0x2000
	s_nop 0
	global_load_lds_dwordx4 v[164:165], off
	s_barrier
	s_waitcnt lgkmcnt(0)
	s_setprio 1
	v_mfma_i32_16x16x64_i8 v[132:135], v[206:209], v[160:163], v[132:135]
	v_mfma_i32_16x16x64_i8 v[128:131], v[214:217], v[160:163], v[128:131]
	v_mfma_i32_16x16x64_i8 v[116:119], v[206:209], v[182:185], v[116:119]
	v_mfma_i32_16x16x64_i8 v[112:115], v[214:217], v[182:185], v[112:115]
	v_mfma_i32_16x16x64_i8 v[100:103], v[206:209], v[190:193], v[100:103]
	v_mfma_i32_16x16x64_i8 v[96:99], v[214:217], v[190:193], v[96:99]
	v_mfma_i32_16x16x64_i8 v[84:87], v[206:209], v[198:201], v[84:87]
	v_mfma_i32_16x16x64_i8 v[80:83], v[214:217], v[198:201], v[80:83]
	v_mfma_i32_16x16x64_i8 v[132:135], v[210:213], v[178:181], v[132:135]
	v_mfma_i32_16x16x64_i8 v[128:131], v[218:221], v[178:181], v[128:131]
	v_mfma_i32_16x16x64_i8 v[116:119], v[210:213], v[186:189], v[116:119]
	v_mfma_i32_16x16x64_i8 v[112:115], v[218:221], v[186:189], v[112:115]
	v_mfma_i32_16x16x64_i8 v[100:103], v[210:213], v[194:197], v[100:103]
	v_mfma_i32_16x16x64_i8 v[96:99], v[218:221], v[194:197], v[96:99]
	v_mfma_i32_16x16x64_i8 v[84:87], v[210:213], v[202:205], v[84:87]
	v_mfma_i32_16x16x64_i8 v[80:83], v[218:221], v[202:205], v[80:83]
	s_setprio 0
	s_mov_b32 m0, s45
	v_lshl_add_u64 v[164:165], v[222:223], 0, s[8:9]
	s_barrier
	ds_read_b128 v[160:163], v170 offset:49152
	ds_read_b128 v[178:181], v170 offset:50176
	ds_read_b128 v[182:185], v170 offset:51200
	ds_read_b128 v[186:189], v170 offset:52224
	ds_read_b128 v[190:193], v170 offset:53248
	ds_read_b128 v[194:197], v170 offset:54272
	ds_read_b128 v[198:201], v170 offset:55296
	ds_read_b128 v[202:205], v170 offset:56320
	global_load_lds_dwordx4 v[164:165], off
	v_lshl_add_u64 v[164:165], v[224:225], 0, s[8:9]
	s_mov_b32 m0, s46
	s_nop 0
	global_load_lds_dwordx4 v[164:165], off
	s_barrier
; __device__ __forceinline__ float rs_of(const float* ssq, int r) { return __builtin_amdgcn_rsqf(ld_agent(ssq + r) * (1.f / 2048.f) + EPS); }
; #define PG8_STAGE(bufoff, gbase, voff) do { _Pragma("unroll") for (int _i = 0; _i < 2; ++_i) \
;         __builtin_amdgcn_global_load_lds((const unsigned*)((const char*)(gbase) + (voff)[_i]), (LAS unsigned*)(lds + (bufoff) + ldsw + _i * 8192), 16, 0, 0); } while (0)
; #define PG8_MMA(ai, bj, At, Bt) do { __builtin_amdgcn_s_setprio(1); _Pragma("unroll") for (int m = 0; m < 4; ++m) _Pragma("unroll") for (int n = 0; n < 2; ++n) _Pragma("unroll") for (int k = 0; k < 2; ++k) \
;         acc[ai][bj][m][n] = MmaOp<Epi::I8>::run(Bt[n][k], At[m][k], acc[ai][bj][m][n]); __builtin_amdgcn_s_setprio(0); } while (0)
; #define PG8_WAIT_V(n) asm volatile("s_waitcnt vmcnt(" #n ")" ::: "memory")
; #define PG8_WAIT_L(n) asm volatile("s_waitcnt lgkmcnt(" #n ")" ::: "memory")
;     __device__ __forceinline__ void operator()(const i32x4 (&acc)[2][2][4][2], const Unit& u, int wr, int wc, int fr, int fq) const {
;         const int row0 = u.pm * BM + wr * 64 + fr, col0 = u.pn * BM + wc * 32 + 8 * fq;
;         f32x4 bv[2][2];
; #pragma unroll
;         for (int bj = 0; bj < 2; ++bj)
; #pragma unroll
;             for (int n = 0; n < 2; ++n) bv[bj][n] = *(const f32x4*)(bias + col0 + bj * HALF + 4 * n);
; #pragma unroll
;         for (int ai = 0; ai < 2; ++ai)
; #pragma unroll
;             for (int m = 0; m < 4; ++m) {
;                 const int r = row0 + ai * HALF + m * 16; const float rs = rs_of(ssq, r);
;                 bf16_t* rowp = O + (size_t)r * ldc + col0;
; #pragma unroll
;                 for (int bj = 0; bj < 2; ++bj) {
;                     const f32x4 s0 = *(const f32x4*)(swp + col0 + bj * HALF), s1 = *(const f32x4*)(swp + col0 + bj * HALF + 4);
;                     f32x4 v0 = __builtin_convertvector(acc[ai][bj][m][0], f32x4) * s0 * rs + bv[bj][0], v1 = __builtin_convertvector(acc[ai][bj][m][1], f32x4) * s1 * rs + bv[bj][1];
; template <class Epi, class Sched>
; __device__ __forceinline__ void gemm_phase(LAS unsigned char* lds, const Gemm g, const Sched& S, const Epi& E) {
;     ...
;             PG8_BAR; PG8_WAIT_L(0); PG8_MMA(1, 0, At, B0); PG8_BAR; PG8_SCHED;
;             PG8_STAGE(PG8_SB(1, 1), b3 + hstepB, voffB);
;             PG8_WAIT_V(6); PG8_BAR; PG8_MMA(1, 1, At, B1); PG8_BAR;
;         }
	s_waitcnt lgkmcnt(0)
	s_setprio 1
	v_mfma_i32_16x16x64_i8 v[68:71], v[56:59], v[160:163], v[68:71]
	v_mfma_i32_16x16x64_i8 v[64:67], v[72:75], v[160:163], v[64:67]
	v_mfma_i32_16x16x64_i8 v[44:47], v[56:59], v[182:185], v[44:47]
	v_mfma_i32_16x16x64_i8 v[40:43], v[72:75], v[182:185], v[40:43]
	v_mfma_i32_16x16x64_i8 v[28:31], v[56:59], v[190:193], v[28:31]
	v_mfma_i32_16x16x64_i8 v[24:27], v[72:75], v[190:193], v[24:27]
	v_mfma_i32_16x16x64_i8 v[12:15], v[56:59], v[198:201], v[12:15]
	v_mfma_i32_16x16x64_i8 v[8:11], v[72:75], v[198:201], v[8:11]
	v_mfma_i32_16x16x64_i8 v[68:71], v[60:63], v[178:181], v[68:71]
	v_mfma_i32_16x16x64_i8 v[64:67], v[76:79], v[178:181], v[64:67]
	v_mfma_i32_16x16x64_i8 v[44:47], v[60:63], v[186:189], v[44:47]
	v_mfma_i32_16x16x64_i8 v[40:43], v[76:79], v[186:189], v[40:43]
	v_mfma_i32_16x16x64_i8 v[28:31], v[60:63], v[194:197], v[28:31]
	v_mfma_i32_16x16x64_i8 v[24:27], v[76:79], v[194:197], v[24:27]
	v_mfma_i32_16x16x64_i8 v[12:15], v[60:63], v[202:205], v[12:15]
	v_mfma_i32_16x16x64_i8 v[8:11], v[76:79], v[202:205], v[8:11]
	s_setprio 0
	s_barrier
	s_add_u32 s30, s30, 0x40080
	s_addc_u32 s31, s31, 0
	s_add_i32 s34, s34, s38
	v_lshl_add_u64 v[56:57], s[30:31], 0, v[148:149]
	s_mov_b32 m0, s34
	s_nop 0
	global_load_lds_dwordx4 v[56:57], off
	v_lshl_add_u64 v[56:57], s[30:31], 0, v[144:145]
	s_add_i32 m0, s34, 0x2000
	s_nop 0
	global_load_lds_dwordx4 v[56:57], off
	s_waitcnt vmcnt(6)
	s_barrier
	s_setprio 1
	v_mfma_i32_16x16x64_i8 v[52:55], v[206:209], v[160:163], v[52:55]
	v_mfma_i32_16x16x64_i8 v[48:51], v[214:217], v[160:163], v[48:51]
	v_mfma_i32_16x16x64_i8 v[36:39], v[206:209], v[182:185], v[36:39]
	v_mfma_i32_16x16x64_i8 v[32:35], v[214:217], v[182:185], v[32:35]
	v_mfma_i32_16x16x64_i8 v[20:23], v[206:209], v[190:193], v[20:23]
	v_mfma_i32_16x16x64_i8 v[16:19], v[214:217], v[190:193], v[16:19]
	v_mfma_i32_16x16x64_i8 v[4:7], v[206:209], v[198:201], v[4:7]
	v_mfma_i32_16x16x64_i8 v[0:3], v[214:217], v[198:201], v[0:3]
	v_mfma_i32_16x16x64_i8 v[52:55], v[210:213], v[178:181], v[52:55]
	v_mfma_i32_16x16x64_i8 v[48:51], v[218:221], v[178:181], v[48:51]
	v_mfma_i32_16x16x64_i8 v[36:39], v[210:213], v[186:189], v[36:39]
	v_mfma_i32_16x16x64_i8 v[32:35], v[218:221], v[186:189], v[32:35]
	v_mfma_i32_16x16x64_i8 v[20:23], v[210:213], v[194:197], v[20:23]
	v_mfma_i32_16x16x64_i8 v[16:19], v[218:221], v[194:197], v[16:19]
	v_mfma_i32_16x16x64_i8 v[4:7], v[210:213], v[202:205], v[4:7]
	v_mfma_i32_16x16x64_i8 v[0:3], v[218:221], v[202:205], v[0:3]
	s_setprio 0
	s_add_i32 s59, s59, 2
	s_add_u32 s28, s28, 0x100
	s_addc_u32 s29, s29, 0
	s_add_u32 s57, s57, 0x100
	s_addc_u32 s58, s58, 0
	s_cmp_gt_u32 s59, 13
	s_barrier
	s_cbranch_scc0 .LBB0_635
	v_lshl_or_b32 v174, s54, 8, v168
	v_ashrrev_i32_e32 v175, 31, v174
	v_readlane_b32 s76, v239, 2
	v_lshl_add_u32 v164, s26, 8, v166
	v_lshlrev_b64 v[160:161], 2, v[174:175]
	v_readlane_b32 s90, v239, 16
	v_readlane_b32 s91, v239, 17
	v_ashrrev_i32_e32 v165, 31, v164
	v_lshl_add_u64 v[162:163], v[164:165], 2, s[4:5]
	v_lshl_add_u64 v[60:61], s[90:91], 0, v[160:161]
	global_load_dwordx4 v[72:75], v[60:61], off offset:16
	global_load_dwordx4 v[76:79], v[60:61], off
	global_load_dwordx4 v[56:59], v[60:61], off offset:528
	s_nop 0
	global_load_dwordx4 v[60:63], v[60:61], off offset:512
	v_lshl_add_u64 v[160:161], s[6:7], 0, v[160:161]
	global_load_dword v173, v[162:163], off sc1
	global_load_dword v206, v[162:163], off offset:64 sc1
	global_load_dword v207, v[162:163], off offset:128 sc1
	global_load_dword v208, v[162:163], off offset:192 sc1
	global_load_dword v209, v[162:163], off offset:512 sc1
	global_load_dword v210, v[162:163], off offset:576 sc1
	global_load_dword v211, v[162:163], off offset:640 sc1
	global_load_dword v212, v[162:163], off offset:704 sc1
	global_load_dwordx4 v[178:181], v[160:161], off
	global_load_dwordx4 v[182:185], v[160:161], off offset:16
	global_load_dwordx4 v[190:193], v[160:161], off
	global_load_dwordx4 v[194:197], v[160:161], off offset:16
	global_load_dwordx4 v[198:201], v[160:161], off offset:512
	global_load_dwordx4 v[202:205], v[160:161], off offset:528
	v_cvt_f32_i32_e32 v141, v141
	v_cvt_f32_i32_e32 v140, v140
	v_cvt_f32_i32_e32 v143, v143
	v_cvt_f32_i32_e32 v142, v142
	v_cvt_f32_i32_e32 v187, v137
	v_cvt_f32_i32_e32 v186, v136
	v_lshlrev_b64 v[136:137], 13, v[164:165]
	v_cvt_f32_i32_e32 v189, v139
	v_cvt_f32_i32_e32 v188, v138
	v_lshlrev_b64 v[138:139], 1, v[174:175]
	v_readlane_b32 s28, v239, 46
	v_readlane_b32 s29, v239, 47
	v_cvt_f32_i32_e32 v133, v133
	v_cvt_f32_i32_e32 v132, v132
	v_lshl_add_u64 v[136:137], s[28:29], 0, v[136:137]
	v_lshl_add_u64 v[136:137], v[136:137], 0, v[138:139]
	v_cvt_f32_i32_e32 v135, v135
	v_cvt_f32_i32_e32 v134, v134
	v_cvt_f32_i32_e32 v129, v129
	v_cvt_f32_i32_e32 v128, v128
	v_cvt_f32_i32_e32 v131, v131
	v_cvt_f32_i32_e32 v130, v130
	v_cvt_f32_i32_e32 v127, v127
	v_cvt_f32_i32_e32 v126, v126
	v_cvt_f32_i32_e32 v125, v125
	v_cvt_f32_i32_e32 v124, v124
	v_cvt_f32_i32_e32 v121, v121
	v_cvt_f32_i32_e32 v120, v120
	v_cvt_f32_i32_e32 v123, v123
	v_cvt_f32_i32_e32 v122, v122
	v_cvt_f32_i32_e32 v117, v117
	v_cvt_f32_i32_e32 v116, v116
	v_cvt_f32_i32_e32 v119, v119
	v_cvt_f32_i32_e32 v118, v118
	v_cvt_f32_i32_e32 v113, v113
	v_cvt_f32_i32_e32 v112, v112
	v_cvt_f32_i32_e32 v115, v115
	v_cvt_f32_i32_e32 v114, v114
	v_cvt_f32_i32_e32 v111, v111
	v_cvt_f32_i32_e32 v110, v110
	v_cvt_f32_i32_e32 v109, v109
	v_cvt_f32_i32_e32 v108, v108
	v_cvt_f32_i32_e32 v105, v105
	v_cvt_f32_i32_e32 v104, v104
	v_cvt_f32_i32_e32 v107, v107
	v_cvt_f32_i32_e32 v106, v106
	v_cvt_f32_i32_e32 v101, v101
	v_cvt_f32_i32_e32 v100, v100
	v_cvt_f32_i32_e32 v103, v103
	v_cvt_f32_i32_e32 v102, v102
	v_cvt_f32_i32_e32 v97, v97
	v_cvt_f32_i32_e32 v96, v96
	v_cvt_f32_i32_e32 v99, v99
	v_cvt_f32_i32_e32 v98, v98
	v_cvt_f32_i32_e32 v95, v95
	v_cvt_f32_i32_e32 v94, v94
	v_cvt_f32_i32_e32 v93, v93
	v_cvt_f32_i32_e32 v92, v92
	v_cvt_f32_i32_e32 v89, v89
	v_cvt_f32_i32_e32 v88, v88
	v_cvt_f32_i32_e32 v91, v91
	v_cvt_f32_i32_e32 v90, v90
	v_cvt_f32_i32_e32 v85, v85
	v_cvt_f32_i32_e32 v84, v84
	v_cvt_f32_i32_e32 v87, v87
	v_cvt_f32_i32_e32 v86, v86
	v_cvt_f32_i32_e32 v81, v81
	v_cvt_f32_i32_e32 v83, v83
	v_cvt_f32_i32_e32 v82, v82
	v_cvt_f32_i32_e32 v80, v80
	v_cvt_f32_i32_e32 v71, v71
	v_cvt_f32_i32_e32 v70, v70
	v_cvt_f32_i32_e32 v69, v69
	v_cvt_f32_i32_e32 v68, v68
	v_cvt_f32_i32_e32 v65, v65
	v_cvt_f32_i32_e32 v64, v64
	v_cvt_f32_i32_e32 v67, v67
	v_cvt_f32_i32_e32 v66, v66
	s_waitcnt vmcnt(0)
; __device__ __forceinline__ unsigned cvt_pk_bf16(float lo, float hi) { unsigned r; asm volatile("v_cvt_pk_bf16_f32 %0, %1, %2" : "=v"(r) : "v"(lo), "v"(hi)); return r; }
; __device__ __forceinline__ float rs_of(const float* ssq, int r) { return __builtin_amdgcn_rsqf(ld_agent(ssq + r) * (1.f / 2048.f) + EPS); }
; __device__ __forceinline__ float sigm(float x) { return __builtin_amdgcn_rcpf(1.f + __builtin_amdgcn_exp2f(-LOG2E * x)); }
;     __device__ __forceinline__ void operator()(const i32x4 (&acc)[2][2][4][2], const Unit& u, int wr, int wc, int fr, int fq) const {
;     ...
;                 const int r = row0 + ai * HALF + m * 16; const float rs = rs_of(ssq, r);
;                 bf16_t* rowp = O + (size_t)r * ldc + col0;
; #pragma unroll
;                 for (int bj = 0; bj < 2; ++bj) {
;                     const f32x4 s0 = *(const f32x4*)(swp + col0 + bj * HALF), s1 = *(const f32x4*)(swp + col0 + bj * HALF + 4);
;                     f32x4 v0 = __builtin_convertvector(acc[ai][bj][m][0], f32x4) * s0 * rs + bv[bj][0], v1 = __builtin_convertvector(acc[ai][bj][m][1], f32x4) * s1 * rs + bv[bj][1];
; #pragma unroll
;                     for (int j = 0; j < 4; ++j) { v0[j] = sigm(v0[j]); v1[j] = sigm(v1[j]); }
;                     u32x4 w; w.x = cvt_pk_bf16(v0[0], v0[1]); w.y = cvt_pk_bf16(v0[2], v0[3]); w.z = cvt_pk_bf16(v1[0], v1[1]); w.w = cvt_pk_bf16(v1[2], v1[3]);
;                     *(u32x4*)(rowp + bj * HALF) = w;
	v_fmamk_f32 v165, v173, 0x3a000000, v172
	v_rsq_f32_e32 v174, v165
	v_pk_mul_f32 v[142:143], v[180:181], v[142:143]
	v_pk_mul_f32 v[140:141], v[178:179], v[140:141]
	v_pk_mul_f32 v[178:179], v[184:185], v[188:189]
	v_pk_mul_f32 v[180:181], v[182:183], v[186:187]
	v_pk_fma_f32 v[142:143], v[142:143], v[174:175], v[78:79] op_sel_hi:[1,0,1]
	v_pk_fma_f32 v[140:141], v[140:141], v[174:175], v[76:77] op_sel_hi:[1,0,1]
	v_pk_fma_f32 v[178:179], v[178:179], v[174:175], v[74:75] op_sel_hi:[1,0,1]
	v_pk_fma_f32 v[180:181], v[180:181], v[174:175], v[72:73] op_sel_hi:[1,0,1]
	v_mul_f32_e32 v140, 0xbfb8aa3b, v140
	v_mul_f32_e32 v141, 0xbfb8aa3b, v141
	v_mul_f32_e32 v142, 0xbfb8aa3b, v142
	v_mul_f32_e32 v143, 0xbfb8aa3b, v143
	v_mul_f32_e32 v165, 0xbfb8aa3b, v180
	v_mul_f32_e32 v173, 0xbfb8aa3b, v181
	v_mul_f32_e32 v175, 0xbfb8aa3b, v178
	v_mul_f32_e32 v178, 0xbfb8aa3b, v179
	v_exp_f32_e32 v140, v140
	v_exp_f32_e32 v141, v141
	v_exp_f32_e32 v142, v142
	v_exp_f32_e32 v143, v143
	v_exp_f32_e32 v165, v165
	v_exp_f32_e32 v173, v173
	v_exp_f32_e32 v175, v175
	v_exp_f32_e32 v178, v178
	v_add_f32_e32 v140, 1.0, v140
	v_add_f32_e32 v141, 1.0, v141
	v_add_f32_e32 v142, 1.0, v142
	v_add_f32_e32 v143, 1.0, v143
	v_add_f32_e32 v165, 1.0, v165
	v_add_f32_e32 v173, 1.0, v173
	v_add_f32_e32 v175, 1.0, v175
	v_add_f32_e32 v178, 1.0, v178
	v_rcp_f32_e32 v140, v140
	v_rcp_f32_e32 v141, v141
	v_rcp_f32_e32 v142, v142
	v_rcp_f32_e32 v143, v143
	v_rcp_f32_e32 v165, v165
	v_rcp_f32_e32 v173, v173
	v_rcp_f32_e32 v175, v175
	v_rcp_f32_e32 v178, v178
	v_cvt_pk_bf16_f32 v140, v140, v141
	v_cvt_pk_bf16_f32 v141, v142, v143
	v_cvt_pk_bf16_f32 v142, v165, v173
	v_cvt_pk_bf16_f32 v143, v175, v178
	global_store_dwordx4 v[136:137], v[140:143], off sc0 sc1
	s_nop 1
	v_mov_b64_e32 v[140:141], v[198:199]
	v_mov_b64_e32 v[142:143], v[200:201]
	s_nop 0
	v_mov_b64_e32 v[178:179], v[202:203]
	v_mov_b64_e32 v[180:181], v[204:205]
	v_or_b32_e32 v182, 16, v164
	v_ashrrev_i32_e32 v183, 31, v182
	v_lshl_add_u64 v[184:185], v[182:183], 2, s[4:5]
	v_cvt_f32_i32_e32 v53, v53
	v_cvt_f32_i32_e32 v52, v52
	v_cvt_f32_i32_e32 v55, v55
	v_cvt_f32_i32_e32 v54, v54
	v_cvt_f32_i32_e32 v49, v49
	v_cvt_f32_i32_e32 v48, v48
	v_cvt_f32_i32_e32 v51, v51
	v_cvt_f32_i32_e32 v50, v50
	v_cvt_f32_i32_e32 v47, v47
	v_cvt_f32_i32_e32 v46, v46
	v_cvt_f32_i32_e32 v45, v45
	v_cvt_f32_i32_e32 v44, v44
	v_cvt_f32_i32_e32 v41, v41
	v_cvt_f32_i32_e32 v40, v40
	v_cvt_f32_i32_e32 v43, v43
	v_cvt_f32_i32_e32 v42, v42
	v_cvt_f32_i32_e32 v37, v37
	v_cvt_f32_i32_e32 v36, v36
	v_cvt_f32_i32_e32 v39, v39
	v_cvt_f32_i32_e32 v38, v38
	v_cvt_f32_i32_e32 v33, v33
	v_cvt_f32_i32_e32 v32, v32
	v_cvt_f32_i32_e32 v35, v35
	v_cvt_f32_i32_e32 v34, v34
	v_cvt_f32_i32_e32 v31, v31
	v_cvt_f32_i32_e32 v30, v30
	v_cvt_f32_i32_e32 v29, v29
	v_cvt_f32_i32_e32 v28, v28
	v_cvt_f32_i32_e32 v25, v25
	v_cvt_f32_i32_e32 v24, v24
	v_cvt_f32_i32_e32 v27, v27
	v_cvt_f32_i32_e32 v26, v26
	v_cvt_f32_i32_e32 v21, v21
	v_cvt_f32_i32_e32 v20, v20
	v_cvt_f32_i32_e32 v23, v23
	v_cvt_f32_i32_e32 v22, v22
	v_cvt_f32_i32_e32 v17, v17
	v_cvt_f32_i32_e32 v16, v16
	v_cvt_f32_i32_e32 v19, v19
	v_cvt_f32_i32_e32 v18, v18
	v_cvt_f32_i32_e32 v15, v15
	v_cvt_f32_i32_e32 v14, v14
	v_cvt_f32_i32_e32 v13, v13
	v_cvt_f32_i32_e32 v12, v12
	v_cvt_f32_i32_e32 v9, v9
	v_cvt_f32_i32_e32 v8, v8
	v_cvt_f32_i32_e32 v11, v11
	v_cvt_f32_i32_e32 v10, v10
	v_cvt_f32_i32_e32 v5, v5
	v_cvt_f32_i32_e32 v4, v4
	v_cvt_f32_i32_e32 v7, v7
	v_cvt_f32_i32_e32 v6, v6
	v_cvt_f32_i32_e32 v1, v1
	v_cvt_f32_i32_e32 v0, v0
	v_cvt_f32_i32_e32 v3, v3
	v_cvt_f32_i32_e32 v2, v2
	s_mov_b32 s54, s18
	s_mov_b32 s26, s20
	s_mov_b64 s[30:31], s[24:25]
	v_readlane_b32 s61, v239, 50
	v_readlane_b32 s77, v239, 3
	v_readlane_b32 s78, v239, 4
	v_readlane_b32 s79, v239, 5
	v_readlane_b32 s80, v239, 6
	v_readlane_b32 s81, v239, 7
	v_readlane_b32 s82, v239, 8
	v_readlane_b32 s83, v239, 9
	v_readlane_b32 s84, v239, 10
	v_readlane_b32 s85, v239, 11
	v_readlane_b32 s86, v239, 12
	v_readlane_b32 s87, v239, 13
	v_readlane_b32 s88, v239, 14
	v_readlane_b32 s89, v239, 15
	v_pk_mul_f32 v[134:135], v[142:143], v[134:135]
	v_pk_mul_f32 v[132:133], v[140:141], v[132:133]
	v_pk_mul_f32 v[130:131], v[180:181], v[130:131]
	v_pk_mul_f32 v[128:129], v[178:179], v[128:129]
	v_pk_fma_f32 v[134:135], v[174:175], v[134:135], v[62:63] op_sel_hi:[0,1,1]
	v_pk_fma_f32 v[132:133], v[174:175], v[132:133], v[60:61] op_sel_hi:[0,1,1]
	v_pk_fma_f32 v[130:131], v[174:175], v[130:131], v[58:59] op_sel_hi:[0,1,1]
	v_pk_fma_f32 v[128:129], v[174:175], v[128:129], v[56:57] op_sel_hi:[0,1,1]
	v_mul_f32_e32 v128, 0xbfb8aa3b, v128
	v_mul_f32_e32 v133, 0xbfb8aa3b, v133
	v_mul_f32_e32 v129, 0xbfb8aa3b, v129
	v_mul_f32_e32 v134, 0xbfb8aa3b, v134
	v_mul_f32_e32 v131, 0xbfb8aa3b, v131
	v_mul_f32_e32 v132, 0xbfb8aa3b, v132
	v_mul_f32_e32 v130, 0xbfb8aa3b, v130
	v_mul_f32_e32 v135, 0xbfb8aa3b, v135
	v_exp_f32_e32 v128, v128
	v_exp_f32_e32 v133, v133
	v_exp_f32_e32 v129, v129
	v_exp_f32_e32 v134, v134
	v_exp_f32_e32 v131, v131
	v_exp_f32_e32 v132, v132
	v_exp_f32_e32 v130, v130
	v_exp_f32_e32 v135, v135
	v_add_f32_e32 v128, 1.0, v128
	v_add_f32_e32 v133, 1.0, v133
	v_add_f32_e32 v129, 1.0, v129
	v_add_f32_e32 v134, 1.0, v134
	v_add_f32_e32 v131, 1.0, v131
	v_add_f32_e32 v132, 1.0, v132
	v_add_f32_e32 v130, 1.0, v130
	v_add_f32_e32 v135, 1.0, v135
	v_rcp_f32_e32 v140, v128
	v_rcp_f32_e32 v128, v133
	v_rcp_f32_e32 v133, v129
	v_rcp_f32_e32 v129, v134
	v_rcp_f32_e32 v131, v131
	v_rcp_f32_e32 v132, v132
	v_rcp_f32_e32 v134, v135
	v_rcp_f32_e32 v135, v130
	v_cvt_pk_bf16_f32 v128, v132, v128
	v_cvt_pk_bf16_f32 v129, v129, v134
	v_cvt_pk_bf16_f32 v130, v140, v133
; __device__ __forceinline__ unsigned cvt_pk_bf16(float lo, float hi) { unsigned r; asm volatile("v_cvt_pk_bf16_f32 %0, %1, %2" : "=v"(r) : "v"(lo), "v"(hi)); return r; }
; __device__ __forceinline__ float rs_of(const float* ssq, int r) { return __builtin_amdgcn_rsqf(ld_agent(ssq + r) * (1.f / 2048.f) + EPS); }
; __device__ __forceinline__ float sigm(float x) { return __builtin_amdgcn_rcpf(1.f + __builtin_amdgcn_exp2f(-LOG2E * x)); }
;     __device__ __forceinline__ void operator()(const i32x4 (&acc)[2][2][4][2], const Unit& u, int wr, int wc, int fr, int fq) const {
;     ...
;                 const int r = row0 + ai * HALF + m * 16; const float rs = rs_of(ssq, r);
;                 bf16_t* rowp = O + (size_t)r * ldc + col0;
; #pragma unroll
;                 for (int bj = 0; bj < 2; ++bj) {
;                     const f32x4 s0 = *(const f32x4*)(swp + col0 + bj * HALF), s1 = *(const f32x4*)(swp + col0 + bj * HALF + 4);
;                     f32x4 v0 = __builtin_convertvector(acc[ai][bj][m][0], f32x4) * s0 * rs + bv[bj][0], v1 = __builtin_convertvector(acc[ai][bj][m][1], f32x4) * s1 * rs + bv[bj][1];
; #pragma unroll
;                     for (int j = 0; j < 4; ++j) { v0[j] = sigm(v0[j]); v1[j] = sigm(v1[j]); }
;                     u32x4 w; w.x = cvt_pk_bf16(v0[0], v0[1]); w.y = cvt_pk_bf16(v0[2], v0[3]); w.z = cvt_pk_bf16(v1[0], v1[1]); w.w = cvt_pk_bf16(v1[2], v1[3]);
;                     *(u32x4*)(rowp + bj * HALF) = w;
	v_cvt_pk_bf16_f32 v131, v135, v131
	global_store_dwordx4 v[136:137], v[128:131], off offset:256 sc0 sc1
	s_nop 1
	v_mov_b32_e32 v142, v206
	s_nop 0
	v_mov_b64_e32 v[128:129], v[190:191]
	v_mov_b64_e32 v[130:131], v[192:193]
	v_mov_b64_e32 v[132:133], v[194:195]
	v_mov_b64_e32 v[134:135], v[196:197]
	v_lshlrev_b64 v[140:141], 13, v[182:183]
	v_lshl_add_u64 v[140:141], s[28:29], 0, v[140:141]
	v_lshl_add_u64 v[140:141], v[140:141], 0, v[138:139]
	v_fmamk_f32 v142, v142, 0x3a000000, v172
	v_pk_mul_f32 v[126:127], v[130:131], v[126:127]
	v_rsq_f32_e32 v130, v142
	v_pk_mul_f32 v[124:125], v[128:129], v[124:125]
	v_pk_mul_f32 v[122:123], v[134:135], v[122:123]
	v_pk_mul_f32 v[120:121], v[132:133], v[120:121]
	v_pk_fma_f32 v[126:127], v[126:127], v[130:131], v[78:79] op_sel_hi:[1,0,1]
	v_pk_fma_f32 v[124:125], v[124:125], v[130:131], v[76:77] op_sel_hi:[1,0,1]
	v_pk_fma_f32 v[122:123], v[122:123], v[130:131], v[74:75] op_sel_hi:[1,0,1]
	v_pk_fma_f32 v[120:121], v[120:121], v[130:131], v[72:73] op_sel_hi:[1,0,1]
	v_mul_f32_e32 v125, 0xbfb8aa3b, v125
	v_mul_f32_e32 v120, 0xbfb8aa3b, v120
	v_mul_f32_e32 v121, 0xbfb8aa3b, v121
	v_mul_f32_e32 v126, 0xbfb8aa3b, v126
	v_mul_f32_e32 v123, 0xbfb8aa3b, v123
	v_mul_f32_e32 v124, 0xbfb8aa3b, v124
	v_mul_f32_e32 v122, 0xbfb8aa3b, v122
	v_mul_f32_e32 v127, 0xbfb8aa3b, v127
	v_exp_f32_e32 v120, v120
	v_exp_f32_e32 v125, v125
	v_exp_f32_e32 v121, v121
	v_exp_f32_e32 v126, v126
	v_exp_f32_e32 v123, v123
	v_exp_f32_e32 v124, v124
	v_exp_f32_e32 v122, v122
	v_exp_f32_e32 v127, v127
	v_add_f32_e32 v120, 1.0, v120
	v_add_f32_e32 v125, 1.0, v125
	v_add_f32_e32 v121, 1.0, v121
	v_add_f32_e32 v126, 1.0, v126
	v_add_f32_e32 v123, 1.0, v123
	v_add_f32_e32 v124, 1.0, v124
	v_add_f32_e32 v122, 1.0, v122
	v_add_f32_e32 v127, 1.0, v127
	v_rcp_f32_e32 v128, v120
	v_rcp_f32_e32 v120, v125
	v_rcp_f32_e32 v125, v121
	v_rcp_f32_e32 v121, v126
	v_rcp_f32_e32 v123, v123
	v_rcp_f32_e32 v124, v124
	v_rcp_f32_e32 v126, v127
	v_rcp_f32_e32 v127, v122
	v_cvt_pk_bf16_f32 v120, v124, v120
	v_cvt_pk_bf16_f32 v121, v121, v126
	v_cvt_pk_bf16_f32 v122, v128, v125
	v_cvt_pk_bf16_f32 v123, v127, v123
	global_store_dwordx4 v[140:141], v[120:123], off sc0 sc1
	s_nop 1
	v_mov_b64_e32 v[120:121], v[198:199]
	v_mov_b64_e32 v[122:123], v[200:201]
	s_nop 0
	v_mov_b64_e32 v[124:125], v[202:203]
	v_mov_b64_e32 v[126:127], v[204:205]
	v_or_b32_e32 v128, 32, v164
	v_ashrrev_i32_e32 v129, 31, v128
	v_lshl_add_u64 v[132:133], v[128:129], 2, s[4:5]
	v_pk_mul_f32 v[118:119], v[122:123], v[118:119]
	v_pk_mul_f32 v[116:117], v[120:121], v[116:117]
	v_pk_mul_f32 v[114:115], v[126:127], v[114:115]
	v_pk_mul_f32 v[112:113], v[124:125], v[112:113]
	v_pk_fma_f32 v[118:119], v[130:131], v[118:119], v[62:63] op_sel_hi:[0,1,1]
	v_pk_fma_f32 v[116:117], v[130:131], v[116:117], v[60:61] op_sel_hi:[0,1,1]
	v_pk_fma_f32 v[114:115], v[130:131], v[114:115], v[58:59] op_sel_hi:[0,1,1]
	v_pk_fma_f32 v[112:113], v[130:131], v[112:113], v[56:57] op_sel_hi:[0,1,1]
	v_mul_f32_e32 v112, 0xbfb8aa3b, v112
	v_mul_f32_e32 v117, 0xbfb8aa3b, v117
	v_mul_f32_e32 v113, 0xbfb8aa3b, v113
	v_mul_f32_e32 v118, 0xbfb8aa3b, v118
	v_mul_f32_e32 v115, 0xbfb8aa3b, v115
	v_mul_f32_e32 v116, 0xbfb8aa3b, v116
	v_mul_f32_e32 v114, 0xbfb8aa3b, v114
	v_mul_f32_e32 v119, 0xbfb8aa3b, v119
	v_exp_f32_e32 v112, v112
	v_exp_f32_e32 v117, v117
	v_exp_f32_e32 v113, v113
	v_exp_f32_e32 v118, v118
	v_exp_f32_e32 v115, v115
	v_exp_f32_e32 v116, v116
	v_exp_f32_e32 v114, v114
	v_exp_f32_e32 v119, v119
	v_add_f32_e32 v112, 1.0, v112
	v_add_f32_e32 v117, 1.0, v117
	v_add_f32_e32 v113, 1.0, v113
	v_add_f32_e32 v118, 1.0, v118
	v_add_f32_e32 v115, 1.0, v115
	v_add_f32_e32 v116, 1.0, v116
	v_add_f32_e32 v114, 1.0, v114
	v_add_f32_e32 v119, 1.0, v119
	v_rcp_f32_e32 v120, v112
	v_rcp_f32_e32 v112, v117
	v_rcp_f32_e32 v117, v113
	v_rcp_f32_e32 v113, v118
	v_rcp_f32_e32 v115, v115
	v_rcp_f32_e32 v116, v116
	v_rcp_f32_e32 v118, v119
	v_rcp_f32_e32 v119, v114
	v_cvt_pk_bf16_f32 v112, v116, v112
	v_cvt_pk_bf16_f32 v113, v113, v118
	v_cvt_pk_bf16_f32 v114, v120, v117
	v_cvt_pk_bf16_f32 v115, v119, v115
	global_store_dwordx4 v[140:141], v[112:115], off offset:256 sc0 sc1
	s_nop 1
	v_mov_b32_e32 v122, v207
	s_nop 0
	v_mov_b64_e32 v[112:113], v[190:191]
	v_mov_b64_e32 v[114:115], v[192:193]
	v_mov_b64_e32 v[116:117], v[194:195]
	v_mov_b64_e32 v[118:119], v[196:197]
	v_lshlrev_b64 v[120:121], 13, v[128:129]
	v_lshl_add_u64 v[120:121], s[28:29], 0, v[120:121]
	v_lshl_add_u64 v[120:121], v[120:121], 0, v[138:139]
	v_fmamk_f32 v122, v122, 0x3a000000, v172
	v_pk_mul_f32 v[110:111], v[114:115], v[110:111]
	v_rsq_f32_e32 v114, v122
	v_pk_mul_f32 v[108:109], v[112:113], v[108:109]
	v_pk_mul_f32 v[106:107], v[118:119], v[106:107]
	v_pk_mul_f32 v[104:105], v[116:117], v[104:105]
	v_pk_fma_f32 v[110:111], v[110:111], v[114:115], v[78:79] op_sel_hi:[1,0,1]
	v_pk_fma_f32 v[108:109], v[108:109], v[114:115], v[76:77] op_sel_hi:[1,0,1]
	v_pk_fma_f32 v[106:107], v[106:107], v[114:115], v[74:75] op_sel_hi:[1,0,1]
	v_pk_fma_f32 v[104:105], v[104:105], v[114:115], v[72:73] op_sel_hi:[1,0,1]
	v_mul_f32_e32 v109, 0xbfb8aa3b, v109
	v_mul_f32_e32 v104, 0xbfb8aa3b, v104
	v_mul_f32_e32 v105, 0xbfb8aa3b, v105
	v_mul_f32_e32 v110, 0xbfb8aa3b, v110
	v_mul_f32_e32 v107, 0xbfb8aa3b, v107
	v_mul_f32_e32 v108, 0xbfb8aa3b, v108
	v_mul_f32_e32 v106, 0xbfb8aa3b, v106
	v_mul_f32_e32 v111, 0xbfb8aa3b, v111
	v_exp_f32_e32 v104, v104
	v_exp_f32_e32 v109, v109
	v_exp_f32_e32 v105, v105
	v_exp_f32_e32 v110, v110
	v_exp_f32_e32 v107, v107
	v_exp_f32_e32 v108, v108
	v_exp_f32_e32 v106, v106
	v_exp_f32_e32 v111, v111
	v_add_f32_e32 v104, 1.0, v104
	v_add_f32_e32 v109, 1.0, v109
; __device__ __forceinline__ unsigned cvt_pk_bf16(float lo, float hi) { unsigned r; asm volatile("v_cvt_pk_bf16_f32 %0, %1, %2" : "=v"(r) : "v"(lo), "v"(hi)); return r; }
; __device__ __forceinline__ float rs_of(const float* ssq, int r) { return __builtin_amdgcn_rsqf(ld_agent(ssq + r) * (1.f / 2048.f) + EPS); }
; __device__ __forceinline__ float sigm(float x) { return __builtin_amdgcn_rcpf(1.f + __builtin_amdgcn_exp2f(-LOG2E * x)); }
;     __device__ __forceinline__ void operator()(const i32x4 (&acc)[2][2][4][2], const Unit& u, int wr, int wc, int fr, int fq) const {
;     ...
;                 const int r = row0 + ai * HALF + m * 16; const float rs = rs_of(ssq, r);
;                 bf16_t* rowp = O + (size_t)r * ldc + col0;
; #pragma unroll
;                 for (int bj = 0; bj < 2; ++bj) {
;                     const f32x4 s0 = *(const f32x4*)(swp + col0 + bj * HALF), s1 = *(const f32x4*)(swp + col0 + bj * HALF + 4);
;                     f32x4 v0 = __builtin_convertvector(acc[ai][bj][m][0], f32x4) * s0 * rs + bv[bj][0], v1 = __builtin_convertvector(acc[ai][bj][m][1], f32x4) * s1 * rs + bv[bj][1];
; #pragma unroll
;                     for (int j = 0; j < 4; ++j) { v0[j] = sigm(v0[j]); v1[j] = sigm(v1[j]); }
;                     u32x4 w; w.x = cvt_pk_bf16(v0[0], v0[1]); w.y = cvt_pk_bf16(v0[2], v0[3]); w.z = cvt_pk_bf16(v1[0], v1[1]); w.w = cvt_pk_bf16(v1[2], v1[3]);
;                     *(u32x4*)(rowp + bj * HALF) = w;
	v_add_f32_e32 v105, 1.0, v105
	v_add_f32_e32 v110, 1.0, v110
	v_add_f32_e32 v107, 1.0, v107
	v_add_f32_e32 v108, 1.0, v108
	v_add_f32_e32 v106, 1.0, v106
	v_add_f32_e32 v111, 1.0, v111
	v_rcp_f32_e32 v112, v104
	v_rcp_f32_e32 v104, v109
	v_rcp_f32_e32 v109, v105
	v_rcp_f32_e32 v105, v110
	v_rcp_f32_e32 v107, v107
	v_rcp_f32_e32 v108, v108
	v_rcp_f32_e32 v110, v111
	v_rcp_f32_e32 v111, v106
	v_cvt_pk_bf16_f32 v104, v108, v104
	v_cvt_pk_bf16_f32 v105, v105, v110
	v_cvt_pk_bf16_f32 v106, v112, v109
	v_cvt_pk_bf16_f32 v107, v111, v107
	global_store_dwordx4 v[120:121], v[104:107], off sc0 sc1
	s_nop 1
	v_mov_b64_e32 v[104:105], v[198:199]
	v_mov_b64_e32 v[106:107], v[200:201]
	s_nop 0
	v_mov_b64_e32 v[108:109], v[202:203]
	v_mov_b64_e32 v[110:111], v[204:205]
	v_or_b32_e32 v112, 48, v164
	v_ashrrev_i32_e32 v113, 31, v112
	v_lshl_add_u64 v[116:117], v[112:113], 2, s[4:5]
	v_pk_mul_f32 v[102:103], v[106:107], v[102:103]
	v_pk_mul_f32 v[100:101], v[104:105], v[100:101]
	v_pk_mul_f32 v[98:99], v[110:111], v[98:99]
	v_pk_mul_f32 v[96:97], v[108:109], v[96:97]
	v_pk_fma_f32 v[102:103], v[114:115], v[102:103], v[62:63] op_sel_hi:[0,1,1]
	v_pk_fma_f32 v[100:101], v[114:115], v[100:101], v[60:61] op_sel_hi:[0,1,1]
	v_pk_fma_f32 v[98:99], v[114:115], v[98:99], v[58:59] op_sel_hi:[0,1,1]
	v_pk_fma_f32 v[96:97], v[114:115], v[96:97], v[56:57] op_sel_hi:[0,1,1]
	v_mul_f32_e32 v96, 0xbfb8aa3b, v96
	v_mul_f32_e32 v101, 0xbfb8aa3b, v101
	v_mul_f32_e32 v97, 0xbfb8aa3b, v97
	v_mul_f32_e32 v102, 0xbfb8aa3b, v102
	v_mul_f32_e32 v99, 0xbfb8aa3b, v99
	v_mul_f32_e32 v100, 0xbfb8aa3b, v100
	v_mul_f32_e32 v98, 0xbfb8aa3b, v98
	v_mul_f32_e32 v103, 0xbfb8aa3b, v103
	v_exp_f32_e32 v96, v96
	v_exp_f32_e32 v101, v101
	v_exp_f32_e32 v97, v97
	v_exp_f32_e32 v102, v102
	v_exp_f32_e32 v99, v99
	v_exp_f32_e32 v100, v100
	v_exp_f32_e32 v98, v98
	v_exp_f32_e32 v103, v103
	v_add_f32_e32 v96, 1.0, v96
	v_add_f32_e32 v101, 1.0, v101
	v_add_f32_e32 v97, 1.0, v97
	v_add_f32_e32 v102, 1.0, v102
	v_add_f32_e32 v99, 1.0, v99
	v_add_f32_e32 v100, 1.0, v100
	v_add_f32_e32 v98, 1.0, v98
	v_add_f32_e32 v103, 1.0, v103
	v_rcp_f32_e32 v104, v96
	v_rcp_f32_e32 v96, v101
	v_rcp_f32_e32 v101, v97
	v_rcp_f32_e32 v97, v102
	v_rcp_f32_e32 v99, v99
	v_rcp_f32_e32 v100, v100
	v_rcp_f32_e32 v102, v103
	v_rcp_f32_e32 v103, v98
	v_cvt_pk_bf16_f32 v96, v100, v96
	v_cvt_pk_bf16_f32 v97, v97, v102
	v_cvt_pk_bf16_f32 v98, v104, v101
	v_cvt_pk_bf16_f32 v99, v103, v99
	global_store_dwordx4 v[120:121], v[96:99], off offset:256 sc0 sc1
	s_nop 1
	v_mov_b32_e32 v106, v208
	s_nop 0
	v_mov_b64_e32 v[96:97], v[190:191]
	v_mov_b64_e32 v[98:99], v[192:193]
	v_mov_b64_e32 v[100:101], v[194:195]
	v_mov_b64_e32 v[102:103], v[196:197]
	v_lshlrev_b64 v[104:105], 13, v[112:113]
	v_lshl_add_u64 v[104:105], s[28:29], 0, v[104:105]
	v_lshl_add_u64 v[104:105], v[104:105], 0, v[138:139]
	s_mov_b64 s[28:29], s[22:23]
	v_fmamk_f32 v106, v106, 0x3a000000, v172
	v_pk_mul_f32 v[94:95], v[98:99], v[94:95]
	v_rsq_f32_e32 v98, v106
	v_pk_mul_f32 v[92:93], v[96:97], v[92:93]
	v_pk_mul_f32 v[90:91], v[102:103], v[90:91]
	v_pk_mul_f32 v[88:89], v[100:101], v[88:89]
	v_pk_fma_f32 v[94:95], v[94:95], v[98:99], v[78:79] op_sel_hi:[1,0,1]
	v_pk_fma_f32 v[92:93], v[92:93], v[98:99], v[76:77] op_sel_hi:[1,0,1]
	v_pk_fma_f32 v[90:91], v[90:91], v[98:99], v[74:75] op_sel_hi:[1,0,1]
	v_pk_fma_f32 v[88:89], v[88:89], v[98:99], v[72:73] op_sel_hi:[1,0,1]
	v_mul_f32_e32 v93, 0xbfb8aa3b, v93
	v_mul_f32_e32 v88, 0xbfb8aa3b, v88
	v_mul_f32_e32 v89, 0xbfb8aa3b, v89
	v_mul_f32_e32 v94, 0xbfb8aa3b, v94
	v_mul_f32_e32 v91, 0xbfb8aa3b, v91
	v_mul_f32_e32 v92, 0xbfb8aa3b, v92
	v_mul_f32_e32 v90, 0xbfb8aa3b, v90
	v_mul_f32_e32 v95, 0xbfb8aa3b, v95
	v_exp_f32_e32 v88, v88
	v_exp_f32_e32 v93, v93
	v_exp_f32_e32 v89, v89
	v_exp_f32_e32 v94, v94
	v_exp_f32_e32 v91, v91
	v_exp_f32_e32 v92, v92
	v_exp_f32_e32 v90, v90
	v_exp_f32_e32 v95, v95
	v_add_f32_e32 v88, 1.0, v88
	v_add_f32_e32 v93, 1.0, v93
	v_add_f32_e32 v89, 1.0, v89
	v_add_f32_e32 v94, 1.0, v94
	v_add_f32_e32 v91, 1.0, v91
	v_add_f32_e32 v92, 1.0, v92
	v_add_f32_e32 v90, 1.0, v90
	v_add_f32_e32 v95, 1.0, v95
	v_rcp_f32_e32 v96, v88
	v_rcp_f32_e32 v88, v93
	v_rcp_f32_e32 v93, v89
	v_rcp_f32_e32 v89, v94
	v_rcp_f32_e32 v91, v91
	v_rcp_f32_e32 v92, v92
	v_rcp_f32_e32 v94, v95
	v_rcp_f32_e32 v95, v90
	v_cvt_pk_bf16_f32 v88, v92, v88
	v_cvt_pk_bf16_f32 v89, v89, v94
	v_cvt_pk_bf16_f32 v90, v96, v93
	v_cvt_pk_bf16_f32 v91, v95, v91
	global_store_dwordx4 v[104:105], v[88:91], off sc0 sc1
	s_nop 1
	v_mov_b64_e32 v[88:89], v[198:199]
	v_mov_b64_e32 v[90:91], v[200:201]
	s_nop 0
	v_mov_b64_e32 v[92:93], v[202:203]
	v_mov_b64_e32 v[94:95], v[204:205]
	v_pk_mul_f32 v[86:87], v[90:91], v[86:87]
	v_pk_mul_f32 v[84:85], v[88:89], v[84:85]
	v_pk_mul_f32 v[82:83], v[94:95], v[82:83]
	v_pk_mul_f32 v[80:81], v[92:93], v[80:81]
	v_pk_fma_f32 v[86:87], v[98:99], v[86:87], v[62:63] op_sel_hi:[0,1,1]
	v_pk_fma_f32 v[84:85], v[98:99], v[84:85], v[60:61] op_sel_hi:[0,1,1]
	v_pk_fma_f32 v[82:83], v[98:99], v[82:83], v[58:59] op_sel_hi:[0,1,1]
	v_pk_fma_f32 v[80:81], v[98:99], v[80:81], v[56:57] op_sel_hi:[0,1,1]
	v_mul_f32_e32 v80, 0xbfb8aa3b, v80
	v_mul_f32_e32 v85, 0xbfb8aa3b, v85
	v_mul_f32_e32 v81, 0xbfb8aa3b, v81
	v_mul_f32_e32 v86, 0xbfb8aa3b, v86
	v_mul_f32_e32 v83, 0xbfb8aa3b, v83
	v_mul_f32_e32 v84, 0xbfb8aa3b, v84
	v_mul_f32_e32 v82, 0xbfb8aa3b, v82
	v_mul_f32_e32 v87, 0xbfb8aa3b, v87
	v_exp_f32_e32 v80, v80
	v_exp_f32_e32 v85, v85
	v_exp_f32_e32 v81, v81
	v_exp_f32_e32 v86, v86
	v_exp_f32_e32 v83, v83
	v_exp_f32_e32 v84, v84
	v_exp_f32_e32 v82, v82
	v_exp_f32_e32 v87, v87
	v_add_f32_e32 v80, 1.0, v80
	v_add_f32_e32 v85, 1.0, v85
; __device__ __forceinline__ unsigned cvt_pk_bf16(float lo, float hi) { unsigned r; asm volatile("v_cvt_pk_bf16_f32 %0, %1, %2" : "=v"(r) : "v"(lo), "v"(hi)); return r; }
; __device__ __forceinline__ float rs_of(const float* ssq, int r) { return __builtin_amdgcn_rsqf(ld_agent(ssq + r) * (1.f / 2048.f) + EPS); }
; __device__ __forceinline__ float sigm(float x) { return __builtin_amdgcn_rcpf(1.f + __builtin_amdgcn_exp2f(-LOG2E * x)); }
;     __device__ __forceinline__ void operator()(const i32x4 (&acc)[2][2][4][2], const Unit& u, int wr, int wc, int fr, int fq) const {
;     ...
;                 const int r = row0 + ai * HALF + m * 16; const float rs = rs_of(ssq, r);
;                 bf16_t* rowp = O + (size_t)r * ldc + col0;
; #pragma unroll
;                 for (int bj = 0; bj < 2; ++bj) {
;                     const f32x4 s0 = *(const f32x4*)(swp + col0 + bj * HALF), s1 = *(const f32x4*)(swp + col0 + bj * HALF + 4);
;                     f32x4 v0 = __builtin_convertvector(acc[ai][bj][m][0], f32x4) * s0 * rs + bv[bj][0], v1 = __builtin_convertvector(acc[ai][bj][m][1], f32x4) * s1 * rs + bv[bj][1];
; #pragma unroll
;                     for (int j = 0; j < 4; ++j) { v0[j] = sigm(v0[j]); v1[j] = sigm(v1[j]); }
;                     u32x4 w; w.x = cvt_pk_bf16(v0[0], v0[1]); w.y = cvt_pk_bf16(v0[2], v0[3]); w.z = cvt_pk_bf16(v1[0], v1[1]); w.w = cvt_pk_bf16(v1[2], v1[3]);
;                     *(u32x4*)(rowp + bj * HALF) = w;
	v_add_f32_e32 v81, 1.0, v81
	v_add_f32_e32 v86, 1.0, v86
	v_add_f32_e32 v83, 1.0, v83
	v_add_f32_e32 v84, 1.0, v84
	v_add_f32_e32 v82, 1.0, v82
	v_add_f32_e32 v87, 1.0, v87
	v_rcp_f32_e32 v88, v80
	v_rcp_f32_e32 v80, v85
	v_rcp_f32_e32 v85, v81
	v_rcp_f32_e32 v81, v86
	v_rcp_f32_e32 v83, v83
	v_rcp_f32_e32 v84, v84
	v_rcp_f32_e32 v86, v87
	v_rcp_f32_e32 v87, v82
	v_cvt_pk_bf16_f32 v80, v84, v80
	v_cvt_pk_bf16_f32 v81, v81, v86
	v_cvt_pk_bf16_f32 v82, v88, v85
	v_cvt_pk_bf16_f32 v83, v87, v83
	global_store_dwordx4 v[104:105], v[80:83], off offset:256 sc0 sc1
	s_nop 1
	v_mov_b32_e32 v90, v209
	s_nop 0
	v_mov_b64_e32 v[80:81], v[190:191]
	v_mov_b64_e32 v[82:83], v[192:193]
	v_mov_b64_e32 v[84:85], v[194:195]
	v_mov_b64_e32 v[86:87], v[196:197]
	v_add_co_u32_e32 v88, vcc, s50, v136
	v_fmamk_f32 v90, v90, 0x3a000000, v172
	v_pk_mul_f32 v[70:71], v[82:83], v[70:71]
	v_rsq_f32_e32 v82, v90
	v_pk_mul_f32 v[68:69], v[80:81], v[68:69]
	v_pk_mul_f32 v[66:67], v[86:87], v[66:67]
	v_pk_mul_f32 v[64:65], v[84:85], v[64:65]
	v_pk_fma_f32 v[70:71], v[70:71], v[82:83], v[78:79] op_sel_hi:[1,0,1]
	v_pk_fma_f32 v[68:69], v[68:69], v[82:83], v[76:77] op_sel_hi:[1,0,1]
	v_pk_fma_f32 v[66:67], v[66:67], v[82:83], v[74:75] op_sel_hi:[1,0,1]
	v_pk_fma_f32 v[64:65], v[64:65], v[82:83], v[72:73] op_sel_hi:[1,0,1]
	v_mul_f32_e32 v69, 0xbfb8aa3b, v69
	v_mul_f32_e32 v64, 0xbfb8aa3b, v64
	v_mul_f32_e32 v65, 0xbfb8aa3b, v65
	v_mul_f32_e32 v70, 0xbfb8aa3b, v70
	v_mul_f32_e32 v67, 0xbfb8aa3b, v67
	v_mul_f32_e32 v68, 0xbfb8aa3b, v68
	v_mul_f32_e32 v66, 0xbfb8aa3b, v66
	v_mul_f32_e32 v71, 0xbfb8aa3b, v71
	v_exp_f32_e32 v64, v64
	v_exp_f32_e32 v69, v69
	v_exp_f32_e32 v65, v65
	v_exp_f32_e32 v70, v70
	v_exp_f32_e32 v67, v67
	v_exp_f32_e32 v68, v68
	v_exp_f32_e32 v66, v66
	v_exp_f32_e32 v71, v71
	v_add_f32_e32 v64, 1.0, v64
	v_add_f32_e32 v69, 1.0, v69
	v_add_f32_e32 v65, 1.0, v65
	v_add_f32_e32 v70, 1.0, v70
	v_add_f32_e32 v67, 1.0, v67
	v_addc_co_u32_e32 v89, vcc, 0, v137, vcc
	v_add_f32_e32 v68, 1.0, v68
	v_add_f32_e32 v66, 1.0, v66
	v_add_f32_e32 v71, 1.0, v71
	v_rcp_f32_e32 v80, v64
	v_rcp_f32_e32 v64, v69
	v_rcp_f32_e32 v69, v65
	v_rcp_f32_e32 v65, v70
	v_rcp_f32_e32 v67, v67
	v_rcp_f32_e32 v68, v68
	v_rcp_f32_e32 v70, v71
	v_rcp_f32_e32 v71, v66
	v_cvt_pk_bf16_f32 v64, v68, v64
	v_cvt_pk_bf16_f32 v65, v65, v70
	v_cvt_pk_bf16_f32 v66, v80, v69
	v_cvt_pk_bf16_f32 v67, v71, v67
	global_store_dwordx4 v[88:89], v[64:67], off sc0 sc1
	s_nop 1
	v_mov_b64_e32 v[64:65], v[198:199]
	v_mov_b64_e32 v[66:67], v[200:201]
	s_nop 0
	v_mov_b64_e32 v[68:69], v[202:203]
	v_mov_b64_e32 v[70:71], v[204:205]
	v_lshl_add_u64 v[80:81], v[136:137], 0, s[10:11]
	v_pk_mul_f32 v[54:55], v[66:67], v[54:55]
	v_pk_mul_f32 v[52:53], v[64:65], v[52:53]
	v_pk_mul_f32 v[50:51], v[70:71], v[50:51]
	v_pk_mul_f32 v[48:49], v[68:69], v[48:49]
	v_pk_fma_f32 v[54:55], v[82:83], v[54:55], v[62:63] op_sel_hi:[0,1,1]
	v_pk_fma_f32 v[52:53], v[82:83], v[52:53], v[60:61] op_sel_hi:[0,1,1]
	v_pk_fma_f32 v[50:51], v[82:83], v[50:51], v[58:59] op_sel_hi:[0,1,1]
	v_pk_fma_f32 v[48:49], v[82:83], v[48:49], v[56:57] op_sel_hi:[0,1,1]
	v_mul_f32_e32 v48, 0xbfb8aa3b, v48
	v_mul_f32_e32 v53, 0xbfb8aa3b, v53
	v_mul_f32_e32 v49, 0xbfb8aa3b, v49
	v_mul_f32_e32 v54, 0xbfb8aa3b, v54
	v_mul_f32_e32 v51, 0xbfb8aa3b, v51
	v_mul_f32_e32 v52, 0xbfb8aa3b, v52
	v_mul_f32_e32 v50, 0xbfb8aa3b, v50
	v_mul_f32_e32 v55, 0xbfb8aa3b, v55
	v_exp_f32_e32 v48, v48
	v_exp_f32_e32 v53, v53
	v_exp_f32_e32 v49, v49
	v_exp_f32_e32 v54, v54
	v_exp_f32_e32 v51, v51
	v_exp_f32_e32 v52, v52
	v_exp_f32_e32 v50, v50
	v_exp_f32_e32 v55, v55
	v_add_f32_e32 v48, 1.0, v48
	v_add_f32_e32 v53, 1.0, v53
	v_add_f32_e32 v49, 1.0, v49
	v_add_f32_e32 v54, 1.0, v54
	v_add_f32_e32 v51, 1.0, v51
	v_add_f32_e32 v52, 1.0, v52
	v_add_f32_e32 v50, 1.0, v50
	v_add_f32_e32 v55, 1.0, v55
	v_rcp_f32_e32 v64, v48
	v_rcp_f32_e32 v48, v53
	v_rcp_f32_e32 v53, v49
	v_rcp_f32_e32 v49, v54
	v_rcp_f32_e32 v51, v51
	v_rcp_f32_e32 v52, v52
	v_rcp_f32_e32 v54, v55
	v_rcp_f32_e32 v55, v50
	v_cvt_pk_bf16_f32 v48, v52, v48
	v_cvt_pk_bf16_f32 v49, v49, v54
	v_cvt_pk_bf16_f32 v50, v64, v53
	v_cvt_pk_bf16_f32 v51, v55, v51
	global_store_dwordx4 v[80:81], v[48:51], off offset:256 sc0 sc1
	s_nop 1
	v_mov_b32_e32 v66, v210
	s_nop 0
	v_mov_b64_e32 v[48:49], v[190:191]
	v_mov_b64_e32 v[50:51], v[192:193]
	v_mov_b64_e32 v[52:53], v[194:195]
	v_mov_b64_e32 v[54:55], v[196:197]
	v_add_co_u32_e32 v64, vcc, s51, v136
	v_fmamk_f32 v66, v66, 0x3a000000, v172
	v_pk_mul_f32 v[46:47], v[50:51], v[46:47]
	v_rsq_f32_e32 v50, v66
	v_pk_mul_f32 v[44:45], v[48:49], v[44:45]
	v_pk_mul_f32 v[42:43], v[54:55], v[42:43]
	v_pk_mul_f32 v[40:41], v[52:53], v[40:41]
	v_pk_fma_f32 v[46:47], v[46:47], v[50:51], v[78:79] op_sel_hi:[1,0,1]
	v_pk_fma_f32 v[44:45], v[44:45], v[50:51], v[76:77] op_sel_hi:[1,0,1]
	v_pk_fma_f32 v[42:43], v[42:43], v[50:51], v[74:75] op_sel_hi:[1,0,1]
	v_pk_fma_f32 v[40:41], v[40:41], v[50:51], v[72:73] op_sel_hi:[1,0,1]
	v_mul_f32_e32 v45, 0xbfb8aa3b, v45
	v_mul_f32_e32 v40, 0xbfb8aa3b, v40
	v_mul_f32_e32 v41, 0xbfb8aa3b, v41
	v_mul_f32_e32 v46, 0xbfb8aa3b, v46
	v_mul_f32_e32 v43, 0xbfb8aa3b, v43
	v_mul_f32_e32 v44, 0xbfb8aa3b, v44
	v_mul_f32_e32 v42, 0xbfb8aa3b, v42
	v_mul_f32_e32 v47, 0xbfb8aa3b, v47
	v_exp_f32_e32 v40, v40
	v_exp_f32_e32 v45, v45
	v_exp_f32_e32 v41, v41
	v_exp_f32_e32 v46, v46
	v_exp_f32_e32 v43, v43
	v_exp_f32_e32 v44, v44
	v_exp_f32_e32 v42, v42
	v_exp_f32_e32 v47, v47
	v_add_f32_e32 v40, 1.0, v40
	v_add_f32_e32 v45, 1.0, v45
	v_add_f32_e32 v41, 1.0, v41
	v_add_f32_e32 v46, 1.0, v46
	v_add_f32_e32 v43, 1.0, v43
	v_addc_co_u32_e32 v65, vcc, 0, v137, vcc
	v_add_f32_e32 v44, 1.0, v44
; __device__ __forceinline__ unsigned cvt_pk_bf16(float lo, float hi) { unsigned r; asm volatile("v_cvt_pk_bf16_f32 %0, %1, %2" : "=v"(r) : "v"(lo), "v"(hi)); return r; }
; __device__ __forceinline__ float rs_of(const float* ssq, int r) { return __builtin_amdgcn_rsqf(ld_agent(ssq + r) * (1.f / 2048.f) + EPS); }
; __device__ __forceinline__ float sigm(float x) { return __builtin_amdgcn_rcpf(1.f + __builtin_amdgcn_exp2f(-LOG2E * x)); }
;     __device__ __forceinline__ void operator()(const i32x4 (&acc)[2][2][4][2], const Unit& u, int wr, int wc, int fr, int fq) const {
;     ...
;                 const int r = row0 + ai * HALF + m * 16; const float rs = rs_of(ssq, r);
;                 bf16_t* rowp = O + (size_t)r * ldc + col0;
; #pragma unroll
;                 for (int bj = 0; bj < 2; ++bj) {
;                     const f32x4 s0 = *(const f32x4*)(swp + col0 + bj * HALF), s1 = *(const f32x4*)(swp + col0 + bj * HALF + 4);
;                     f32x4 v0 = __builtin_convertvector(acc[ai][bj][m][0], f32x4) * s0 * rs + bv[bj][0], v1 = __builtin_convertvector(acc[ai][bj][m][1], f32x4) * s1 * rs + bv[bj][1];
; #pragma unroll
;                     for (int j = 0; j < 4; ++j) { v0[j] = sigm(v0[j]); v1[j] = sigm(v1[j]); }
;                     u32x4 w; w.x = cvt_pk_bf16(v0[0], v0[1]); w.y = cvt_pk_bf16(v0[2], v0[3]); w.z = cvt_pk_bf16(v1[0], v1[1]); w.w = cvt_pk_bf16(v1[2], v1[3]);
;                     *(u32x4*)(rowp + bj * HALF) = w;
	v_add_f32_e32 v42, 1.0, v42
	v_add_f32_e32 v47, 1.0, v47
	v_rcp_f32_e32 v48, v40
	v_rcp_f32_e32 v40, v45
	v_rcp_f32_e32 v45, v41
	v_rcp_f32_e32 v41, v46
	v_rcp_f32_e32 v43, v43
	v_rcp_f32_e32 v44, v44
	v_rcp_f32_e32 v46, v47
	v_rcp_f32_e32 v47, v42
	v_cvt_pk_bf16_f32 v40, v44, v40
	v_cvt_pk_bf16_f32 v41, v41, v46
	v_cvt_pk_bf16_f32 v42, v48, v45
	v_cvt_pk_bf16_f32 v43, v47, v43
	global_store_dwordx4 v[64:65], v[40:43], off sc0 sc1
	s_nop 1
	v_mov_b64_e32 v[40:41], v[198:199]
	v_mov_b64_e32 v[42:43], v[200:201]
	s_nop 0
	v_mov_b64_e32 v[44:45], v[202:203]
	v_mov_b64_e32 v[46:47], v[204:205]
	v_lshl_add_u64 v[48:49], v[136:137], 0, s[12:13]
	v_pk_mul_f32 v[38:39], v[42:43], v[38:39]
	v_pk_mul_f32 v[36:37], v[40:41], v[36:37]
	v_pk_mul_f32 v[34:35], v[46:47], v[34:35]
	v_pk_mul_f32 v[32:33], v[44:45], v[32:33]
	v_pk_fma_f32 v[38:39], v[50:51], v[38:39], v[62:63] op_sel_hi:[0,1,1]
	v_pk_fma_f32 v[36:37], v[50:51], v[36:37], v[60:61] op_sel_hi:[0,1,1]
	v_pk_fma_f32 v[34:35], v[50:51], v[34:35], v[58:59] op_sel_hi:[0,1,1]
	v_pk_fma_f32 v[32:33], v[50:51], v[32:33], v[56:57] op_sel_hi:[0,1,1]
	v_mul_f32_e32 v32, 0xbfb8aa3b, v32
	v_mul_f32_e32 v37, 0xbfb8aa3b, v37
	v_mul_f32_e32 v33, 0xbfb8aa3b, v33
	v_mul_f32_e32 v38, 0xbfb8aa3b, v38
	v_mul_f32_e32 v35, 0xbfb8aa3b, v35
	v_mul_f32_e32 v36, 0xbfb8aa3b, v36
	v_mul_f32_e32 v34, 0xbfb8aa3b, v34
	v_mul_f32_e32 v39, 0xbfb8aa3b, v39
	v_exp_f32_e32 v32, v32
	v_exp_f32_e32 v37, v37
	v_exp_f32_e32 v33, v33
	v_exp_f32_e32 v38, v38
	v_exp_f32_e32 v35, v35
	v_exp_f32_e32 v36, v36
	v_exp_f32_e32 v34, v34
	v_exp_f32_e32 v39, v39
	v_add_f32_e32 v32, 1.0, v32
	v_add_f32_e32 v37, 1.0, v37
	v_add_f32_e32 v33, 1.0, v33
	v_add_f32_e32 v38, 1.0, v38
	v_add_f32_e32 v35, 1.0, v35
	v_add_f32_e32 v36, 1.0, v36
	v_add_f32_e32 v34, 1.0, v34
	v_add_f32_e32 v39, 1.0, v39
	v_rcp_f32_e32 v40, v32
	v_rcp_f32_e32 v32, v37
	v_rcp_f32_e32 v37, v33
	v_rcp_f32_e32 v33, v38
	v_rcp_f32_e32 v35, v35
	v_rcp_f32_e32 v36, v36
	v_rcp_f32_e32 v38, v39
	v_rcp_f32_e32 v39, v34
	v_cvt_pk_bf16_f32 v32, v36, v32
	v_cvt_pk_bf16_f32 v33, v33, v38
	v_cvt_pk_bf16_f32 v34, v40, v37
	v_cvt_pk_bf16_f32 v35, v39, v35
	global_store_dwordx4 v[48:49], v[32:35], off offset:256 sc0 sc1
	s_nop 1
	v_mov_b32_e32 v42, v211
	s_nop 0
	v_mov_b64_e32 v[32:33], v[190:191]
	v_mov_b64_e32 v[34:35], v[192:193]
	v_mov_b64_e32 v[36:37], v[194:195]
	v_mov_b64_e32 v[38:39], v[196:197]
	v_add_co_u32_e32 v40, vcc, s52, v136
	v_fmamk_f32 v42, v42, 0x3a000000, v172
	v_pk_mul_f32 v[30:31], v[34:35], v[30:31]
	v_rsq_f32_e32 v34, v42
	v_pk_mul_f32 v[28:29], v[32:33], v[28:29]
	v_pk_mul_f32 v[26:27], v[38:39], v[26:27]
	v_pk_mul_f32 v[24:25], v[36:37], v[24:25]
	v_pk_fma_f32 v[30:31], v[30:31], v[34:35], v[78:79] op_sel_hi:[1,0,1]
	v_pk_fma_f32 v[28:29], v[28:29], v[34:35], v[76:77] op_sel_hi:[1,0,1]
	v_pk_fma_f32 v[26:27], v[26:27], v[34:35], v[74:75] op_sel_hi:[1,0,1]
	v_pk_fma_f32 v[24:25], v[24:25], v[34:35], v[72:73] op_sel_hi:[1,0,1]
	v_mul_f32_e32 v29, 0xbfb8aa3b, v29
	v_mul_f32_e32 v24, 0xbfb8aa3b, v24
	v_mul_f32_e32 v25, 0xbfb8aa3b, v25
	v_mul_f32_e32 v30, 0xbfb8aa3b, v30
	v_mul_f32_e32 v27, 0xbfb8aa3b, v27
	v_mul_f32_e32 v28, 0xbfb8aa3b, v28
	v_mul_f32_e32 v26, 0xbfb8aa3b, v26
	v_mul_f32_e32 v31, 0xbfb8aa3b, v31
	v_exp_f32_e32 v24, v24
	v_exp_f32_e32 v29, v29
	v_exp_f32_e32 v25, v25
	v_exp_f32_e32 v30, v30
	v_exp_f32_e32 v27, v27
	v_exp_f32_e32 v28, v28
	v_exp_f32_e32 v26, v26
	v_exp_f32_e32 v31, v31
	v_add_f32_e32 v24, 1.0, v24
	v_add_f32_e32 v29, 1.0, v29
	v_add_f32_e32 v25, 1.0, v25
	v_add_f32_e32 v30, 1.0, v30
	v_add_f32_e32 v27, 1.0, v27
	v_addc_co_u32_e32 v41, vcc, 0, v137, vcc
	v_add_f32_e32 v28, 1.0, v28
	v_add_f32_e32 v26, 1.0, v26
	v_add_f32_e32 v31, 1.0, v31
	v_rcp_f32_e32 v32, v24
	v_rcp_f32_e32 v24, v29
	v_rcp_f32_e32 v29, v25
	v_rcp_f32_e32 v25, v30
	v_rcp_f32_e32 v27, v27
	v_rcp_f32_e32 v28, v28
	v_rcp_f32_e32 v30, v31
	v_rcp_f32_e32 v31, v26
	v_cvt_pk_bf16_f32 v24, v28, v24
	v_cvt_pk_bf16_f32 v25, v25, v30
	v_cvt_pk_bf16_f32 v26, v32, v29
	v_cvt_pk_bf16_f32 v27, v31, v27
	global_store_dwordx4 v[40:41], v[24:27], off sc0 sc1
	s_nop 1
	v_mov_b64_e32 v[24:25], v[198:199]
	v_mov_b64_e32 v[26:27], v[200:201]
	s_nop 0
	v_mov_b64_e32 v[28:29], v[202:203]
	v_mov_b64_e32 v[30:31], v[204:205]
	v_lshl_add_u64 v[32:33], v[136:137], 0, s[14:15]
	v_pk_mul_f32 v[22:23], v[26:27], v[22:23]
	v_pk_mul_f32 v[20:21], v[24:25], v[20:21]
	v_pk_mul_f32 v[18:19], v[30:31], v[18:19]
	v_pk_mul_f32 v[16:17], v[28:29], v[16:17]
	v_pk_fma_f32 v[22:23], v[34:35], v[22:23], v[62:63] op_sel_hi:[0,1,1]
	v_pk_fma_f32 v[20:21], v[34:35], v[20:21], v[60:61] op_sel_hi:[0,1,1]
	v_pk_fma_f32 v[18:19], v[34:35], v[18:19], v[58:59] op_sel_hi:[0,1,1]
	v_pk_fma_f32 v[16:17], v[34:35], v[16:17], v[56:57] op_sel_hi:[0,1,1]
; __device__ __forceinline__ unsigned cvt_pk_bf16(float lo, float hi) { unsigned r; asm volatile("v_cvt_pk_bf16_f32 %0, %1, %2" : "=v"(r) : "v"(lo), "v"(hi)); return r; }
; __device__ __forceinline__ float rs_of(const float* ssq, int r) { return __builtin_amdgcn_rsqf(ld_agent(ssq + r) * (1.f / 2048.f) + EPS); }
; __device__ __forceinline__ float sigm(float x) { return __builtin_amdgcn_rcpf(1.f + __builtin_amdgcn_exp2f(-LOG2E * x)); }
; #define PG8_WAIT_V(n) asm volatile("s_waitcnt vmcnt(" #n ")" ::: "memory")
; #define PG8_BAR __builtin_amdgcn_s_barrier()
;     __device__ __forceinline__ void operator()(const i32x4 (&acc)[2][2][4][2], const Unit& u, int wr, int wc, int fr, int fq) const {
;     ...
;                 const int r = row0 + ai * HALF + m * 16; const float rs = rs_of(ssq, r);
;                 bf16_t* rowp = O + (size_t)r * ldc + col0;
; #pragma unroll
;                 for (int bj = 0; bj < 2; ++bj) {
;                     const f32x4 s0 = *(const f32x4*)(swp + col0 + bj * HALF), s1 = *(const f32x4*)(swp + col0 + bj * HALF + 4);
;                     f32x4 v0 = __builtin_convertvector(acc[ai][bj][m][0], f32x4) * s0 * rs + bv[bj][0], v1 = __builtin_convertvector(acc[ai][bj][m][1], f32x4) * s1 * rs + bv[bj][1];
; #pragma unroll
;                     for (int j = 0; j < 4; ++j) { v0[j] = sigm(v0[j]); v1[j] = sigm(v1[j]); }
;                     u32x4 w; w.x = cvt_pk_bf16(v0[0], v0[1]); w.y = cvt_pk_bf16(v0[2], v0[3]); w.z = cvt_pk_bf16(v1[0], v1[1]); w.w = cvt_pk_bf16(v1[2], v1[3]);
;                     *(u32x4*)(rowp + bj * HALF) = w;
;                 }
;             }
; template <class Epi, class Sched>
; __device__ __forceinline__ void gemm_phase(LAS unsigned char* lds, const Gemm g, const Sched& S, const Epi& E) {
;     ...
;         if (!has_next) break;
; #pragma unroll
;         for (int a = 0; a < 2; ++a)
; #pragma unroll
;             for (int b = 0; b < 2; ++b)
; #pragma unroll
;                 for (int m = 0; m < 4; ++m)
; #pragma unroll
;                     for (int n = 0; n < 2; ++n) acc[a][b][m][n] = (acc_t){0, 0, 0, 0};
;         cur = nxt; cA = nA; cB = nB; ++ui;
;     }
;     PG8_WAIT_V(0);
;     if (wr == 0) PG8_BAR;
;     PG8_BAR;
	v_mul_f32_e32 v16, 0xbfb8aa3b, v16
	v_mul_f32_e32 v21, 0xbfb8aa3b, v21
	v_mul_f32_e32 v17, 0xbfb8aa3b, v17
	v_mul_f32_e32 v22, 0xbfb8aa3b, v22
	v_mul_f32_e32 v19, 0xbfb8aa3b, v19
	v_mul_f32_e32 v20, 0xbfb8aa3b, v20
	v_mul_f32_e32 v18, 0xbfb8aa3b, v18
	v_mul_f32_e32 v23, 0xbfb8aa3b, v23
	v_exp_f32_e32 v16, v16
	v_exp_f32_e32 v21, v21
	v_exp_f32_e32 v17, v17
	v_exp_f32_e32 v22, v22
	v_exp_f32_e32 v19, v19
	v_exp_f32_e32 v20, v20
	v_exp_f32_e32 v18, v18
	v_exp_f32_e32 v23, v23
	v_add_f32_e32 v16, 1.0, v16
	v_add_f32_e32 v21, 1.0, v21
	v_add_f32_e32 v17, 1.0, v17
	v_add_f32_e32 v22, 1.0, v22
	v_add_f32_e32 v19, 1.0, v19
	v_add_f32_e32 v20, 1.0, v20
	v_add_f32_e32 v18, 1.0, v18
	v_add_f32_e32 v23, 1.0, v23
	v_rcp_f32_e32 v24, v16
	v_rcp_f32_e32 v16, v21
	v_rcp_f32_e32 v21, v17
	v_rcp_f32_e32 v17, v22
	v_rcp_f32_e32 v19, v19
	v_rcp_f32_e32 v20, v20
	v_rcp_f32_e32 v22, v23
	v_rcp_f32_e32 v23, v18
	v_cvt_pk_bf16_f32 v16, v20, v16
	v_cvt_pk_bf16_f32 v17, v17, v22
	v_cvt_pk_bf16_f32 v18, v24, v21
	v_cvt_pk_bf16_f32 v19, v23, v19
	global_store_dwordx4 v[32:33], v[16:19], off offset:256 sc0 sc1
	s_nop 1
	v_mov_b32_e32 v26, v212
	s_nop 0
	v_mov_b64_e32 v[16:17], v[190:191]
	v_mov_b64_e32 v[18:19], v[192:193]
	v_mov_b64_e32 v[20:21], v[194:195]
	v_mov_b64_e32 v[22:23], v[196:197]
	v_add_co_u32_e32 v24, vcc, s53, v136
	v_fmamk_f32 v26, v26, 0x3a000000, v172
	v_pk_mul_f32 v[14:15], v[18:19], v[14:15]
	v_rsq_f32_e32 v18, v26
	v_pk_mul_f32 v[12:13], v[16:17], v[12:13]
	v_pk_mul_f32 v[10:11], v[22:23], v[10:11]
	v_pk_mul_f32 v[8:9], v[20:21], v[8:9]
	v_pk_fma_f32 v[14:15], v[14:15], v[18:19], v[78:79] op_sel_hi:[1,0,1]
	v_pk_fma_f32 v[12:13], v[12:13], v[18:19], v[76:77] op_sel_hi:[1,0,1]
	v_pk_fma_f32 v[10:11], v[10:11], v[18:19], v[74:75] op_sel_hi:[1,0,1]
	v_pk_fma_f32 v[8:9], v[8:9], v[18:19], v[72:73] op_sel_hi:[1,0,1]
	v_mul_f32_e32 v13, 0xbfb8aa3b, v13
	v_mul_f32_e32 v8, 0xbfb8aa3b, v8
	v_mul_f32_e32 v9, 0xbfb8aa3b, v9
	v_mul_f32_e32 v14, 0xbfb8aa3b, v14
	v_mul_f32_e32 v11, 0xbfb8aa3b, v11
	v_mul_f32_e32 v12, 0xbfb8aa3b, v12
	v_mul_f32_e32 v10, 0xbfb8aa3b, v10
	v_mul_f32_e32 v15, 0xbfb8aa3b, v15
	v_exp_f32_e32 v8, v8
	v_exp_f32_e32 v13, v13
	v_exp_f32_e32 v9, v9
	v_exp_f32_e32 v14, v14
	v_exp_f32_e32 v11, v11
	v_exp_f32_e32 v12, v12
	v_exp_f32_e32 v10, v10
	v_exp_f32_e32 v15, v15
	v_add_f32_e32 v8, 1.0, v8
	v_add_f32_e32 v13, 1.0, v13
	v_add_f32_e32 v9, 1.0, v9
	v_add_f32_e32 v14, 1.0, v14
	v_add_f32_e32 v11, 1.0, v11
	v_addc_co_u32_e32 v25, vcc, 0, v137, vcc
	v_add_f32_e32 v12, 1.0, v12
	v_add_f32_e32 v10, 1.0, v10
	v_add_f32_e32 v15, 1.0, v15
	v_rcp_f32_e32 v16, v8
	v_rcp_f32_e32 v8, v13
	v_rcp_f32_e32 v13, v9
	v_rcp_f32_e32 v9, v14
	v_rcp_f32_e32 v11, v11
	v_rcp_f32_e32 v12, v12
	v_rcp_f32_e32 v14, v15
	v_rcp_f32_e32 v15, v10
	v_cvt_pk_bf16_f32 v8, v12, v8
	v_cvt_pk_bf16_f32 v9, v9, v14
	v_cvt_pk_bf16_f32 v10, v16, v13
	v_cvt_pk_bf16_f32 v11, v15, v11
	global_store_dwordx4 v[24:25], v[8:11], off sc0 sc1
	s_nop 1
	v_mov_b64_e32 v[8:9], v[198:199]
	v_mov_b64_e32 v[10:11], v[200:201]
	s_nop 0
	v_mov_b64_e32 v[12:13], v[202:203]
	v_mov_b64_e32 v[14:15], v[204:205]
	s_and_b64 vcc, exec, s[0:1]
	v_lshl_add_u64 v[16:17], v[136:137], 0, s[16:17]
	v_pk_mul_f32 v[6:7], v[10:11], v[6:7]
	v_pk_mul_f32 v[4:5], v[8:9], v[4:5]
	v_pk_mul_f32 v[2:3], v[14:15], v[2:3]
	v_pk_mul_f32 v[0:1], v[12:13], v[0:1]
	v_pk_fma_f32 v[6:7], v[18:19], v[6:7], v[62:63] op_sel_hi:[0,1,1]
	v_pk_fma_f32 v[4:5], v[18:19], v[4:5], v[60:61] op_sel_hi:[0,1,1]
	v_pk_fma_f32 v[2:3], v[18:19], v[2:3], v[58:59] op_sel_hi:[0,1,1]
	v_pk_fma_f32 v[0:1], v[18:19], v[0:1], v[56:57] op_sel_hi:[0,1,1]
	v_mul_f32_e32 v0, 0xbfb8aa3b, v0
	v_mul_f32_e32 v5, 0xbfb8aa3b, v5
	v_mul_f32_e32 v1, 0xbfb8aa3b, v1
	v_mul_f32_e32 v6, 0xbfb8aa3b, v6
	v_mul_f32_e32 v3, 0xbfb8aa3b, v3
	v_mul_f32_e32 v4, 0xbfb8aa3b, v4
	v_mul_f32_e32 v2, 0xbfb8aa3b, v2
	v_mul_f32_e32 v7, 0xbfb8aa3b, v7
	v_exp_f32_e32 v0, v0
	v_exp_f32_e32 v5, v5
	v_exp_f32_e32 v1, v1
	v_exp_f32_e32 v6, v6
	v_exp_f32_e32 v3, v3
	v_exp_f32_e32 v4, v4
	v_exp_f32_e32 v2, v2
	v_exp_f32_e32 v7, v7
	v_add_f32_e32 v0, 1.0, v0
	v_add_f32_e32 v5, 1.0, v5
	v_add_f32_e32 v1, 1.0, v1
	v_add_f32_e32 v6, 1.0, v6
	v_add_f32_e32 v3, 1.0, v3
	v_add_f32_e32 v4, 1.0, v4
	v_add_f32_e32 v2, 1.0, v2
	v_add_f32_e32 v7, 1.0, v7
	v_rcp_f32_e32 v8, v0
	v_rcp_f32_e32 v0, v5
	v_rcp_f32_e32 v5, v1
	v_rcp_f32_e32 v1, v6
	v_rcp_f32_e32 v3, v3
	v_rcp_f32_e32 v4, v4
	v_rcp_f32_e32 v6, v7
	v_rcp_f32_e32 v7, v2
	v_cvt_pk_bf16_f32 v0, v4, v0
	v_cvt_pk_bf16_f32 v1, v1, v6
	v_cvt_pk_bf16_f32 v2, v8, v5
	v_cvt_pk_bf16_f32 v3, v7, v3
	global_store_dwordx4 v[16:17], v[0:3], off offset:256 sc0 sc1
	s_nop 1
	s_cbranch_vccz .LBB0_632
	s_waitcnt vmcnt(0)
	s_cmpk_gt_u32 s33, 0xff
	s_cbranch_scc1 .LBB0_639
	s_barrier

; #define PG8_STAGE(bufoff, gbase, voff) do { _Pragma("unroll") for (int _i = 0; _i < 2; ++_i) \
;         __builtin_amdgcn_global_load_lds((const unsigned*)((const char*)(gbase) + (voff)[_i]), (LAS unsigned*)(lds + (bufoff) + ldsw + _i * 8192), 16, 0, 0); } while (0)
; #define PG8_LDA(dst, b, h) do { _Pragma("unroll") for (int m = 0; m < 4; ++m) _Pragma("unroll") for (int k = 0; k < 2; ++k) dst[m][k] = *(const LAS bf16x8*)(lds + PG8_SA(b, h) + aoff + m * 2048 + k * 1024); } while (0)
; #define PG8_LDB(dst, b, h) do { _Pragma("unroll") for (int n = 0; n < 2; ++n) _Pragma("unroll") for (int k = 0; k < 2; ++k) dst[n][k] = *(const LAS bf16x8*)(lds + PG8_SB(b, h) + boff + n * 2048 + k * 1024); } while (0)
; #define PG8_MMA(ai, bj, At, Bt) do { __builtin_amdgcn_s_setprio(1); _Pragma("unroll") for (int m = 0; m < 4; ++m) _Pragma("unroll") for (int n = 0; n < 2; ++n) _Pragma("unroll") for (int k = 0; k < 2; ++k) \
;         acc[ai][bj][m][n] = MmaOp<Epi::I8>::run(Bt[n][k], At[m][k], acc[ai][bj][m][n]); __builtin_amdgcn_s_setprio(0); } while (0)
; #define PG8_WAIT_V(n) asm volatile("s_waitcnt vmcnt(" #n ")" ::: "memory")
; #define PG8_WAIT_L(n) asm volatile("s_waitcnt lgkmcnt(" #n ")" ::: "memory")
; #define PG8_BAR __builtin_amdgcn_s_barrier()
; #define PG8_SCHED __builtin_amdgcn_sched_barrier(0)
; template <class Epi, class Sched>
; __device__ __forceinline__ void gemm_phase(LAS unsigned char* lds, const Gemm g, const Sched& S, const Epi& E) {
;     ...
;             PG8_LDB(B0, 0, 0); PG8_SCHED; PG8_LDA(At, 0, 0); PG8_STAGE(PG8_SA(1, 1), a1 + hstepA, voffA);
;             PG8_WAIT_L(8); PG8_BAR; PG8_WAIT_L(0); PG8_MMA(0, 0, At, B0); PG8_BAR; PG8_SCHED;
;             PG8_LDB(B1, 0, 1); PG8_STAGE(PG8_SB(0, 0), b2, voffB);
;             PG8_BAR; PG8_WAIT_L(0); PG8_MMA(0, 1, At, B1); PG8_BAR;
;             PG8_LDA(At, 0, 1); PG8_STAGE(PG8_SA(0, 0), a2, voffA);
;             PG8_BAR; PG8_WAIT_L(0); PG8_MMA(1, 0, At, B0); PG8_BAR; PG8_SCHED;
;             PG8_STAGE(PG8_SB(0, 1), b2 + hstepB, voffB);
;             PG8_WAIT_V(6); PG8_BAR; PG8_MMA(1, 1, At, B1); PG8_BAR;
.LBB0_702:
	ds_read_b128 v[144:147], v153
	ds_read_b128 v[156:159], v153 offset:1024
	ds_read_b128 v[160:163], v153 offset:2048
	ds_read_b128 v[164:167], v153 offset:3072
	s_add_u32 s16, s14, 0xfff80080
	s_addc_u32 s17, s15, -1
	s_cmp_eq_u32 s46, 12
	s_cselect_b32 s19, s7, s17
	s_cselect_b32 s18, s42, s16
	s_cselect_b32 s17, s5, s45
	s_cselect_b32 s16, s43, s44
	v_lshl_add_u64 v[148:149], s[14:15], 0, v[136:137]
	s_add_i32 m0, s13, 0xc000
	ds_read_b128 v[168:171], v154
	ds_read_b128 v[172:175], v154 offset:1024
	ds_read_b128 v[178:181], v154 offset:2048
	ds_read_b128 v[182:185], v154 offset:3072
	ds_read_b128 v[186:189], v154 offset:4096
	ds_read_b128 v[190:193], v154 offset:5120
	ds_read_b128 v[194:197], v154 offset:6144
	ds_read_b128 v[198:201], v154 offset:7168
	global_load_lds_dwordx4 v[148:149], off
	v_lshl_add_u64 v[148:149], s[14:15], 0, v[138:139]
	s_add_i32 m0, s13, 0xe000
	s_nop 0
	global_load_lds_dwordx4 v[148:149], off
	s_waitcnt lgkmcnt(8)
	s_barrier
	s_waitcnt lgkmcnt(0)
	s_setprio 1
	v_mfma_f32_16x16x32_bf16 v[124:127], v[144:147], v[168:171], v[124:127]
	v_mfma_f32_16x16x32_bf16 v[120:123], v[160:163], v[168:171], v[120:123]
	v_mfma_f32_16x16x32_bf16 v[108:111], v[144:147], v[178:181], v[108:111]
	v_mfma_f32_16x16x32_bf16 v[104:107], v[160:163], v[178:181], v[104:107]
	v_mfma_f32_16x16x32_bf16 v[92:95], v[144:147], v[186:189], v[92:95]
	v_mfma_f32_16x16x32_bf16 v[88:91], v[160:163], v[186:189], v[88:91]
	v_mfma_f32_16x16x32_bf16 v[76:79], v[144:147], v[194:197], v[76:79]
	v_mfma_f32_16x16x32_bf16 v[72:75], v[160:163], v[194:197], v[72:75]
	v_mfma_f32_16x16x32_bf16 v[124:127], v[156:159], v[172:175], v[124:127]
	v_mfma_f32_16x16x32_bf16 v[120:123], v[164:167], v[172:175], v[120:123]
	v_mfma_f32_16x16x32_bf16 v[108:111], v[156:159], v[182:185], v[108:111]
	v_mfma_f32_16x16x32_bf16 v[104:107], v[164:167], v[182:185], v[104:107]
	v_mfma_f32_16x16x32_bf16 v[92:95], v[156:159], v[190:193], v[92:95]
	v_mfma_f32_16x16x32_bf16 v[88:91], v[164:167], v[190:193], v[88:91]
	v_mfma_f32_16x16x32_bf16 v[76:79], v[156:159], v[198:201], v[76:79]
	v_mfma_f32_16x16x32_bf16 v[72:75], v[164:167], v[198:201], v[72:75]
	s_setprio 0
	s_barrier
	s_add_i32 s47, s31, s21
	v_lshl_add_u64 v[148:149], s[16:17], 0, v[132:133]
	s_mov_b32 m0, s47
	ds_read_b128 v[202:205], v155
	ds_read_b128 v[206:209], v155 offset:1024
	ds_read_b128 v[210:213], v155 offset:2048
	ds_read_b128 v[214:217], v155 offset:3072
	global_load_lds_dwordx4 v[148:149], off
	v_lshl_add_u64 v[218:219], s[16:17], 0, v[128:129]
	s_add_i32 m0, s47, 0x2000
	s_nop 0
	global_load_lds_dwordx4 v[218:219], off
	s_barrier
	s_waitcnt lgkmcnt(0)
	s_setprio 1
	v_mfma_f32_16x16x32_bf16 v[116:119], v[202:205], v[168:171], v[116:119]
	v_mfma_f32_16x16x32_bf16 v[112:115], v[210:213], v[168:171], v[112:115]
	v_mfma_f32_16x16x32_bf16 v[100:103], v[202:205], v[178:181], v[100:103]
	v_mfma_f32_16x16x32_bf16 v[96:99], v[210:213], v[178:181], v[96:99]
	v_mfma_f32_16x16x32_bf16 v[84:87], v[202:205], v[186:189], v[84:87]
	v_mfma_f32_16x16x32_bf16 v[80:83], v[210:213], v[186:189], v[80:83]
	v_mfma_f32_16x16x32_bf16 v[68:71], v[202:205], v[194:197], v[68:71]
	v_mfma_f32_16x16x32_bf16 v[64:67], v[210:213], v[194:197], v[64:67]
	v_mfma_f32_16x16x32_bf16 v[116:119], v[206:209], v[172:175], v[116:119]
	v_mfma_f32_16x16x32_bf16 v[112:115], v[214:217], v[172:175], v[112:115]
	v_mfma_f32_16x16x32_bf16 v[100:103], v[206:209], v[182:185], v[100:103]
	v_mfma_f32_16x16x32_bf16 v[96:99], v[214:217], v[182:185], v[96:99]
	v_mfma_f32_16x16x32_bf16 v[84:87], v[206:209], v[190:193], v[84:87]
	v_mfma_f32_16x16x32_bf16 v[80:83], v[214:217], v[190:193], v[80:83]
	v_mfma_f32_16x16x32_bf16 v[68:71], v[206:209], v[198:201], v[68:71]
	v_mfma_f32_16x16x32_bf16 v[64:67], v[214:217], v[198:201], v[64:67]
	s_setprio 0
	s_mov_b32 m0, s13
	v_lshl_add_u64 v[220:221], s[18:19], 0, v[134:135]
	s_barrier
	ds_read_b128 v[168:171], v154 offset:16384
	ds_read_b128 v[172:175], v154 offset:17408
	ds_read_b128 v[178:181], v154 offset:18432
	ds_read_b128 v[182:185], v154 offset:19456
	ds_read_b128 v[186:189], v154 offset:20480
	ds_read_b128 v[190:193], v154 offset:21504
	ds_read_b128 v[194:197], v154 offset:22528
	ds_read_b128 v[198:201], v154 offset:23552
	global_load_lds_dwordx4 v[220:221], off
	v_lshl_add_u64 v[222:223], s[18:19], 0, v[130:131]
	s_mov_b32 m0, s24
	s_nop 0
	global_load_lds_dwordx4 v[222:223], off
	s_barrier
	s_waitcnt lgkmcnt(0)
	s_setprio 1
	v_mfma_f32_16x16x32_bf16 v[60:63], v[144:147], v[168:171], v[60:63]
	v_mfma_f32_16x16x32_bf16 v[56:59], v[160:163], v[168:171], v[56:59]
	v_mfma_f32_16x16x32_bf16 v[48:51], v[144:147], v[178:181], v[48:51]
	v_mfma_f32_16x16x32_bf16 v[40:43], v[160:163], v[178:181], v[40:43]
	v_mfma_f32_16x16x32_bf16 v[28:31], v[144:147], v[186:189], v[28:31]
	v_mfma_f32_16x16x32_bf16 v[24:27], v[160:163], v[186:189], v[24:27]
	v_mfma_f32_16x16x32_bf16 v[16:19], v[144:147], v[194:197], v[16:19]
	v_mfma_f32_16x16x32_bf16 v[8:11], v[160:163], v[194:197], v[8:11]
	v_mfma_f32_16x16x32_bf16 v[60:63], v[156:159], v[172:175], v[60:63]
	v_mfma_f32_16x16x32_bf16 v[56:59], v[164:167], v[172:175], v[56:59]
	v_mfma_f32_16x16x32_bf16 v[48:51], v[156:159], v[182:185], v[48:51]
	v_mfma_f32_16x16x32_bf16 v[40:43], v[164:167], v[182:185], v[40:43]
	v_mfma_f32_16x16x32_bf16 v[28:31], v[156:159], v[190:193], v[28:31]
	v_mfma_f32_16x16x32_bf16 v[24:27], v[164:167], v[190:193], v[24:27]
	v_mfma_f32_16x16x32_bf16 v[16:19], v[156:159], v[198:201], v[16:19]
	v_mfma_f32_16x16x32_bf16 v[8:11], v[164:167], v[198:201], v[8:11]
	s_setprio 0
	s_barrier
; #define PG8_STAGE(bufoff, gbase, voff) do { _Pragma("unroll") for (int _i = 0; _i < 2; ++_i) \
;         __builtin_amdgcn_global_load_lds((const unsigned*)((const char*)(gbase) + (voff)[_i]), (LAS unsigned*)(lds + (bufoff) + ldsw + _i * 8192), 16, 0, 0); } while (0)
; #define PG8_LDA(dst, b, h) do { _Pragma("unroll") for (int m = 0; m < 4; ++m) _Pragma("unroll") for (int k = 0; k < 2; ++k) dst[m][k] = *(const LAS bf16x8*)(lds + PG8_SA(b, h) + aoff + m * 2048 + k * 1024); } while (0)
; #define PG8_LDB(dst, b, h) do { _Pragma("unroll") for (int n = 0; n < 2; ++n) _Pragma("unroll") for (int k = 0; k < 2; ++k) dst[n][k] = *(const LAS bf16x8*)(lds + PG8_SB(b, h) + boff + n * 2048 + k * 1024); } while (0)
; #define PG8_MMA(ai, bj, At, Bt) do { __builtin_amdgcn_s_setprio(1); _Pragma("unroll") for (int m = 0; m < 4; ++m) _Pragma("unroll") for (int n = 0; n < 2; ++n) _Pragma("unroll") for (int k = 0; k < 2; ++k) \
;         acc[ai][bj][m][n] = MmaOp<Epi::I8>::run(Bt[n][k], At[m][k], acc[ai][bj][m][n]); __builtin_amdgcn_s_setprio(0); } while (0)
; #define PG8_WAIT_V(n) asm volatile("s_waitcnt vmcnt(" #n ")" ::: "memory")
; #define PG8_WAIT_L(n) asm volatile("s_waitcnt lgkmcnt(" #n ")" ::: "memory")
; #define PG8_BAR __builtin_amdgcn_s_barrier()
; #define PG8_SCHED __builtin_amdgcn_sched_barrier(0)
; template <class Epi, class Sched>
; __device__ __forceinline__ void gemm_phase(LAS unsigned char* lds, const Gemm g, const Sched& S, const Epi& E) {
;     ...
;             PG8_WAIT_V(6); PG8_BAR; PG8_MMA(1, 1, At, B1); PG8_BAR;
;             PG8_LDB(B0, 1, 0); PG8_SCHED; PG8_LDA(At, 1, 0); PG8_STAGE(PG8_SA(0, 1), a2 + hstepA, voffA);
;             PG8_WAIT_L(8); PG8_BAR; PG8_WAIT_L(0); PG8_MMA(0, 0, At, B0); PG8_BAR; PG8_SCHED;
;             PG8_LDB(B1, 1, 1); PG8_STAGE(PG8_SB(1, 0), b3, voffB);
;             PG8_BAR; PG8_WAIT_L(0); PG8_MMA(0, 1, At, B1); PG8_BAR;
;             PG8_LDA(At, 1, 1); PG8_STAGE(PG8_SA(1, 0), a3, voffA);
;             PG8_BAR; PG8_WAIT_L(0); PG8_MMA(1, 0, At, B0); PG8_BAR; PG8_SCHED;
	s_add_u32 s48, s16, 0x40000
	s_addc_u32 s49, s17, 0
	s_add_i32 s47, s33, s21
	v_lshl_add_u64 v[144:145], s[48:49], 0, v[132:133]
	s_mov_b32 m0, s47
	s_nop 0
	global_load_lds_dwordx4 v[144:145], off
	v_lshl_add_u64 v[144:145], s[48:49], 0, v[128:129]
	s_add_i32 m0, s47, 0x2000
	s_nop 0
	global_load_lds_dwordx4 v[144:145], off
	s_waitcnt vmcnt(6)
	s_barrier
	s_setprio 1
	v_mfma_f32_16x16x32_bf16 v[52:55], v[202:205], v[168:171], v[52:55]
	v_mfma_f32_16x16x32_bf16 v[44:47], v[210:213], v[168:171], v[44:47]
	v_mfma_f32_16x16x32_bf16 v[36:39], v[202:205], v[178:181], v[36:39]
	v_mfma_f32_16x16x32_bf16 v[32:35], v[210:213], v[178:181], v[32:35]
	v_mfma_f32_16x16x32_bf16 v[20:23], v[202:205], v[186:189], v[20:23]
	v_mfma_f32_16x16x32_bf16 v[12:15], v[210:213], v[186:189], v[12:15]
	v_mfma_f32_16x16x32_bf16 v[4:7], v[202:205], v[194:197], v[4:7]
	v_mfma_f32_16x16x32_bf16 v[0:3], v[210:213], v[194:197], v[0:3]
	v_mfma_f32_16x16x32_bf16 v[52:55], v[206:209], v[172:175], v[52:55]
	v_mfma_f32_16x16x32_bf16 v[44:47], v[214:217], v[172:175], v[44:47]
	v_mfma_f32_16x16x32_bf16 v[36:39], v[206:209], v[182:185], v[36:39]
	v_mfma_f32_16x16x32_bf16 v[32:35], v[214:217], v[182:185], v[32:35]
	v_mfma_f32_16x16x32_bf16 v[20:23], v[206:209], v[190:193], v[20:23]
	v_mfma_f32_16x16x32_bf16 v[12:15], v[214:217], v[190:193], v[12:15]
	v_mfma_f32_16x16x32_bf16 v[4:7], v[206:209], v[198:201], v[4:7]
	v_mfma_f32_16x16x32_bf16 v[0:3], v[214:217], v[198:201], v[0:3]
	s_setprio 0
	s_add_i32 s47, 0, 0x18000
	v_add_u32_e32 v164, s47, v151
	s_barrier
	ds_read_b128 v[144:147], v164
	ds_read_b128 v[156:159], v164 offset:1024
	ds_read_b128 v[160:163], v164 offset:2048
	ds_read_b128 v[164:167], v164 offset:3072
	s_add_u32 s18, s18, 0x80000
	s_addc_u32 s19, s19, 0
	s_mov_b32 m0, s25
	v_lshl_add_u64 v[202:203], s[18:19], 0, v[134:135]
	ds_read_b128 v[168:171], v154 offset:32768
	ds_read_b128 v[172:175], v154 offset:33792
	ds_read_b128 v[178:181], v154 offset:34816
	ds_read_b128 v[182:185], v154 offset:35840
	ds_read_b128 v[186:189], v154 offset:36864
	ds_read_b128 v[190:193], v154 offset:37888
	ds_read_b128 v[194:197], v154 offset:38912
	ds_read_b128 v[198:201], v154 offset:39936
	global_load_lds_dwordx4 v[202:203], off
	v_lshl_add_u64 v[202:203], s[18:19], 0, v[130:131]
	s_mov_b32 m0, s26
	s_nop 0
	global_load_lds_dwordx4 v[202:203], off
	s_waitcnt lgkmcnt(8)
	s_barrier
	s_waitcnt lgkmcnt(0)
	s_setprio 1
	v_mfma_f32_16x16x32_bf16 v[124:127], v[144:147], v[168:171], v[124:127]
	v_mfma_f32_16x16x32_bf16 v[120:123], v[160:163], v[168:171], v[120:123]
	v_mfma_f32_16x16x32_bf16 v[108:111], v[144:147], v[178:181], v[108:111]
	v_mfma_f32_16x16x32_bf16 v[104:107], v[160:163], v[178:181], v[104:107]
	v_mfma_f32_16x16x32_bf16 v[92:95], v[144:147], v[186:189], v[92:95]
	v_mfma_f32_16x16x32_bf16 v[88:91], v[160:163], v[186:189], v[88:91]
	v_mfma_f32_16x16x32_bf16 v[76:79], v[144:147], v[194:197], v[76:79]
	v_mfma_f32_16x16x32_bf16 v[72:75], v[160:163], v[194:197], v[72:75]
	v_mfma_f32_16x16x32_bf16 v[124:127], v[156:159], v[172:175], v[124:127]
	v_mfma_f32_16x16x32_bf16 v[120:123], v[164:167], v[172:175], v[120:123]
	v_mfma_f32_16x16x32_bf16 v[108:111], v[156:159], v[182:185], v[108:111]
	v_mfma_f32_16x16x32_bf16 v[104:107], v[164:167], v[182:185], v[104:107]
	v_mfma_f32_16x16x32_bf16 v[92:95], v[156:159], v[190:193], v[92:95]
	v_mfma_f32_16x16x32_bf16 v[88:91], v[164:167], v[190:193], v[88:91]
	v_mfma_f32_16x16x32_bf16 v[76:79], v[156:159], v[198:201], v[76:79]
	v_mfma_f32_16x16x32_bf16 v[72:75], v[164:167], v[198:201], v[72:75]
	s_setprio 0
	s_barrier
	s_add_i32 s18, 0, 0x1c000
	s_add_i32 s19, s47, s21
	v_add_u32_e32 v214, s18, v151
	v_lshl_add_u64 v[148:149], v[148:149], 0, s[2:3]
	s_mov_b32 m0, s19
	ds_read_b128 v[202:205], v214
	ds_read_b128 v[206:209], v214 offset:1024
	ds_read_b128 v[210:213], v214 offset:2048
	ds_read_b128 v[214:217], v214 offset:3072
	global_load_lds_dwordx4 v[148:149], off
	v_lshl_add_u64 v[148:149], v[218:219], 0, s[2:3]
	s_add_i32 m0, s19, 0x2000
	s_nop 0
	global_load_lds_dwordx4 v[148:149], off
	s_barrier
	s_waitcnt lgkmcnt(0)
	s_setprio 1
	v_mfma_f32_16x16x32_bf16 v[116:119], v[202:205], v[168:171], v[116:119]
	v_mfma_f32_16x16x32_bf16 v[112:115], v[210:213], v[168:171], v[112:115]
	v_mfma_f32_16x16x32_bf16 v[100:103], v[202:205], v[178:181], v[100:103]
	v_mfma_f32_16x16x32_bf16 v[96:99], v[210:213], v[178:181], v[96:99]
	v_mfma_f32_16x16x32_bf16 v[84:87], v[202:205], v[186:189], v[84:87]
	v_mfma_f32_16x16x32_bf16 v[80:83], v[210:213], v[186:189], v[80:83]
	v_mfma_f32_16x16x32_bf16 v[68:71], v[202:205], v[194:197], v[68:71]
	v_mfma_f32_16x16x32_bf16 v[64:67], v[210:213], v[194:197], v[64:67]
	v_mfma_f32_16x16x32_bf16 v[116:119], v[206:209], v[172:175], v[116:119]
	v_mfma_f32_16x16x32_bf16 v[112:115], v[214:217], v[172:175], v[112:115]
	v_mfma_f32_16x16x32_bf16 v[100:103], v[206:209], v[182:185], v[100:103]
	v_mfma_f32_16x16x32_bf16 v[96:99], v[214:217], v[182:185], v[96:99]
	v_mfma_f32_16x16x32_bf16 v[84:87], v[206:209], v[190:193], v[84:87]
	v_mfma_f32_16x16x32_bf16 v[80:83], v[214:217], v[190:193], v[80:83]
	v_mfma_f32_16x16x32_bf16 v[68:71], v[206:209], v[198:201], v[68:71]
	v_mfma_f32_16x16x32_bf16 v[64:67], v[214:217], v[198:201], v[64:67]
	s_setprio 0
	s_mov_b32 m0, s28
	v_lshl_add_u64 v[148:149], v[220:221], 0, s[2:3]
	s_barrier
	ds_read_b128 v[168:171], v154 offset:49152
	ds_read_b128 v[172:175], v154 offset:50176
	ds_read_b128 v[178:181], v154 offset:51200
	ds_read_b128 v[182:185], v154 offset:52224
	ds_read_b128 v[186:189], v154 offset:53248
	ds_read_b128 v[190:193], v154 offset:54272
	ds_read_b128 v[194:197], v154 offset:55296
	ds_read_b128 v[198:201], v154 offset:56320
	global_load_lds_dwordx4 v[148:149], off
	v_lshl_add_u64 v[148:149], v[222:223], 0, s[2:3]
	s_mov_b32 m0, s29
	s_nop 0
	global_load_lds_dwordx4 v[148:149], off
	s_barrier
; __device__ __forceinline__ float bf_lo(unsigned w) { return __uint_as_float(w << 16); }
;     __device__ __forceinline__ void operator()(const f32x4 (&acc)[2][2][4][2], const Unit& u, int wr, int wc, int fr, int fq) const {
;         const int row0 = u.pm * BM + wr * 64 + fr, col0 = u.pn * BM + wc * 32 + 8 * fq;
;         bf16_t* base = G + (size_t)row0 * NGATE + col0;
;         u32x4 ga[2], gb[2], na[2], nb[2];
; #pragma unroll
;         for (int bj = 0; bj < 2; ++bj) { ga[bj] = *(const u32x4*)(base + bj * HALF); if (STEP == 1) gb[bj] = *(const u32x4*)(base + bj * HALF + DM); }
; #pragma unroll
;         for (int g = 0; g < 8; ++g) {
;             const int ai = g >> 2, m = g & 3;
;             bf16_t* rowp = base + (size_t)(ai * HALF + m * 16) * NGATE;
;             if (g < 7) { const bf16_t* nrow = base + (size_t)(((g + 1) >> 2) * HALF + ((g + 1) & 3) * 16) * NGATE;
; #pragma unroll
;                 for (int bj = 0; bj < 2; ++bj) { na[bj] = *(const u32x4*)(nrow + bj * HALF); if (STEP == 1) nb[bj] = *(const u32x4*)(nrow + bj * HALF + DM); } }
; #pragma unroll
;             for (int bj = 0; bj < 2; ++bj) {
;                 const f32x4 a0 = acc[ai][bj][m][0], a1 = acc[ai][bj][m][1];
;                 float v[8];
;                 if (STEP == 0) {
;                     v[0] = bf_lo(ga[bj].x) * a0[0]; v[1] = bf_hi(ga[bj].x) * a0[1]; v[2] = bf_lo(ga[bj].y) * a0[2]; v[3] = bf_hi(ga[bj].y) * a0[3];
;                     v[4] = bf_lo(ga[bj].z) * a1[0]; v[5] = bf_hi(ga[bj].z) * a1[1]; v[6] = bf_lo(ga[bj].w) * a1[2]; v[7] = bf_hi(ga[bj].w) * a1[3];
;                 } else {
; template <class Epi, class Sched>
; __device__ __forceinline__ void gemm_phase(LAS unsigned char* lds, const Gemm g, const Sched& S, const Epi& E) {
;     ...
;             PG8_LDB(B0, 1, 0); PG8_SCHED; PG8_LDA(At, 1, 0); PG8_STAGE(PG8_SA(0, 1), a2 + hstepA, voffA);
;             PG8_WAIT_L(8); PG8_BAR; PG8_WAIT_L(0); PG8_MMA(0, 0, At, B0); PG8_BAR; PG8_SCHED;
;             PG8_LDB(B1, 1, 1); PG8_STAGE(PG8_SB(1, 0), b3, voffB);
;             PG8_BAR; PG8_WAIT_L(0); PG8_MMA(0, 1, At, B1); PG8_BAR;
;             PG8_LDA(At, 1, 1); PG8_STAGE(PG8_SA(1, 0), a3, voffA);
;             PG8_BAR; PG8_WAIT_L(0); PG8_MMA(1, 0, At, B0); PG8_BAR; PG8_SCHED;
;             PG8_STAGE(PG8_SB(1, 1), b3 + hstepB, voffB);
;             PG8_WAIT_V(6); PG8_BAR; PG8_MMA(1, 1, At, B1); PG8_BAR;
	s_waitcnt lgkmcnt(0)
	s_setprio 1
	v_mfma_f32_16x16x32_bf16 v[60:63], v[144:147], v[168:171], v[60:63]
	v_mfma_f32_16x16x32_bf16 v[56:59], v[160:163], v[168:171], v[56:59]
	v_mfma_f32_16x16x32_bf16 v[48:51], v[144:147], v[178:181], v[48:51]
	v_mfma_f32_16x16x32_bf16 v[40:43], v[160:163], v[178:181], v[40:43]
	v_mfma_f32_16x16x32_bf16 v[28:31], v[144:147], v[186:189], v[28:31]
	v_mfma_f32_16x16x32_bf16 v[24:27], v[160:163], v[186:189], v[24:27]
	v_mfma_f32_16x16x32_bf16 v[16:19], v[144:147], v[194:197], v[16:19]
	v_mfma_f32_16x16x32_bf16 v[8:11], v[160:163], v[194:197], v[8:11]
	v_mfma_f32_16x16x32_bf16 v[60:63], v[156:159], v[172:175], v[60:63]
	v_mfma_f32_16x16x32_bf16 v[56:59], v[164:167], v[172:175], v[56:59]
	v_mfma_f32_16x16x32_bf16 v[48:51], v[156:159], v[182:185], v[48:51]
	v_mfma_f32_16x16x32_bf16 v[40:43], v[164:167], v[182:185], v[40:43]
	v_mfma_f32_16x16x32_bf16 v[28:31], v[156:159], v[190:193], v[28:31]
	v_mfma_f32_16x16x32_bf16 v[24:27], v[164:167], v[190:193], v[24:27]
	v_mfma_f32_16x16x32_bf16 v[16:19], v[156:159], v[198:201], v[16:19]
	v_mfma_f32_16x16x32_bf16 v[8:11], v[164:167], v[198:201], v[8:11]
	s_setprio 0
	s_barrier
	s_add_u32 s16, s16, 0x40080
	s_addc_u32 s17, s17, 0
	s_add_i32 s18, s18, s21
	v_lshl_add_u64 v[144:145], s[16:17], 0, v[132:133]
	s_mov_b32 m0, s18
	s_nop 0
	global_load_lds_dwordx4 v[144:145], off
	v_lshl_add_u64 v[144:145], s[16:17], 0, v[128:129]
	s_add_i32 m0, s18, 0x2000
	s_nop 0
	global_load_lds_dwordx4 v[144:145], off
	s_waitcnt vmcnt(6)
	s_barrier
	s_setprio 1
	v_mfma_f32_16x16x32_bf16 v[52:55], v[202:205], v[168:171], v[52:55]
	v_mfma_f32_16x16x32_bf16 v[44:47], v[210:213], v[168:171], v[44:47]
	v_mfma_f32_16x16x32_bf16 v[36:39], v[202:205], v[178:181], v[36:39]
	v_mfma_f32_16x16x32_bf16 v[32:35], v[210:213], v[178:181], v[32:35]
	v_mfma_f32_16x16x32_bf16 v[20:23], v[202:205], v[186:189], v[20:23]
	v_mfma_f32_16x16x32_bf16 v[12:15], v[210:213], v[186:189], v[12:15]
	v_mfma_f32_16x16x32_bf16 v[4:7], v[202:205], v[194:197], v[4:7]
	v_mfma_f32_16x16x32_bf16 v[0:3], v[210:213], v[194:197], v[0:3]
	v_mfma_f32_16x16x32_bf16 v[52:55], v[206:209], v[172:175], v[52:55]
	v_mfma_f32_16x16x32_bf16 v[44:47], v[214:217], v[172:175], v[44:47]
	v_mfma_f32_16x16x32_bf16 v[36:39], v[206:209], v[182:185], v[36:39]
	v_mfma_f32_16x16x32_bf16 v[32:35], v[214:217], v[182:185], v[32:35]
	v_mfma_f32_16x16x32_bf16 v[20:23], v[206:209], v[190:193], v[20:23]
	v_mfma_f32_16x16x32_bf16 v[12:15], v[214:217], v[190:193], v[12:15]
	v_mfma_f32_16x16x32_bf16 v[4:7], v[206:209], v[198:201], v[4:7]
	v_mfma_f32_16x16x32_bf16 v[0:3], v[214:217], v[198:201], v[0:3]
	s_setprio 0
	s_add_i32 s46, s46, 2
	s_add_u32 s14, s14, 0x100
	s_addc_u32 s15, s15, 0
	s_add_u32 s44, s44, 0x100
	s_addc_u32 s45, s45, 0
	s_cmp_gt_u32 s46, 13
	s_barrier
	s_cbranch_scc0 .LBB0_702
	v_lshl_add_u32 v144, s12, 8, v150
	v_ashrrev_i32_e32 v145, 31, v144
	v_lshl_or_b32 v146, s41, 8, v152
	v_lshlrev_b64 v[144:145], 13, v[144:145]
	v_lshl_add_u64 v[144:145], s[54:55], 0, v[144:145]
	v_ashrrev_i32_e32 v147, 31, v146
	v_lshl_add_u64 v[144:145], v[146:147], 1, v[144:145]
	global_load_dwordx4 v[156:159], v[144:145], off
	global_load_dwordx4 v[160:163], v[144:145], off offset:256
	v_add_co_u32_e32 v172, vcc, s34, v144
	s_mov_b32 s41, s4
	s_nop 0
	v_addc_co_u32_e32 v173, vcc, 0, v145, vcc
	global_load_dwordx4 v[164:167], v[172:173], off
	global_load_dwordx4 v[168:171], v[172:173], off offset:256
	v_add_co_u32_e32 v146, vcc, s35, v144
	s_mov_b32 s12, s6
	s_nop 0
	v_addc_co_u32_e32 v147, vcc, 0, v145, vcc
	v_add_co_u32_e32 v148, vcc, s36, v144
	s_mov_b64 s[16:17], s[10:11]
	s_nop 0
	v_addc_co_u32_e32 v149, vcc, 0, v145, vcc
	s_mov_b64 s[14:15], s[8:9]
	s_waitcnt vmcnt(0)
	v_lshlrev_b32_e32 v174, 16, v156
	v_and_b32_e32 v156, 0xffff0000, v156
	v_lshlrev_b32_e32 v175, 16, v157
	v_and_b32_e32 v157, 0xffff0000, v157
	v_lshlrev_b32_e32 v178, 16, v158
	v_and_b32_e32 v158, 0xffff0000, v158
	v_lshlrev_b32_e32 v179, 16, v159
	v_and_b32_e32 v159, 0xffff0000, v159
	v_lshlrev_b32_e32 v182, 16, v162
	v_and_b32_e32 v162, 0xffff0000, v162
	v_lshlrev_b32_e32 v183, 16, v163
	v_and_b32_e32 v163, 0xffff0000, v163
	v_lshlrev_b32_e32 v180, 16, v160
	v_and_b32_e32 v160, 0xffff0000, v160
	v_lshlrev_b32_e32 v181, 16, v161
	v_and_b32_e32 v161, 0xffff0000, v161
	v_mul_f32_e32 v124, v124, v174
	v_mul_f32_e32 v125, v125, v156
	v_mul_f32_e32 v126, v126, v175
	v_mul_f32_e32 v127, v127, v157
	v_mul_f32_e32 v120, v120, v178
	v_mul_f32_e32 v121, v121, v158
	v_mul_f32_e32 v122, v122, v179
	v_mul_f32_e32 v123, v123, v159
	v_mul_f32_e32 v156, v112, v182
	v_mul_f32_e32 v157, v113, v162
	v_mul_f32_e32 v158, v114, v183
	v_mul_f32_e32 v159, v115, v163
	v_cvt_pk_bf16_f32 v112, v124, v125
	v_cvt_pk_bf16_f32 v113, v126, v127
	v_cvt_pk_bf16_f32 v114, v120, v121
	v_cvt_pk_bf16_f32 v115, v122, v123
	v_mul_f32_e32 v116, v116, v180
	v_mul_f32_e32 v117, v117, v160
	v_mul_f32_e32 v118, v118, v181
	v_mul_f32_e32 v119, v119, v161
	global_store_dwordx4 v[144:145], v[112:115], off
	v_lshlrev_b32_e32 v120, 16, v164
	v_and_b32_e32 v121, 0xffff0000, v164
	v_cvt_pk_bf16_f32 v112, v116, v117
	v_cvt_pk_bf16_f32 v113, v118, v119
	v_cvt_pk_bf16_f32 v114, v156, v157
	v_cvt_pk_bf16_f32 v115, v158, v159
	global_store_dwordx4 v[144:145], v[112:115], off offset:256
	v_lshlrev_b32_e32 v122, 16, v165
	v_and_b32_e32 v123, 0xffff0000, v165
	v_lshlrev_b32_e32 v124, 16, v166
	v_and_b32_e32 v125, 0xffff0000, v166
	v_lshlrev_b32_e32 v126, 16, v167
	v_and_b32_e32 v127, 0xffff0000, v167
	v_lshlrev_b32_e32 v160, 16, v170
	v_and_b32_e32 v161, 0xffff0000, v170
	v_lshlrev_b32_e32 v162, 16, v171
	v_and_b32_e32 v163, 0xffff0000, v171
	global_load_dwordx4 v[112:115], v[146:147], off offset:256
	global_load_dwordx4 v[116:119], v[146:147], off
	v_lshlrev_b32_e32 v156, 16, v168
	v_and_b32_e32 v157, 0xffff0000, v168
	v_lshlrev_b32_e32 v158, 16, v169
	v_and_b32_e32 v159, 0xffff0000, v169
	v_mul_f32_e32 v108, v108, v120
	v_mul_f32_e32 v109, v109, v121
	v_mul_f32_e32 v110, v110, v122
	v_mul_f32_e32 v111, v111, v123
	v_mul_f32_e32 v104, v104, v124
	v_mul_f32_e32 v105, v105, v125
	v_mul_f32_e32 v106, v106, v126
	v_mul_f32_e32 v107, v107, v127
	v_mul_f32_e32 v120, v96, v160
	v_mul_f32_e32 v121, v97, v161
	v_mul_f32_e32 v122, v98, v162
	v_mul_f32_e32 v123, v99, v163
	v_cvt_pk_bf16_f32 v96, v108, v109
	v_cvt_pk_bf16_f32 v97, v110, v111
	v_cvt_pk_bf16_f32 v98, v104, v105
	v_cvt_pk_bf16_f32 v99, v106, v107
	v_mul_f32_e32 v100, v100, v156
	v_mul_f32_e32 v101, v101, v157
	v_mul_f32_e32 v102, v102, v158
	v_mul_f32_e32 v103, v103, v159
	global_store_dwordx4 v[172:173], v[96:99], off
	v_add_co_u32_e32 v104, vcc, s37, v144
	s_nop 0
	v_cvt_pk_bf16_f32 v96, v100, v101
	v_cvt_pk_bf16_f32 v97, v102, v103
	v_cvt_pk_bf16_f32 v98, v120, v121
	v_cvt_pk_bf16_f32 v99, v122, v123
	global_store_dwordx4 v[172:173], v[96:99], off offset:256
	global_load_dwordx4 v[96:99], v[148:149], off
	global_load_dwordx4 v[100:103], v[148:149], off offset:256
	v_addc_co_u32_e32 v105, vcc, 0, v145, vcc
	v_add_co_u32_e32 v106, vcc, s38, v144
	s_waitcnt vmcnt(0)
; __device__ __forceinline__ unsigned cvt_pk_bf16(float lo, float hi) { unsigned r; asm volatile("v_cvt_pk_bf16_f32 %0, %1, %2" : "=v"(r) : "v"(lo), "v"(hi)); return r; }
; __device__ __forceinline__ float bf_lo(unsigned w) { return __uint_as_float(w << 16); }
; __device__ __forceinline__ float bf_hi(unsigned w) { return __uint_as_float(w & 0xffff0000u); }
;     __device__ __forceinline__ void operator()(const f32x4 (&acc)[2][2][4][2], const Unit& u, int wr, int wc, int fr, int fq) const {
;     ...
;         for (int g = 0; g < 8; ++g) {
;             const int ai = g >> 2, m = g & 3;
;             bf16_t* rowp = base + (size_t)(ai * HALF + m * 16) * NGATE;
;             if (g < 7) { const bf16_t* nrow = base + (size_t)(((g + 1) >> 2) * HALF + ((g + 1) & 3) * 16) * NGATE;
; #pragma unroll
;                 for (int bj = 0; bj < 2; ++bj) { na[bj] = *(const u32x4*)(nrow + bj * HALF); if (STEP == 1) nb[bj] = *(const u32x4*)(nrow + bj * HALF + DM); } }
; #pragma unroll
;             for (int bj = 0; bj < 2; ++bj) {
;                 const f32x4 a0 = acc[ai][bj][m][0], a1 = acc[ai][bj][m][1];
;                 float v[8];
;                 if (STEP == 0) {
;                     v[0] = bf_lo(ga[bj].x) * a0[0]; v[1] = bf_hi(ga[bj].x) * a0[1]; v[2] = bf_lo(ga[bj].y) * a0[2]; v[3] = bf_hi(ga[bj].y) * a0[3];
;                     v[4] = bf_lo(ga[bj].z) * a1[0]; v[5] = bf_hi(ga[bj].z) * a1[1]; v[6] = bf_lo(ga[bj].w) * a1[2]; v[7] = bf_hi(ga[bj].w) * a1[3];
;                 } else {
;                     v[0] = bf_lo(ga[bj].x) + bf_lo(gb[bj].x) * a0[0]; v[1] = bf_hi(ga[bj].x) + bf_hi(gb[bj].x) * a0[1]; v[2] = bf_lo(ga[bj].y) + bf_lo(gb[bj].y) * a0[2]; v[3] = bf_hi(ga[bj].y) + bf_hi(gb[bj].y) * a0[3];
;                     v[4] = bf_lo(ga[bj].z) + bf_lo(gb[bj].z) * a1[0]; v[5] = bf_hi(ga[bj].z) + bf_hi(gb[bj].z) * a1[1]; v[6] = bf_lo(ga[bj].w) + bf_lo(gb[bj].w) * a1[2]; v[7] = bf_hi(ga[bj].w) + bf_hi(gb[bj].w) * a1[3];
;                 }
;                 u32x4 w; w.x = cvt_pk_bf16(v[0], v[1]); w.y = cvt_pk_bf16(v[2], v[3]); w.z = cvt_pk_bf16(v[4], v[5]); w.w = cvt_pk_bf16(v[6], v[7]);
;                 *(u32x4*)(rowp + bj * HALF) = w;
;             }
;             asm volatile("" ::: "memory");
; #pragma unroll
;             for (int bj = 0; bj < 2; ++bj) { ga[bj] = na[bj]; if (STEP == 1) gb[bj] = nb[bj]; }
;         }
	v_lshlrev_b32_e32 v122, 16, v114
	v_lshlrev_b32_e32 v108, 16, v116
	v_and_b32_e32 v109, 0xffff0000, v116
	v_lshlrev_b32_e32 v110, 16, v117
	v_and_b32_e32 v111, 0xffff0000, v117
	v_lshlrev_b32_e32 v116, 16, v118
	v_and_b32_e32 v117, 0xffff0000, v118
	v_lshlrev_b32_e32 v118, 16, v119
	v_and_b32_e32 v119, 0xffff0000, v119
	v_and_b32_e32 v114, 0xffff0000, v114
	v_lshlrev_b32_e32 v123, 16, v115
	v_and_b32_e32 v115, 0xffff0000, v115
	v_lshlrev_b32_e32 v120, 16, v112
	v_and_b32_e32 v112, 0xffff0000, v112
	v_lshlrev_b32_e32 v121, 16, v113
	v_and_b32_e32 v113, 0xffff0000, v113
	v_mul_f32_e32 v92, v92, v108
	v_mul_f32_e32 v93, v93, v109
	v_mul_f32_e32 v94, v94, v110
	v_mul_f32_e32 v95, v95, v111
	v_mul_f32_e32 v88, v88, v116
	v_mul_f32_e32 v89, v89, v117
	v_mul_f32_e32 v90, v90, v118
	v_mul_f32_e32 v91, v91, v119
	v_mul_f32_e32 v108, v80, v122
	v_mul_f32_e32 v109, v81, v114
	v_mul_f32_e32 v110, v82, v123
	v_mul_f32_e32 v111, v83, v115
	v_cvt_pk_bf16_f32 v80, v92, v93
	v_cvt_pk_bf16_f32 v81, v94, v95
	v_cvt_pk_bf16_f32 v82, v88, v89
	v_cvt_pk_bf16_f32 v83, v90, v91
	v_mul_f32_e32 v84, v84, v120
	v_mul_f32_e32 v85, v85, v112
	v_mul_f32_e32 v86, v86, v121
	v_mul_f32_e32 v87, v87, v113
	global_store_dwordx4 v[146:147], v[80:83], off
	v_lshlrev_b32_e32 v88, 16, v96
	v_and_b32_e32 v89, 0xffff0000, v96
	v_cvt_pk_bf16_f32 v80, v84, v85
	v_cvt_pk_bf16_f32 v81, v86, v87
	v_cvt_pk_bf16_f32 v82, v108, v109
	v_cvt_pk_bf16_f32 v83, v110, v111
	global_store_dwordx4 v[146:147], v[80:83], off offset:256
	v_lshlrev_b32_e32 v90, 16, v97
	v_and_b32_e32 v91, 0xffff0000, v97
	v_lshlrev_b32_e32 v92, 16, v98
	v_and_b32_e32 v93, 0xffff0000, v98
	v_lshlrev_b32_e32 v94, 16, v99
	v_and_b32_e32 v95, 0xffff0000, v99
	v_lshlrev_b32_e32 v96, 16, v100
	v_and_b32_e32 v97, 0xffff0000, v100
	v_lshlrev_b32_e32 v98, 16, v101
	v_and_b32_e32 v99, 0xffff0000, v101
	v_lshlrev_b32_e32 v100, 16, v102
	v_and_b32_e32 v101, 0xffff0000, v102
	v_lshlrev_b32_e32 v102, 16, v103
	v_and_b32_e32 v103, 0xffff0000, v103
	global_load_dwordx4 v[80:83], v[104:105], off offset:256
	global_load_dwordx4 v[84:87], v[104:105], off
	v_mul_f32_e32 v76, v76, v88
	v_mul_f32_e32 v77, v77, v89
	v_mul_f32_e32 v78, v78, v90
	v_mul_f32_e32 v79, v79, v91
	v_mul_f32_e32 v72, v72, v92
	v_mul_f32_e32 v73, v73, v93
	v_mul_f32_e32 v74, v74, v94
	v_mul_f32_e32 v75, v75, v95
	v_mul_f32_e32 v88, v64, v100
	v_mul_f32_e32 v89, v65, v101
	v_mul_f32_e32 v90, v66, v102
	v_mul_f32_e32 v91, v67, v103
	v_cvt_pk_bf16_f32 v64, v76, v77
	v_cvt_pk_bf16_f32 v65, v78, v79
	v_cvt_pk_bf16_f32 v66, v72, v73
	v_cvt_pk_bf16_f32 v67, v74, v75
	v_mul_f32_e32 v68, v68, v96
	v_mul_f32_e32 v69, v69, v97
	v_mul_f32_e32 v70, v70, v98
	v_mul_f32_e32 v71, v71, v99
	global_store_dwordx4 v[148:149], v[64:67], off
	v_addc_co_u32_e32 v107, vcc, 0, v145, vcc
	s_nop 0
	v_cvt_pk_bf16_f32 v64, v68, v69
	v_cvt_pk_bf16_f32 v65, v70, v71
	v_cvt_pk_bf16_f32 v66, v88, v89
	v_cvt_pk_bf16_f32 v67, v90, v91
	global_store_dwordx4 v[148:149], v[64:67], off offset:256
	global_load_dwordx4 v[64:67], v[106:107], off
	global_load_dwordx4 v[68:71], v[106:107], off offset:256
	v_add_co_u32_e32 v72, vcc, s39, v144
	s_waitcnt vmcnt(0)
	v_lshlrev_b32_e32 v88, 16, v82
	v_lshlrev_b32_e32 v78, 16, v86
	v_lshlrev_b32_e32 v74, 16, v84
	v_and_b32_e32 v75, 0xffff0000, v84
	v_lshlrev_b32_e32 v76, 16, v85
	v_and_b32_e32 v77, 0xffff0000, v85
	v_and_b32_e32 v79, 0xffff0000, v86
	v_and_b32_e32 v82, 0xffff0000, v82
	v_lshlrev_b32_e32 v89, 16, v83
	v_mul_f32_e32 v56, v56, v78
	v_mul_f32_e32 v60, v60, v74
	v_mul_f32_e32 v61, v61, v75
	v_mul_f32_e32 v62, v62, v76
	v_mul_f32_e32 v63, v63, v77
	v_mul_f32_e32 v57, v57, v79
	v_mul_f32_e32 v74, v44, v88
	v_mul_f32_e32 v75, v45, v82
	v_mul_f32_e32 v76, v46, v89
	v_cvt_pk_bf16_f32 v44, v60, v61
	v_cvt_pk_bf16_f32 v45, v62, v63
	v_cvt_pk_bf16_f32 v46, v56, v57
	v_lshlrev_b32_e32 v84, 16, v87
	v_and_b32_e32 v85, 0xffff0000, v87
	v_and_b32_e32 v83, 0xffff0000, v83
	v_lshlrev_b32_e32 v86, 16, v80
	v_and_b32_e32 v80, 0xffff0000, v80
	v_lshlrev_b32_e32 v87, 16, v81
	v_and_b32_e32 v81, 0xffff0000, v81
	v_mul_f32_e32 v58, v58, v84
	v_mul_f32_e32 v59, v59, v85
	v_and_b32_e32 v56, 0xffff0000, v64
	v_mul_f32_e32 v49, v49, v56
	v_lshlrev_b32_e32 v56, 16, v65
	v_mul_f32_e32 v50, v50, v56
	v_and_b32_e32 v56, 0xffff0000, v65
	v_mul_f32_e32 v51, v51, v56
	v_lshlrev_b32_e32 v56, 16, v66
	v_mul_f32_e32 v77, v47, v83
	v_cvt_pk_bf16_f32 v47, v58, v59
	v_mul_f32_e32 v56, v40, v56
	v_and_b32_e32 v40, 0xffff0000, v66
	v_mul_f32_e32 v52, v52, v86
	v_mul_f32_e32 v53, v53, v80
	v_mul_f32_e32 v54, v54, v87
	v_mul_f32_e32 v55, v55, v81
	global_store_dwordx4 v[104:105], v[44:47], off
	v_mul_f32_e32 v57, v41, v40
	v_lshlrev_b32_e32 v40, 16, v67
	v_cvt_pk_bf16_f32 v44, v52, v53
	v_cvt_pk_bf16_f32 v45, v54, v55
	v_cvt_pk_bf16_f32 v46, v74, v75
	v_cvt_pk_bf16_f32 v47, v76, v77
	global_store_dwordx4 v[104:105], v[44:47], off offset:256
	v_addc_co_u32_e32 v73, vcc, 0, v145, vcc
	s_nop 0
	v_lshlrev_b32_e32 v44, 16, v64
	v_mul_f32_e32 v58, v42, v40
	v_and_b32_e32 v40, 0xffff0000, v67
	v_mul_f32_e32 v48, v48, v44
	global_load_dwordx4 v[44:47], v[72:73], off offset:256
	global_load_dwordx4 v[52:55], v[72:73], off
	v_mul_f32_e32 v43, v43, v40
	v_cvt_pk_bf16_f32 v40, v48, v49
	v_cvt_pk_bf16_f32 v41, v50, v51
	v_cvt_pk_bf16_f32 v42, v56, v57
	v_cvt_pk_bf16_f32 v43, v58, v43
	global_store_dwordx4 v[106:107], v[40:43], off
	s_waitcnt vmcnt(0)
; __device__ __forceinline__ float bf_lo(unsigned w) { return __uint_as_float(w << 16); }
; #define PG8_WAIT_V(n) asm volatile("s_waitcnt vmcnt(" #n ")" ::: "memory")
;     __device__ __forceinline__ void operator()(const f32x4 (&acc)[2][2][4][2], const Unit& u, int wr, int wc, int fr, int fq) const {
;     ...
;         for (int g = 0; g < 8; ++g) {
;             const int ai = g >> 2, m = g & 3;
;             bf16_t* rowp = base + (size_t)(ai * HALF + m * 16) * NGATE;
;             if (g < 7) { const bf16_t* nrow = base + (size_t)(((g + 1) >> 2) * HALF + ((g + 1) & 3) * 16) * NGATE;
; #pragma unroll
;                 for (int bj = 0; bj < 2; ++bj) { na[bj] = *(const u32x4*)(nrow + bj * HALF); if (STEP == 1) nb[bj] = *(const u32x4*)(nrow + bj * HALF + DM); } }
; #pragma unroll
;             for (int bj = 0; bj < 2; ++bj) {
;                 const f32x4 a0 = acc[ai][bj][m][0], a1 = acc[ai][bj][m][1];
;                 float v[8];
;                 if (STEP == 0) {
;                     v[0] = bf_lo(ga[bj].x) * a0[0]; v[1] = bf_hi(ga[bj].x) * a0[1]; v[2] = bf_lo(ga[bj].y) * a0[2]; v[3] = bf_hi(ga[bj].y) * a0[3];
;                     v[4] = bf_lo(ga[bj].z) * a1[0]; v[5] = bf_hi(ga[bj].z) * a1[1]; v[6] = bf_lo(ga[bj].w) * a1[2]; v[7] = bf_hi(ga[bj].w) * a1[3];
;                 } else {
;                     v[0] = bf_lo(ga[bj].x) + bf_lo(gb[bj].x) * a0[0]; v[1] = bf_hi(ga[bj].x) + bf_hi(gb[bj].x) * a0[1]; v[2] = bf_lo(ga[bj].y) + bf_lo(gb[bj].y) * a0[2]; v[3] = bf_hi(ga[bj].y) + bf_hi(gb[bj].y) * a0[3];
;                     v[4] = bf_lo(ga[bj].z) + bf_lo(gb[bj].z) * a1[0]; v[5] = bf_hi(ga[bj].z) + bf_hi(gb[bj].z) * a1[1]; v[6] = bf_lo(ga[bj].w) + bf_lo(gb[bj].w) * a1[2]; v[7] = bf_hi(ga[bj].w) + bf_hi(gb[bj].w) * a1[3];
;                 }
;                 u32x4 w; w.x = cvt_pk_bf16(v[0], v[1]); w.y = cvt_pk_bf16(v[2], v[3]); w.z = cvt_pk_bf16(v[4], v[5]); w.w = cvt_pk_bf16(v[6], v[7]);
;                 *(u32x4*)(rowp + bj * HALF) = w;
;             }
;             asm volatile("" ::: "memory");
; #pragma unroll
;             for (int bj = 0; bj < 2; ++bj) { ga[bj] = na[bj]; if (STEP == 1) gb[bj] = nb[bj]; }
;         }
; template <class Epi, class Sched>
; __device__ __forceinline__ void gemm_phase(LAS unsigned char* lds, const Gemm g, const Sched& S, const Epi& E) {
;     ...
;         if (!has_next) break;
;     ...
;     PG8_WAIT_V(0);
;     if (wr == 0) PG8_BAR;
;     PG8_BAR;
	v_lshlrev_b32_e32 v56, 16, v46
	v_lshlrev_b32_e32 v40, 16, v68
	v_mul_f32_e32 v36, v36, v40
	v_and_b32_e32 v40, 0xffff0000, v68
	v_mul_f32_e32 v37, v37, v40
	v_lshlrev_b32_e32 v40, 16, v69
	v_mul_f32_e32 v38, v38, v40
	v_and_b32_e32 v40, 0xffff0000, v69
	v_mul_f32_e32 v39, v39, v40
	v_lshlrev_b32_e32 v40, 16, v70
	v_mul_f32_e32 v40, v32, v40
	v_and_b32_e32 v32, 0xffff0000, v70
	v_mul_f32_e32 v41, v33, v32
	v_lshlrev_b32_e32 v32, 16, v71
	v_mul_f32_e32 v42, v34, v32
	v_and_b32_e32 v32, 0xffff0000, v71
	v_mul_f32_e32 v35, v35, v32
	v_cvt_pk_bf16_f32 v32, v36, v37
	v_cvt_pk_bf16_f32 v33, v38, v39
	v_cvt_pk_bf16_f32 v34, v40, v41
	v_cvt_pk_bf16_f32 v35, v42, v35
	global_store_dwordx4 v[106:107], v[32:35], off offset:256
	v_add_co_u32_e32 v40, vcc, s40, v144
	v_lshlrev_b32_e32 v42, 16, v52
	s_nop 0
	v_addc_co_u32_e32 v41, vcc, 0, v145, vcc
	global_load_dwordx4 v[32:35], v[40:41], off
	global_load_dwordx4 v[36:39], v[40:41], off offset:256
	v_and_b32_e32 v43, 0xffff0000, v52
	v_lshlrev_b32_e32 v48, 16, v53
	v_and_b32_e32 v49, 0xffff0000, v53
	v_lshlrev_b32_e32 v50, 16, v54
	v_and_b32_e32 v51, 0xffff0000, v54
	v_lshlrev_b32_e32 v52, 16, v55
	v_and_b32_e32 v53, 0xffff0000, v55
	v_lshlrev_b32_e32 v54, 16, v44
	v_and_b32_e32 v44, 0xffff0000, v44
	v_lshlrev_b32_e32 v55, 16, v45
	v_and_b32_e32 v45, 0xffff0000, v45
	v_and_b32_e32 v46, 0xffff0000, v46
	v_lshlrev_b32_e32 v57, 16, v47
	v_and_b32_e32 v47, 0xffff0000, v47
	v_mul_f32_e32 v28, v28, v42
	v_mul_f32_e32 v29, v29, v43
	v_mul_f32_e32 v42, v12, v56
	v_cvt_pk_bf16_f32 v12, v28, v29
	v_mul_f32_e32 v30, v30, v48
	v_mul_f32_e32 v31, v31, v49
	v_mul_f32_e32 v24, v24, v50
	v_mul_f32_e32 v25, v25, v51
	v_mul_f32_e32 v26, v26, v52
	v_mul_f32_e32 v27, v27, v53
	v_mul_f32_e32 v20, v20, v54
	v_mul_f32_e32 v21, v21, v44
	v_mul_f32_e32 v23, v23, v45
	v_mul_f32_e32 v43, v13, v46
	v_mul_f32_e32 v44, v14, v57
	v_mul_f32_e32 v45, v15, v47
	v_cvt_pk_bf16_f32 v13, v30, v31
	v_cvt_pk_bf16_f32 v14, v24, v25
	v_cvt_pk_bf16_f32 v15, v26, v27
	global_store_dwordx4 v[72:73], v[12:15], off
	v_mul_f32_e32 v22, v22, v55
	s_and_b64 vcc, exec, s[0:1]
	v_cvt_pk_bf16_f32 v12, v20, v21
	v_cvt_pk_bf16_f32 v13, v22, v23
	v_cvt_pk_bf16_f32 v14, v42, v43
	v_cvt_pk_bf16_f32 v15, v44, v45
	global_store_dwordx4 v[72:73], v[12:15], off offset:256
	s_waitcnt vmcnt(0)
	s_nop 0
	v_lshlrev_b32_e32 v12, 16, v32
	v_mul_f32_e32 v12, v16, v12
	v_lshlrev_b32_e32 v16, 16, v34
	v_and_b32_e32 v13, 0xffff0000, v32
	v_mul_f32_e32 v16, v8, v16
	v_and_b32_e32 v8, 0xffff0000, v34
	v_mul_f32_e32 v13, v17, v13
	v_lshlrev_b32_e32 v14, 16, v33
	v_mul_f32_e32 v17, v9, v8
	v_lshlrev_b32_e32 v8, 16, v35
	v_mul_f32_e32 v14, v18, v14
	v_mul_f32_e32 v18, v10, v8
	v_and_b32_e32 v8, 0xffff0000, v35
	v_and_b32_e32 v15, 0xffff0000, v33
	v_mul_f32_e32 v11, v11, v8
	v_cvt_pk_bf16_f32 v8, v12, v13
	v_mul_f32_e32 v15, v19, v15
	v_cvt_pk_bf16_f32 v9, v14, v15
	v_cvt_pk_bf16_f32 v10, v16, v17
	v_cvt_pk_bf16_f32 v11, v18, v11
	global_store_dwordx4 v[40:41], v[8:11], off
	s_nop 1
	v_lshlrev_b32_e32 v8, 16, v36
	v_mul_f32_e32 v4, v4, v8
	v_and_b32_e32 v8, 0xffff0000, v36
	v_mul_f32_e32 v5, v5, v8
	v_lshlrev_b32_e32 v8, 16, v37
	v_mul_f32_e32 v6, v6, v8
	v_and_b32_e32 v8, 0xffff0000, v37
	v_mul_f32_e32 v7, v7, v8
	v_lshlrev_b32_e32 v8, 16, v38
	v_mul_f32_e32 v8, v0, v8
	v_and_b32_e32 v0, 0xffff0000, v38
	v_mul_f32_e32 v9, v1, v0
	v_lshlrev_b32_e32 v0, 16, v39
	v_mul_f32_e32 v10, v2, v0
	v_and_b32_e32 v0, 0xffff0000, v39
	v_mul_f32_e32 v3, v3, v0
	v_cvt_pk_bf16_f32 v0, v4, v5
	v_cvt_pk_bf16_f32 v1, v6, v7
	v_cvt_pk_bf16_f32 v2, v8, v9
	v_cvt_pk_bf16_f32 v3, v10, v3
	global_store_dwordx4 v[40:41], v[0:3], off offset:256
	s_cbranch_vccz .LBB0_699
	s_waitcnt vmcnt(0)
	s_cmpk_gt_u32 s20, 0xff
	s_cbranch_scc1 .LBB0_706
	s_barrier

; #define PG8_STAGE(bufoff, gbase, voff) do { _Pragma("unroll") for (int _i = 0; _i < 2; ++_i) \
;         __builtin_amdgcn_global_load_lds((const unsigned*)((const char*)(gbase) + (voff)[_i]), (LAS unsigned*)(lds + (bufoff) + ldsw + _i * 8192), 16, 0, 0); } while (0)
; #define PG8_LDA(dst, b, h) do { _Pragma("unroll") for (int m = 0; m < 4; ++m) _Pragma("unroll") for (int k = 0; k < 2; ++k) dst[m][k] = *(const LAS bf16x8*)(lds + PG8_SA(b, h) + aoff + m * 2048 + k * 1024); } while (0)
; #define PG8_LDB(dst, b, h) do { _Pragma("unroll") for (int n = 0; n < 2; ++n) _Pragma("unroll") for (int k = 0; k < 2; ++k) dst[n][k] = *(const LAS bf16x8*)(lds + PG8_SB(b, h) + boff + n * 2048 + k * 1024); } while (0)
; #define PG8_MMA(ai, bj, At, Bt) do { __builtin_amdgcn_s_setprio(1); _Pragma("unroll") for (int m = 0; m < 4; ++m) _Pragma("unroll") for (int n = 0; n < 2; ++n) _Pragma("unroll") for (int k = 0; k < 2; ++k) \
;         acc[ai][bj][m][n] = MmaOp<Epi::I8>::run(Bt[n][k], At[m][k], acc[ai][bj][m][n]); __builtin_amdgcn_s_setprio(0); } while (0)
; #define PG8_WAIT_L(n) asm volatile("s_waitcnt lgkmcnt(" #n ")" ::: "memory")
; #define PG8_BAR __builtin_amdgcn_s_barrier()
; #define PG8_SCHED __builtin_amdgcn_sched_barrier(0)
; template <class Epi, class Sched>
; __device__ __forceinline__ void gemm_phase(LAS unsigned char* lds, const Gemm g, const Sched& S, const Epi& E) {
;     ...
;             PG8_LDB(B0, 0, 0); PG8_SCHED; PG8_LDA(At, 0, 0); PG8_STAGE(PG8_SA(1, 1), a1 + hstepA, voffA);
;             PG8_WAIT_L(8); PG8_BAR; PG8_WAIT_L(0); PG8_MMA(0, 0, At, B0); PG8_BAR; PG8_SCHED;
;             PG8_LDB(B1, 0, 1); PG8_STAGE(PG8_SB(0, 0), b2, voffB);
;             PG8_BAR; PG8_WAIT_L(0); PG8_MMA(0, 1, At, B1); PG8_BAR;
;             PG8_LDA(At, 0, 1); PG8_STAGE(PG8_SA(0, 0), a2, voffA);
;             PG8_BAR; PG8_WAIT_L(0); PG8_MMA(1, 0, At, B0); PG8_BAR; PG8_SCHED;
.LBB0_715:
	ds_read_b128 v[152:155], v149
	ds_read_b128 v[156:159], v149 offset:1024
	ds_read_b128 v[160:163], v149 offset:2048
	ds_read_b128 v[164:167], v149 offset:3072
	s_add_u32 s18, s16, 0xfff80080
	s_addc_u32 s19, s17, -1
	s_cmp_eq_u32 s57, 12
	s_cselect_b32 s21, s9, s19
	s_cselect_b32 s20, s53, s18
	s_cselect_b32 s19, s7, s56
	s_cselect_b32 s18, s54, s55
	v_lshl_add_u64 v[144:145], s[16:17], 0, v[136:137]
	s_add_i32 m0, s15, 0xc000
	ds_read_b128 v[168:171], v150
	ds_read_b128 v[172:175], v150 offset:1024
	ds_read_b128 v[178:181], v150 offset:2048
	ds_read_b128 v[182:185], v150 offset:3072
	ds_read_b128 v[186:189], v150 offset:4096
	ds_read_b128 v[190:193], v150 offset:5120
	ds_read_b128 v[194:197], v150 offset:6144
	ds_read_b128 v[198:201], v150 offset:7168
	global_load_lds_dwordx4 v[144:145], off
	v_lshl_add_u64 v[144:145], s[16:17], 0, v[138:139]
	s_add_i32 m0, s15, 0xe000
	s_nop 0
	global_load_lds_dwordx4 v[144:145], off
	s_waitcnt lgkmcnt(8)
	s_barrier
	s_waitcnt lgkmcnt(0)
	s_setprio 1
	v_mfma_f32_16x16x32_bf16 v[124:127], v[152:155], v[168:171], v[124:127]
	v_mfma_f32_16x16x32_bf16 v[120:123], v[160:163], v[168:171], v[120:123]
	v_mfma_f32_16x16x32_bf16 v[108:111], v[152:155], v[178:181], v[108:111]
	v_mfma_f32_16x16x32_bf16 v[104:107], v[160:163], v[178:181], v[104:107]
	v_mfma_f32_16x16x32_bf16 v[92:95], v[152:155], v[186:189], v[92:95]
	v_mfma_f32_16x16x32_bf16 v[88:91], v[160:163], v[186:189], v[88:91]
	v_mfma_f32_16x16x32_bf16 v[76:79], v[152:155], v[194:197], v[76:79]
	v_mfma_f32_16x16x32_bf16 v[72:75], v[160:163], v[194:197], v[72:75]
	v_mfma_f32_16x16x32_bf16 v[124:127], v[156:159], v[172:175], v[124:127]
	v_mfma_f32_16x16x32_bf16 v[120:123], v[164:167], v[172:175], v[120:123]
	v_mfma_f32_16x16x32_bf16 v[108:111], v[156:159], v[182:185], v[108:111]
	v_mfma_f32_16x16x32_bf16 v[104:107], v[164:167], v[182:185], v[104:107]
	v_mfma_f32_16x16x32_bf16 v[92:95], v[156:159], v[190:193], v[92:95]
	v_mfma_f32_16x16x32_bf16 v[88:91], v[164:167], v[190:193], v[88:91]
	v_mfma_f32_16x16x32_bf16 v[76:79], v[156:159], v[198:201], v[76:79]
	v_mfma_f32_16x16x32_bf16 v[72:75], v[164:167], v[198:201], v[72:75]
	s_setprio 0
	s_barrier
	s_add_i32 s58, s36, s25
	v_lshl_add_u64 v[144:145], s[18:19], 0, v[132:133]
	s_mov_b32 m0, s58
	ds_read_b128 v[202:205], v151
	ds_read_b128 v[206:209], v151 offset:1024
	ds_read_b128 v[210:213], v151 offset:2048
	ds_read_b128 v[214:217], v151 offset:3072
	global_load_lds_dwordx4 v[144:145], off
	v_lshl_add_u64 v[218:219], s[18:19], 0, v[128:129]
	s_add_i32 m0, s58, 0x2000
	s_nop 0
	global_load_lds_dwordx4 v[218:219], off
	s_barrier
	s_waitcnt lgkmcnt(0)
	s_setprio 1
	v_mfma_f32_16x16x32_bf16 v[116:119], v[202:205], v[168:171], v[116:119]
	v_mfma_f32_16x16x32_bf16 v[112:115], v[210:213], v[168:171], v[112:115]
	v_mfma_f32_16x16x32_bf16 v[100:103], v[202:205], v[178:181], v[100:103]
	v_mfma_f32_16x16x32_bf16 v[96:99], v[210:213], v[178:181], v[96:99]
	v_mfma_f32_16x16x32_bf16 v[84:87], v[202:205], v[186:189], v[84:87]
	v_mfma_f32_16x16x32_bf16 v[80:83], v[210:213], v[186:189], v[80:83]
	v_mfma_f32_16x16x32_bf16 v[68:71], v[202:205], v[194:197], v[68:71]
	v_mfma_f32_16x16x32_bf16 v[64:67], v[210:213], v[194:197], v[64:67]
	v_mfma_f32_16x16x32_bf16 v[116:119], v[206:209], v[172:175], v[116:119]
	v_mfma_f32_16x16x32_bf16 v[112:115], v[214:217], v[172:175], v[112:115]
	v_mfma_f32_16x16x32_bf16 v[100:103], v[206:209], v[182:185], v[100:103]
	v_mfma_f32_16x16x32_bf16 v[96:99], v[214:217], v[182:185], v[96:99]
	v_mfma_f32_16x16x32_bf16 v[84:87], v[206:209], v[190:193], v[84:87]
	v_mfma_f32_16x16x32_bf16 v[80:83], v[214:217], v[190:193], v[80:83]
	v_mfma_f32_16x16x32_bf16 v[68:71], v[206:209], v[198:201], v[68:71]
	v_mfma_f32_16x16x32_bf16 v[64:67], v[214:217], v[198:201], v[64:67]
	s_setprio 0
	s_mov_b32 m0, s15
	v_lshl_add_u64 v[220:221], s[20:21], 0, v[134:135]
	s_barrier
	ds_read_b128 v[168:171], v150 offset:16384
	ds_read_b128 v[172:175], v150 offset:17408
	ds_read_b128 v[178:181], v150 offset:18432
	ds_read_b128 v[182:185], v150 offset:19456
	ds_read_b128 v[186:189], v150 offset:20480
	ds_read_b128 v[190:193], v150 offset:21504
	ds_read_b128 v[194:197], v150 offset:22528
	ds_read_b128 v[198:201], v150 offset:23552
	global_load_lds_dwordx4 v[220:221], off
	v_lshl_add_u64 v[222:223], s[20:21], 0, v[130:131]
	s_mov_b32 m0, s28
	s_nop 0
	global_load_lds_dwordx4 v[222:223], off
	s_barrier
	s_waitcnt lgkmcnt(0)
	s_setprio 1
	v_mfma_f32_16x16x32_bf16 v[60:63], v[152:155], v[168:171], v[60:63]
	v_mfma_f32_16x16x32_bf16 v[56:59], v[160:163], v[168:171], v[56:59]
	v_mfma_f32_16x16x32_bf16 v[44:47], v[152:155], v[178:181], v[44:47]
	v_mfma_f32_16x16x32_bf16 v[40:43], v[160:163], v[178:181], v[40:43]
	v_mfma_f32_16x16x32_bf16 v[28:31], v[152:155], v[186:189], v[28:31]
	v_mfma_f32_16x16x32_bf16 v[24:27], v[160:163], v[186:189], v[24:27]
	v_mfma_f32_16x16x32_bf16 v[16:19], v[152:155], v[194:197], v[16:19]
	v_mfma_f32_16x16x32_bf16 v[8:11], v[160:163], v[194:197], v[8:11]
	v_mfma_f32_16x16x32_bf16 v[60:63], v[156:159], v[172:175], v[60:63]
	v_mfma_f32_16x16x32_bf16 v[56:59], v[164:167], v[172:175], v[56:59]
	v_mfma_f32_16x16x32_bf16 v[44:47], v[156:159], v[182:185], v[44:47]
	v_mfma_f32_16x16x32_bf16 v[40:43], v[164:167], v[182:185], v[40:43]
	v_mfma_f32_16x16x32_bf16 v[28:31], v[156:159], v[190:193], v[28:31]
	v_mfma_f32_16x16x32_bf16 v[24:27], v[164:167], v[190:193], v[24:27]
	v_mfma_f32_16x16x32_bf16 v[16:19], v[156:159], v[198:201], v[16:19]
	v_mfma_f32_16x16x32_bf16 v[8:11], v[164:167], v[198:201], v[8:11]
	s_setprio 0
	s_barrier
; #define PG8_STAGE(bufoff, gbase, voff) do { _Pragma("unroll") for (int _i = 0; _i < 2; ++_i) \
;         __builtin_amdgcn_global_load_lds((const unsigned*)((const char*)(gbase) + (voff)[_i]), (LAS unsigned*)(lds + (bufoff) + ldsw + _i * 8192), 16, 0, 0); } while (0)
; #define PG8_LDA(dst, b, h) do { _Pragma("unroll") for (int m = 0; m < 4; ++m) _Pragma("unroll") for (int k = 0; k < 2; ++k) dst[m][k] = *(const LAS bf16x8*)(lds + PG8_SA(b, h) + aoff + m * 2048 + k * 1024); } while (0)
; #define PG8_LDB(dst, b, h) do { _Pragma("unroll") for (int n = 0; n < 2; ++n) _Pragma("unroll") for (int k = 0; k < 2; ++k) dst[n][k] = *(const LAS bf16x8*)(lds + PG8_SB(b, h) + boff + n * 2048 + k * 1024); } while (0)
; #define PG8_MMA(ai, bj, At, Bt) do { __builtin_amdgcn_s_setprio(1); _Pragma("unroll") for (int m = 0; m < 4; ++m) _Pragma("unroll") for (int n = 0; n < 2; ++n) _Pragma("unroll") for (int k = 0; k < 2; ++k) \
;         acc[ai][bj][m][n] = MmaOp<Epi::I8>::run(Bt[n][k], At[m][k], acc[ai][bj][m][n]); __builtin_amdgcn_s_setprio(0); } while (0)
; #define PG8_WAIT_V(n) asm volatile("s_waitcnt vmcnt(" #n ")" ::: "memory")
; #define PG8_WAIT_L(n) asm volatile("s_waitcnt lgkmcnt(" #n ")" ::: "memory")
; #define PG8_BAR __builtin_amdgcn_s_barrier()
; #define PG8_SCHED __builtin_amdgcn_sched_barrier(0)
; template <class Epi, class Sched>
; __device__ __forceinline__ void gemm_phase(LAS unsigned char* lds, const Gemm g, const Sched& S, const Epi& E) {
;     ...
;             PG8_STAGE(PG8_SB(0, 1), b2 + hstepB, voffB);
;             PG8_WAIT_V(6); PG8_BAR; PG8_MMA(1, 1, At, B1); PG8_BAR;
;             PG8_LDB(B0, 1, 0); PG8_SCHED; PG8_LDA(At, 1, 0); PG8_STAGE(PG8_SA(0, 1), a2 + hstepA, voffA);
;             PG8_WAIT_L(8); PG8_BAR; PG8_WAIT_L(0); PG8_MMA(0, 0, At, B0); PG8_BAR; PG8_SCHED;
;             PG8_LDB(B1, 1, 1); PG8_STAGE(PG8_SB(1, 0), b3, voffB);
;             PG8_BAR; PG8_WAIT_L(0); PG8_MMA(0, 1, At, B1); PG8_BAR;
;             PG8_LDA(At, 1, 1); PG8_STAGE(PG8_SA(1, 0), a3, voffA);
	s_add_u32 s58, s18, 0x40000
	s_addc_u32 s59, s19, 0
	s_add_i32 s60, s37, s25
	v_lshl_add_u64 v[152:153], s[58:59], 0, v[132:133]
	s_mov_b32 m0, s60
	s_nop 0
	global_load_lds_dwordx4 v[152:153], off
	v_lshl_add_u64 v[152:153], s[58:59], 0, v[128:129]
	s_add_i32 m0, s60, 0x2000
	s_nop 0
	global_load_lds_dwordx4 v[152:153], off
	s_waitcnt vmcnt(6)
	s_barrier
	s_setprio 1
	v_mfma_f32_16x16x32_bf16 v[52:55], v[202:205], v[168:171], v[52:55]
	v_mfma_f32_16x16x32_bf16 v[48:51], v[210:213], v[168:171], v[48:51]
	v_mfma_f32_16x16x32_bf16 v[36:39], v[202:205], v[178:181], v[36:39]
	v_mfma_f32_16x16x32_bf16 v[32:35], v[210:213], v[178:181], v[32:35]
	v_mfma_f32_16x16x32_bf16 v[20:23], v[202:205], v[186:189], v[20:23]
	v_mfma_f32_16x16x32_bf16 v[12:15], v[210:213], v[186:189], v[12:15]
	v_mfma_f32_16x16x32_bf16 v[4:7], v[202:205], v[194:197], v[4:7]
	v_mfma_f32_16x16x32_bf16 v[0:3], v[210:213], v[194:197], v[0:3]
	v_mfma_f32_16x16x32_bf16 v[52:55], v[206:209], v[172:175], v[52:55]
	v_mfma_f32_16x16x32_bf16 v[48:51], v[214:217], v[172:175], v[48:51]
	v_mfma_f32_16x16x32_bf16 v[36:39], v[206:209], v[182:185], v[36:39]
	v_mfma_f32_16x16x32_bf16 v[32:35], v[214:217], v[182:185], v[32:35]
	v_mfma_f32_16x16x32_bf16 v[20:23], v[206:209], v[190:193], v[20:23]
	v_mfma_f32_16x16x32_bf16 v[12:15], v[214:217], v[190:193], v[12:15]
	v_mfma_f32_16x16x32_bf16 v[4:7], v[206:209], v[198:201], v[4:7]
	v_mfma_f32_16x16x32_bf16 v[0:3], v[214:217], v[198:201], v[0:3]
	s_setprio 0
	s_add_i32 s58, 0, 0x18000
	v_add_u32_e32 v164, s58, v147
	s_barrier
	ds_read_b128 v[152:155], v164
	ds_read_b128 v[156:159], v164 offset:1024
	ds_read_b128 v[160:163], v164 offset:2048
	ds_read_b128 v[164:167], v164 offset:3072
	s_add_u32 s20, s20, 0x80000
	s_addc_u32 s21, s21, 0
	s_mov_b32 m0, s29
	v_lshl_add_u64 v[202:203], s[20:21], 0, v[134:135]
	ds_read_b128 v[168:171], v150 offset:32768
	ds_read_b128 v[172:175], v150 offset:33792
	ds_read_b128 v[178:181], v150 offset:34816
	ds_read_b128 v[182:185], v150 offset:35840
	ds_read_b128 v[186:189], v150 offset:36864
	ds_read_b128 v[190:193], v150 offset:37888
	ds_read_b128 v[194:197], v150 offset:38912
	ds_read_b128 v[198:201], v150 offset:39936
	global_load_lds_dwordx4 v[202:203], off
	v_lshl_add_u64 v[202:203], s[20:21], 0, v[130:131]
	s_mov_b32 m0, s30
	s_nop 0
	global_load_lds_dwordx4 v[202:203], off
	s_waitcnt lgkmcnt(8)
	s_barrier
	s_waitcnt lgkmcnt(0)
	s_setprio 1
	v_mfma_f32_16x16x32_bf16 v[124:127], v[152:155], v[168:171], v[124:127]
	v_mfma_f32_16x16x32_bf16 v[120:123], v[160:163], v[168:171], v[120:123]
	v_mfma_f32_16x16x32_bf16 v[108:111], v[152:155], v[178:181], v[108:111]
	v_mfma_f32_16x16x32_bf16 v[104:107], v[160:163], v[178:181], v[104:107]
	v_mfma_f32_16x16x32_bf16 v[92:95], v[152:155], v[186:189], v[92:95]
	v_mfma_f32_16x16x32_bf16 v[88:91], v[160:163], v[186:189], v[88:91]
	v_mfma_f32_16x16x32_bf16 v[76:79], v[152:155], v[194:197], v[76:79]
	v_mfma_f32_16x16x32_bf16 v[72:75], v[160:163], v[194:197], v[72:75]
	v_mfma_f32_16x16x32_bf16 v[124:127], v[156:159], v[172:175], v[124:127]
	v_mfma_f32_16x16x32_bf16 v[120:123], v[164:167], v[172:175], v[120:123]
	v_mfma_f32_16x16x32_bf16 v[108:111], v[156:159], v[182:185], v[108:111]
	v_mfma_f32_16x16x32_bf16 v[104:107], v[164:167], v[182:185], v[104:107]
	v_mfma_f32_16x16x32_bf16 v[92:95], v[156:159], v[190:193], v[92:95]
	v_mfma_f32_16x16x32_bf16 v[88:91], v[164:167], v[190:193], v[88:91]
	v_mfma_f32_16x16x32_bf16 v[76:79], v[156:159], v[198:201], v[76:79]
	v_mfma_f32_16x16x32_bf16 v[72:75], v[164:167], v[198:201], v[72:75]
	s_setprio 0
	s_barrier
	s_add_i32 s20, 0, 0x1c000
	s_add_i32 s21, s58, s25
	v_add_u32_e32 v214, s20, v147
	v_lshl_add_u64 v[144:145], v[144:145], 0, s[4:5]
	s_mov_b32 m0, s21
	ds_read_b128 v[202:205], v214
	ds_read_b128 v[206:209], v214 offset:1024
	ds_read_b128 v[210:213], v214 offset:2048
	ds_read_b128 v[214:217], v214 offset:3072
	global_load_lds_dwordx4 v[144:145], off
	v_lshl_add_u64 v[144:145], v[218:219], 0, s[4:5]
	s_add_i32 m0, s21, 0x2000
	s_nop 0
	global_load_lds_dwordx4 v[144:145], off
	s_barrier
	s_waitcnt lgkmcnt(0)
	s_setprio 1
	v_mfma_f32_16x16x32_bf16 v[116:119], v[202:205], v[168:171], v[116:119]
	v_mfma_f32_16x16x32_bf16 v[112:115], v[210:213], v[168:171], v[112:115]
	v_mfma_f32_16x16x32_bf16 v[100:103], v[202:205], v[178:181], v[100:103]
	v_mfma_f32_16x16x32_bf16 v[96:99], v[210:213], v[178:181], v[96:99]
	v_mfma_f32_16x16x32_bf16 v[84:87], v[202:205], v[186:189], v[84:87]
	v_mfma_f32_16x16x32_bf16 v[80:83], v[210:213], v[186:189], v[80:83]
	v_mfma_f32_16x16x32_bf16 v[68:71], v[202:205], v[194:197], v[68:71]
	v_mfma_f32_16x16x32_bf16 v[64:67], v[210:213], v[194:197], v[64:67]
	v_mfma_f32_16x16x32_bf16 v[116:119], v[206:209], v[172:175], v[116:119]
	v_mfma_f32_16x16x32_bf16 v[112:115], v[214:217], v[172:175], v[112:115]
	v_mfma_f32_16x16x32_bf16 v[100:103], v[206:209], v[182:185], v[100:103]
	v_mfma_f32_16x16x32_bf16 v[96:99], v[214:217], v[182:185], v[96:99]
	v_mfma_f32_16x16x32_bf16 v[84:87], v[206:209], v[190:193], v[84:87]
	v_mfma_f32_16x16x32_bf16 v[80:83], v[214:217], v[190:193], v[80:83]
	v_mfma_f32_16x16x32_bf16 v[68:71], v[206:209], v[198:201], v[68:71]
	v_mfma_f32_16x16x32_bf16 v[64:67], v[214:217], v[198:201], v[64:67]
	s_setprio 0
	s_mov_b32 m0, s33
	v_lshl_add_u64 v[144:145], v[220:221], 0, s[4:5]
	s_barrier
	ds_read_b128 v[168:171], v150 offset:49152
	ds_read_b128 v[172:175], v150 offset:50176
	ds_read_b128 v[178:181], v150 offset:51200
	ds_read_b128 v[182:185], v150 offset:52224
	ds_read_b128 v[186:189], v150 offset:53248
	ds_read_b128 v[190:193], v150 offset:54272
	ds_read_b128 v[194:197], v150 offset:55296
	ds_read_b128 v[198:201], v150 offset:56320
	global_load_lds_dwordx4 v[144:145], off
	v_lshl_add_u64 v[144:145], v[222:223], 0, s[4:5]
	s_mov_b32 m0, s34
	s_nop 0
	global_load_lds_dwordx4 v[144:145], off
	s_barrier
; #define PG8_BAR __builtin_amdgcn_s_barrier()
;     __device__ __forceinline__ void operator()(const f32x4 (&acc)[2][2][4][2], const Unit& u, int wr, int wc, int fr, int fq) const {
;         const int row0 = u.pm * BM + wr * 64 + fr, col0 = u.pn * BM + wc * 32 + 8 * fq;
;         bf16_t* base = G + (size_t)row0 * NGATE + col0;
;         u32x4 ga[2], gb[2], na[2], nb[2];
; #pragma unroll
;         for (int bj = 0; bj < 2; ++bj) { ga[bj] = *(const u32x4*)(base + bj * HALF); if (STEP == 1) gb[bj] = *(const u32x4*)(base + bj * HALF + DM); }
; #pragma unroll
;         for (int g = 0; g < 8; ++g) {
;             const int ai = g >> 2, m = g & 3;
;             bf16_t* rowp = base + (size_t)(ai * HALF + m * 16) * NGATE;
;             if (g < 7) { const bf16_t* nrow = base + (size_t)(((g + 1) >> 2) * HALF + ((g + 1) & 3) * 16) * NGATE;
; #pragma unroll
;                 for (int bj = 0; bj < 2; ++bj) { na[bj] = *(const u32x4*)(nrow + bj * HALF); if (STEP == 1) nb[bj] = *(const u32x4*)(nrow + bj * HALF + DM); } }
; #pragma unroll
;             for (int bj = 0; bj < 2; ++bj) {
;                 const f32x4 a0 = acc[ai][bj][m][0], a1 = acc[ai][bj][m][1];
;                 float v[8];
;                 if (STEP == 0) {
;                     v[0] = bf_lo(ga[bj].x) * a0[0]; v[1] = bf_hi(ga[bj].x) * a0[1]; v[2] = bf_lo(ga[bj].y) * a0[2]; v[3] = bf_hi(ga[bj].y) * a0[3];
;                     v[4] = bf_lo(ga[bj].z) * a1[0]; v[5] = bf_hi(ga[bj].z) * a1[1]; v[6] = bf_lo(ga[bj].w) * a1[2]; v[7] = bf_hi(ga[bj].w) * a1[3];
;                 } else {
;                     v[0] = bf_lo(ga[bj].x) + bf_lo(gb[bj].x) * a0[0]; v[1] = bf_hi(ga[bj].x) + bf_hi(gb[bj].x) * a0[1]; v[2] = bf_lo(ga[bj].y) + bf_lo(gb[bj].y) * a0[2]; v[3] = bf_hi(ga[bj].y) + bf_hi(gb[bj].y) * a0[3];
;                     v[4] = bf_lo(ga[bj].z) + bf_lo(gb[bj].z) * a1[0]; v[5] = bf_hi(ga[bj].z) + bf_hi(gb[bj].z) * a1[1]; v[6] = bf_lo(ga[bj].w) + bf_lo(gb[bj].w) * a1[2]; v[7] = bf_hi(ga[bj].w) + bf_hi(gb[bj].w) * a1[3];
;                 }
; template <class Epi, class Sched>
; __device__ __forceinline__ void gemm_phase(LAS unsigned char* lds, const Gemm g, const Sched& S, const Epi& E) {
;     ...
;             PG8_BAR; PG8_WAIT_L(0); PG8_MMA(1, 0, At, B0); PG8_BAR; PG8_SCHED;
;             PG8_STAGE(PG8_SB(1, 1), b3 + hstepB, voffB);
;             PG8_WAIT_V(6); PG8_BAR; PG8_MMA(1, 1, At, B1); PG8_BAR;
	s_waitcnt lgkmcnt(0)
	s_setprio 1
	v_mfma_f32_16x16x32_bf16 v[60:63], v[152:155], v[168:171], v[60:63]
	v_mfma_f32_16x16x32_bf16 v[56:59], v[160:163], v[168:171], v[56:59]
	v_mfma_f32_16x16x32_bf16 v[44:47], v[152:155], v[178:181], v[44:47]
	v_mfma_f32_16x16x32_bf16 v[40:43], v[160:163], v[178:181], v[40:43]
	v_mfma_f32_16x16x32_bf16 v[28:31], v[152:155], v[186:189], v[28:31]
	v_mfma_f32_16x16x32_bf16 v[24:27], v[160:163], v[186:189], v[24:27]
	v_mfma_f32_16x16x32_bf16 v[16:19], v[152:155], v[194:197], v[16:19]
	v_mfma_f32_16x16x32_bf16 v[8:11], v[160:163], v[194:197], v[8:11]
	v_mfma_f32_16x16x32_bf16 v[60:63], v[156:159], v[172:175], v[60:63]
	v_mfma_f32_16x16x32_bf16 v[56:59], v[164:167], v[172:175], v[56:59]
	v_mfma_f32_16x16x32_bf16 v[44:47], v[156:159], v[182:185], v[44:47]
	v_mfma_f32_16x16x32_bf16 v[40:43], v[164:167], v[182:185], v[40:43]
	v_mfma_f32_16x16x32_bf16 v[28:31], v[156:159], v[190:193], v[28:31]
	v_mfma_f32_16x16x32_bf16 v[24:27], v[164:167], v[190:193], v[24:27]
	v_mfma_f32_16x16x32_bf16 v[16:19], v[156:159], v[198:201], v[16:19]
	v_mfma_f32_16x16x32_bf16 v[8:11], v[164:167], v[198:201], v[8:11]
	s_setprio 0
	s_barrier
	s_add_u32 s18, s18, 0x40080
	s_addc_u32 s19, s19, 0
	s_add_i32 s20, s20, s25
	v_lshl_add_u64 v[144:145], s[18:19], 0, v[132:133]
	s_mov_b32 m0, s20
	s_nop 0
	global_load_lds_dwordx4 v[144:145], off
	v_lshl_add_u64 v[144:145], s[18:19], 0, v[128:129]
	s_add_i32 m0, s20, 0x2000
	s_nop 0
	global_load_lds_dwordx4 v[144:145], off
	s_waitcnt vmcnt(6)
	s_barrier
	s_setprio 1
	v_mfma_f32_16x16x32_bf16 v[52:55], v[202:205], v[168:171], v[52:55]
	v_mfma_f32_16x16x32_bf16 v[48:51], v[210:213], v[168:171], v[48:51]
	v_mfma_f32_16x16x32_bf16 v[36:39], v[202:205], v[178:181], v[36:39]
	v_mfma_f32_16x16x32_bf16 v[32:35], v[210:213], v[178:181], v[32:35]
	v_mfma_f32_16x16x32_bf16 v[20:23], v[202:205], v[186:189], v[20:23]
	v_mfma_f32_16x16x32_bf16 v[12:15], v[210:213], v[186:189], v[12:15]
	v_mfma_f32_16x16x32_bf16 v[4:7], v[202:205], v[194:197], v[4:7]
	v_mfma_f32_16x16x32_bf16 v[0:3], v[210:213], v[194:197], v[0:3]
	v_mfma_f32_16x16x32_bf16 v[52:55], v[206:209], v[172:175], v[52:55]
	v_mfma_f32_16x16x32_bf16 v[48:51], v[214:217], v[172:175], v[48:51]
	v_mfma_f32_16x16x32_bf16 v[36:39], v[206:209], v[182:185], v[36:39]
	v_mfma_f32_16x16x32_bf16 v[32:35], v[214:217], v[182:185], v[32:35]
	v_mfma_f32_16x16x32_bf16 v[20:23], v[206:209], v[190:193], v[20:23]
	v_mfma_f32_16x16x32_bf16 v[12:15], v[214:217], v[190:193], v[12:15]
	v_mfma_f32_16x16x32_bf16 v[4:7], v[206:209], v[198:201], v[4:7]
	v_mfma_f32_16x16x32_bf16 v[0:3], v[214:217], v[198:201], v[0:3]
	s_setprio 0
	s_add_i32 s57, s57, 2
	s_add_u32 s16, s16, 0x100
	s_addc_u32 s17, s17, 0
	s_add_u32 s55, s55, 0x100
	s_addc_u32 s56, s56, 0
	s_cmp_gt_u32 s57, 13
	s_barrier
	s_cbranch_scc0 .LBB0_715
	v_lshl_add_u32 v144, s14, 8, v146
	v_ashrrev_i32_e32 v145, 31, v144
	v_readlane_b32 s54, v239, 46
	v_lshl_or_b32 v152, s52, 8, v148
	v_lshlrev_b64 v[144:145], 13, v[144:145]
	v_readlane_b32 s55, v239, 47
	v_ashrrev_i32_e32 v153, 31, v152
	s_mov_b32 s52, s6
	v_lshl_add_u64 v[144:145], s[54:55], 0, v[144:145]
	v_lshl_add_u64 v[144:145], v[152:153], 1, v[144:145]
	v_add_co_u32_e32 v164, vcc, 0x1000, v144
	global_load_dwordx4 v[152:155], v[144:145], off
	global_load_dwordx4 v[156:159], v[144:145], off offset:256
	v_addc_co_u32_e32 v165, vcc, 0, v145, vcc
	global_load_dwordx4 v[160:163], v[164:165], off
	s_nop 0
	global_load_dwordx4 v[164:167], v[164:165], off offset:256
	v_add_co_u32_e32 v178, vcc, s38, v144
	s_mov_b32 s14, s8
	s_nop 0
	v_addc_co_u32_e32 v179, vcc, 0, v145, vcc
	v_add_co_u32_e32 v186, vcc, s39, v144
	s_mov_b64 s[18:19], s[12:13]
	s_nop 0
	v_addc_co_u32_e32 v187, vcc, 0, v145, vcc
	global_load_dwordx4 v[168:171], v[186:187], off
	global_load_dwordx4 v[172:175], v[178:179], off
	s_nop 0
	global_load_dwordx4 v[178:181], v[178:179], off offset:256
	s_nop 0
	global_load_dwordx4 v[182:185], v[186:187], off offset:256
	v_add_co_u32_e32 v188, vcc, s40, v144
	s_mov_b64 s[16:17], s[10:11]
	s_nop 0
	v_addc_co_u32_e32 v189, vcc, 0, v145, vcc
	s_waitcnt vmcnt(0)
	v_lshlrev_b32_e32 v190, 16, v152
	v_and_b32_e32 v152, 0xffff0000, v152
	v_lshlrev_b32_e32 v191, 16, v153
	v_and_b32_e32 v153, 0xffff0000, v153
	v_lshlrev_b32_e32 v192, 16, v154
	v_and_b32_e32 v154, 0xffff0000, v154
	v_lshlrev_b32_e32 v193, 16, v155
	v_and_b32_e32 v155, 0xffff0000, v155
	v_lshlrev_b32_e32 v196, 16, v158
	v_and_b32_e32 v158, 0xffff0000, v158
	v_lshlrev_b32_e32 v197, 16, v159
	v_and_b32_e32 v159, 0xffff0000, v159
	v_lshlrev_b32_e32 v198, 16, v160
	v_and_b32_e32 v160, 0xffff0000, v160
	v_lshlrev_b32_e32 v199, 16, v161
	v_and_b32_e32 v161, 0xffff0000, v161
	v_lshlrev_b32_e32 v200, 16, v162
	v_and_b32_e32 v162, 0xffff0000, v162
	v_lshlrev_b32_e32 v201, 16, v163
	v_and_b32_e32 v163, 0xffff0000, v163
	v_lshlrev_b32_e32 v204, 16, v166
	v_and_b32_e32 v166, 0xffff0000, v166
	v_lshlrev_b32_e32 v205, 16, v167
	v_and_b32_e32 v167, 0xffff0000, v167
	v_lshlrev_b32_e32 v194, 16, v156
	v_and_b32_e32 v156, 0xffff0000, v156
	v_lshlrev_b32_e32 v195, 16, v157
	v_and_b32_e32 v157, 0xffff0000, v157
	v_lshlrev_b32_e32 v202, 16, v164
	v_and_b32_e32 v164, 0xffff0000, v164
	v_lshlrev_b32_e32 v203, 16, v165
	v_and_b32_e32 v165, 0xffff0000, v165
	v_fmac_f32_e32 v190, v124, v198
	v_fmac_f32_e32 v152, v125, v160
	v_fmac_f32_e32 v191, v126, v199
	v_fmac_f32_e32 v153, v127, v161
	v_fmac_f32_e32 v192, v120, v200
	v_fmac_f32_e32 v154, v121, v162
	v_fmac_f32_e32 v193, v122, v201
	v_fmac_f32_e32 v155, v123, v163
	v_fmac_f32_e32 v196, v112, v204
	v_fmac_f32_e32 v158, v113, v166
	v_fmac_f32_e32 v197, v114, v205
	v_fmac_f32_e32 v159, v115, v167
; __device__ __forceinline__ unsigned cvt_pk_bf16(float lo, float hi) { unsigned r; asm volatile("v_cvt_pk_bf16_f32 %0, %1, %2" : "=v"(r) : "v"(lo), "v"(hi)); return r; }
; __device__ __forceinline__ float bf_lo(unsigned w) { return __uint_as_float(w << 16); }
; __device__ __forceinline__ float bf_hi(unsigned w) { return __uint_as_float(w & 0xffff0000u); }
;     __device__ __forceinline__ void operator()(const f32x4 (&acc)[2][2][4][2], const Unit& u, int wr, int wc, int fr, int fq) const {
;     ...
;         for (int g = 0; g < 8; ++g) {
;             const int ai = g >> 2, m = g & 3;
;             bf16_t* rowp = base + (size_t)(ai * HALF + m * 16) * NGATE;
;             if (g < 7) { const bf16_t* nrow = base + (size_t)(((g + 1) >> 2) * HALF + ((g + 1) & 3) * 16) * NGATE;
; #pragma unroll
;                 for (int bj = 0; bj < 2; ++bj) { na[bj] = *(const u32x4*)(nrow + bj * HALF); if (STEP == 1) nb[bj] = *(const u32x4*)(nrow + bj * HALF + DM); } }
; #pragma unroll
;             for (int bj = 0; bj < 2; ++bj) {
;                 const f32x4 a0 = acc[ai][bj][m][0], a1 = acc[ai][bj][m][1];
;                 float v[8];
;                 if (STEP == 0) {
;                     v[0] = bf_lo(ga[bj].x) * a0[0]; v[1] = bf_hi(ga[bj].x) * a0[1]; v[2] = bf_lo(ga[bj].y) * a0[2]; v[3] = bf_hi(ga[bj].y) * a0[3];
;                     v[4] = bf_lo(ga[bj].z) * a1[0]; v[5] = bf_hi(ga[bj].z) * a1[1]; v[6] = bf_lo(ga[bj].w) * a1[2]; v[7] = bf_hi(ga[bj].w) * a1[3];
;                 } else {
;                     v[0] = bf_lo(ga[bj].x) + bf_lo(gb[bj].x) * a0[0]; v[1] = bf_hi(ga[bj].x) + bf_hi(gb[bj].x) * a0[1]; v[2] = bf_lo(ga[bj].y) + bf_lo(gb[bj].y) * a0[2]; v[3] = bf_hi(ga[bj].y) + bf_hi(gb[bj].y) * a0[3];
;                     v[4] = bf_lo(ga[bj].z) + bf_lo(gb[bj].z) * a1[0]; v[5] = bf_hi(ga[bj].z) + bf_hi(gb[bj].z) * a1[1]; v[6] = bf_lo(ga[bj].w) + bf_lo(gb[bj].w) * a1[2]; v[7] = bf_hi(ga[bj].w) + bf_hi(gb[bj].w) * a1[3];
;                 }
;                 u32x4 w; w.x = cvt_pk_bf16(v[0], v[1]); w.y = cvt_pk_bf16(v[2], v[3]); w.z = cvt_pk_bf16(v[4], v[5]); w.w = cvt_pk_bf16(v[6], v[7]);
;                 *(u32x4*)(rowp + bj * HALF) = w;
;             }
;             asm volatile("" ::: "memory");
; #pragma unroll
;             for (int bj = 0; bj < 2; ++bj) { ga[bj] = na[bj]; if (STEP == 1) gb[bj] = nb[bj]; }
;         }
	v_cvt_pk_bf16_f32 v112, v190, v152
	v_cvt_pk_bf16_f32 v113, v191, v153
	v_cvt_pk_bf16_f32 v114, v192, v154
	v_cvt_pk_bf16_f32 v115, v193, v155
	v_fmac_f32_e32 v194, v116, v202
	v_fmac_f32_e32 v156, v117, v164
	v_fmac_f32_e32 v195, v118, v203
	v_fmac_f32_e32 v157, v119, v165
	global_store_dwordx4 v[144:145], v[112:115], off sc0 sc1
	v_add_co_u32_e32 v152, vcc, s41, v144
	s_nop 0
	v_cvt_pk_bf16_f32 v112, v194, v156
	v_cvt_pk_bf16_f32 v113, v195, v157
	v_cvt_pk_bf16_f32 v114, v196, v158
	v_cvt_pk_bf16_f32 v115, v197, v159
	global_store_dwordx4 v[144:145], v[112:115], off offset:256 sc0 sc1
	v_lshlrev_b32_e32 v154, 16, v168
	v_lshlrev_b32_e32 v155, 16, v172
	v_addc_co_u32_e32 v153, vcc, 0, v145, vcc
	v_fmac_f32_e32 v154, v108, v155
	v_and_b32_e32 v108, 0xffff0000, v168
	v_and_b32_e32 v155, 0xffff0000, v172
	global_load_dwordx4 v[112:115], v[152:153], off
	global_load_dwordx4 v[116:119], v[188:189], off
	global_load_dwordx4 v[120:123], v[188:189], off offset:256
	global_load_dwordx4 v[124:127], v[152:153], off offset:256
	v_fmac_f32_e32 v108, v109, v155
	v_lshlrev_b32_e32 v109, 16, v169
	v_lshlrev_b32_e32 v155, 16, v173
	v_fmac_f32_e32 v109, v110, v155
	v_and_b32_e32 v110, 0xffff0000, v169
	v_and_b32_e32 v155, 0xffff0000, v173
	v_fmac_f32_e32 v110, v111, v155
	v_lshlrev_b32_e32 v111, 16, v170
	v_lshlrev_b32_e32 v155, 16, v174
	v_fmac_f32_e32 v111, v104, v155
	v_and_b32_e32 v155, 0xffff0000, v170
	v_and_b32_e32 v104, 0xffff0000, v174
	v_fmac_f32_e32 v155, v105, v104
	v_lshlrev_b32_e32 v156, 16, v171
	v_lshlrev_b32_e32 v104, 16, v175
	v_fmac_f32_e32 v156, v106, v104
	v_and_b32_e32 v157, 0xffff0000, v171
	v_and_b32_e32 v104, 0xffff0000, v175
	v_fmac_f32_e32 v157, v107, v104
	v_cvt_pk_bf16_f32 v104, v154, v108
	v_cvt_pk_bf16_f32 v105, v109, v110
	v_cvt_pk_bf16_f32 v106, v111, v155
	v_cvt_pk_bf16_f32 v107, v156, v157
	global_store_dwordx4 v[186:187], v[104:107], off sc0 sc1
	s_waitcnt vmcnt(0)
	v_lshlrev_b32_e32 v156, 16, v112
	v_lshlrev_b32_e32 v104, 16, v182
	v_lshlrev_b32_e32 v105, 16, v178
	v_fmac_f32_e32 v104, v100, v105
	v_and_b32_e32 v100, 0xffff0000, v182
	v_and_b32_e32 v105, 0xffff0000, v178
	v_fmac_f32_e32 v100, v101, v105
	v_lshlrev_b32_e32 v101, 16, v183
	v_lshlrev_b32_e32 v105, 16, v179
	v_fmac_f32_e32 v101, v102, v105
	v_and_b32_e32 v102, 0xffff0000, v183
	v_and_b32_e32 v105, 0xffff0000, v179
	v_fmac_f32_e32 v102, v103, v105
	v_lshlrev_b32_e32 v103, 16, v184
	v_lshlrev_b32_e32 v105, 16, v180
	v_fmac_f32_e32 v103, v96, v105
	v_and_b32_e32 v105, 0xffff0000, v184
	v_and_b32_e32 v96, 0xffff0000, v180
	v_fmac_f32_e32 v105, v97, v96
	v_lshlrev_b32_e32 v106, 16, v185
	v_lshlrev_b32_e32 v96, 16, v181
	v_fmac_f32_e32 v106, v98, v96
	v_and_b32_e32 v107, 0xffff0000, v185
	v_and_b32_e32 v96, 0xffff0000, v181
	v_fmac_f32_e32 v107, v99, v96
	v_cvt_pk_bf16_f32 v96, v104, v100
	v_add_co_u32_e32 v104, vcc, s42, v144
	v_cvt_pk_bf16_f32 v97, v101, v102
	v_cvt_pk_bf16_f32 v98, v103, v105
	v_cvt_pk_bf16_f32 v99, v106, v107
	global_store_dwordx4 v[186:187], v[96:99], off offset:256 sc0 sc1
	s_nop 0
	v_addc_co_u32_e32 v105, vcc, 0, v145, vcc
	v_add_co_u32_e32 v154, vcc, s43, v144
	v_lshlrev_b32_e32 v157, 16, v116
	s_nop 0
	v_addc_co_u32_e32 v155, vcc, 0, v145, vcc
	global_load_dwordx4 v[96:99], v[154:155], off
	global_load_dwordx4 v[100:103], v[104:105], off
	s_nop 0
	global_load_dwordx4 v[104:107], v[104:105], off offset:256
	s_nop 0
	global_load_dwordx4 v[108:111], v[154:155], off offset:256
	v_fmac_f32_e32 v156, v92, v157
	v_and_b32_e32 v92, 0xffff0000, v112
	v_and_b32_e32 v112, 0xffff0000, v116
	v_fmac_f32_e32 v92, v93, v112
	v_lshlrev_b32_e32 v93, 16, v113
	v_lshlrev_b32_e32 v112, 16, v117
	v_fmac_f32_e32 v93, v94, v112
	v_and_b32_e32 v94, 0xffff0000, v113
	v_and_b32_e32 v112, 0xffff0000, v117
	v_fmac_f32_e32 v94, v95, v112
	v_lshlrev_b32_e32 v95, 16, v114
	v_lshlrev_b32_e32 v112, 16, v118
	v_fmac_f32_e32 v95, v88, v112
	v_and_b32_e32 v112, 0xffff0000, v114
	v_and_b32_e32 v88, 0xffff0000, v118
	v_fmac_f32_e32 v112, v89, v88
	v_lshlrev_b32_e32 v113, 16, v115
	v_lshlrev_b32_e32 v88, 16, v119
	v_fmac_f32_e32 v113, v90, v88
	v_and_b32_e32 v114, 0xffff0000, v115
	v_and_b32_e32 v88, 0xffff0000, v119
	v_fmac_f32_e32 v114, v91, v88
	v_cvt_pk_bf16_f32 v88, v156, v92
	v_cvt_pk_bf16_f32 v89, v93, v94
	v_cvt_pk_bf16_f32 v90, v95, v112
	v_cvt_pk_bf16_f32 v91, v113, v114
	global_store_dwordx4 v[152:153], v[88:91], off sc0 sc1
	s_waitcnt vmcnt(0)
	v_lshlrev_b32_e32 v114, 16, v96
	v_lshlrev_b32_e32 v88, 16, v124
	v_lshlrev_b32_e32 v89, 16, v120
	v_fmac_f32_e32 v88, v84, v89
	v_and_b32_e32 v84, 0xffff0000, v124
	v_and_b32_e32 v89, 0xffff0000, v120
	v_fmac_f32_e32 v84, v85, v89
	v_lshlrev_b32_e32 v85, 16, v125
	v_lshlrev_b32_e32 v89, 16, v121
	v_fmac_f32_e32 v85, v86, v89
	v_and_b32_e32 v86, 0xffff0000, v125
	v_and_b32_e32 v89, 0xffff0000, v121
	v_fmac_f32_e32 v86, v87, v89
	v_lshlrev_b32_e32 v87, 16, v126
	v_lshlrev_b32_e32 v89, 16, v122
	v_fmac_f32_e32 v87, v80, v89
	v_and_b32_e32 v89, 0xffff0000, v126
	v_and_b32_e32 v80, 0xffff0000, v122
	v_fmac_f32_e32 v89, v81, v80
	v_lshlrev_b32_e32 v90, 16, v127
	v_lshlrev_b32_e32 v80, 16, v123
	v_fmac_f32_e32 v90, v82, v80
	v_and_b32_e32 v91, 0xffff0000, v127
	v_and_b32_e32 v80, 0xffff0000, v123
	v_fmac_f32_e32 v91, v83, v80
	v_cvt_pk_bf16_f32 v80, v88, v84
	v_add_co_u32_e32 v88, vcc, s44, v144
	v_cvt_pk_bf16_f32 v81, v85, v86
	v_cvt_pk_bf16_f32 v82, v87, v89
	v_cvt_pk_bf16_f32 v83, v90, v91
	global_store_dwordx4 v[152:153], v[80:83], off offset:256 sc0 sc1
	s_nop 0
	v_addc_co_u32_e32 v89, vcc, 0, v145, vcc
	v_add_co_u32_e32 v112, vcc, s45, v144
	v_lshlrev_b32_e32 v115, 16, v100
	s_nop 0
	v_addc_co_u32_e32 v113, vcc, 0, v145, vcc
	v_fmac_f32_e32 v114, v76, v115
	v_and_b32_e32 v76, 0xffff0000, v96
	v_and_b32_e32 v96, 0xffff0000, v100
	global_load_dwordx4 v[80:83], v[112:113], off
	global_load_dwordx4 v[84:87], v[88:89], off
	s_nop 0
	global_load_dwordx4 v[88:91], v[88:89], off offset:256
	s_nop 0
	global_load_dwordx4 v[92:95], v[112:113], off offset:256
	v_fmac_f32_e32 v76, v77, v96
	v_lshlrev_b32_e32 v77, 16, v97
	v_lshlrev_b32_e32 v96, 16, v101
	v_fmac_f32_e32 v77, v78, v96
	v_and_b32_e32 v78, 0xffff0000, v97
	v_and_b32_e32 v96, 0xffff0000, v101
	v_fmac_f32_e32 v78, v79, v96
	v_lshlrev_b32_e32 v79, 16, v98
	v_lshlrev_b32_e32 v96, 16, v102
	v_fmac_f32_e32 v79, v72, v96
	v_and_b32_e32 v96, 0xffff0000, v98
	v_and_b32_e32 v72, 0xffff0000, v102
	v_fmac_f32_e32 v96, v73, v72
	v_lshlrev_b32_e32 v97, 16, v99
	v_lshlrev_b32_e32 v72, 16, v103
	v_fmac_f32_e32 v97, v74, v72
	v_and_b32_e32 v98, 0xffff0000, v99
	v_and_b32_e32 v72, 0xffff0000, v103
	v_fmac_f32_e32 v98, v75, v72
	v_cvt_pk_bf16_f32 v72, v114, v76
	v_cvt_pk_bf16_f32 v73, v77, v78
	v_cvt_pk_bf16_f32 v74, v79, v96
	v_cvt_pk_bf16_f32 v75, v97, v98
	global_store_dwordx4 v[154:155], v[72:75], off sc0 sc1
	s_waitcnt vmcnt(0)
; __device__ __forceinline__ unsigned cvt_pk_bf16(float lo, float hi) { unsigned r; asm volatile("v_cvt_pk_bf16_f32 %0, %1, %2" : "=v"(r) : "v"(lo), "v"(hi)); return r; }
; __device__ __forceinline__ float bf_lo(unsigned w) { return __uint_as_float(w << 16); }
; __device__ __forceinline__ float bf_hi(unsigned w) { return __uint_as_float(w & 0xffff0000u); }
;     __device__ __forceinline__ void operator()(const f32x4 (&acc)[2][2][4][2], const Unit& u, int wr, int wc, int fr, int fq) const {
;     ...
;         for (int g = 0; g < 8; ++g) {
;             const int ai = g >> 2, m = g & 3;
;             bf16_t* rowp = base + (size_t)(ai * HALF + m * 16) * NGATE;
;             if (g < 7) { const bf16_t* nrow = base + (size_t)(((g + 1) >> 2) * HALF + ((g + 1) & 3) * 16) * NGATE;
; #pragma unroll
;                 for (int bj = 0; bj < 2; ++bj) { na[bj] = *(const u32x4*)(nrow + bj * HALF); if (STEP == 1) nb[bj] = *(const u32x4*)(nrow + bj * HALF + DM); } }
; #pragma unroll
;             for (int bj = 0; bj < 2; ++bj) {
;                 const f32x4 a0 = acc[ai][bj][m][0], a1 = acc[ai][bj][m][1];
;                 float v[8];
;                 if (STEP == 0) {
;                     v[0] = bf_lo(ga[bj].x) * a0[0]; v[1] = bf_hi(ga[bj].x) * a0[1]; v[2] = bf_lo(ga[bj].y) * a0[2]; v[3] = bf_hi(ga[bj].y) * a0[3];
;                     v[4] = bf_lo(ga[bj].z) * a1[0]; v[5] = bf_hi(ga[bj].z) * a1[1]; v[6] = bf_lo(ga[bj].w) * a1[2]; v[7] = bf_hi(ga[bj].w) * a1[3];
;                 } else {
;                     v[0] = bf_lo(ga[bj].x) + bf_lo(gb[bj].x) * a0[0]; v[1] = bf_hi(ga[bj].x) + bf_hi(gb[bj].x) * a0[1]; v[2] = bf_lo(ga[bj].y) + bf_lo(gb[bj].y) * a0[2]; v[3] = bf_hi(ga[bj].y) + bf_hi(gb[bj].y) * a0[3];
;                     v[4] = bf_lo(ga[bj].z) + bf_lo(gb[bj].z) * a1[0]; v[5] = bf_hi(ga[bj].z) + bf_hi(gb[bj].z) * a1[1]; v[6] = bf_lo(ga[bj].w) + bf_lo(gb[bj].w) * a1[2]; v[7] = bf_hi(ga[bj].w) + bf_hi(gb[bj].w) * a1[3];
;                 }
;                 u32x4 w; w.x = cvt_pk_bf16(v[0], v[1]); w.y = cvt_pk_bf16(v[2], v[3]); w.z = cvt_pk_bf16(v[4], v[5]); w.w = cvt_pk_bf16(v[6], v[7]);
;                 *(u32x4*)(rowp + bj * HALF) = w;
;             }
;             asm volatile("" ::: "memory");
; #pragma unroll
;             for (int bj = 0; bj < 2; ++bj) { ga[bj] = na[bj]; if (STEP == 1) gb[bj] = nb[bj]; }
;         }
	v_lshlrev_b32_e32 v98, 16, v80
	v_lshlrev_b32_e32 v72, 16, v108
	v_lshlrev_b32_e32 v73, 16, v104
	v_fmac_f32_e32 v72, v68, v73
	v_and_b32_e32 v68, 0xffff0000, v108
	v_and_b32_e32 v73, 0xffff0000, v104
	v_fmac_f32_e32 v68, v69, v73
	v_lshlrev_b32_e32 v69, 16, v109
	v_lshlrev_b32_e32 v73, 16, v105
	v_fmac_f32_e32 v69, v70, v73
	v_and_b32_e32 v70, 0xffff0000, v109
	v_and_b32_e32 v73, 0xffff0000, v105
	v_fmac_f32_e32 v70, v71, v73
	v_lshlrev_b32_e32 v71, 16, v110
	v_lshlrev_b32_e32 v73, 16, v106
	v_fmac_f32_e32 v71, v64, v73
	v_and_b32_e32 v73, 0xffff0000, v110
	v_and_b32_e32 v64, 0xffff0000, v106
	v_fmac_f32_e32 v73, v65, v64
	v_lshlrev_b32_e32 v74, 16, v111
	v_lshlrev_b32_e32 v64, 16, v107
	v_fmac_f32_e32 v74, v66, v64
	v_and_b32_e32 v75, 0xffff0000, v111
	v_and_b32_e32 v64, 0xffff0000, v107
	v_fmac_f32_e32 v75, v67, v64
	v_cvt_pk_bf16_f32 v64, v72, v68
	v_add_co_u32_e32 v72, vcc, s46, v144
	v_cvt_pk_bf16_f32 v65, v69, v70
	v_cvt_pk_bf16_f32 v66, v71, v73
	v_cvt_pk_bf16_f32 v67, v74, v75
	global_store_dwordx4 v[154:155], v[64:67], off offset:256 sc0 sc1
	s_nop 0
	v_addc_co_u32_e32 v73, vcc, 0, v145, vcc
	v_add_co_u32_e32 v96, vcc, s47, v144
	v_lshlrev_b32_e32 v99, 16, v84
	s_nop 0
	v_addc_co_u32_e32 v97, vcc, 0, v145, vcc
	global_load_dwordx4 v[64:67], v[96:97], off
	global_load_dwordx4 v[68:71], v[72:73], off
	s_nop 0
	global_load_dwordx4 v[72:75], v[72:73], off offset:256
	s_nop 0
	global_load_dwordx4 v[76:79], v[96:97], off offset:256
	v_fmac_f32_e32 v98, v60, v99
	v_and_b32_e32 v60, 0xffff0000, v80
	v_and_b32_e32 v80, 0xffff0000, v84
	v_fmac_f32_e32 v60, v61, v80
	v_lshlrev_b32_e32 v61, 16, v81
	v_lshlrev_b32_e32 v80, 16, v85
	v_fmac_f32_e32 v61, v62, v80
	v_and_b32_e32 v62, 0xffff0000, v81
	v_and_b32_e32 v80, 0xffff0000, v85
	v_fmac_f32_e32 v62, v63, v80
	v_lshlrev_b32_e32 v63, 16, v82
	v_lshlrev_b32_e32 v80, 16, v86
	v_fmac_f32_e32 v63, v56, v80
	v_and_b32_e32 v80, 0xffff0000, v82
	v_and_b32_e32 v56, 0xffff0000, v86
	v_fmac_f32_e32 v80, v57, v56
	v_lshlrev_b32_e32 v81, 16, v83
	v_lshlrev_b32_e32 v56, 16, v87
	v_fmac_f32_e32 v81, v58, v56
	v_and_b32_e32 v82, 0xffff0000, v83
	v_and_b32_e32 v56, 0xffff0000, v87
	v_fmac_f32_e32 v82, v59, v56
	v_cvt_pk_bf16_f32 v56, v98, v60
	v_cvt_pk_bf16_f32 v57, v61, v62
	v_cvt_pk_bf16_f32 v58, v63, v80
	v_cvt_pk_bf16_f32 v59, v81, v82
	global_store_dwordx4 v[112:113], v[56:59], off sc0 sc1
	s_waitcnt vmcnt(0)
	v_lshlrev_b32_e32 v82, 16, v64
	v_lshlrev_b32_e32 v56, 16, v92
	v_lshlrev_b32_e32 v57, 16, v88
	v_fmac_f32_e32 v56, v52, v57
	v_and_b32_e32 v52, 0xffff0000, v92
	v_and_b32_e32 v57, 0xffff0000, v88
	v_fmac_f32_e32 v52, v53, v57
	v_lshlrev_b32_e32 v53, 16, v93
	v_lshlrev_b32_e32 v57, 16, v89
	v_fmac_f32_e32 v53, v54, v57
	v_and_b32_e32 v54, 0xffff0000, v93
	v_and_b32_e32 v57, 0xffff0000, v89
	v_fmac_f32_e32 v54, v55, v57
	v_lshlrev_b32_e32 v55, 16, v94
	v_lshlrev_b32_e32 v57, 16, v90
	v_fmac_f32_e32 v55, v48, v57
	v_and_b32_e32 v57, 0xffff0000, v94
	v_and_b32_e32 v48, 0xffff0000, v90
	v_fmac_f32_e32 v57, v49, v48
	v_lshlrev_b32_e32 v58, 16, v95
	v_lshlrev_b32_e32 v48, 16, v91
	v_fmac_f32_e32 v58, v50, v48
	v_and_b32_e32 v59, 0xffff0000, v95
	v_and_b32_e32 v48, 0xffff0000, v91
	v_fmac_f32_e32 v59, v51, v48
	v_cvt_pk_bf16_f32 v48, v56, v52
	v_add_co_u32_e32 v52, vcc, s48, v144
	v_cvt_pk_bf16_f32 v49, v53, v54
	v_cvt_pk_bf16_f32 v50, v55, v57
	v_cvt_pk_bf16_f32 v51, v58, v59
	global_store_dwordx4 v[112:113], v[48:51], off offset:256 sc0 sc1
	s_nop 0
	v_addc_co_u32_e32 v53, vcc, 0, v145, vcc
	v_add_co_u32_e32 v80, vcc, s49, v144
	v_lshlrev_b32_e32 v83, 16, v68
	s_nop 0
	v_addc_co_u32_e32 v81, vcc, 0, v145, vcc
	global_load_dwordx4 v[48:51], v[52:53], off offset:256
	s_nop 0
	global_load_dwordx4 v[52:55], v[52:53], off
	s_nop 0
	global_load_dwordx4 v[56:59], v[80:81], off offset:256
	global_load_dwordx4 v[60:63], v[80:81], off
	v_fmac_f32_e32 v82, v44, v83
	v_and_b32_e32 v44, 0xffff0000, v64
	v_and_b32_e32 v64, 0xffff0000, v68
	v_fmac_f32_e32 v44, v45, v64
	v_lshlrev_b32_e32 v45, 16, v65
	v_lshlrev_b32_e32 v64, 16, v69
	v_fmac_f32_e32 v45, v46, v64
	v_and_b32_e32 v46, 0xffff0000, v65
	v_and_b32_e32 v64, 0xffff0000, v69
	v_fmac_f32_e32 v46, v47, v64
	v_lshlrev_b32_e32 v47, 16, v66
	v_lshlrev_b32_e32 v64, 16, v70
	v_fmac_f32_e32 v47, v40, v64
	v_and_b32_e32 v64, 0xffff0000, v66
	v_and_b32_e32 v40, 0xffff0000, v70
	v_fmac_f32_e32 v64, v41, v40
	v_lshlrev_b32_e32 v65, 16, v67
	v_lshlrev_b32_e32 v40, 16, v71
	v_fmac_f32_e32 v65, v42, v40
	v_and_b32_e32 v66, 0xffff0000, v67
	v_and_b32_e32 v40, 0xffff0000, v71
	v_fmac_f32_e32 v66, v43, v40
	v_cvt_pk_bf16_f32 v40, v82, v44
	v_cvt_pk_bf16_f32 v41, v45, v46
	v_cvt_pk_bf16_f32 v42, v47, v64
	v_cvt_pk_bf16_f32 v43, v65, v66
	global_store_dwordx4 v[96:97], v[40:43], off sc0 sc1
	s_waitcnt vmcnt(0)
; __device__ __forceinline__ float bf_lo(unsigned w) { return __uint_as_float(w << 16); }
; #define PG8_WAIT_V(n) asm volatile("s_waitcnt vmcnt(" #n ")" ::: "memory")
;     __device__ __forceinline__ void operator()(const f32x4 (&acc)[2][2][4][2], const Unit& u, int wr, int wc, int fr, int fq) const {
;     ...
;         for (int g = 0; g < 8; ++g) {
;             const int ai = g >> 2, m = g & 3;
;             bf16_t* rowp = base + (size_t)(ai * HALF + m * 16) * NGATE;
;             if (g < 7) { const bf16_t* nrow = base + (size_t)(((g + 1) >> 2) * HALF + ((g + 1) & 3) * 16) * NGATE;
; #pragma unroll
;                 for (int bj = 0; bj < 2; ++bj) { na[bj] = *(const u32x4*)(nrow + bj * HALF); if (STEP == 1) nb[bj] = *(const u32x4*)(nrow + bj * HALF + DM); } }
; #pragma unroll
;             for (int bj = 0; bj < 2; ++bj) {
;                 const f32x4 a0 = acc[ai][bj][m][0], a1 = acc[ai][bj][m][1];
;                 float v[8];
;                 if (STEP == 0) {
;                     v[0] = bf_lo(ga[bj].x) * a0[0]; v[1] = bf_hi(ga[bj].x) * a0[1]; v[2] = bf_lo(ga[bj].y) * a0[2]; v[3] = bf_hi(ga[bj].y) * a0[3];
;                     v[4] = bf_lo(ga[bj].z) * a1[0]; v[5] = bf_hi(ga[bj].z) * a1[1]; v[6] = bf_lo(ga[bj].w) * a1[2]; v[7] = bf_hi(ga[bj].w) * a1[3];
;                 } else {
;                     v[0] = bf_lo(ga[bj].x) + bf_lo(gb[bj].x) * a0[0]; v[1] = bf_hi(ga[bj].x) + bf_hi(gb[bj].x) * a0[1]; v[2] = bf_lo(ga[bj].y) + bf_lo(gb[bj].y) * a0[2]; v[3] = bf_hi(ga[bj].y) + bf_hi(gb[bj].y) * a0[3];
;                     v[4] = bf_lo(ga[bj].z) + bf_lo(gb[bj].z) * a1[0]; v[5] = bf_hi(ga[bj].z) + bf_hi(gb[bj].z) * a1[1]; v[6] = bf_lo(ga[bj].w) + bf_lo(gb[bj].w) * a1[2]; v[7] = bf_hi(ga[bj].w) + bf_hi(gb[bj].w) * a1[3];
;                 }
;                 u32x4 w; w.x = cvt_pk_bf16(v[0], v[1]); w.y = cvt_pk_bf16(v[2], v[3]); w.z = cvt_pk_bf16(v[4], v[5]); w.w = cvt_pk_bf16(v[6], v[7]);
;                 *(u32x4*)(rowp + bj * HALF) = w;
;             }
;             asm volatile("" ::: "memory");
; #pragma unroll
;             for (int bj = 0; bj < 2; ++bj) { ga[bj] = na[bj]; if (STEP == 1) gb[bj] = nb[bj]; }
;         }
; template <class Epi, class Sched>
; __device__ __forceinline__ void gemm_phase(LAS unsigned char* lds, const Gemm g, const Sched& S, const Epi& E) {
;     ...
;         if (!has_next) break;
;     ...
;     PG8_WAIT_V(0);
;     if (wr == 0) PG8_BAR;
;     PG8_BAR;
	v_lshlrev_b32_e32 v67, 16, v52
	v_lshlrev_b32_e32 v40, 16, v76
	v_lshlrev_b32_e32 v41, 16, v72
	v_fmac_f32_e32 v40, v36, v41
	v_and_b32_e32 v36, 0xffff0000, v76
	v_and_b32_e32 v41, 0xffff0000, v72
	v_fmac_f32_e32 v36, v37, v41
	v_lshlrev_b32_e32 v37, 16, v77
	v_lshlrev_b32_e32 v41, 16, v73
	v_fmac_f32_e32 v37, v38, v41
	v_and_b32_e32 v38, 0xffff0000, v77
	v_and_b32_e32 v41, 0xffff0000, v73
	v_fmac_f32_e32 v38, v39, v41
	v_lshlrev_b32_e32 v39, 16, v78
	v_lshlrev_b32_e32 v41, 16, v74
	v_fmac_f32_e32 v39, v32, v41
	v_and_b32_e32 v41, 0xffff0000, v78
	v_and_b32_e32 v32, 0xffff0000, v74
	v_fmac_f32_e32 v41, v33, v32
	v_lshlrev_b32_e32 v42, 16, v79
	v_lshlrev_b32_e32 v32, 16, v75
	v_fmac_f32_e32 v42, v34, v32
	v_and_b32_e32 v43, 0xffff0000, v79
	v_and_b32_e32 v32, 0xffff0000, v75
	v_fmac_f32_e32 v43, v35, v32
	v_cvt_pk_bf16_f32 v32, v40, v36
	v_add_co_u32_e32 v40, vcc, s50, v144
	v_cvt_pk_bf16_f32 v33, v37, v38
	v_cvt_pk_bf16_f32 v34, v39, v41
	v_cvt_pk_bf16_f32 v35, v42, v43
	global_store_dwordx4 v[96:97], v[32:35], off offset:256 sc0 sc1
	s_nop 0
	v_addc_co_u32_e32 v41, vcc, 0, v145, vcc
	v_add_co_u32_e32 v64, vcc, s51, v144
	v_lshlrev_b32_e32 v66, 16, v60
	s_nop 0
	v_addc_co_u32_e32 v65, vcc, 0, v145, vcc
	global_load_dwordx4 v[32:35], v[64:65], off
	global_load_dwordx4 v[36:39], v[40:41], off
	s_nop 0
	global_load_dwordx4 v[40:43], v[40:41], off offset:256
	s_nop 0
	global_load_dwordx4 v[44:47], v[64:65], off offset:256
	v_fmac_f32_e32 v66, v28, v67
	v_and_b32_e32 v28, 0xffff0000, v60
	v_and_b32_e32 v52, 0xffff0000, v52
	v_fmac_f32_e32 v28, v29, v52
	v_lshlrev_b32_e32 v29, 16, v61
	v_lshlrev_b32_e32 v52, 16, v53
	v_fmac_f32_e32 v29, v30, v52
	v_and_b32_e32 v30, 0xffff0000, v61
	v_and_b32_e32 v52, 0xffff0000, v53
	v_fmac_f32_e32 v30, v31, v52
	v_lshlrev_b32_e32 v31, 16, v62
	v_lshlrev_b32_e32 v52, 16, v54
	v_fmac_f32_e32 v31, v24, v52
	v_and_b32_e32 v52, 0xffff0000, v62
	v_and_b32_e32 v24, 0xffff0000, v54
	v_fmac_f32_e32 v52, v25, v24
	v_lshlrev_b32_e32 v53, 16, v63
	v_lshlrev_b32_e32 v24, 16, v55
	v_fmac_f32_e32 v53, v26, v24
	v_and_b32_e32 v54, 0xffff0000, v63
	v_and_b32_e32 v24, 0xffff0000, v55
	v_fmac_f32_e32 v54, v27, v24
	v_cvt_pk_bf16_f32 v24, v66, v28
	v_cvt_pk_bf16_f32 v25, v29, v30
	v_cvt_pk_bf16_f32 v26, v31, v52
	v_cvt_pk_bf16_f32 v27, v53, v54
	global_store_dwordx4 v[80:81], v[24:27], off sc0 sc1
	s_and_b64 vcc, exec, s[0:1]
	s_nop 0
	v_lshlrev_b32_e32 v24, 16, v56
	v_lshlrev_b32_e32 v25, 16, v48
	v_fmac_f32_e32 v24, v20, v25
	v_and_b32_e32 v20, 0xffff0000, v56
	v_and_b32_e32 v25, 0xffff0000, v48
	v_fmac_f32_e32 v20, v21, v25
	v_lshlrev_b32_e32 v21, 16, v57
	v_lshlrev_b32_e32 v25, 16, v49
	v_fmac_f32_e32 v21, v22, v25
	v_and_b32_e32 v22, 0xffff0000, v57
	v_and_b32_e32 v25, 0xffff0000, v49
	v_fmac_f32_e32 v22, v23, v25
	v_lshlrev_b32_e32 v23, 16, v58
	v_lshlrev_b32_e32 v25, 16, v50
	v_fmac_f32_e32 v23, v12, v25
	v_and_b32_e32 v25, 0xffff0000, v58
	v_and_b32_e32 v12, 0xffff0000, v50
	v_fmac_f32_e32 v25, v13, v12
	v_lshlrev_b32_e32 v26, 16, v59
	v_lshlrev_b32_e32 v12, 16, v51
	v_fmac_f32_e32 v26, v14, v12
	v_and_b32_e32 v27, 0xffff0000, v59
	v_and_b32_e32 v12, 0xffff0000, v51
	v_fmac_f32_e32 v27, v15, v12
	v_cvt_pk_bf16_f32 v12, v24, v20
	v_cvt_pk_bf16_f32 v13, v21, v22
	v_cvt_pk_bf16_f32 v14, v23, v25
	v_cvt_pk_bf16_f32 v15, v26, v27
	global_store_dwordx4 v[80:81], v[12:15], off offset:256 sc0 sc1
	s_waitcnt vmcnt(0)
	s_nop 0
	v_lshlrev_b32_e32 v12, 16, v32
	v_lshlrev_b32_e32 v13, 16, v36
	v_fmac_f32_e32 v12, v16, v13
	v_and_b32_e32 v13, 0xffff0000, v32
	v_and_b32_e32 v14, 0xffff0000, v36
	v_fmac_f32_e32 v13, v17, v14
	v_lshlrev_b32_e32 v14, 16, v33
	v_lshlrev_b32_e32 v15, 16, v37
	v_fmac_f32_e32 v14, v18, v15
	v_and_b32_e32 v15, 0xffff0000, v33
	v_and_b32_e32 v16, 0xffff0000, v37
	v_fmac_f32_e32 v15, v19, v16
	v_lshlrev_b32_e32 v16, 16, v34
	v_lshlrev_b32_e32 v17, 16, v38
	v_fmac_f32_e32 v16, v8, v17
	v_and_b32_e32 v17, 0xffff0000, v34
	v_and_b32_e32 v8, 0xffff0000, v38
	v_fmac_f32_e32 v17, v9, v8
	v_lshlrev_b32_e32 v18, 16, v35
	v_lshlrev_b32_e32 v8, 16, v39
	v_fmac_f32_e32 v18, v10, v8
	v_and_b32_e32 v19, 0xffff0000, v35
	v_and_b32_e32 v8, 0xffff0000, v39
	v_fmac_f32_e32 v19, v11, v8
	v_cvt_pk_bf16_f32 v8, v12, v13
	v_cvt_pk_bf16_f32 v9, v14, v15
	v_cvt_pk_bf16_f32 v10, v16, v17
	v_cvt_pk_bf16_f32 v11, v18, v19
	global_store_dwordx4 v[64:65], v[8:11], off sc0 sc1
	s_nop 1
	v_lshlrev_b32_e32 v8, 16, v44
	v_lshlrev_b32_e32 v9, 16, v40
	v_fmac_f32_e32 v8, v4, v9
	v_and_b32_e32 v4, 0xffff0000, v44
	v_and_b32_e32 v9, 0xffff0000, v40
	v_fmac_f32_e32 v4, v5, v9
	v_lshlrev_b32_e32 v5, 16, v45
	v_lshlrev_b32_e32 v9, 16, v41
	v_fmac_f32_e32 v5, v6, v9
	v_and_b32_e32 v6, 0xffff0000, v45
	v_and_b32_e32 v9, 0xffff0000, v41
	v_fmac_f32_e32 v6, v7, v9
	v_lshlrev_b32_e32 v7, 16, v46
	v_lshlrev_b32_e32 v9, 16, v42
	v_fmac_f32_e32 v7, v0, v9
	v_and_b32_e32 v9, 0xffff0000, v46
	v_and_b32_e32 v0, 0xffff0000, v42
	v_fmac_f32_e32 v9, v1, v0
	v_lshlrev_b32_e32 v10, 16, v47
	v_lshlrev_b32_e32 v0, 16, v43
	v_fmac_f32_e32 v10, v2, v0
	v_and_b32_e32 v11, 0xffff0000, v47
	v_and_b32_e32 v0, 0xffff0000, v43
	v_fmac_f32_e32 v11, v3, v0
	v_cvt_pk_bf16_f32 v0, v8, v4
	v_cvt_pk_bf16_f32 v1, v5, v6
	v_cvt_pk_bf16_f32 v2, v7, v9
	v_cvt_pk_bf16_f32 v3, v10, v11
	global_store_dwordx4 v[64:65], v[0:3], off offset:256 sc0 sc1
	s_cbranch_vccz .LBB0_712
	s_waitcnt vmcnt(0)
	s_cmpk_gt_u32 s22, 0xff
	s_cbranch_scc1 .LBB0_719
	s_barrier

; #define PG8_STAGE(bufoff, gbase, voff) do { _Pragma("unroll") for (int _i = 0; _i < 2; ++_i) \
;         __builtin_amdgcn_global_load_lds((const unsigned*)((const char*)(gbase) + (voff)[_i]), (LAS unsigned*)(lds + (bufoff) + ldsw + _i * 8192), 16, 0, 0); } while (0)
; #define PG8_LDA(dst, b, h) do { _Pragma("unroll") for (int m = 0; m < 4; ++m) _Pragma("unroll") for (int k = 0; k < 2; ++k) dst[m][k] = *(const LAS bf16x8*)(lds + PG8_SA(b, h) + aoff + m * 2048 + k * 1024); } while (0)
; #define PG8_LDB(dst, b, h) do { _Pragma("unroll") for (int n = 0; n < 2; ++n) _Pragma("unroll") for (int k = 0; k < 2; ++k) dst[n][k] = *(const LAS bf16x8*)(lds + PG8_SB(b, h) + boff + n * 2048 + k * 1024); } while (0)
; #define PG8_MMA(ai, bj, At, Bt) do { __builtin_amdgcn_s_setprio(1); _Pragma("unroll") for (int m = 0; m < 4; ++m) _Pragma("unroll") for (int n = 0; n < 2; ++n) _Pragma("unroll") for (int k = 0; k < 2; ++k) \
;         acc[ai][bj][m][n] = MmaOp<Epi::I8>::run(Bt[n][k], At[m][k], acc[ai][bj][m][n]); __builtin_amdgcn_s_setprio(0); } while (0)
; #define PG8_WAIT_L(n) asm volatile("s_waitcnt lgkmcnt(" #n ")" ::: "memory")
; #define PG8_BAR __builtin_amdgcn_s_barrier()
; #define PG8_SCHED __builtin_amdgcn_sched_barrier(0)
; template <class Epi, class Sched>
; __device__ __forceinline__ void gemm_phase(LAS unsigned char* lds, const Gemm g, const Sched& S, const Epi& E) {
;     ...
;             PG8_LDB(B0, 0, 0); PG8_SCHED; PG8_LDA(At, 0, 0); PG8_STAGE(PG8_SA(1, 1), a1 + hstepA, voffA);
;             PG8_WAIT_L(8); PG8_BAR; PG8_WAIT_L(0); PG8_MMA(0, 0, At, B0); PG8_BAR; PG8_SCHED;
;             PG8_LDB(B1, 0, 1); PG8_STAGE(PG8_SB(0, 0), b2, voffB);
;             PG8_BAR; PG8_WAIT_L(0); PG8_MMA(0, 1, At, B1); PG8_BAR;
;             PG8_LDA(At, 0, 1); PG8_STAGE(PG8_SA(0, 0), a2, voffA);
;             PG8_BAR; PG8_WAIT_L(0); PG8_MMA(1, 0, At, B0); PG8_BAR; PG8_SCHED;
.LBB0_783:
	ds_read_b128 v[128:131], v171
	ds_read_b128 v[132:135], v171 offset:1024
	ds_read_b128 v[136:139], v171 offset:2048
	ds_read_b128 v[140:143], v171 offset:3072
	s_add_u32 s22, s20, 0xfff00080
	s_addc_u32 s23, s21, -1
	s_cmp_eq_u32 s46, 28
	s_cselect_b32 s25, s13, s23
	s_cselect_b32 s24, s42, s22
	s_cselect_b32 s23, s11, s45
	s_cselect_b32 s22, s43, s44
	v_lshl_add_u64 v[202:203], s[20:21], 0, v[152:153]
	s_add_i32 m0, s30, 0xc000
	ds_read_b128 v[160:163], v172
	ds_read_b128 v[164:167], v172 offset:1024
	ds_read_b128 v[178:181], v172 offset:2048
	ds_read_b128 v[182:185], v172 offset:3072
	ds_read_b128 v[186:189], v172 offset:4096
	ds_read_b128 v[190:193], v172 offset:5120
	ds_read_b128 v[194:197], v172 offset:6144
	ds_read_b128 v[198:201], v172 offset:7168
	global_load_lds_dwordx4 v[202:203], off
	v_lshl_add_u64 v[202:203], s[20:21], 0, v[154:155]
	s_add_i32 m0, s30, 0xe000
	s_nop 0
	global_load_lds_dwordx4 v[202:203], off
	s_waitcnt lgkmcnt(8)
	s_barrier
	s_waitcnt lgkmcnt(0)
	s_setprio 1
	v_mfma_f32_16x16x32_bf16 v[124:127], v[128:131], v[160:163], v[124:127]
	v_mfma_f32_16x16x32_bf16 v[120:123], v[136:139], v[160:163], v[120:123]
	v_mfma_f32_16x16x32_bf16 v[108:111], v[128:131], v[178:181], v[108:111]
	v_mfma_f32_16x16x32_bf16 v[104:107], v[136:139], v[178:181], v[104:107]
	v_mfma_f32_16x16x32_bf16 v[92:95], v[128:131], v[186:189], v[92:95]
	v_mfma_f32_16x16x32_bf16 v[88:91], v[136:139], v[186:189], v[88:91]
	v_mfma_f32_16x16x32_bf16 v[76:79], v[128:131], v[194:197], v[76:79]
	v_mfma_f32_16x16x32_bf16 v[72:75], v[136:139], v[194:197], v[72:75]
	v_mfma_f32_16x16x32_bf16 v[124:127], v[132:135], v[164:167], v[124:127]
	v_mfma_f32_16x16x32_bf16 v[120:123], v[140:143], v[164:167], v[120:123]
	v_mfma_f32_16x16x32_bf16 v[108:111], v[132:135], v[182:185], v[108:111]
	v_mfma_f32_16x16x32_bf16 v[104:107], v[140:143], v[182:185], v[104:107]
	v_mfma_f32_16x16x32_bf16 v[92:95], v[132:135], v[190:193], v[92:95]
	v_mfma_f32_16x16x32_bf16 v[88:91], v[140:143], v[190:193], v[88:91]
	v_mfma_f32_16x16x32_bf16 v[76:79], v[132:135], v[198:201], v[76:79]
	v_mfma_f32_16x16x32_bf16 v[72:75], v[140:143], v[198:201], v[72:75]
	s_setprio 0
	s_barrier
	s_add_i32 s47, s39, s27
	v_lshl_add_u64 v[218:219], s[22:23], 0, v[148:149]
	s_mov_b32 m0, s47
	ds_read_b128 v[202:205], v173
	ds_read_b128 v[206:209], v173 offset:1024
	ds_read_b128 v[210:213], v173 offset:2048
	ds_read_b128 v[214:217], v173 offset:3072
	global_load_lds_dwordx4 v[218:219], off
	v_lshl_add_u64 v[220:221], s[22:23], 0, v[144:145]
	s_add_i32 m0, s47, 0x2000
	s_nop 0
	global_load_lds_dwordx4 v[220:221], off
	s_barrier
	s_waitcnt lgkmcnt(0)
	s_setprio 1
	v_mfma_f32_16x16x32_bf16 v[116:119], v[202:205], v[160:163], v[116:119]
	v_mfma_f32_16x16x32_bf16 v[112:115], v[210:213], v[160:163], v[112:115]
	v_mfma_f32_16x16x32_bf16 v[100:103], v[202:205], v[178:181], v[100:103]
	v_mfma_f32_16x16x32_bf16 v[96:99], v[210:213], v[178:181], v[96:99]
	v_mfma_f32_16x16x32_bf16 v[84:87], v[202:205], v[186:189], v[84:87]
	v_mfma_f32_16x16x32_bf16 v[80:83], v[210:213], v[186:189], v[80:83]
	v_mfma_f32_16x16x32_bf16 v[68:71], v[202:205], v[194:197], v[68:71]
	v_mfma_f32_16x16x32_bf16 v[64:67], v[210:213], v[194:197], v[64:67]
	v_mfma_f32_16x16x32_bf16 v[116:119], v[206:209], v[164:167], v[116:119]
	v_mfma_f32_16x16x32_bf16 v[112:115], v[214:217], v[164:167], v[112:115]
	v_mfma_f32_16x16x32_bf16 v[100:103], v[206:209], v[182:185], v[100:103]
	v_mfma_f32_16x16x32_bf16 v[96:99], v[214:217], v[182:185], v[96:99]
	v_mfma_f32_16x16x32_bf16 v[84:87], v[206:209], v[190:193], v[84:87]
	v_mfma_f32_16x16x32_bf16 v[80:83], v[214:217], v[190:193], v[80:83]
	v_mfma_f32_16x16x32_bf16 v[68:71], v[206:209], v[198:201], v[68:71]
	v_mfma_f32_16x16x32_bf16 v[64:67], v[214:217], v[198:201], v[64:67]
	s_setprio 0
	s_mov_b32 m0, s30
	v_lshl_add_u64 v[222:223], s[24:25], 0, v[150:151]
	s_barrier
	ds_read_b128 v[160:163], v172 offset:16384
	ds_read_b128 v[164:167], v172 offset:17408
	ds_read_b128 v[178:181], v172 offset:18432
	ds_read_b128 v[182:185], v172 offset:19456
	ds_read_b128 v[186:189], v172 offset:20480
	ds_read_b128 v[190:193], v172 offset:21504
	ds_read_b128 v[194:197], v172 offset:22528
	ds_read_b128 v[198:201], v172 offset:23552
	global_load_lds_dwordx4 v[222:223], off
	v_lshl_add_u64 v[224:225], s[24:25], 0, v[146:147]
	s_mov_b32 m0, s31
	s_nop 0
	global_load_lds_dwordx4 v[224:225], off
	s_barrier
	s_waitcnt lgkmcnt(0)
	s_setprio 1
	v_mfma_f32_16x16x32_bf16 v[60:63], v[128:131], v[160:163], v[60:63]
	v_mfma_f32_16x16x32_bf16 v[56:59], v[136:139], v[160:163], v[56:59]
	v_mfma_f32_16x16x32_bf16 v[44:47], v[128:131], v[178:181], v[44:47]
	v_mfma_f32_16x16x32_bf16 v[40:43], v[136:139], v[178:181], v[40:43]
	v_mfma_f32_16x16x32_bf16 v[28:31], v[128:131], v[186:189], v[28:31]
	v_mfma_f32_16x16x32_bf16 v[24:27], v[136:139], v[186:189], v[24:27]
	v_mfma_f32_16x16x32_bf16 v[12:15], v[128:131], v[194:197], v[12:15]
	v_mfma_f32_16x16x32_bf16 v[8:11], v[136:139], v[194:197], v[8:11]
	v_mfma_f32_16x16x32_bf16 v[60:63], v[132:135], v[164:167], v[60:63]
	v_mfma_f32_16x16x32_bf16 v[56:59], v[140:143], v[164:167], v[56:59]
	v_mfma_f32_16x16x32_bf16 v[44:47], v[132:135], v[182:185], v[44:47]
	v_mfma_f32_16x16x32_bf16 v[40:43], v[140:143], v[182:185], v[40:43]
	v_mfma_f32_16x16x32_bf16 v[28:31], v[132:135], v[190:193], v[28:31]
	v_mfma_f32_16x16x32_bf16 v[24:27], v[140:143], v[190:193], v[24:27]
	v_mfma_f32_16x16x32_bf16 v[12:15], v[132:135], v[198:201], v[12:15]
	v_mfma_f32_16x16x32_bf16 v[8:11], v[140:143], v[198:201], v[8:11]
	s_setprio 0
	s_barrier
; #define PG8_STAGE(bufoff, gbase, voff) do { _Pragma("unroll") for (int _i = 0; _i < 2; ++_i) \
;         __builtin_amdgcn_global_load_lds((const unsigned*)((const char*)(gbase) + (voff)[_i]), (LAS unsigned*)(lds + (bufoff) + ldsw + _i * 8192), 16, 0, 0); } while (0)
; #define PG8_LDA(dst, b, h) do { _Pragma("unroll") for (int m = 0; m < 4; ++m) _Pragma("unroll") for (int k = 0; k < 2; ++k) dst[m][k] = *(const LAS bf16x8*)(lds + PG8_SA(b, h) + aoff + m * 2048 + k * 1024); } while (0)
; #define PG8_LDB(dst, b, h) do { _Pragma("unroll") for (int n = 0; n < 2; ++n) _Pragma("unroll") for (int k = 0; k < 2; ++k) dst[n][k] = *(const LAS bf16x8*)(lds + PG8_SB(b, h) + boff + n * 2048 + k * 1024); } while (0)
; #define PG8_MMA(ai, bj, At, Bt) do { __builtin_amdgcn_s_setprio(1); _Pragma("unroll") for (int m = 0; m < 4; ++m) _Pragma("unroll") for (int n = 0; n < 2; ++n) _Pragma("unroll") for (int k = 0; k < 2; ++k) \
;         acc[ai][bj][m][n] = MmaOp<Epi::I8>::run(Bt[n][k], At[m][k], acc[ai][bj][m][n]); __builtin_amdgcn_s_setprio(0); } while (0)
; #define PG8_WAIT_V(n) asm volatile("s_waitcnt vmcnt(" #n ")" ::: "memory")
; #define PG8_WAIT_L(n) asm volatile("s_waitcnt lgkmcnt(" #n ")" ::: "memory")
; #define PG8_BAR __builtin_amdgcn_s_barrier()
; #define PG8_SCHED __builtin_amdgcn_sched_barrier(0)
; template <class Epi, class Sched>
; __device__ __forceinline__ void gemm_phase(LAS unsigned char* lds, const Gemm g, const Sched& S, const Epi& E) {
;     ...
;             PG8_STAGE(PG8_SB(0, 1), b2 + hstepB, voffB);
;             PG8_WAIT_V(6); PG8_BAR; PG8_MMA(1, 1, At, B1); PG8_BAR;
;             PG8_LDB(B0, 1, 0); PG8_SCHED; PG8_LDA(At, 1, 0); PG8_STAGE(PG8_SA(0, 1), a2 + hstepA, voffA);
;             PG8_WAIT_L(8); PG8_BAR; PG8_WAIT_L(0); PG8_MMA(0, 0, At, B0); PG8_BAR; PG8_SCHED;
;             PG8_LDB(B1, 1, 1); PG8_STAGE(PG8_SB(1, 0), b3, voffB);
;             PG8_BAR; PG8_WAIT_L(0); PG8_MMA(0, 1, At, B1); PG8_BAR;
;             PG8_LDA(At, 1, 1); PG8_STAGE(PG8_SA(1, 0), a3, voffA);
	s_add_u32 s48, s22, 0x80000
	s_addc_u32 s49, s23, 0
	s_add_i32 s47, s40, s27
	v_lshl_add_u64 v[128:129], s[48:49], 0, v[148:149]
	s_mov_b32 m0, s47
	s_nop 0
	global_load_lds_dwordx4 v[128:129], off
	v_lshl_add_u64 v[128:129], s[48:49], 0, v[144:145]
	s_add_i32 m0, s47, 0x2000
	s_nop 0
	global_load_lds_dwordx4 v[128:129], off
	s_waitcnt vmcnt(6)
	s_barrier
	s_setprio 1
	v_mfma_f32_16x16x32_bf16 v[52:55], v[202:205], v[160:163], v[52:55]
	v_mfma_f32_16x16x32_bf16 v[48:51], v[210:213], v[160:163], v[48:51]
	v_mfma_f32_16x16x32_bf16 v[36:39], v[202:205], v[178:181], v[36:39]
	v_mfma_f32_16x16x32_bf16 v[32:35], v[210:213], v[178:181], v[32:35]
	v_mfma_f32_16x16x32_bf16 v[20:23], v[202:205], v[186:189], v[20:23]
	v_mfma_f32_16x16x32_bf16 v[16:19], v[210:213], v[186:189], v[16:19]
	v_mfma_f32_16x16x32_bf16 v[4:7], v[202:205], v[194:197], v[4:7]
	v_mfma_f32_16x16x32_bf16 v[0:3], v[210:213], v[194:197], v[0:3]
	v_mfma_f32_16x16x32_bf16 v[52:55], v[206:209], v[164:167], v[52:55]
	v_mfma_f32_16x16x32_bf16 v[48:51], v[214:217], v[164:167], v[48:51]
	v_mfma_f32_16x16x32_bf16 v[36:39], v[206:209], v[182:185], v[36:39]
	v_mfma_f32_16x16x32_bf16 v[32:35], v[214:217], v[182:185], v[32:35]
	v_mfma_f32_16x16x32_bf16 v[20:23], v[206:209], v[190:193], v[20:23]
	v_mfma_f32_16x16x32_bf16 v[16:19], v[214:217], v[190:193], v[16:19]
	v_mfma_f32_16x16x32_bf16 v[4:7], v[206:209], v[198:201], v[4:7]
	v_mfma_f32_16x16x32_bf16 v[0:3], v[214:217], v[198:201], v[0:3]
	s_setprio 0
	s_add_i32 s47, 0, 0x18000
	v_add_u32_e32 v140, s47, v169
	s_barrier
	ds_read_b128 v[128:131], v140
	ds_read_b128 v[132:135], v140 offset:1024
	ds_read_b128 v[136:139], v140 offset:2048
	ds_read_b128 v[140:143], v140 offset:3072
	s_add_u32 s24, s24, 0x100000
	s_addc_u32 s25, s25, 0
	s_mov_b32 m0, s33
	v_lshl_add_u64 v[202:203], s[24:25], 0, v[150:151]
	ds_read_b128 v[160:163], v172 offset:32768
	ds_read_b128 v[164:167], v172 offset:33792
	ds_read_b128 v[178:181], v172 offset:34816
	ds_read_b128 v[182:185], v172 offset:35840
	ds_read_b128 v[186:189], v172 offset:36864
	ds_read_b128 v[190:193], v172 offset:37888
	ds_read_b128 v[194:197], v172 offset:38912
	ds_read_b128 v[198:201], v172 offset:39936
	global_load_lds_dwordx4 v[202:203], off
	v_lshl_add_u64 v[202:203], s[24:25], 0, v[146:147]
	s_mov_b32 m0, s34
	s_nop 0
	global_load_lds_dwordx4 v[202:203], off
	s_waitcnt lgkmcnt(8)
	s_barrier
	s_waitcnt lgkmcnt(0)
	s_setprio 1
	v_mfma_f32_16x16x32_bf16 v[124:127], v[128:131], v[160:163], v[124:127]
	v_mfma_f32_16x16x32_bf16 v[120:123], v[136:139], v[160:163], v[120:123]
	v_mfma_f32_16x16x32_bf16 v[108:111], v[128:131], v[178:181], v[108:111]
	v_mfma_f32_16x16x32_bf16 v[104:107], v[136:139], v[178:181], v[104:107]
	v_mfma_f32_16x16x32_bf16 v[92:95], v[128:131], v[186:189], v[92:95]
	v_mfma_f32_16x16x32_bf16 v[88:91], v[136:139], v[186:189], v[88:91]
	v_mfma_f32_16x16x32_bf16 v[76:79], v[128:131], v[194:197], v[76:79]
	v_mfma_f32_16x16x32_bf16 v[72:75], v[136:139], v[194:197], v[72:75]
	v_mfma_f32_16x16x32_bf16 v[124:127], v[132:135], v[164:167], v[124:127]
	v_mfma_f32_16x16x32_bf16 v[120:123], v[140:143], v[164:167], v[120:123]
	v_mfma_f32_16x16x32_bf16 v[108:111], v[132:135], v[182:185], v[108:111]
	v_mfma_f32_16x16x32_bf16 v[104:107], v[140:143], v[182:185], v[104:107]
	v_mfma_f32_16x16x32_bf16 v[92:95], v[132:135], v[190:193], v[92:95]
	v_mfma_f32_16x16x32_bf16 v[88:91], v[140:143], v[190:193], v[88:91]
	v_mfma_f32_16x16x32_bf16 v[76:79], v[132:135], v[198:201], v[76:79]
	v_mfma_f32_16x16x32_bf16 v[72:75], v[140:143], v[198:201], v[72:75]
	s_setprio 0
	s_barrier
	s_add_i32 s24, 0, 0x1c000
	s_add_i32 s25, s47, s27
	v_add_u32_e32 v175, s24, v169
	v_lshl_add_u64 v[218:219], v[218:219], 0, s[8:9]
	s_mov_b32 m0, s25
	ds_read_b128 v[202:205], v175
	ds_read_b128 v[206:209], v175 offset:1024
	ds_read_b128 v[210:213], v175 offset:2048
	ds_read_b128 v[214:217], v175 offset:3072
	global_load_lds_dwordx4 v[218:219], off
	v_lshl_add_u64 v[218:219], v[220:221], 0, s[8:9]
	s_add_i32 m0, s25, 0x2000
	s_nop 0
	global_load_lds_dwordx4 v[218:219], off
	s_barrier
	s_waitcnt lgkmcnt(0)
	s_setprio 1
	v_mfma_f32_16x16x32_bf16 v[116:119], v[202:205], v[160:163], v[116:119]
	v_mfma_f32_16x16x32_bf16 v[112:115], v[210:213], v[160:163], v[112:115]
	v_mfma_f32_16x16x32_bf16 v[100:103], v[202:205], v[178:181], v[100:103]
	v_mfma_f32_16x16x32_bf16 v[96:99], v[210:213], v[178:181], v[96:99]
	v_mfma_f32_16x16x32_bf16 v[84:87], v[202:205], v[186:189], v[84:87]
	v_mfma_f32_16x16x32_bf16 v[80:83], v[210:213], v[186:189], v[80:83]
	v_mfma_f32_16x16x32_bf16 v[68:71], v[202:205], v[194:197], v[68:71]
	v_mfma_f32_16x16x32_bf16 v[64:67], v[210:213], v[194:197], v[64:67]
	v_mfma_f32_16x16x32_bf16 v[116:119], v[206:209], v[164:167], v[116:119]
	v_mfma_f32_16x16x32_bf16 v[112:115], v[214:217], v[164:167], v[112:115]
	v_mfma_f32_16x16x32_bf16 v[100:103], v[206:209], v[182:185], v[100:103]
	v_mfma_f32_16x16x32_bf16 v[96:99], v[214:217], v[182:185], v[96:99]
	v_mfma_f32_16x16x32_bf16 v[84:87], v[206:209], v[190:193], v[84:87]
	v_mfma_f32_16x16x32_bf16 v[80:83], v[214:217], v[190:193], v[80:83]
	v_mfma_f32_16x16x32_bf16 v[68:71], v[206:209], v[198:201], v[68:71]
	v_mfma_f32_16x16x32_bf16 v[64:67], v[214:217], v[198:201], v[64:67]
	s_setprio 0
	s_mov_b32 m0, s36
	v_lshl_add_u64 v[218:219], v[222:223], 0, s[8:9]
	s_barrier
	ds_read_b128 v[160:163], v172 offset:49152
	ds_read_b128 v[164:167], v172 offset:50176
	ds_read_b128 v[178:181], v172 offset:51200
	ds_read_b128 v[182:185], v172 offset:52224
	ds_read_b128 v[186:189], v172 offset:53248
	ds_read_b128 v[190:193], v172 offset:54272
	ds_read_b128 v[194:197], v172 offset:55296
	ds_read_b128 v[198:201], v172 offset:56320
	global_load_lds_dwordx4 v[218:219], off
	v_lshl_add_u64 v[218:219], v[224:225], 0, s[8:9]
	s_mov_b32 m0, s37
	s_nop 0
	global_load_lds_dwordx4 v[218:219], off
	s_barrier
; __device__ __forceinline__ unsigned cvt_pk_bf16(float lo, float hi) { unsigned r; asm volatile("v_cvt_pk_bf16_f32 %0, %1, %2" : "=v"(r) : "v"(lo), "v"(hi)); return r; }
; #define PG8_WAIT_V(n) asm volatile("s_waitcnt vmcnt(" #n ")" ::: "memory")
; #define PG8_BAR __builtin_amdgcn_s_barrier()
;     __device__ __forceinline__ void operator()(const f32x4 (&acc)[2][2][4][2], const Unit& u, int wr, int wc, int fr, int fq) const {
;         const int row0 = u.pm * BM + wr * 64 + fr, col0 = u.pn * BM + wc * 32 + 4 * fq;
;         const float* base = ((u.pm < MP / BM) ? base_lo : base_hi - (size_t)MP * DM) + (size_t)row0 * DM + col0;
;         f32x4 b[2][2], nb[2][2];
; #pragma unroll
;         for (int bj = 0; bj < 2; ++bj)
; #pragma unroll
;             for (int n = 0; n < 2; ++n) b[bj][n] = *(const f32x4*)(base + bj * HALF + n * 16);
; #pragma unroll
;         for (int g = 0; g < 8; ++g) {
;             const int ai = g >> 2, m = g & 3;
;             const int r = row0 + ai * HALF + m * 16; const size_t off = (size_t)r * DM + col0; float s = 0.f;
;             if (g < 7) { const float* nrow = base + (size_t)(((g + 1) >> 2) * HALF + ((g + 1) & 3) * 16) * DM;
; #pragma unroll
;                 for (int bj = 0; bj < 2; ++bj)
; #pragma unroll
;                     for (int n = 0; n < 2; ++n) nb[bj][n] = *(const f32x4*)(nrow + bj * HALF + n * 16); }
; #pragma unroll
;             for (int bj = 0; bj < 2; ++bj)
; #pragma unroll
;                 for (int n = 0; n < 2; ++n) {
;                     const f32x4 o = b[bj][n] + acc[ai][bj][m][n] * alpha;
;                     *(f32x4*)(out + off + bj * HALF + n * 16) = o;
;                     if (WITH_SSQ) s += (o[0] * o[0] + o[1] * o[1]) + (o[2] * o[2] + o[3] * o[3]);
;                     if (WITH_HB) { u32x2 w; w.x = cvt_pk_bf16(o[0], o[1]); w.y = cvt_pk_bf16(o[2], o[3]); *(u32x2*)(hb + off + bj * HALF + n * 16) = w; }
;                 }
;             if (WITH_SSQ) { s += __shfl_xor(s, 16); s += __shfl_xor(s, 32); if (fq == 0) atomicAdd(ssq + r, s); }
; template <class Epi, class Sched>
; __device__ __forceinline__ void gemm_phase(LAS unsigned char* lds, const Gemm g, const Sched& S, const Epi& E) {
;     ...
;             PG8_BAR; PG8_WAIT_L(0); PG8_MMA(1, 0, At, B0); PG8_BAR; PG8_SCHED;
;             PG8_STAGE(PG8_SB(1, 1), b3 + hstepB, voffB);
;             PG8_WAIT_V(6); PG8_BAR; PG8_MMA(1, 1, At, B1); PG8_BAR;
	s_waitcnt lgkmcnt(0)
	s_setprio 1
	v_mfma_f32_16x16x32_bf16 v[60:63], v[128:131], v[160:163], v[60:63]
	v_mfma_f32_16x16x32_bf16 v[56:59], v[136:139], v[160:163], v[56:59]
	v_mfma_f32_16x16x32_bf16 v[44:47], v[128:131], v[178:181], v[44:47]
	v_mfma_f32_16x16x32_bf16 v[40:43], v[136:139], v[178:181], v[40:43]
	v_mfma_f32_16x16x32_bf16 v[28:31], v[128:131], v[186:189], v[28:31]
	v_mfma_f32_16x16x32_bf16 v[24:27], v[136:139], v[186:189], v[24:27]
	v_mfma_f32_16x16x32_bf16 v[12:15], v[128:131], v[194:197], v[12:15]
	v_mfma_f32_16x16x32_bf16 v[8:11], v[136:139], v[194:197], v[8:11]
	v_mfma_f32_16x16x32_bf16 v[60:63], v[132:135], v[164:167], v[60:63]
	v_mfma_f32_16x16x32_bf16 v[56:59], v[140:143], v[164:167], v[56:59]
	v_mfma_f32_16x16x32_bf16 v[44:47], v[132:135], v[182:185], v[44:47]
	v_mfma_f32_16x16x32_bf16 v[40:43], v[140:143], v[182:185], v[40:43]
	v_mfma_f32_16x16x32_bf16 v[28:31], v[132:135], v[190:193], v[28:31]
	v_mfma_f32_16x16x32_bf16 v[24:27], v[140:143], v[190:193], v[24:27]
	v_mfma_f32_16x16x32_bf16 v[12:15], v[132:135], v[198:201], v[12:15]
	v_mfma_f32_16x16x32_bf16 v[8:11], v[140:143], v[198:201], v[8:11]
	s_setprio 0
	s_barrier
	s_add_u32 s22, s22, 0x80080
	s_addc_u32 s23, s23, 0
	s_add_i32 s24, s24, s27
	v_lshl_add_u64 v[128:129], s[22:23], 0, v[148:149]
	s_mov_b32 m0, s24
	s_nop 0
	global_load_lds_dwordx4 v[128:129], off
	v_lshl_add_u64 v[128:129], s[22:23], 0, v[144:145]
	s_add_i32 m0, s24, 0x2000
	s_nop 0
	global_load_lds_dwordx4 v[128:129], off
	s_waitcnt vmcnt(6)
	s_barrier
	s_setprio 1
	v_mfma_f32_16x16x32_bf16 v[52:55], v[202:205], v[160:163], v[52:55]
	v_mfma_f32_16x16x32_bf16 v[48:51], v[210:213], v[160:163], v[48:51]
	v_mfma_f32_16x16x32_bf16 v[36:39], v[202:205], v[178:181], v[36:39]
	v_mfma_f32_16x16x32_bf16 v[32:35], v[210:213], v[178:181], v[32:35]
	v_mfma_f32_16x16x32_bf16 v[20:23], v[202:205], v[186:189], v[20:23]
	v_mfma_f32_16x16x32_bf16 v[16:19], v[210:213], v[186:189], v[16:19]
	v_mfma_f32_16x16x32_bf16 v[4:7], v[202:205], v[194:197], v[4:7]
	v_mfma_f32_16x16x32_bf16 v[0:3], v[210:213], v[194:197], v[0:3]
	v_mfma_f32_16x16x32_bf16 v[52:55], v[206:209], v[164:167], v[52:55]
	v_mfma_f32_16x16x32_bf16 v[48:51], v[214:217], v[164:167], v[48:51]
	v_mfma_f32_16x16x32_bf16 v[36:39], v[206:209], v[182:185], v[36:39]
	v_mfma_f32_16x16x32_bf16 v[32:35], v[214:217], v[182:185], v[32:35]
	v_mfma_f32_16x16x32_bf16 v[20:23], v[206:209], v[190:193], v[20:23]
	v_mfma_f32_16x16x32_bf16 v[16:19], v[214:217], v[190:193], v[16:19]
	v_mfma_f32_16x16x32_bf16 v[4:7], v[206:209], v[198:201], v[4:7]
	v_mfma_f32_16x16x32_bf16 v[0:3], v[214:217], v[198:201], v[0:3]
	s_setprio 0
	s_add_i32 s46, s46, 2
	s_add_u32 s20, s20, 0x100
	s_addc_u32 s21, s21, 0
	s_add_u32 s44, s44, 0x100
	s_addc_u32 s45, s45, 0
	s_cmp_gt_u32 s46, 29
	s_barrier
	s_cbranch_scc0 .LBB0_783
	v_lshl_add_u32 v164, s18, 8, v168
	v_ashrrev_i32_e32 v165, 31, v164
	v_lshl_or_b32 v160, s19, 8, v170
	v_lshlrev_b64 v[128:129], 13, v[164:165]
	v_lshl_add_u64 v[128:129], s[68:69], 0, v[128:129]
	v_ashrrev_i32_e32 v161, 31, v160
	v_lshl_add_u64 v[162:163], v[160:161], 2, v[128:129]
	global_load_dwordx4 v[178:181], v[162:163], off
	global_load_dwordx4 v[182:185], v[162:163], off offset:64
	global_load_dwordx4 v[186:189], v[162:163], off offset:512
	global_load_dwordx4 v[190:193], v[162:163], off offset:576
	v_add_co_u32_e32 v128, vcc, s41, v162
	v_and_b32_e32 v166, 64, v174
	s_nop 0
	v_addc_co_u32_e32 v129, vcc, 0, v163, vcc
	global_load_dwordx4 v[140:143], v[128:129], off
	global_load_dwordx4 v[136:139], v[128:129], off offset:64
	global_load_dwordx4 v[132:135], v[128:129], off offset:512
	s_nop 0
	global_load_dwordx4 v[128:131], v[128:129], off offset:576
	v_add_u32_e32 v195, 64, v166
	v_lshlrev_b64 v[166:167], 11, v[164:165]
	v_readlane_b32 s18, v239, 25
	v_lshl_add_u64 v[166:167], v[166:167], 0, v[160:161]
	v_readlane_b32 s19, v239, 26
	v_xor_b32_e32 v175, 16, v174
	v_cmp_lt_i32_e32 vcc, v175, v195
	v_lshl_add_u64 v[166:167], v[166:167], 1, s[18:19]
	v_xor_b32_e32 v194, 32, v174
	v_cndmask_b32_e32 v175, v174, v175, vcc
	v_lshlrev_b32_e32 v175, 2, v175
	v_cmp_lt_i32_e32 vcc, v194, v195
	s_waitcnt vmcnt(0)
	v_pk_add_f32 v[126:127], v[126:127], v[180:181]
	v_pk_add_f32 v[124:125], v[124:125], v[178:179]
	v_pk_add_f32 v[122:123], v[122:123], v[184:185]
	v_pk_add_f32 v[120:121], v[120:121], v[182:183]
	v_pk_add_f32 v[118:119], v[118:119], v[188:189]
	v_pk_add_f32 v[116:117], v[116:117], v[186:187]
	v_pk_add_f32 v[182:183], v[114:115], v[192:193]
	v_pk_add_f32 v[180:181], v[112:113], v[190:191]
	global_store_dwordx4 v[162:163], v[124:127], off sc0 sc1
	v_mul_f32_e32 v114, v125, v125
	v_mul_f32_e32 v115, v127, v127
	v_cvt_pk_bf16_f32 v112, v124, v125
	v_cvt_pk_bf16_f32 v113, v126, v127
	v_mul_f32_e32 v125, v121, v121
	v_mul_f32_e32 v127, v123, v123
	v_mul_f32_e32 v178, v117, v117
	v_mul_f32_e32 v179, v119, v119
	v_fmac_f32_e32 v114, v124, v124
	v_fmac_f32_e32 v115, v126, v126
	v_fmac_f32_e32 v125, v120, v120
	v_fmac_f32_e32 v127, v122, v122
	v_mul_f32_e32 v184, v181, v181
	v_mul_f32_e32 v185, v183, v183
	global_store_dwordx2 v[166:167], v[112:113], off sc0 sc1
	global_store_dwordx4 v[162:163], v[120:123], off offset:64 sc0 sc1
	v_cvt_pk_bf16_f32 v112, v120, v121
	v_fmac_f32_e32 v178, v116, v116
	v_fmac_f32_e32 v179, v118, v118
	v_add_f32_e32 v114, v114, v115
	v_add_f32_e32 v115, v125, v127
	v_cvt_pk_bf16_f32 v113, v122, v123
	v_fmac_f32_e32 v184, v180, v180
	v_fmac_f32_e32 v185, v182, v182
	global_store_dwordx2 v[166:167], v[112:113], off offset:32 sc0 sc1
	v_add_f32_e32 v112, v178, v179
	v_add_f32_e32 v114, v114, v115
	v_add_f32_e32 v113, v184, v185
	v_add_f32_e32 v112, v114, v112
	v_add_f32_e32 v114, v112, v113
	ds_bpermute_b32 v115, v175, v114
	v_cndmask_b32_e32 v194, v174, v194, vcc
	global_store_dwordx4 v[162:163], v[116:119], off offset:512 sc0 sc1
	v_cvt_pk_bf16_f32 v112, v116, v117
	v_cvt_pk_bf16_f32 v113, v118, v119
	global_store_dwordx2 v[166:167], v[112:113], off offset:256 sc0 sc1
	s_waitcnt lgkmcnt(0)
	v_add_f32_e32 v112, v114, v115
	v_lshlrev_b32_e32 v178, 2, v194
	ds_bpermute_b32 v113, v178, v112
	global_store_dwordx4 v[162:163], v[180:183], off offset:576 sc0 sc1
	v_cvt_pk_bf16_f32 v114, v180, v181
	v_cvt_pk_bf16_f32 v115, v182, v183
	global_store_dwordx2 v[166:167], v[114:115], off offset:288 sc0 sc1
	s_and_saveexec_b64 s[18:19], s[0:1]
	s_cbranch_execz .LBB0_786
	v_lshl_add_u64 v[114:115], v[164:165], 2, s[2:3]
	s_waitcnt lgkmcnt(0)
	v_add_f32_e32 v112, v112, v113
	global_atomic_add_f32 v[114:115], v112, off

; #define PG8_STAGE(bufoff, gbase, voff) do { _Pragma("unroll") for (int _i = 0; _i < 2; ++_i) \
;         __builtin_amdgcn_global_load_lds((const unsigned*)((const char*)(gbase) + (voff)[_i]), (LAS unsigned*)(lds + (bufoff) + ldsw + _i * 8192), 16, 0, 0); } while (0)
; #define PG8_LDA(dst, b, h) do { _Pragma("unroll") for (int m = 0; m < 4; ++m) _Pragma("unroll") for (int k = 0; k < 2; ++k) dst[m][k] = *(const LAS bf16x8*)(lds + PG8_SA(b, h) + aoff + m * 2048 + k * 1024); } while (0)
; #define PG8_LDB(dst, b, h) do { _Pragma("unroll") for (int n = 0; n < 2; ++n) _Pragma("unroll") for (int k = 0; k < 2; ++k) dst[n][k] = *(const LAS bf16x8*)(lds + PG8_SB(b, h) + boff + n * 2048 + k * 1024); } while (0)
; #define PG8_MMA(ai, bj, At, Bt) do { __builtin_amdgcn_s_setprio(1); _Pragma("unroll") for (int m = 0; m < 4; ++m) _Pragma("unroll") for (int n = 0; n < 2; ++n) _Pragma("unroll") for (int k = 0; k < 2; ++k) \
;         acc[ai][bj][m][n] = MmaOp<Epi::I8>::run(Bt[n][k], At[m][k], acc[ai][bj][m][n]); __builtin_amdgcn_s_setprio(0); } while (0)
; #define PG8_WAIT_L(n) asm volatile("s_waitcnt lgkmcnt(" #n ")" ::: "memory")
; #define PG8_BAR __builtin_amdgcn_s_barrier()
; #define PG8_SCHED __builtin_amdgcn_sched_barrier(0)
; template <class Epi, class Sched>
; __device__ __forceinline__ void gemm_phase(LAS unsigned char* lds, const Gemm g, const Sched& S, const Epi& E) {
;     ...
;             PG8_LDB(B0, 0, 0); PG8_SCHED; PG8_LDA(At, 0, 0); PG8_STAGE(PG8_SA(1, 1), a1 + hstepA, voffA);
;             PG8_WAIT_L(8); PG8_BAR; PG8_WAIT_L(0); PG8_MMA(0, 0, At, B0); PG8_BAR; PG8_SCHED;
;             PG8_LDB(B1, 0, 1); PG8_STAGE(PG8_SB(0, 0), b2, voffB);
;             PG8_BAR; PG8_WAIT_L(0); PG8_MMA(0, 1, At, B1); PG8_BAR;
;             PG8_LDA(At, 0, 1); PG8_STAGE(PG8_SA(0, 0), a2, voffA);
;             PG8_BAR; PG8_WAIT_L(0); PG8_MMA(1, 0, At, B0); PG8_BAR; PG8_SCHED;
.LBB0_865:
	ds_read_b128 v[154:157], v149
	ds_read_b128 v[158:161], v149 offset:1024
	ds_read_b128 v[162:165], v149 offset:2048
	ds_read_b128 v[166:169], v149 offset:3072
	s_add_u32 s20, s18, 0xfff80080
	s_addc_u32 s21, s19, -1
	s_cmp_eq_u32 s44, 28
	s_cselect_b32 s23, s11, s21
	s_cselect_b32 s22, s40, s20
	s_cselect_b32 s21, s9, s43
	s_cselect_b32 s20, s41, s42
	v_lshl_add_u64 v[144:145], s[18:19], 0, v[136:137]
	s_add_i32 m0, s17, 0xc000
	ds_read_b128 v[170:173], v150
	ds_read_b128 v[178:181], v150 offset:1024
	ds_read_b128 v[182:185], v150 offset:2048
	ds_read_b128 v[186:189], v150 offset:3072
	ds_read_b128 v[190:193], v150 offset:4096
	ds_read_b128 v[194:197], v150 offset:5120
	ds_read_b128 v[198:201], v150 offset:6144
	ds_read_b128 v[202:205], v150 offset:7168
	global_load_lds_dwordx4 v[144:145], off
	v_lshl_add_u64 v[144:145], s[18:19], 0, v[138:139]
	s_add_i32 m0, s17, 0xe000
	s_nop 0
	global_load_lds_dwordx4 v[144:145], off
	s_waitcnt lgkmcnt(8)
	s_barrier
	s_waitcnt lgkmcnt(0)
	s_setprio 1
	v_mfma_f32_16x16x32_bf16 v[116:119], v[154:157], v[170:173], v[116:119]
	v_mfma_f32_16x16x32_bf16 v[112:115], v[162:165], v[170:173], v[112:115]
	v_mfma_f32_16x16x32_bf16 v[108:111], v[154:157], v[182:185], v[108:111]
	v_mfma_f32_16x16x32_bf16 v[100:103], v[162:165], v[182:185], v[100:103]
	v_mfma_f32_16x16x32_bf16 v[92:95], v[154:157], v[190:193], v[92:95]
	v_mfma_f32_16x16x32_bf16 v[84:87], v[162:165], v[190:193], v[84:87]
	v_mfma_f32_16x16x32_bf16 v[76:79], v[154:157], v[198:201], v[76:79]
	v_mfma_f32_16x16x32_bf16 v[68:71], v[162:165], v[198:201], v[68:71]
	v_mfma_f32_16x16x32_bf16 v[116:119], v[158:161], v[178:181], v[116:119]
	v_mfma_f32_16x16x32_bf16 v[112:115], v[166:169], v[178:181], v[112:115]
	v_mfma_f32_16x16x32_bf16 v[108:111], v[158:161], v[186:189], v[108:111]
	v_mfma_f32_16x16x32_bf16 v[100:103], v[166:169], v[186:189], v[100:103]
	v_mfma_f32_16x16x32_bf16 v[92:95], v[158:161], v[194:197], v[92:95]
	v_mfma_f32_16x16x32_bf16 v[84:87], v[166:169], v[194:197], v[84:87]
	v_mfma_f32_16x16x32_bf16 v[76:79], v[158:161], v[202:205], v[76:79]
	v_mfma_f32_16x16x32_bf16 v[68:71], v[166:169], v[202:205], v[68:71]
	s_setprio 0
	s_barrier
	s_add_i32 s45, s36, s25
	v_lshl_add_u64 v[144:145], s[20:21], 0, v[132:133]
	s_mov_b32 m0, s45
	ds_read_b128 v[206:209], v151
	ds_read_b128 v[210:213], v151 offset:1024
	ds_read_b128 v[214:217], v151 offset:2048
	ds_read_b128 v[218:221], v151 offset:3072
	global_load_lds_dwordx4 v[144:145], off
	v_lshl_add_u64 v[174:175], s[20:21], 0, v[128:129]
	s_add_i32 m0, s45, 0x2000
	s_nop 0
	global_load_lds_dwordx4 v[174:175], off
	s_barrier
	s_waitcnt lgkmcnt(0)
	s_setprio 1
	v_mfma_f32_16x16x32_bf16 v[124:127], v[206:209], v[170:173], v[124:127]
	v_mfma_f32_16x16x32_bf16 v[120:123], v[214:217], v[170:173], v[120:123]
	v_mfma_f32_16x16x32_bf16 v[104:107], v[206:209], v[182:185], v[104:107]
	v_mfma_f32_16x16x32_bf16 v[96:99], v[214:217], v[182:185], v[96:99]
	v_mfma_f32_16x16x32_bf16 v[88:91], v[206:209], v[190:193], v[88:91]
	v_mfma_f32_16x16x32_bf16 v[80:83], v[214:217], v[190:193], v[80:83]
	v_mfma_f32_16x16x32_bf16 v[72:75], v[206:209], v[198:201], v[72:75]
	v_mfma_f32_16x16x32_bf16 v[64:67], v[214:217], v[198:201], v[64:67]
	v_mfma_f32_16x16x32_bf16 v[124:127], v[210:213], v[178:181], v[124:127]
	v_mfma_f32_16x16x32_bf16 v[120:123], v[218:221], v[178:181], v[120:123]
	v_mfma_f32_16x16x32_bf16 v[104:107], v[210:213], v[186:189], v[104:107]
	v_mfma_f32_16x16x32_bf16 v[96:99], v[218:221], v[186:189], v[96:99]
	v_mfma_f32_16x16x32_bf16 v[88:91], v[210:213], v[194:197], v[88:91]
	v_mfma_f32_16x16x32_bf16 v[80:83], v[218:221], v[194:197], v[80:83]
	v_mfma_f32_16x16x32_bf16 v[72:75], v[210:213], v[202:205], v[72:75]
	v_mfma_f32_16x16x32_bf16 v[64:67], v[218:221], v[202:205], v[64:67]
	s_setprio 0
	s_mov_b32 m0, s17
	v_lshl_add_u64 v[222:223], s[22:23], 0, v[134:135]
	s_barrier
	ds_read_b128 v[170:173], v150 offset:16384
	ds_read_b128 v[178:181], v150 offset:17408
	ds_read_b128 v[182:185], v150 offset:18432
	ds_read_b128 v[186:189], v150 offset:19456
	ds_read_b128 v[190:193], v150 offset:20480
	ds_read_b128 v[194:197], v150 offset:21504
	ds_read_b128 v[198:201], v150 offset:22528
	ds_read_b128 v[202:205], v150 offset:23552
	global_load_lds_dwordx4 v[222:223], off
	v_lshl_add_u64 v[224:225], s[22:23], 0, v[130:131]
	s_mov_b32 m0, s28
	s_nop 0
	global_load_lds_dwordx4 v[224:225], off
	s_barrier
	s_waitcnt lgkmcnt(0)
	s_setprio 1
	v_mfma_f32_16x16x32_bf16 v[60:63], v[154:157], v[170:173], v[60:63]
	v_mfma_f32_16x16x32_bf16 v[52:55], v[162:165], v[170:173], v[52:55]
	v_mfma_f32_16x16x32_bf16 v[44:47], v[154:157], v[182:185], v[44:47]
	v_mfma_f32_16x16x32_bf16 v[36:39], v[162:165], v[182:185], v[36:39]
	v_mfma_f32_16x16x32_bf16 v[28:31], v[154:157], v[190:193], v[28:31]
	v_mfma_f32_16x16x32_bf16 v[20:23], v[162:165], v[190:193], v[20:23]
	v_mfma_f32_16x16x32_bf16 v[12:15], v[154:157], v[198:201], v[12:15]
	v_mfma_f32_16x16x32_bf16 v[4:7], v[162:165], v[198:201], v[4:7]
	v_mfma_f32_16x16x32_bf16 v[60:63], v[158:161], v[178:181], v[60:63]
	v_mfma_f32_16x16x32_bf16 v[52:55], v[166:169], v[178:181], v[52:55]
	v_mfma_f32_16x16x32_bf16 v[44:47], v[158:161], v[186:189], v[44:47]
	v_mfma_f32_16x16x32_bf16 v[36:39], v[166:169], v[186:189], v[36:39]
	v_mfma_f32_16x16x32_bf16 v[28:31], v[158:161], v[194:197], v[28:31]
	v_mfma_f32_16x16x32_bf16 v[20:23], v[166:169], v[194:197], v[20:23]
	v_mfma_f32_16x16x32_bf16 v[12:15], v[158:161], v[202:205], v[12:15]
	v_mfma_f32_16x16x32_bf16 v[4:7], v[166:169], v[202:205], v[4:7]
	s_setprio 0
	s_barrier
; #define PG8_STAGE(bufoff, gbase, voff) do { _Pragma("unroll") for (int _i = 0; _i < 2; ++_i) \
;         __builtin_amdgcn_global_load_lds((const unsigned*)((const char*)(gbase) + (voff)[_i]), (LAS unsigned*)(lds + (bufoff) + ldsw + _i * 8192), 16, 0, 0); } while (0)
; #define PG8_LDA(dst, b, h) do { _Pragma("unroll") for (int m = 0; m < 4; ++m) _Pragma("unroll") for (int k = 0; k < 2; ++k) dst[m][k] = *(const LAS bf16x8*)(lds + PG8_SA(b, h) + aoff + m * 2048 + k * 1024); } while (0)
; #define PG8_LDB(dst, b, h) do { _Pragma("unroll") for (int n = 0; n < 2; ++n) _Pragma("unroll") for (int k = 0; k < 2; ++k) dst[n][k] = *(const LAS bf16x8*)(lds + PG8_SB(b, h) + boff + n * 2048 + k * 1024); } while (0)
; #define PG8_MMA(ai, bj, At, Bt) do { __builtin_amdgcn_s_setprio(1); _Pragma("unroll") for (int m = 0; m < 4; ++m) _Pragma("unroll") for (int n = 0; n < 2; ++n) _Pragma("unroll") for (int k = 0; k < 2; ++k) \
;         acc[ai][bj][m][n] = MmaOp<Epi::I8>::run(Bt[n][k], At[m][k], acc[ai][bj][m][n]); __builtin_amdgcn_s_setprio(0); } while (0)
; #define PG8_WAIT_V(n) asm volatile("s_waitcnt vmcnt(" #n ")" ::: "memory")
; #define PG8_WAIT_L(n) asm volatile("s_waitcnt lgkmcnt(" #n ")" ::: "memory")
; #define PG8_BAR __builtin_amdgcn_s_barrier()
; #define PG8_SCHED __builtin_amdgcn_sched_barrier(0)
; template <class Epi, class Sched>
; __device__ __forceinline__ void gemm_phase(LAS unsigned char* lds, const Gemm g, const Sched& S, const Epi& E) {
;     ...
;             PG8_STAGE(PG8_SB(0, 1), b2 + hstepB, voffB);
;             PG8_WAIT_V(6); PG8_BAR; PG8_MMA(1, 1, At, B1); PG8_BAR;
;             PG8_LDB(B0, 1, 0); PG8_SCHED; PG8_LDA(At, 1, 0); PG8_STAGE(PG8_SA(0, 1), a2 + hstepA, voffA);
;             PG8_WAIT_L(8); PG8_BAR; PG8_WAIT_L(0); PG8_MMA(0, 0, At, B0); PG8_BAR; PG8_SCHED;
;             PG8_LDB(B1, 1, 1); PG8_STAGE(PG8_SB(1, 0), b3, voffB);
;             PG8_BAR; PG8_WAIT_L(0); PG8_MMA(0, 1, At, B1); PG8_BAR;
;             PG8_LDA(At, 1, 1); PG8_STAGE(PG8_SA(1, 0), a3, voffA);
	s_add_u32 s46, s20, 0x80000
	s_addc_u32 s47, s21, 0
	s_add_i32 s45, s37, s25
	v_lshl_add_u64 v[154:155], s[46:47], 0, v[132:133]
	s_mov_b32 m0, s45
	s_nop 0
	global_load_lds_dwordx4 v[154:155], off
	v_lshl_add_u64 v[154:155], s[46:47], 0, v[128:129]
	s_add_i32 m0, s45, 0x2000
	s_nop 0
	global_load_lds_dwordx4 v[154:155], off
	s_waitcnt vmcnt(6)
	s_barrier
	s_setprio 1
	v_mfma_f32_16x16x32_bf16 v[56:59], v[206:209], v[170:173], v[56:59]
	v_mfma_f32_16x16x32_bf16 v[48:51], v[214:217], v[170:173], v[48:51]
	v_mfma_f32_16x16x32_bf16 v[40:43], v[206:209], v[182:185], v[40:43]
	v_mfma_f32_16x16x32_bf16 v[32:35], v[214:217], v[182:185], v[32:35]
	v_mfma_f32_16x16x32_bf16 v[24:27], v[206:209], v[190:193], v[24:27]
	v_mfma_f32_16x16x32_bf16 v[16:19], v[214:217], v[190:193], v[16:19]
	v_mfma_f32_16x16x32_bf16 v[8:11], v[206:209], v[198:201], v[8:11]
	v_mfma_f32_16x16x32_bf16 v[0:3], v[214:217], v[198:201], v[0:3]
	v_mfma_f32_16x16x32_bf16 v[56:59], v[210:213], v[178:181], v[56:59]
	v_mfma_f32_16x16x32_bf16 v[48:51], v[218:221], v[178:181], v[48:51]
	v_mfma_f32_16x16x32_bf16 v[40:43], v[210:213], v[186:189], v[40:43]
	v_mfma_f32_16x16x32_bf16 v[32:35], v[218:221], v[186:189], v[32:35]
	v_mfma_f32_16x16x32_bf16 v[24:27], v[210:213], v[194:197], v[24:27]
	v_mfma_f32_16x16x32_bf16 v[16:19], v[218:221], v[194:197], v[16:19]
	v_mfma_f32_16x16x32_bf16 v[8:11], v[210:213], v[202:205], v[8:11]
	v_mfma_f32_16x16x32_bf16 v[0:3], v[218:221], v[202:205], v[0:3]
	s_setprio 0
	s_add_i32 s45, 0, 0x18000
	v_add_u32_e32 v153, s45, v147
	s_barrier
	ds_read_b128 v[154:157], v153
	ds_read_b128 v[158:161], v153 offset:1024
	ds_read_b128 v[162:165], v153 offset:2048
	ds_read_b128 v[166:169], v153 offset:3072
	s_add_u32 s22, s22, 0x80000
	s_addc_u32 s23, s23, 0
	s_mov_b32 m0, s29
	v_lshl_add_u64 v[206:207], s[22:23], 0, v[134:135]
	ds_read_b128 v[170:173], v150 offset:32768
	ds_read_b128 v[178:181], v150 offset:33792
	ds_read_b128 v[182:185], v150 offset:34816
	ds_read_b128 v[186:189], v150 offset:35840
	ds_read_b128 v[190:193], v150 offset:36864
	ds_read_b128 v[194:197], v150 offset:37888
	ds_read_b128 v[198:201], v150 offset:38912
	ds_read_b128 v[202:205], v150 offset:39936
	global_load_lds_dwordx4 v[206:207], off
	v_lshl_add_u64 v[206:207], s[22:23], 0, v[130:131]
	s_mov_b32 m0, s30
	s_nop 0
	global_load_lds_dwordx4 v[206:207], off
	s_waitcnt lgkmcnt(8)
	s_barrier
	s_waitcnt lgkmcnt(0)
	s_setprio 1
	v_mfma_f32_16x16x32_bf16 v[116:119], v[154:157], v[170:173], v[116:119]
	v_mfma_f32_16x16x32_bf16 v[112:115], v[162:165], v[170:173], v[112:115]
	v_mfma_f32_16x16x32_bf16 v[108:111], v[154:157], v[182:185], v[108:111]
	v_mfma_f32_16x16x32_bf16 v[100:103], v[162:165], v[182:185], v[100:103]
	v_mfma_f32_16x16x32_bf16 v[92:95], v[154:157], v[190:193], v[92:95]
	v_mfma_f32_16x16x32_bf16 v[84:87], v[162:165], v[190:193], v[84:87]
	v_mfma_f32_16x16x32_bf16 v[76:79], v[154:157], v[198:201], v[76:79]
	v_mfma_f32_16x16x32_bf16 v[68:71], v[162:165], v[198:201], v[68:71]
	v_mfma_f32_16x16x32_bf16 v[116:119], v[158:161], v[178:181], v[116:119]
	v_mfma_f32_16x16x32_bf16 v[112:115], v[166:169], v[178:181], v[112:115]
	v_mfma_f32_16x16x32_bf16 v[108:111], v[158:161], v[186:189], v[108:111]
	v_mfma_f32_16x16x32_bf16 v[100:103], v[166:169], v[186:189], v[100:103]
	v_mfma_f32_16x16x32_bf16 v[92:95], v[158:161], v[194:197], v[92:95]
	v_mfma_f32_16x16x32_bf16 v[84:87], v[166:169], v[194:197], v[84:87]
	v_mfma_f32_16x16x32_bf16 v[76:79], v[158:161], v[202:205], v[76:79]
	v_mfma_f32_16x16x32_bf16 v[68:71], v[166:169], v[202:205], v[68:71]
	s_setprio 0
	s_barrier
	s_add_i32 s22, 0, 0x1c000
	s_add_i32 s23, s45, s25
	v_add_u32_e32 v153, s22, v147
	v_lshl_add_u64 v[144:145], v[144:145], 0, s[6:7]
	s_mov_b32 m0, s23
	ds_read_b128 v[206:209], v153
	ds_read_b128 v[210:213], v153 offset:1024
	ds_read_b128 v[214:217], v153 offset:2048
	ds_read_b128 v[218:221], v153 offset:3072
	global_load_lds_dwordx4 v[144:145], off
	v_lshl_add_u64 v[144:145], v[174:175], 0, s[6:7]
	s_add_i32 m0, s23, 0x2000
	s_nop 0
	global_load_lds_dwordx4 v[144:145], off
	s_barrier
	s_waitcnt lgkmcnt(0)
	s_setprio 1
	v_mfma_f32_16x16x32_bf16 v[124:127], v[206:209], v[170:173], v[124:127]
	v_mfma_f32_16x16x32_bf16 v[120:123], v[214:217], v[170:173], v[120:123]
	v_mfma_f32_16x16x32_bf16 v[104:107], v[206:209], v[182:185], v[104:107]
	v_mfma_f32_16x16x32_bf16 v[96:99], v[214:217], v[182:185], v[96:99]
	v_mfma_f32_16x16x32_bf16 v[88:91], v[206:209], v[190:193], v[88:91]
	v_mfma_f32_16x16x32_bf16 v[80:83], v[214:217], v[190:193], v[80:83]
	v_mfma_f32_16x16x32_bf16 v[72:75], v[206:209], v[198:201], v[72:75]
	v_mfma_f32_16x16x32_bf16 v[64:67], v[214:217], v[198:201], v[64:67]
	v_mfma_f32_16x16x32_bf16 v[124:127], v[210:213], v[178:181], v[124:127]
	v_mfma_f32_16x16x32_bf16 v[120:123], v[218:221], v[178:181], v[120:123]
	v_mfma_f32_16x16x32_bf16 v[104:107], v[210:213], v[186:189], v[104:107]
	v_mfma_f32_16x16x32_bf16 v[96:99], v[218:221], v[186:189], v[96:99]
	v_mfma_f32_16x16x32_bf16 v[88:91], v[210:213], v[194:197], v[88:91]
	v_mfma_f32_16x16x32_bf16 v[80:83], v[218:221], v[194:197], v[80:83]
	v_mfma_f32_16x16x32_bf16 v[72:75], v[210:213], v[202:205], v[72:75]
	v_mfma_f32_16x16x32_bf16 v[64:67], v[218:221], v[202:205], v[64:67]
	s_setprio 0
	s_mov_b32 m0, s33
	v_lshl_add_u64 v[144:145], v[222:223], 0, s[6:7]
	s_barrier
	ds_read_b128 v[170:173], v150 offset:49152
	ds_read_b128 v[178:181], v150 offset:50176
	ds_read_b128 v[182:185], v150 offset:51200
	ds_read_b128 v[186:189], v150 offset:52224
	ds_read_b128 v[190:193], v150 offset:53248
	ds_read_b128 v[194:197], v150 offset:54272
	ds_read_b128 v[198:201], v150 offset:55296
	ds_read_b128 v[202:205], v150 offset:56320
	global_load_lds_dwordx4 v[144:145], off
	v_lshl_add_u64 v[144:145], v[224:225], 0, s[6:7]
	s_mov_b32 m0, s34
	s_nop 0
	global_load_lds_dwordx4 v[144:145], off
	s_barrier
; __device__ __forceinline__ unsigned cvt_pk_bf16(float lo, float hi) { unsigned r; asm volatile("v_cvt_pk_bf16_f32 %0, %1, %2" : "=v"(r) : "v"(lo), "v"(hi)); return r; }
; __device__ __forceinline__ float ld_agent(const float* p) { return __hip_atomic_load(p, __ATOMIC_RELAXED, __HIP_MEMORY_SCOPE_AGENT); }
; __device__ __forceinline__ float sigm(float x) { return __builtin_amdgcn_rcpf(1.f + __builtin_amdgcn_exp2f(-LOG2E * x)); }
; #define PG8_STAGE(bufoff, gbase, voff) do { _Pragma("unroll") for (int _i = 0; _i < 2; ++_i) \
;         __builtin_amdgcn_global_load_lds((const unsigned*)((const char*)(gbase) + (voff)[_i]), (LAS unsigned*)(lds + (bufoff) + ldsw + _i * 8192), 16, 0, 0); } while (0)
; #define PG8_WAIT_V(n) asm volatile("s_waitcnt vmcnt(" #n ")" ::: "memory")
; #define PG8_WAIT_L(n) asm volatile("s_waitcnt lgkmcnt(" #n ")" ::: "memory")
; #define PG8_BAR __builtin_amdgcn_s_barrier()
;     __device__ __forceinline__ void operator()(const f32x4 (&acc)[2][2][4][2], const Unit& u, int wr, int wc, int fr, int fq) const {
;         const int row0 = u.pm * BM + wr * 64 + fr, col0 = u.pn * HALF + wc * 32 + 8 * fq;
;         float sq[8];
; #pragma unroll
;         for (int g = 0; g < 8; ++g) sq[g] = ld_agent(ssq + row0 + (g >> 2) * HALF + (g & 3) * 16);
; #pragma unroll
;         for (int ai = 0; ai < 2; ++ai)
; #pragma unroll
;             for (int m = 0; m < 4; ++m) {
;                 const int r = row0 + ai * HALF + m * 16; const float rs = __builtin_amdgcn_rsqf(sq[ai * 4 + m] * (1.f / 2048.f) + EPS);
;                 float v[8];
; #pragma unroll
;                 for (int n = 0; n < 2; ++n)
; #pragma unroll
;                     for (int j = 0; j < 4; ++j) { const float g = acc[ai][0][m][n][j] * rs, up = acc[ai][1][m][n][j] * rs; v[n * 4 + j] = g * sigm(g) * up; }
;                 u32x4 w; w.x = cvt_pk_bf16(v[0], v[1]); w.y = cvt_pk_bf16(v[2], v[3]); w.z = cvt_pk_bf16(v[4], v[5]); w.w = cvt_pk_bf16(v[6], v[7]);
;                 *(u32x4*)(O + (size_t)r * FF + col0) = w;
; template <class Epi, class Sched>
; __device__ __forceinline__ void gemm_phase(LAS unsigned char* lds, const Gemm g, const Sched& S, const Epi& E) {
;     ...
;             PG8_BAR; PG8_WAIT_L(0); PG8_MMA(1, 0, At, B0); PG8_BAR; PG8_SCHED;
;             PG8_STAGE(PG8_SB(1, 1), b3 + hstepB, voffB);
;             PG8_WAIT_V(6); PG8_BAR; PG8_MMA(1, 1, At, B1); PG8_BAR;
	s_waitcnt lgkmcnt(0)
	s_setprio 1
	v_mfma_f32_16x16x32_bf16 v[60:63], v[154:157], v[170:173], v[60:63]
	v_mfma_f32_16x16x32_bf16 v[52:55], v[162:165], v[170:173], v[52:55]
	v_mfma_f32_16x16x32_bf16 v[44:47], v[154:157], v[182:185], v[44:47]
	v_mfma_f32_16x16x32_bf16 v[36:39], v[162:165], v[182:185], v[36:39]
	v_mfma_f32_16x16x32_bf16 v[28:31], v[154:157], v[190:193], v[28:31]
	v_mfma_f32_16x16x32_bf16 v[20:23], v[162:165], v[190:193], v[20:23]
	v_mfma_f32_16x16x32_bf16 v[12:15], v[154:157], v[198:201], v[12:15]
	v_mfma_f32_16x16x32_bf16 v[4:7], v[162:165], v[198:201], v[4:7]
	v_mfma_f32_16x16x32_bf16 v[60:63], v[158:161], v[178:181], v[60:63]
	v_mfma_f32_16x16x32_bf16 v[52:55], v[166:169], v[178:181], v[52:55]
	v_mfma_f32_16x16x32_bf16 v[44:47], v[158:161], v[186:189], v[44:47]
	v_mfma_f32_16x16x32_bf16 v[36:39], v[166:169], v[186:189], v[36:39]
	v_mfma_f32_16x16x32_bf16 v[28:31], v[158:161], v[194:197], v[28:31]
	v_mfma_f32_16x16x32_bf16 v[20:23], v[166:169], v[194:197], v[20:23]
	v_mfma_f32_16x16x32_bf16 v[12:15], v[158:161], v[202:205], v[12:15]
	v_mfma_f32_16x16x32_bf16 v[4:7], v[166:169], v[202:205], v[4:7]
	s_setprio 0
	s_barrier
	s_add_u32 s20, s20, 0x80080
	s_addc_u32 s21, s21, 0
	s_add_i32 s22, s22, s25
	v_lshl_add_u64 v[144:145], s[20:21], 0, v[132:133]
	s_mov_b32 m0, s22
	s_nop 0
	global_load_lds_dwordx4 v[144:145], off
	v_lshl_add_u64 v[144:145], s[20:21], 0, v[128:129]
	s_add_i32 m0, s22, 0x2000
	s_nop 0
	global_load_lds_dwordx4 v[144:145], off
	s_waitcnt vmcnt(6)
	s_barrier
	s_setprio 1
	v_mfma_f32_16x16x32_bf16 v[56:59], v[206:209], v[170:173], v[56:59]
	v_mfma_f32_16x16x32_bf16 v[48:51], v[214:217], v[170:173], v[48:51]
	v_mfma_f32_16x16x32_bf16 v[40:43], v[206:209], v[182:185], v[40:43]
	v_mfma_f32_16x16x32_bf16 v[32:35], v[214:217], v[182:185], v[32:35]
	v_mfma_f32_16x16x32_bf16 v[24:27], v[206:209], v[190:193], v[24:27]
	v_mfma_f32_16x16x32_bf16 v[16:19], v[214:217], v[190:193], v[16:19]
	v_mfma_f32_16x16x32_bf16 v[8:11], v[206:209], v[198:201], v[8:11]
	v_mfma_f32_16x16x32_bf16 v[0:3], v[214:217], v[198:201], v[0:3]
	v_mfma_f32_16x16x32_bf16 v[56:59], v[210:213], v[178:181], v[56:59]
	v_mfma_f32_16x16x32_bf16 v[48:51], v[218:221], v[178:181], v[48:51]
	v_mfma_f32_16x16x32_bf16 v[40:43], v[210:213], v[186:189], v[40:43]
	v_mfma_f32_16x16x32_bf16 v[32:35], v[218:221], v[186:189], v[32:35]
	v_mfma_f32_16x16x32_bf16 v[24:27], v[210:213], v[194:197], v[24:27]
	v_mfma_f32_16x16x32_bf16 v[16:19], v[218:221], v[194:197], v[16:19]
	v_mfma_f32_16x16x32_bf16 v[8:11], v[210:213], v[202:205], v[8:11]
	v_mfma_f32_16x16x32_bf16 v[0:3], v[218:221], v[202:205], v[0:3]
	s_setprio 0
	s_add_i32 s44, s44, 2
	s_add_u32 s18, s18, 0x100
	s_addc_u32 s19, s19, 0
	s_add_u32 s42, s42, 0x100
	s_addc_u32 s43, s43, 0
	s_cmp_gt_u32 s44, 29
	s_barrier
	s_cbranch_scc0 .LBB0_865
	v_lshl_add_u32 v144, s16, 8, v146
	v_ashrrev_i32_e32 v145, 31, v144
	v_lshl_add_u64 v[154:155], v[144:145], 2, s[2:3]
	global_load_dword v145, v[154:155], off sc1
	global_load_dword v153, v[154:155], off offset:64 sc1
	v_mov_b32_e32 v158, v124
	v_mov_b32_e32 v159, v116
	v_mov_b32_e32 v116, v125
	v_mov_b32_e32 v163, v114
	v_mov_b32_e32 v114, v123
	global_load_dword v125, v[154:155], off offset:128 sc1
	global_load_dword v168, v[154:155], off offset:192 sc1
	global_load_dword v169, v[154:155], off offset:512 sc1
	global_load_dword v124, v[154:155], off offset:576 sc1
	global_load_dword v123, v[154:155], off offset:640 sc1
	global_load_dword v190, v[154:155], off offset:704 sc1
	v_lshl_or_b32 v156, s39, 7, v148
	v_mov_b32_e32 v162, v122
	v_ashrrev_i32_e32 v157, 31, v156
	v_mov_b32_e32 v164, v104
	v_mov_b32_e32 v165, v108
	v_mov_b32_e32 v108, v105
	v_lshlrev_b64 v[104:105], 1, v[156:157]
	v_mov_b32_e32 v161, v118
	v_mov_b32_e32 v118, v127
	v_mov_b32_e32 v160, v126
	v_mov_b32_e32 v126, v120
	v_mov_b32_e32 v127, v112
	v_mov_b32_e32 v112, v121
	v_mov_b64_e32 v[120:121], s[54:55]
	v_mad_i64_i32 v[166:167], s[18:19], v144, s38, v[120:121]
	s_and_b64 vcc, exec, s[0:1]
	s_mov_b32 s39, s8
	s_mov_b32 s16, s10
	s_mov_b64 s[20:21], s[14:15]
	s_waitcnt vmcnt(0)
	v_fmamk_f32 v122, v145, 0x3a000000, v152
	v_rsq_f32_e32 v156, v122
	v_fmamk_f32 v145, v153, 0x3a000000, v152
	v_rsq_f32_e32 v154, v145
	v_pk_mul_f32 v[118:119], v[118:119], v[156:157] op_sel_hi:[1,0]
	v_pk_mul_f32 v[158:159], v[158:159], v[156:157] op_sel_hi:[1,0]
	v_pk_mul_f32 v[116:117], v[116:117], v[156:157] op_sel_hi:[1,0]
	v_pk_mul_f32 v[160:161], v[160:161], v[156:157] op_sel_hi:[1,0]
	v_pk_mul_f32 v[126:127], v[126:127], v[156:157] op_sel_hi:[1,0]
	v_pk_mul_f32 v[112:113], v[112:113], v[156:157] op_sel_hi:[1,0]
	v_pk_mul_f32 v[162:163], v[162:163], v[156:157] op_sel_hi:[1,0]
	v_pk_mul_f32 v[114:115], v[114:115], v[156:157] op_sel_hi:[1,0]
	v_pk_mul_f32 v[156:157], v[164:165], v[154:155] op_sel_hi:[1,0]
	v_mul_f32_e32 v164, 0xbfb8aa3b, v119
	v_pk_mul_f32 v[108:109], v[108:109], v[154:155] op_sel_hi:[1,0]
	v_mul_f32_e32 v145, 0xbfb8aa3b, v159
	v_mul_f32_e32 v153, 0xbfb8aa3b, v117
	v_mul_f32_e32 v155, 0xbfb8aa3b, v161
	v_mul_f32_e32 v165, 0xbfb8aa3b, v127
	v_mul_f32_e32 v170, 0xbfb8aa3b, v113
	v_exp_f32_e32 v164, v164
	v_exp_f32_e32 v145, v145
	v_exp_f32_e32 v153, v153
	v_exp_f32_e32 v155, v155
	v_exp_f32_e32 v165, v165
	v_exp_f32_e32 v170, v170
	v_mul_f32_e32 v172, 0xbfb8aa3b, v115
	v_add_f32_e32 v164, 1.0, v164
	v_mul_f32_e32 v171, 0xbfb8aa3b, v163
	v_exp_f32_e32 v172, v172
	v_add_f32_e32 v145, 1.0, v145
	v_add_f32_e32 v153, 1.0, v153
	v_add_f32_e32 v155, 1.0, v155
	v_add_f32_e32 v165, 1.0, v165
	v_add_f32_e32 v170, 1.0, v170
	v_rcp_f32_e32 v164, v164
	v_mul_f32_e32 v173, 0xbfb8aa3b, v157
	v_exp_f32_e32 v171, v171
; __device__ __forceinline__ unsigned cvt_pk_bf16(float lo, float hi) { unsigned r; asm volatile("v_cvt_pk_bf16_f32 %0, %1, %2" : "=v"(r) : "v"(lo), "v"(hi)); return r; }
; __device__ __forceinline__ float sigm(float x) { return __builtin_amdgcn_rcpf(1.f + __builtin_amdgcn_exp2f(-LOG2E * x)); }
;     __device__ __forceinline__ void operator()(const f32x4 (&acc)[2][2][4][2], const Unit& u, int wr, int wc, int fr, int fq) const {
;     ...
;         for (int ai = 0; ai < 2; ++ai)
; #pragma unroll
;             for (int m = 0; m < 4; ++m) {
;                 const int r = row0 + ai * HALF + m * 16; const float rs = __builtin_amdgcn_rsqf(sq[ai * 4 + m] * (1.f / 2048.f) + EPS);
;                 float v[8];
; #pragma unroll
;                 for (int n = 0; n < 2; ++n)
; #pragma unroll
;                     for (int j = 0; j < 4; ++j) { const float g = acc[ai][0][m][n][j] * rs, up = acc[ai][1][m][n][j] * rs; v[n * 4 + j] = g * sigm(g) * up; }
;                 u32x4 w; w.x = cvt_pk_bf16(v[0], v[1]); w.y = cvt_pk_bf16(v[2], v[3]); w.z = cvt_pk_bf16(v[4], v[5]); w.w = cvt_pk_bf16(v[6], v[7]);
;                 *(u32x4*)(O + (size_t)r * FF + col0) = w;
;             }
	v_rcp_f32_e32 v145, v145
	v_rcp_f32_e32 v153, v153
	v_rcp_f32_e32 v155, v155
	v_rcp_f32_e32 v165, v165
	v_rcp_f32_e32 v170, v170
	v_exp_f32_e32 v173, v173
	v_add_f32_e32 v172, 1.0, v172
	v_mul_f32_e32 v119, v119, v164
	v_add_f32_e32 v171, 1.0, v171
	v_rcp_f32_e32 v172, v172
	v_mul_f32_e32 v145, v159, v145
	v_mul_f32_e32 v117, v117, v153
	v_mul_f32_e32 v153, v161, v155
	v_mul_f32_e32 v127, v127, v165
	v_mul_f32_e32 v113, v113, v170
	v_mul_f32_e32 v118, v118, v119
	v_rcp_f32_e32 v171, v171
	v_mul_f32_e32 v145, v158, v145
	v_mul_f32_e32 v116, v116, v117
	v_mul_f32_e32 v117, v160, v153
	v_mul_f32_e32 v119, v126, v127
	v_mul_f32_e32 v126, v112, v113
	v_cvt_pk_bf16_f32 v112, v145, v116
	v_cvt_pk_bf16_f32 v113, v117, v118
	v_add_f32_e32 v118, 1.0, v173
	v_rcp_f32_e32 v118, v118
	v_mul_f32_e32 v174, 0xbfb8aa3b, v109
	v_mul_f32_e32 v115, v115, v172
	v_exp_f32_e32 v174, v174
	v_mul_f32_e32 v155, v163, v171
	v_mul_f32_e32 v115, v114, v115
	v_lshl_add_u64 v[116:117], v[166:167], 0, v[104:105]
	v_mul_f32_e32 v127, v162, v155
	v_cvt_pk_bf16_f32 v114, v119, v126
	v_cvt_pk_bf16_f32 v115, v127, v115
	global_store_dwordx4 v[116:117], v[112:115], off sc0 sc1
	v_add_f32_e32 v119, 1.0, v174
	v_rcp_f32_e32 v119, v119
	v_mul_f32_e32 v112, v157, v118
	v_mul_f32_e32 v114, v156, v112
	v_mov_b32_e32 v112, v106
	v_mov_b32_e32 v113, v110
	v_pk_mul_f32 v[112:113], v[112:113], v[154:155] op_sel_hi:[1,0]
	v_mov_b32_e32 v110, v107
	v_mul_f32_e32 v106, 0xbfb8aa3b, v113
	v_exp_f32_e32 v115, v106
	v_pk_mul_f32 v[106:107], v[110:111], v[154:155] op_sel_hi:[1,0]
	v_mul_f32_e32 v109, v109, v119
	v_mul_f32_e32 v110, 0xbfb8aa3b, v107
	v_exp_f32_e32 v110, v110
	v_mul_f32_e32 v111, v108, v109
	v_add_f32_e32 v108, 1.0, v115
	v_rcp_f32_e32 v115, v108
	v_add_f32_e32 v108, 1.0, v110
	v_rcp_f32_e32 v110, v108
	v_mov_b32_e32 v108, v96
	v_mov_b32_e32 v109, v100
	v_pk_mul_f32 v[108:109], v[108:109], v[154:155] op_sel_hi:[1,0]
	v_mul_f32_e32 v100, v113, v115
	v_mul_f32_e32 v96, 0xbfb8aa3b, v109
	v_exp_f32_e32 v96, v96
	v_mul_f32_e32 v112, v112, v100
	v_mov_b32_e32 v100, v97
	v_mul_f32_e32 v107, v107, v110
	v_add_f32_e32 v96, 1.0, v96
	v_rcp_f32_e32 v110, v96
	v_pk_mul_f32 v[96:97], v[100:101], v[154:155] op_sel_hi:[1,0]
	v_mul_f32_e32 v106, v106, v107
	v_mul_f32_e32 v100, 0xbfb8aa3b, v97
	v_exp_f32_e32 v100, v100
	v_mul_f32_e32 v101, v109, v110
	v_mul_f32_e32 v107, v108, v101
	v_mov_b32_e32 v101, v102
	v_add_f32_e32 v100, 1.0, v100
	v_rcp_f32_e32 v108, v100
	v_mov_b32_e32 v100, v98
	v_pk_mul_f32 v[100:101], v[100:101], v[154:155] op_sel_hi:[1,0]
	v_mov_b32_e32 v102, v99
	v_mul_f32_e32 v98, 0xbfb8aa3b, v101
	v_exp_f32_e32 v109, v98
	v_pk_mul_f32 v[98:99], v[102:103], v[154:155] op_sel_hi:[1,0]
	v_mul_f32_e32 v97, v97, v108
	v_mul_f32_e32 v102, 0xbfb8aa3b, v99
	v_exp_f32_e32 v102, v102
	v_add_f32_e32 v103, 1.0, v109
	v_rcp_f32_e32 v103, v103
	v_mul_f32_e32 v108, v96, v97
	v_add_f32_e32 v102, 1.0, v102
	v_rcp_f32_e32 v102, v102
	v_mul_f32_e32 v96, v101, v103
	v_mul_f32_e32 v100, v100, v96
	v_or_b32_e32 v101, 16, v144
	v_mul_f32_e32 v96, v99, v102
	v_mul_f32_e32 v99, v98, v96
	v_cvt_pk_bf16_f32 v96, v114, v111
	v_cvt_pk_bf16_f32 v97, v112, v106
	v_cvt_pk_bf16_f32 v98, v107, v108
	v_cvt_pk_bf16_f32 v99, v100, v99
	v_fmamk_f32 v100, v125, 0x3a000000, v152
	v_rsq_f32_e32 v100, v100
	v_mov_b32_e32 v106, v88
	v_mov_b32_e32 v107, v92
	v_mad_i64_i32 v[102:103], s[18:19], v101, s38, v[120:121]
	v_pk_mul_f32 v[106:107], v[106:107], v[100:101] op_sel_hi:[1,0]
	v_mov_b32_e32 v92, v89
	v_mul_f32_e32 v88, 0xbfb8aa3b, v107
	v_exp_f32_e32 v101, v88
	s_nop 0
	v_pk_mul_f32 v[88:89], v[92:93], v[100:101] op_sel_hi:[1,0]
	v_add_f32_e32 v101, 1.0, v101
	v_rcp_f32_e32 v101, v101
	v_mul_f32_e32 v92, 0xbfb8aa3b, v89
	v_exp_f32_e32 v108, v92
	v_lshl_add_u64 v[92:93], v[102:103], 0, v[104:105]
	global_store_dwordx4 v[92:93], v[96:99], off sc0 sc1
	v_mul_f32_e32 v92, v107, v101
	v_mov_b32_e32 v93, v94
	v_mul_f32_e32 v96, v106, v92
	v_mov_b32_e32 v92, v90
	v_pk_mul_f32 v[92:93], v[92:93], v[100:101] op_sel_hi:[1,0]
	v_add_f32_e32 v102, 1.0, v108
	v_mul_f32_e32 v90, 0xbfb8aa3b, v93
	v_mov_b32_e32 v94, v91
	v_rcp_f32_e32 v102, v102
	v_exp_f32_e32 v97, v90
	v_pk_mul_f32 v[90:91], v[94:95], v[100:101] op_sel_hi:[1,0]
	v_mul_f32_e32 v89, v89, v102
	v_mul_f32_e32 v94, 0xbfb8aa3b, v91
	v_exp_f32_e32 v94, v94
	v_mul_f32_e32 v95, v88, v89
	v_add_f32_e32 v88, 1.0, v97
	v_rcp_f32_e32 v97, v88
	v_add_f32_e32 v88, 1.0, v94
	v_rcp_f32_e32 v94, v88
	v_mov_b32_e32 v88, v80
	v_mov_b32_e32 v89, v84
	v_pk_mul_f32 v[88:89], v[88:89], v[100:101] op_sel_hi:[1,0]
	v_mul_f32_e32 v84, v93, v97
	v_mul_f32_e32 v80, 0xbfb8aa3b, v89
	v_exp_f32_e32 v80, v80
	v_mul_f32_e32 v92, v92, v84
	v_mov_b32_e32 v84, v81
	v_mul_f32_e32 v91, v91, v94
	v_add_f32_e32 v80, 1.0, v80
	v_rcp_f32_e32 v93, v80
	v_pk_mul_f32 v[80:81], v[84:85], v[100:101] op_sel_hi:[1,0]
	v_mul_f32_e32 v90, v90, v91
	v_mul_f32_e32 v84, 0xbfb8aa3b, v81
	v_exp_f32_e32 v84, v84
	v_mul_f32_e32 v85, v89, v93
	v_mul_f32_e32 v88, v88, v85
	v_mov_b32_e32 v85, v86
	v_add_f32_e32 v84, 1.0, v84
	v_rcp_f32_e32 v89, v84
	v_mov_b32_e32 v84, v82
	v_pk_mul_f32 v[84:85], v[84:85], v[100:101] op_sel_hi:[1,0]
	v_mov_b32_e32 v86, v83
	v_mul_f32_e32 v82, 0xbfb8aa3b, v85
	v_exp_f32_e32 v91, v82
	v_pk_mul_f32 v[82:83], v[86:87], v[100:101] op_sel_hi:[1,0]
	v_mul_f32_e32 v81, v81, v89
	v_mul_f32_e32 v86, 0xbfb8aa3b, v83
	v_exp_f32_e32 v86, v86
	v_add_f32_e32 v87, 1.0, v91
	v_rcp_f32_e32 v87, v87
	v_mul_f32_e32 v89, v80, v81
	v_add_f32_e32 v86, 1.0, v86
	v_rcp_f32_e32 v86, v86
	v_mul_f32_e32 v80, v85, v87
	v_mul_f32_e32 v84, v84, v80
	v_or_b32_e32 v85, 32, v144
	v_mul_f32_e32 v80, v83, v86
	v_mul_f32_e32 v83, v82, v80
; __device__ __forceinline__ unsigned cvt_pk_bf16(float lo, float hi) { unsigned r; asm volatile("v_cvt_pk_bf16_f32 %0, %1, %2" : "=v"(r) : "v"(lo), "v"(hi)); return r; }
; __device__ __forceinline__ float sigm(float x) { return __builtin_amdgcn_rcpf(1.f + __builtin_amdgcn_exp2f(-LOG2E * x)); }
;     __device__ __forceinline__ void operator()(const f32x4 (&acc)[2][2][4][2], const Unit& u, int wr, int wc, int fr, int fq) const {
;     ...
;         for (int ai = 0; ai < 2; ++ai)
; #pragma unroll
;             for (int m = 0; m < 4; ++m) {
;                 const int r = row0 + ai * HALF + m * 16; const float rs = __builtin_amdgcn_rsqf(sq[ai * 4 + m] * (1.f / 2048.f) + EPS);
;                 float v[8];
; #pragma unroll
;                 for (int n = 0; n < 2; ++n)
; #pragma unroll
;                     for (int j = 0; j < 4; ++j) { const float g = acc[ai][0][m][n][j] * rs, up = acc[ai][1][m][n][j] * rs; v[n * 4 + j] = g * sigm(g) * up; }
;                 u32x4 w; w.x = cvt_pk_bf16(v[0], v[1]); w.y = cvt_pk_bf16(v[2], v[3]); w.z = cvt_pk_bf16(v[4], v[5]); w.w = cvt_pk_bf16(v[6], v[7]);
;                 *(u32x4*)(O + (size_t)r * FF + col0) = w;
;             }
	v_cvt_pk_bf16_f32 v80, v96, v95
	v_cvt_pk_bf16_f32 v81, v92, v90
	v_cvt_pk_bf16_f32 v82, v88, v89
	v_cvt_pk_bf16_f32 v83, v84, v83
	v_fmamk_f32 v84, v168, 0x3a000000, v152
	v_rsq_f32_e32 v84, v84
	v_mov_b32_e32 v88, v72
	v_mov_b32_e32 v89, v76
	v_mad_i64_i32 v[86:87], s[18:19], v85, s38, v[120:121]
	v_pk_mul_f32 v[88:89], v[88:89], v[84:85] op_sel_hi:[1,0]
	v_mov_b32_e32 v76, v73
	v_mul_f32_e32 v72, 0xbfb8aa3b, v89
	v_exp_f32_e32 v85, v72
	s_nop 0
	v_pk_mul_f32 v[72:73], v[76:77], v[84:85] op_sel_hi:[1,0]
	v_add_f32_e32 v85, 1.0, v85
	v_rcp_f32_e32 v85, v85
	v_mul_f32_e32 v76, 0xbfb8aa3b, v73
	v_exp_f32_e32 v90, v76
	v_lshl_add_u64 v[76:77], v[86:87], 0, v[104:105]
	global_store_dwordx4 v[76:77], v[80:83], off sc0 sc1
	v_mul_f32_e32 v76, v89, v85
	v_mov_b32_e32 v77, v78
	v_mul_f32_e32 v80, v88, v76
	v_mov_b32_e32 v76, v74
	v_pk_mul_f32 v[76:77], v[76:77], v[84:85] op_sel_hi:[1,0]
	v_add_f32_e32 v86, 1.0, v90
	v_mul_f32_e32 v74, 0xbfb8aa3b, v77
	v_mov_b32_e32 v78, v75
	v_rcp_f32_e32 v86, v86
	v_exp_f32_e32 v81, v74
	v_pk_mul_f32 v[74:75], v[78:79], v[84:85] op_sel_hi:[1,0]
	v_mul_f32_e32 v73, v73, v86
	v_mul_f32_e32 v78, 0xbfb8aa3b, v75
	v_exp_f32_e32 v78, v78
	v_mul_f32_e32 v79, v72, v73
	v_add_f32_e32 v72, 1.0, v81
	v_rcp_f32_e32 v81, v72
	v_add_f32_e32 v72, 1.0, v78
	v_rcp_f32_e32 v78, v72
	v_mov_b32_e32 v72, v64
	v_mov_b32_e32 v73, v68
	v_pk_mul_f32 v[72:73], v[72:73], v[84:85] op_sel_hi:[1,0]
	v_mul_f32_e32 v68, v77, v81
	v_mul_f32_e32 v64, 0xbfb8aa3b, v73
	v_exp_f32_e32 v64, v64
	v_mul_f32_e32 v76, v76, v68
	v_mov_b32_e32 v68, v65
	v_mul_f32_e32 v75, v75, v78
	v_add_f32_e32 v64, 1.0, v64
	v_rcp_f32_e32 v77, v64
	v_pk_mul_f32 v[64:65], v[68:69], v[84:85] op_sel_hi:[1,0]
	v_mul_f32_e32 v74, v74, v75
	v_mul_f32_e32 v68, 0xbfb8aa3b, v65
	v_exp_f32_e32 v68, v68
	v_mul_f32_e32 v69, v73, v77
	v_mul_f32_e32 v72, v72, v69
	v_mov_b32_e32 v69, v70
	v_add_f32_e32 v68, 1.0, v68
	v_rcp_f32_e32 v73, v68
	v_mov_b32_e32 v68, v66
	v_pk_mul_f32 v[68:69], v[68:69], v[84:85] op_sel_hi:[1,0]
	v_mov_b32_e32 v70, v67
	v_mul_f32_e32 v66, 0xbfb8aa3b, v69
	v_exp_f32_e32 v75, v66
	v_pk_mul_f32 v[66:67], v[70:71], v[84:85] op_sel_hi:[1,0]
	v_mul_f32_e32 v65, v65, v73
	v_mul_f32_e32 v70, 0xbfb8aa3b, v67
	v_exp_f32_e32 v70, v70
	v_add_f32_e32 v71, 1.0, v75
	v_rcp_f32_e32 v71, v71
	v_mul_f32_e32 v73, v64, v65
	v_add_f32_e32 v70, 1.0, v70
	v_rcp_f32_e32 v70, v70
	v_mul_f32_e32 v64, v69, v71
	v_mul_f32_e32 v68, v68, v64
	v_or_b32_e32 v69, 48, v144
	v_mul_f32_e32 v64, v67, v70
	v_fmamk_f32 v70, v169, 0x3a000000, v152
	v_rsq_f32_e32 v70, v70
	v_mul_f32_e32 v67, v66, v64
	v_cvt_pk_bf16_f32 v64, v80, v79
	v_cvt_pk_bf16_f32 v65, v76, v74
	v_cvt_pk_bf16_f32 v66, v72, v73
	v_mov_b32_e32 v72, v56
	v_mov_b32_e32 v73, v60
	v_pk_mul_f32 v[72:73], v[72:73], v[70:71] op_sel_hi:[1,0]
	v_mov_b32_e32 v60, v57
	v_mul_f32_e32 v56, 0xbfb8aa3b, v73
	v_exp_f32_e32 v71, v56
	v_cvt_pk_bf16_f32 v67, v68, v67
	v_mad_i64_i32 v[68:69], s[18:19], v69, s38, v[120:121]
	v_pk_mul_f32 v[56:57], v[60:61], v[70:71] op_sel_hi:[1,0]
	v_add_f32_e32 v61, 1.0, v71
	v_mul_f32_e32 v60, 0xbfb8aa3b, v57
	v_exp_f32_e32 v60, v60
	v_rcp_f32_e32 v61, v61
	v_lshl_add_u64 v[68:69], v[68:69], 0, v[104:105]
	global_store_dwordx4 v[68:69], v[64:67], off sc0 sc1
	v_add_f32_e32 v60, 1.0, v60
	v_rcp_f32_e32 v60, v60
	v_mul_f32_e32 v61, v73, v61
	v_mul_f32_e32 v65, v72, v61
	v_mov_b32_e32 v61, v62
	v_mul_f32_e32 v57, v57, v60
	v_mov_b32_e32 v60, v58
	v_pk_mul_f32 v[60:61], v[60:61], v[70:71] op_sel_hi:[1,0]
	v_mov_b32_e32 v62, v59
	v_mul_f32_e32 v58, 0xbfb8aa3b, v61
	v_exp_f32_e32 v66, v58
	v_pk_mul_f32 v[58:59], v[62:63], v[70:71] op_sel_hi:[1,0]
	v_mul_f32_e32 v63, v56, v57
	v_mul_f32_e32 v62, 0xbfb8aa3b, v59
	v_exp_f32_e32 v62, v62
	v_add_f32_e32 v56, 1.0, v66
	v_rcp_f32_e32 v66, v56
	v_mov_b32_e32 v57, v52
	v_add_f32_e32 v56, 1.0, v62
	v_rcp_f32_e32 v62, v56
	v_mov_b32_e32 v56, v48
	v_pk_mul_f32 v[56:57], v[56:57], v[70:71] op_sel_hi:[1,0]
	v_mul_f32_e32 v52, v61, v66
	v_mul_f32_e32 v48, 0xbfb8aa3b, v57
	v_exp_f32_e32 v48, v48
	v_mul_f32_e32 v60, v60, v52
	v_mov_b32_e32 v52, v49
	v_mul_f32_e32 v59, v59, v62
	v_add_f32_e32 v48, 1.0, v48
	v_rcp_f32_e32 v61, v48
	v_pk_mul_f32 v[48:49], v[52:53], v[70:71] op_sel_hi:[1,0]
	v_mul_f32_e32 v58, v58, v59
	v_mul_f32_e32 v52, 0xbfb8aa3b, v49
	v_exp_f32_e32 v52, v52
	v_mul_f32_e32 v53, v57, v61
	v_mul_f32_e32 v56, v56, v53
	v_mov_b32_e32 v53, v54
	v_add_f32_e32 v52, 1.0, v52
	v_rcp_f32_e32 v57, v52
	v_mov_b32_e32 v52, v50
	v_pk_mul_f32 v[52:53], v[52:53], v[70:71] op_sel_hi:[1,0]
	v_mov_b32_e32 v54, v51
	v_mul_f32_e32 v50, 0xbfb8aa3b, v53
	v_exp_f32_e32 v59, v50
	v_pk_mul_f32 v[50:51], v[54:55], v[70:71] op_sel_hi:[1,0]
	v_mul_f32_e32 v49, v49, v57
	v_mul_f32_e32 v54, 0xbfb8aa3b, v51
	v_exp_f32_e32 v54, v54
	v_add_f32_e32 v55, 1.0, v59
	v_rcp_f32_e32 v55, v55
	v_mul_f32_e32 v57, v48, v49
	v_add_f32_e32 v54, 1.0, v54
	v_rcp_f32_e32 v54, v54
	v_mul_f32_e32 v48, v53, v55
	v_mul_f32_e32 v52, v52, v48
	v_add_u32_e32 v64, 0x80, v144
	v_mul_f32_e32 v48, v51, v54
	v_mul_f32_e32 v51, v50, v48
	v_cvt_pk_bf16_f32 v48, v65, v63
	v_cvt_pk_bf16_f32 v49, v60, v58
	v_cvt_pk_bf16_f32 v50, v56, v57
	v_cvt_pk_bf16_f32 v51, v52, v51
	v_fmamk_f32 v52, v124, 0x3a000000, v152
	v_rsq_f32_e32 v52, v52
	v_mov_b32_e32 v56, v40
	v_mov_b32_e32 v57, v44
	v_mov_b32_e32 v44, v41
	v_pk_mul_f32 v[56:57], v[56:57], v[52:53] op_sel_hi:[1,0]
	v_mad_i64_i32 v[54:55], s[18:19], v64, s38, v[120:121]
	v_mul_f32_e32 v40, 0xbfb8aa3b, v57
	v_exp_f32_e32 v53, v40
	s_nop 0
	v_pk_mul_f32 v[40:41], v[44:45], v[52:53] op_sel_hi:[1,0]
	v_add_f32_e32 v53, 1.0, v53
	v_rcp_f32_e32 v53, v53
	v_mul_f32_e32 v44, 0xbfb8aa3b, v41
; __device__ __forceinline__ unsigned cvt_pk_bf16(float lo, float hi) { unsigned r; asm volatile("v_cvt_pk_bf16_f32 %0, %1, %2" : "=v"(r) : "v"(lo), "v"(hi)); return r; }
; __device__ __forceinline__ float sigm(float x) { return __builtin_amdgcn_rcpf(1.f + __builtin_amdgcn_exp2f(-LOG2E * x)); }
;     __device__ __forceinline__ void operator()(const f32x4 (&acc)[2][2][4][2], const Unit& u, int wr, int wc, int fr, int fq) const {
;     ...
;         for (int ai = 0; ai < 2; ++ai)
; #pragma unroll
;             for (int m = 0; m < 4; ++m) {
;                 const int r = row0 + ai * HALF + m * 16; const float rs = __builtin_amdgcn_rsqf(sq[ai * 4 + m] * (1.f / 2048.f) + EPS);
;                 float v[8];
; #pragma unroll
;                 for (int n = 0; n < 2; ++n)
; #pragma unroll
;                     for (int j = 0; j < 4; ++j) { const float g = acc[ai][0][m][n][j] * rs, up = acc[ai][1][m][n][j] * rs; v[n * 4 + j] = g * sigm(g) * up; }
;                 u32x4 w; w.x = cvt_pk_bf16(v[0], v[1]); w.y = cvt_pk_bf16(v[2], v[3]); w.z = cvt_pk_bf16(v[4], v[5]); w.w = cvt_pk_bf16(v[6], v[7]);
;                 *(u32x4*)(O + (size_t)r * FF + col0) = w;
;             }
	v_exp_f32_e32 v58, v44
	v_lshl_add_u64 v[44:45], v[54:55], 0, v[104:105]
	global_store_dwordx4 v[44:45], v[48:51], off sc0 sc1
	v_mul_f32_e32 v44, v57, v53
	v_mov_b32_e32 v45, v46
	v_mul_f32_e32 v48, v56, v44
	v_mov_b32_e32 v44, v42
	v_pk_mul_f32 v[44:45], v[44:45], v[52:53] op_sel_hi:[1,0]
	v_add_f32_e32 v54, 1.0, v58
	v_mul_f32_e32 v42, 0xbfb8aa3b, v45
	v_mov_b32_e32 v46, v43
	v_rcp_f32_e32 v54, v54
	v_exp_f32_e32 v49, v42
	v_pk_mul_f32 v[42:43], v[46:47], v[52:53] op_sel_hi:[1,0]
	v_mul_f32_e32 v41, v41, v54
	v_mul_f32_e32 v46, 0xbfb8aa3b, v43
	v_exp_f32_e32 v46, v46
	v_mul_f32_e32 v47, v40, v41
	v_add_f32_e32 v40, 1.0, v49
	v_rcp_f32_e32 v49, v40
	v_add_f32_e32 v40, 1.0, v46
	v_rcp_f32_e32 v46, v40
	v_mov_b32_e32 v40, v32
	v_mov_b32_e32 v41, v36
	v_pk_mul_f32 v[40:41], v[40:41], v[52:53] op_sel_hi:[1,0]
	v_mul_f32_e32 v36, v45, v49
	v_mul_f32_e32 v32, 0xbfb8aa3b, v41
	v_exp_f32_e32 v32, v32
	v_mul_f32_e32 v44, v44, v36
	v_mov_b32_e32 v36, v33
	v_mul_f32_e32 v43, v43, v46
	v_add_f32_e32 v32, 1.0, v32
	v_rcp_f32_e32 v45, v32
	v_pk_mul_f32 v[32:33], v[36:37], v[52:53] op_sel_hi:[1,0]
	v_mul_f32_e32 v42, v42, v43
	v_mul_f32_e32 v36, 0xbfb8aa3b, v33
	v_exp_f32_e32 v36, v36
	v_mul_f32_e32 v37, v41, v45
	v_mul_f32_e32 v40, v40, v37
	v_mov_b32_e32 v37, v38
	v_add_f32_e32 v36, 1.0, v36
	v_rcp_f32_e32 v41, v36
	v_mov_b32_e32 v36, v34
	v_pk_mul_f32 v[36:37], v[36:37], v[52:53] op_sel_hi:[1,0]
	v_mov_b32_e32 v38, v35
	v_mul_f32_e32 v34, 0xbfb8aa3b, v37
	v_exp_f32_e32 v43, v34
	v_pk_mul_f32 v[34:35], v[38:39], v[52:53] op_sel_hi:[1,0]
	v_mul_f32_e32 v33, v33, v41
	v_mul_f32_e32 v38, 0xbfb8aa3b, v35
	v_exp_f32_e32 v38, v38
	v_add_f32_e32 v39, 1.0, v43
	v_rcp_f32_e32 v39, v39
	v_mul_f32_e32 v41, v32, v33
	v_add_f32_e32 v38, 1.0, v38
	v_rcp_f32_e32 v38, v38
	v_mul_f32_e32 v32, v37, v39
	v_mul_f32_e32 v36, v36, v32
	v_add_u32_e32 v37, 0x90, v144
	v_mul_f32_e32 v32, v35, v38
	v_mul_f32_e32 v35, v34, v32
	v_cvt_pk_bf16_f32 v32, v48, v47
	v_cvt_pk_bf16_f32 v33, v44, v42
	v_cvt_pk_bf16_f32 v34, v40, v41
	v_cvt_pk_bf16_f32 v35, v36, v35
	v_fmamk_f32 v36, v123, 0x3a000000, v152
	v_rsq_f32_e32 v36, v36
	v_mov_b32_e32 v40, v24
	v_mov_b32_e32 v41, v28
	v_mad_i64_i32 v[38:39], s[18:19], v37, s38, v[120:121]
	v_pk_mul_f32 v[40:41], v[40:41], v[36:37] op_sel_hi:[1,0]
	v_mov_b32_e32 v28, v25
	v_mul_f32_e32 v24, 0xbfb8aa3b, v41
	v_exp_f32_e32 v37, v24
	s_nop 0
	v_pk_mul_f32 v[24:25], v[28:29], v[36:37] op_sel_hi:[1,0]
	v_add_f32_e32 v37, 1.0, v37
	v_rcp_f32_e32 v37, v37
	v_mul_f32_e32 v28, 0xbfb8aa3b, v25
	v_exp_f32_e32 v42, v28
	v_lshl_add_u64 v[28:29], v[38:39], 0, v[104:105]
	global_store_dwordx4 v[28:29], v[32:35], off sc0 sc1
	v_mul_f32_e32 v28, v41, v37
	v_mov_b32_e32 v29, v30
	v_mul_f32_e32 v32, v40, v28
	v_mov_b32_e32 v28, v26
	v_pk_mul_f32 v[28:29], v[28:29], v[36:37] op_sel_hi:[1,0]
	v_add_f32_e32 v38, 1.0, v42
	v_mul_f32_e32 v26, 0xbfb8aa3b, v29
	v_mov_b32_e32 v30, v27
	v_rcp_f32_e32 v38, v38
	v_exp_f32_e32 v33, v26
	v_pk_mul_f32 v[26:27], v[30:31], v[36:37] op_sel_hi:[1,0]
	v_mul_f32_e32 v25, v25, v38
	v_mul_f32_e32 v30, 0xbfb8aa3b, v27
	v_exp_f32_e32 v30, v30
	v_mul_f32_e32 v31, v24, v25
	v_add_f32_e32 v24, 1.0, v33
	v_rcp_f32_e32 v33, v24
	v_add_f32_e32 v24, 1.0, v30
	v_rcp_f32_e32 v30, v24
	v_mov_b32_e32 v24, v16
	v_mov_b32_e32 v25, v20
	v_pk_mul_f32 v[24:25], v[24:25], v[36:37] op_sel_hi:[1,0]
	v_mul_f32_e32 v20, v29, v33
	v_mul_f32_e32 v16, 0xbfb8aa3b, v25
	v_exp_f32_e32 v16, v16
	v_mul_f32_e32 v28, v28, v20
	v_mov_b32_e32 v20, v17
	v_mul_f32_e32 v27, v27, v30
	v_add_f32_e32 v16, 1.0, v16
	v_rcp_f32_e32 v29, v16
	v_pk_mul_f32 v[16:17], v[20:21], v[36:37] op_sel_hi:[1,0]
	v_mul_f32_e32 v26, v26, v27
; __device__ __forceinline__ unsigned cvt_pk_bf16(float lo, float hi) { unsigned r; asm volatile("v_cvt_pk_bf16_f32 %0, %1, %2" : "=v"(r) : "v"(lo), "v"(hi)); return r; }
; __device__ __forceinline__ float sigm(float x) { return __builtin_amdgcn_rcpf(1.f + __builtin_amdgcn_exp2f(-LOG2E * x)); }
; #define PG8_WAIT_V(n) asm volatile("s_waitcnt vmcnt(" #n ")" ::: "memory")
; #define PG8_BAR __builtin_amdgcn_s_barrier()
;     __device__ __forceinline__ void operator()(const f32x4 (&acc)[2][2][4][2], const Unit& u, int wr, int wc, int fr, int fq) const {
;     ...
;         for (int ai = 0; ai < 2; ++ai)
; #pragma unroll
;             for (int m = 0; m < 4; ++m) {
;                 const int r = row0 + ai * HALF + m * 16; const float rs = __builtin_amdgcn_rsqf(sq[ai * 4 + m] * (1.f / 2048.f) + EPS);
;                 float v[8];
; #pragma unroll
;                 for (int n = 0; n < 2; ++n)
; #pragma unroll
;                     for (int j = 0; j < 4; ++j) { const float g = acc[ai][0][m][n][j] * rs, up = acc[ai][1][m][n][j] * rs; v[n * 4 + j] = g * sigm(g) * up; }
;                 u32x4 w; w.x = cvt_pk_bf16(v[0], v[1]); w.y = cvt_pk_bf16(v[2], v[3]); w.z = cvt_pk_bf16(v[4], v[5]); w.w = cvt_pk_bf16(v[6], v[7]);
;                 *(u32x4*)(O + (size_t)r * FF + col0) = w;
;             }
; template <class Epi, class Sched>
; __device__ __forceinline__ void gemm_phase(LAS unsigned char* lds, const Gemm g, const Sched& S, const Epi& E) {
;     ...
;         if (!has_next) break;
;     ...
;     PG8_WAIT_V(0);
;     if (wr == 0) PG8_BAR;
;     PG8_BAR;
	v_mul_f32_e32 v20, 0xbfb8aa3b, v17
	v_exp_f32_e32 v20, v20
	v_mul_f32_e32 v21, v25, v29
	v_mul_f32_e32 v24, v24, v21
	v_mov_b32_e32 v21, v22
	v_add_f32_e32 v20, 1.0, v20
	v_rcp_f32_e32 v25, v20
	v_mov_b32_e32 v20, v18
	v_pk_mul_f32 v[20:21], v[20:21], v[36:37] op_sel_hi:[1,0]
	v_mov_b32_e32 v22, v19
	v_mul_f32_e32 v18, 0xbfb8aa3b, v21
	v_exp_f32_e32 v27, v18
	v_pk_mul_f32 v[18:19], v[22:23], v[36:37] op_sel_hi:[1,0]
	v_mul_f32_e32 v17, v17, v25
	v_mul_f32_e32 v22, 0xbfb8aa3b, v19
	v_exp_f32_e32 v22, v22
	v_add_f32_e32 v23, 1.0, v27
	v_rcp_f32_e32 v23, v23
	v_mul_f32_e32 v25, v16, v17
	v_add_f32_e32 v22, 1.0, v22
	v_rcp_f32_e32 v22, v22
	v_mul_f32_e32 v16, v21, v23
	v_mul_f32_e32 v20, v20, v16
	v_add_u32_e32 v21, 0xa0, v144
	v_mul_f32_e32 v16, v19, v22
	v_mul_f32_e32 v19, v18, v16
	v_cvt_pk_bf16_f32 v16, v32, v31
	v_cvt_pk_bf16_f32 v17, v28, v26
	v_cvt_pk_bf16_f32 v18, v24, v25
	v_cvt_pk_bf16_f32 v19, v20, v19
	v_fmamk_f32 v20, v190, 0x3a000000, v152
	v_rsq_f32_e32 v20, v20
	v_mov_b32_e32 v24, v8
	v_mov_b32_e32 v25, v12
	v_mad_i64_i32 v[22:23], s[18:19], v21, s38, v[120:121]
	v_pk_mul_f32 v[24:25], v[24:25], v[20:21] op_sel_hi:[1,0]
	v_mov_b32_e32 v12, v9
	v_mul_f32_e32 v8, 0xbfb8aa3b, v25
	v_exp_f32_e32 v21, v8
	s_nop 0
	v_pk_mul_f32 v[8:9], v[12:13], v[20:21] op_sel_hi:[1,0]
	v_add_f32_e32 v21, 1.0, v21
	v_rcp_f32_e32 v21, v21
	v_mul_f32_e32 v12, 0xbfb8aa3b, v9
	v_exp_f32_e32 v26, v12
	v_lshl_add_u64 v[12:13], v[22:23], 0, v[104:105]
	global_store_dwordx4 v[12:13], v[16:19], off sc0 sc1
	v_mul_f32_e32 v12, v25, v21
	v_mov_b32_e32 v13, v14
	v_mul_f32_e32 v16, v24, v12
	v_mov_b32_e32 v12, v10
	v_pk_mul_f32 v[12:13], v[12:13], v[20:21] op_sel_hi:[1,0]
	v_add_f32_e32 v22, 1.0, v26
	v_mul_f32_e32 v10, 0xbfb8aa3b, v13
	v_mov_b32_e32 v14, v11
	v_rcp_f32_e32 v22, v22
	v_exp_f32_e32 v17, v10
	v_pk_mul_f32 v[10:11], v[14:15], v[20:21] op_sel_hi:[1,0]
	v_mul_f32_e32 v9, v9, v22
	v_mul_f32_e32 v14, 0xbfb8aa3b, v11
	v_exp_f32_e32 v14, v14
	v_mul_f32_e32 v15, v8, v9
	v_add_f32_e32 v8, 1.0, v17
	v_rcp_f32_e32 v17, v8
	v_add_f32_e32 v8, 1.0, v14
	v_rcp_f32_e32 v14, v8
	v_mov_b32_e32 v8, v0
	v_mov_b32_e32 v9, v4
	v_pk_mul_f32 v[8:9], v[8:9], v[20:21] op_sel_hi:[1,0]
	v_mul_f32_e32 v4, v13, v17
	v_mul_f32_e32 v0, 0xbfb8aa3b, v9
	v_exp_f32_e32 v0, v0
	v_mul_f32_e32 v12, v12, v4
	v_mov_b32_e32 v4, v1
	v_mul_f32_e32 v11, v11, v14
	v_add_f32_e32 v0, 1.0, v0
	v_rcp_f32_e32 v13, v0
	v_pk_mul_f32 v[0:1], v[4:5], v[20:21] op_sel_hi:[1,0]
	v_mul_f32_e32 v10, v10, v11
	v_mul_f32_e32 v4, 0xbfb8aa3b, v1
	v_exp_f32_e32 v4, v4
	v_mul_f32_e32 v5, v9, v13
	v_mul_f32_e32 v8, v8, v5
	v_mov_b32_e32 v5, v6
	v_add_f32_e32 v4, 1.0, v4
	v_rcp_f32_e32 v9, v4
	v_mov_b32_e32 v4, v2
	v_pk_mul_f32 v[4:5], v[4:5], v[20:21] op_sel_hi:[1,0]
	v_mov_b32_e32 v6, v3
	v_mul_f32_e32 v2, 0xbfb8aa3b, v5
	v_exp_f32_e32 v11, v2
	v_pk_mul_f32 v[2:3], v[6:7], v[20:21] op_sel_hi:[1,0]
	v_mul_f32_e32 v1, v1, v9
	v_mul_f32_e32 v6, 0xbfb8aa3b, v3
	v_exp_f32_e32 v6, v6
	v_add_f32_e32 v7, 1.0, v11
	v_rcp_f32_e32 v7, v7
	v_mul_f32_e32 v9, v0, v1
	v_add_f32_e32 v6, 1.0, v6
	v_rcp_f32_e32 v6, v6
	v_mul_f32_e32 v0, v5, v7
	v_mul_f32_e32 v4, v4, v0
	v_add_u32_e32 v5, 0xb0, v144
	v_mul_f32_e32 v0, v3, v6
	v_mul_f32_e32 v3, v2, v0
	v_cvt_pk_bf16_f32 v0, v16, v15
	v_cvt_pk_bf16_f32 v1, v12, v10
	v_cvt_pk_bf16_f32 v2, v8, v9
	v_cvt_pk_bf16_f32 v3, v4, v3
	v_mad_i64_i32 v[4:5], s[18:19], v5, s38, v[120:121]
	v_lshl_add_u64 v[4:5], v[4:5], 0, v[104:105]
	s_mov_b64 s[18:19], s[12:13]
	global_store_dwordx4 v[4:5], v[0:3], off sc0 sc1
	s_cbranch_vccz .LBB0_862
	s_waitcnt vmcnt(0)
	s_cmpk_gt_u32 s24, 0xff
	s_cbranch_scc1 .LBB0_869
	s_barrier

; #define PG8_STAGE(bufoff, gbase, voff) do { _Pragma("unroll") for (int _i = 0; _i < 2; ++_i) \
;         __builtin_amdgcn_global_load_lds((const unsigned*)((const char*)(gbase) + (voff)[_i]), (LAS unsigned*)(lds + (bufoff) + ldsw + _i * 8192), 16, 0, 0); } while (0)
; #define PG8_LDA(dst, b, h) do { _Pragma("unroll") for (int m = 0; m < 4; ++m) _Pragma("unroll") for (int k = 0; k < 2; ++k) dst[m][k] = *(const LAS bf16x8*)(lds + PG8_SA(b, h) + aoff + m * 2048 + k * 1024); } while (0)
; #define PG8_LDB(dst, b, h) do { _Pragma("unroll") for (int n = 0; n < 2; ++n) _Pragma("unroll") for (int k = 0; k < 2; ++k) dst[n][k] = *(const LAS bf16x8*)(lds + PG8_SB(b, h) + boff + n * 2048 + k * 1024); } while (0)
; #define PG8_MMA(ai, bj, At, Bt) do { __builtin_amdgcn_s_setprio(1); _Pragma("unroll") for (int m = 0; m < 4; ++m) _Pragma("unroll") for (int n = 0; n < 2; ++n) _Pragma("unroll") for (int k = 0; k < 2; ++k) \
;         acc[ai][bj][m][n] = MmaOp<Epi::I8>::run(Bt[n][k], At[m][k], acc[ai][bj][m][n]); __builtin_amdgcn_s_setprio(0); } while (0)
; #define PG8_WAIT_L(n) asm volatile("s_waitcnt lgkmcnt(" #n ")" ::: "memory")
; #define PG8_BAR __builtin_amdgcn_s_barrier()
; #define PG8_SCHED __builtin_amdgcn_sched_barrier(0)
; template <class Epi, class Sched>
; __device__ __forceinline__ void gemm_phase(LAS unsigned char* lds, const Gemm g, const Sched& S, const Epi& E) {
;     ...
;             PG8_LDB(B0, 0, 0); PG8_SCHED; PG8_LDA(At, 0, 0); PG8_STAGE(PG8_SA(1, 1), a1 + hstepA, voffA);
;             PG8_WAIT_L(8); PG8_BAR; PG8_WAIT_L(0); PG8_MMA(0, 0, At, B0); PG8_BAR; PG8_SCHED;
;             PG8_LDB(B1, 0, 1); PG8_STAGE(PG8_SB(0, 0), b2, voffB);
;             PG8_BAR; PG8_WAIT_L(0); PG8_MMA(0, 1, At, B1); PG8_BAR;
;             PG8_LDA(At, 0, 1); PG8_STAGE(PG8_SA(0, 0), a2, voffA);
;             PG8_BAR; PG8_WAIT_L(0); PG8_MMA(1, 0, At, B0); PG8_BAR; PG8_SCHED;
.LBB0_936:
	ds_read_b128 v[140:143], v149
	ds_read_b128 v[152:155], v149 offset:1024
	ds_read_b128 v[156:159], v149 offset:2048
	ds_read_b128 v[160:163], v149 offset:3072
	s_add_u32 s14, s12, 0xffea8080
	s_addc_u32 s15, s13, -1
	s_cmpk_eq_i32 s45, 0x52
	s_cselect_b32 s17, s5, s15
	s_cselect_b32 s16, s4, s14
	s_cselect_b32 s15, s7, s44
	s_cselect_b32 s14, s6, s43
	v_lshl_add_u64 v[144:145], s[12:13], 0, v[132:133]
	s_add_i32 m0, s22, 0xc000
	ds_read_b128 v[164:167], v150
	ds_read_b128 v[168:171], v150 offset:1024
	ds_read_b128 v[172:175], v150 offset:2048
	ds_read_b128 v[178:181], v150 offset:3072
	ds_read_b128 v[182:185], v150 offset:4096
	ds_read_b128 v[186:189], v150 offset:5120
	ds_read_b128 v[190:193], v150 offset:6144
	ds_read_b128 v[194:197], v150 offset:7168
	global_load_lds_dwordx4 v[144:145], off
	v_lshl_add_u64 v[144:145], s[12:13], 0, v[134:135]
	s_add_i32 m0, s22, 0xe000
	s_nop 0
	global_load_lds_dwordx4 v[144:145], off
	s_waitcnt lgkmcnt(8)
	s_barrier
	s_waitcnt lgkmcnt(0)
	s_setprio 1
	v_mfma_f32_16x16x32_bf16 v[124:127], v[140:143], v[164:167], v[124:127]
	v_mfma_f32_16x16x32_bf16 v[120:123], v[156:159], v[164:167], v[120:123]
	v_mfma_f32_16x16x32_bf16 v[116:119], v[140:143], v[172:175], v[116:119]
	v_mfma_f32_16x16x32_bf16 v[112:115], v[156:159], v[172:175], v[112:115]
	v_mfma_f32_16x16x32_bf16 v[92:95], v[140:143], v[182:185], v[92:95]
	v_mfma_f32_16x16x32_bf16 v[88:91], v[156:159], v[182:185], v[88:91]
	v_mfma_f32_16x16x32_bf16 v[84:87], v[140:143], v[190:193], v[84:87]
	v_mfma_f32_16x16x32_bf16 v[80:83], v[156:159], v[190:193], v[80:83]
	v_mfma_f32_16x16x32_bf16 v[124:127], v[152:155], v[168:171], v[124:127]
	v_mfma_f32_16x16x32_bf16 v[120:123], v[160:163], v[168:171], v[120:123]
	v_mfma_f32_16x16x32_bf16 v[116:119], v[152:155], v[178:181], v[116:119]
	v_mfma_f32_16x16x32_bf16 v[112:115], v[160:163], v[178:181], v[112:115]
	v_mfma_f32_16x16x32_bf16 v[92:95], v[152:155], v[186:189], v[92:95]
	v_mfma_f32_16x16x32_bf16 v[88:91], v[160:163], v[186:189], v[88:91]
	v_mfma_f32_16x16x32_bf16 v[84:87], v[152:155], v[194:197], v[84:87]
	v_mfma_f32_16x16x32_bf16 v[80:83], v[160:163], v[194:197], v[80:83]
	s_setprio 0
	s_barrier
	s_add_i32 s46, s30, s19
	v_lshl_add_u64 v[144:145], s[14:15], 0, v[130:131]
	s_mov_b32 m0, s46
	ds_read_b128 v[198:201], v151
	ds_read_b128 v[202:205], v151 offset:1024
	ds_read_b128 v[206:209], v151 offset:2048
	ds_read_b128 v[210:213], v151 offset:3072
	global_load_lds_dwordx4 v[144:145], off
	v_lshl_add_u64 v[214:215], s[14:15], 0, v[128:129]
	s_add_i32 m0, s46, 0x2000
	s_nop 0
	global_load_lds_dwordx4 v[214:215], off
	s_barrier
	s_waitcnt lgkmcnt(0)
	s_setprio 1
	v_mfma_f32_16x16x32_bf16 v[108:111], v[198:201], v[164:167], v[108:111]
	v_mfma_f32_16x16x32_bf16 v[104:107], v[206:209], v[164:167], v[104:107]
	v_mfma_f32_16x16x32_bf16 v[100:103], v[198:201], v[172:175], v[100:103]
	v_mfma_f32_16x16x32_bf16 v[96:99], v[206:209], v[172:175], v[96:99]
	v_mfma_f32_16x16x32_bf16 v[76:79], v[198:201], v[182:185], v[76:79]
	v_mfma_f32_16x16x32_bf16 v[72:75], v[206:209], v[182:185], v[72:75]
	v_mfma_f32_16x16x32_bf16 v[68:71], v[198:201], v[190:193], v[68:71]
	v_mfma_f32_16x16x32_bf16 v[64:67], v[206:209], v[190:193], v[64:67]
	v_mfma_f32_16x16x32_bf16 v[108:111], v[202:205], v[168:171], v[108:111]
	v_mfma_f32_16x16x32_bf16 v[104:107], v[210:213], v[168:171], v[104:107]
	v_mfma_f32_16x16x32_bf16 v[100:103], v[202:205], v[178:181], v[100:103]
	v_mfma_f32_16x16x32_bf16 v[96:99], v[210:213], v[178:181], v[96:99]
	v_mfma_f32_16x16x32_bf16 v[76:79], v[202:205], v[186:189], v[76:79]
	v_mfma_f32_16x16x32_bf16 v[72:75], v[210:213], v[186:189], v[72:75]
	v_mfma_f32_16x16x32_bf16 v[68:71], v[202:205], v[194:197], v[68:71]
	v_mfma_f32_16x16x32_bf16 v[64:67], v[210:213], v[194:197], v[64:67]
	s_setprio 0
	s_mov_b32 m0, s22
	v_lshl_add_u64 v[216:217], s[16:17], 0, v[130:131]
	s_barrier
	ds_read_b128 v[164:167], v150 offset:16384
	ds_read_b128 v[168:171], v150 offset:17408
	ds_read_b128 v[172:175], v150 offset:18432
	ds_read_b128 v[178:181], v150 offset:19456
	ds_read_b128 v[182:185], v150 offset:20480
	ds_read_b128 v[186:189], v150 offset:21504
	ds_read_b128 v[190:193], v150 offset:22528
	ds_read_b128 v[194:197], v150 offset:23552
	global_load_lds_dwordx4 v[216:217], off
	v_lshl_add_u64 v[218:219], s[16:17], 0, v[128:129]
	s_mov_b32 m0, s23
	s_nop 0
	global_load_lds_dwordx4 v[218:219], off
	s_barrier
	s_waitcnt lgkmcnt(0)
	s_setprio 1
	v_mfma_f32_16x16x32_bf16 v[60:63], v[140:143], v[164:167], v[60:63]
	v_mfma_f32_16x16x32_bf16 v[56:59], v[156:159], v[164:167], v[56:59]
	v_mfma_f32_16x16x32_bf16 v[52:55], v[140:143], v[172:175], v[52:55]
	v_mfma_f32_16x16x32_bf16 v[48:51], v[156:159], v[172:175], v[48:51]
	v_mfma_f32_16x16x32_bf16 v[28:31], v[140:143], v[182:185], v[28:31]
	v_mfma_f32_16x16x32_bf16 v[24:27], v[156:159], v[182:185], v[24:27]
	v_mfma_f32_16x16x32_bf16 v[20:23], v[140:143], v[190:193], v[20:23]
	v_mfma_f32_16x16x32_bf16 v[16:19], v[156:159], v[190:193], v[16:19]
	v_mfma_f32_16x16x32_bf16 v[60:63], v[152:155], v[168:171], v[60:63]
	v_mfma_f32_16x16x32_bf16 v[56:59], v[160:163], v[168:171], v[56:59]
	v_mfma_f32_16x16x32_bf16 v[52:55], v[152:155], v[178:181], v[52:55]
	v_mfma_f32_16x16x32_bf16 v[48:51], v[160:163], v[178:181], v[48:51]
	v_mfma_f32_16x16x32_bf16 v[28:31], v[152:155], v[186:189], v[28:31]
	v_mfma_f32_16x16x32_bf16 v[24:27], v[160:163], v[186:189], v[24:27]
	v_mfma_f32_16x16x32_bf16 v[20:23], v[152:155], v[194:197], v[20:23]
	v_mfma_f32_16x16x32_bf16 v[16:19], v[160:163], v[194:197], v[16:19]
	s_setprio 0
	s_barrier
; #define PG8_STAGE(bufoff, gbase, voff) do { _Pragma("unroll") for (int _i = 0; _i < 2; ++_i) \
;         __builtin_amdgcn_global_load_lds((const unsigned*)((const char*)(gbase) + (voff)[_i]), (LAS unsigned*)(lds + (bufoff) + ldsw + _i * 8192), 16, 0, 0); } while (0)
; #define PG8_LDA(dst, b, h) do { _Pragma("unroll") for (int m = 0; m < 4; ++m) _Pragma("unroll") for (int k = 0; k < 2; ++k) dst[m][k] = *(const LAS bf16x8*)(lds + PG8_SA(b, h) + aoff + m * 2048 + k * 1024); } while (0)
; #define PG8_LDB(dst, b, h) do { _Pragma("unroll") for (int n = 0; n < 2; ++n) _Pragma("unroll") for (int k = 0; k < 2; ++k) dst[n][k] = *(const LAS bf16x8*)(lds + PG8_SB(b, h) + boff + n * 2048 + k * 1024); } while (0)
; #define PG8_MMA(ai, bj, At, Bt) do { __builtin_amdgcn_s_setprio(1); _Pragma("unroll") for (int m = 0; m < 4; ++m) _Pragma("unroll") for (int n = 0; n < 2; ++n) _Pragma("unroll") for (int k = 0; k < 2; ++k) \
;         acc[ai][bj][m][n] = MmaOp<Epi::I8>::run(Bt[n][k], At[m][k], acc[ai][bj][m][n]); __builtin_amdgcn_s_setprio(0); } while (0)
; #define PG8_WAIT_V(n) asm volatile("s_waitcnt vmcnt(" #n ")" ::: "memory")
; #define PG8_WAIT_L(n) asm volatile("s_waitcnt lgkmcnt(" #n ")" ::: "memory")
; #define PG8_BAR __builtin_amdgcn_s_barrier()
; #define PG8_SCHED __builtin_amdgcn_sched_barrier(0)
; template <class Epi, class Sched>
; __device__ __forceinline__ void gemm_phase(LAS unsigned char* lds, const Gemm g, const Sched& S, const Epi& E) {
;     ...
;             PG8_STAGE(PG8_SB(0, 1), b2 + hstepB, voffB);
;             PG8_WAIT_V(6); PG8_BAR; PG8_MMA(1, 1, At, B1); PG8_BAR;
;             PG8_LDB(B0, 1, 0); PG8_SCHED; PG8_LDA(At, 1, 0); PG8_STAGE(PG8_SA(0, 1), a2 + hstepA, voffA);
;             PG8_WAIT_L(8); PG8_BAR; PG8_WAIT_L(0); PG8_MMA(0, 0, At, B0); PG8_BAR; PG8_SCHED;
;             PG8_LDB(B1, 1, 1); PG8_STAGE(PG8_SB(1, 0), b3, voffB);
;             PG8_BAR; PG8_WAIT_L(0); PG8_MMA(0, 1, At, B1); PG8_BAR;
;             PG8_LDA(At, 1, 1); PG8_STAGE(PG8_SA(1, 0), a3, voffA);
	s_add_u32 s46, s14, 0x158000
	s_addc_u32 s47, s15, 0
	s_add_i32 s48, s31, s19
	v_lshl_add_u64 v[140:141], s[46:47], 0, v[130:131]
	s_mov_b32 m0, s48
	s_nop 0
	global_load_lds_dwordx4 v[140:141], off
	v_lshl_add_u64 v[140:141], s[46:47], 0, v[128:129]
	s_add_i32 m0, s48, 0x2000
	s_nop 0
	global_load_lds_dwordx4 v[140:141], off
	s_waitcnt vmcnt(6)
	s_barrier
	s_setprio 1
	v_mfma_f32_16x16x32_bf16 v[44:47], v[198:201], v[164:167], v[44:47]
	v_mfma_f32_16x16x32_bf16 v[40:43], v[206:209], v[164:167], v[40:43]
	v_mfma_f32_16x16x32_bf16 v[36:39], v[198:201], v[172:175], v[36:39]
	v_mfma_f32_16x16x32_bf16 v[32:35], v[206:209], v[172:175], v[32:35]
	v_mfma_f32_16x16x32_bf16 v[12:15], v[198:201], v[182:185], v[12:15]
	v_mfma_f32_16x16x32_bf16 v[8:11], v[206:209], v[182:185], v[8:11]
	v_mfma_f32_16x16x32_bf16 v[4:7], v[198:201], v[190:193], v[4:7]
	v_mfma_f32_16x16x32_bf16 v[0:3], v[206:209], v[190:193], v[0:3]
	v_mfma_f32_16x16x32_bf16 v[44:47], v[202:205], v[168:171], v[44:47]
	v_mfma_f32_16x16x32_bf16 v[40:43], v[210:213], v[168:171], v[40:43]
	v_mfma_f32_16x16x32_bf16 v[36:39], v[202:205], v[178:181], v[36:39]
	v_mfma_f32_16x16x32_bf16 v[32:35], v[210:213], v[178:181], v[32:35]
	v_mfma_f32_16x16x32_bf16 v[12:15], v[202:205], v[186:189], v[12:15]
	v_mfma_f32_16x16x32_bf16 v[8:11], v[210:213], v[186:189], v[8:11]
	v_mfma_f32_16x16x32_bf16 v[4:7], v[202:205], v[194:197], v[4:7]
	v_mfma_f32_16x16x32_bf16 v[0:3], v[210:213], v[194:197], v[0:3]
	s_setprio 0
	s_add_i32 s46, 0, 0x18000
	v_add_u32_e32 v160, s46, v147
	s_barrier
	ds_read_b128 v[140:143], v160
	ds_read_b128 v[152:155], v160 offset:1024
	ds_read_b128 v[156:159], v160 offset:2048
	ds_read_b128 v[160:163], v160 offset:3072
	s_add_u32 s16, s16, 0x158000
	s_addc_u32 s17, s17, 0
	s_mov_b32 m0, s24
	v_lshl_add_u64 v[198:199], s[16:17], 0, v[130:131]
	ds_read_b128 v[164:167], v150 offset:32768
	ds_read_b128 v[168:171], v150 offset:33792
	ds_read_b128 v[172:175], v150 offset:34816
	ds_read_b128 v[178:181], v150 offset:35840
	ds_read_b128 v[182:185], v150 offset:36864
	ds_read_b128 v[186:189], v150 offset:37888
	ds_read_b128 v[190:193], v150 offset:38912
	ds_read_b128 v[194:197], v150 offset:39936
	global_load_lds_dwordx4 v[198:199], off
	v_lshl_add_u64 v[198:199], s[16:17], 0, v[128:129]
	s_mov_b32 m0, s25
	s_nop 0
	global_load_lds_dwordx4 v[198:199], off
	s_waitcnt lgkmcnt(8)
	s_barrier
	s_waitcnt lgkmcnt(0)
	s_setprio 1
	v_mfma_f32_16x16x32_bf16 v[124:127], v[140:143], v[164:167], v[124:127]
	v_mfma_f32_16x16x32_bf16 v[120:123], v[156:159], v[164:167], v[120:123]
	v_mfma_f32_16x16x32_bf16 v[116:119], v[140:143], v[172:175], v[116:119]
	v_mfma_f32_16x16x32_bf16 v[112:115], v[156:159], v[172:175], v[112:115]
	v_mfma_f32_16x16x32_bf16 v[92:95], v[140:143], v[182:185], v[92:95]
	v_mfma_f32_16x16x32_bf16 v[88:91], v[156:159], v[182:185], v[88:91]
	v_mfma_f32_16x16x32_bf16 v[84:87], v[140:143], v[190:193], v[84:87]
	v_mfma_f32_16x16x32_bf16 v[80:83], v[156:159], v[190:193], v[80:83]
	v_mfma_f32_16x16x32_bf16 v[124:127], v[152:155], v[168:171], v[124:127]
	v_mfma_f32_16x16x32_bf16 v[120:123], v[160:163], v[168:171], v[120:123]
	v_mfma_f32_16x16x32_bf16 v[116:119], v[152:155], v[178:181], v[116:119]
	v_mfma_f32_16x16x32_bf16 v[112:115], v[160:163], v[178:181], v[112:115]
	v_mfma_f32_16x16x32_bf16 v[92:95], v[152:155], v[186:189], v[92:95]
	v_mfma_f32_16x16x32_bf16 v[88:91], v[160:163], v[186:189], v[88:91]
	v_mfma_f32_16x16x32_bf16 v[84:87], v[152:155], v[194:197], v[84:87]
	v_mfma_f32_16x16x32_bf16 v[80:83], v[160:163], v[194:197], v[80:83]
	s_setprio 0
	s_barrier
	s_add_i32 s16, 0, 0x1c000
	s_add_i32 s17, s46, s19
	v_add_u32_e32 v177, s16, v147
	v_lshl_add_u64 v[144:145], v[144:145], 0, s[8:9]
	s_mov_b32 m0, s17
	ds_read_b128 v[198:201], v177
	ds_read_b128 v[202:205], v177 offset:1024
	ds_read_b128 v[206:209], v177 offset:2048
	ds_read_b128 v[210:213], v177 offset:3072
	global_load_lds_dwordx4 v[144:145], off
	v_lshl_add_u64 v[144:145], v[214:215], 0, s[8:9]
	s_add_i32 m0, s17, 0x2000
	s_nop 0
	global_load_lds_dwordx4 v[144:145], off
	s_barrier
	s_waitcnt lgkmcnt(0)
	s_setprio 1
	v_mfma_f32_16x16x32_bf16 v[108:111], v[198:201], v[164:167], v[108:111]
	v_mfma_f32_16x16x32_bf16 v[104:107], v[206:209], v[164:167], v[104:107]
	v_mfma_f32_16x16x32_bf16 v[100:103], v[198:201], v[172:175], v[100:103]
	v_mfma_f32_16x16x32_bf16 v[96:99], v[206:209], v[172:175], v[96:99]
	v_mfma_f32_16x16x32_bf16 v[76:79], v[198:201], v[182:185], v[76:79]
	v_mfma_f32_16x16x32_bf16 v[72:75], v[206:209], v[182:185], v[72:75]
	v_mfma_f32_16x16x32_bf16 v[68:71], v[198:201], v[190:193], v[68:71]
	v_mfma_f32_16x16x32_bf16 v[64:67], v[206:209], v[190:193], v[64:67]
	v_mfma_f32_16x16x32_bf16 v[108:111], v[202:205], v[168:171], v[108:111]
	v_mfma_f32_16x16x32_bf16 v[104:107], v[210:213], v[168:171], v[104:107]
	v_mfma_f32_16x16x32_bf16 v[100:103], v[202:205], v[178:181], v[100:103]
	v_mfma_f32_16x16x32_bf16 v[96:99], v[210:213], v[178:181], v[96:99]
	v_mfma_f32_16x16x32_bf16 v[76:79], v[202:205], v[186:189], v[76:79]
	v_mfma_f32_16x16x32_bf16 v[72:75], v[210:213], v[186:189], v[72:75]
	v_mfma_f32_16x16x32_bf16 v[68:71], v[202:205], v[194:197], v[68:71]
	v_mfma_f32_16x16x32_bf16 v[64:67], v[210:213], v[194:197], v[64:67]
	s_setprio 0
	s_mov_b32 m0, s27
	v_lshl_add_u64 v[144:145], v[216:217], 0, s[8:9]
	s_barrier
	ds_read_b128 v[164:167], v150 offset:49152
	ds_read_b128 v[168:171], v150 offset:50176
	ds_read_b128 v[172:175], v150 offset:51200
	ds_read_b128 v[178:181], v150 offset:52224
	ds_read_b128 v[182:185], v150 offset:53248
	ds_read_b128 v[186:189], v150 offset:54272
	ds_read_b128 v[190:193], v150 offset:55296
	ds_read_b128 v[194:197], v150 offset:56320
	global_load_lds_dwordx4 v[144:145], off
	v_lshl_add_u64 v[144:145], v[218:219], 0, s[8:9]
	s_mov_b32 m0, s28
	s_nop 0
	global_load_lds_dwordx4 v[144:145], off
	s_barrier
; #define PG8_STAGE(bufoff, gbase, voff) do { _Pragma("unroll") for (int _i = 0; _i < 2; ++_i) \
;         __builtin_amdgcn_global_load_lds((const unsigned*)((const char*)(gbase) + (voff)[_i]), (LAS unsigned*)(lds + (bufoff) + ldsw + _i * 8192), 16, 0, 0); } while (0)
; #define PG8_MMA(ai, bj, At, Bt) do { __builtin_amdgcn_s_setprio(1); _Pragma("unroll") for (int m = 0; m < 4; ++m) _Pragma("unroll") for (int n = 0; n < 2; ++n) _Pragma("unroll") for (int k = 0; k < 2; ++k) \
;         acc[ai][bj][m][n] = MmaOp<Epi::I8>::run(Bt[n][k], At[m][k], acc[ai][bj][m][n]); __builtin_amdgcn_s_setprio(0); } while (0)
; #define PG8_WAIT_V(n) asm volatile("s_waitcnt vmcnt(" #n ")" ::: "memory")
;     __device__ __forceinline__ void operator()(const f32x4 (&acc)[2][2][4][2], const Unit& u, int wr, int wc, int fr, int fq) const {
;         const int row0 = u.pm * BM + wr * 64 + fr, col0 = u.pn * BM + wc * 32 + 4 * fq;
;         const float* base = ((u.pm < MP / BM) ? base_lo : base_hi - (size_t)MP * DM) + (size_t)row0 * DM + col0;
;         f32x4 b[2][2], nb[2][2];
; #pragma unroll
;         for (int bj = 0; bj < 2; ++bj)
; #pragma unroll
;             for (int n = 0; n < 2; ++n) b[bj][n] = *(const f32x4*)(base + bj * HALF + n * 16);
; #pragma unroll
;         for (int g = 0; g < 8; ++g) {
;             const int ai = g >> 2, m = g & 3;
;             const int r = row0 + ai * HALF + m * 16; const size_t off = (size_t)r * DM + col0; float s = 0.f;
;             if (g < 7) { const float* nrow = base + (size_t)(((g + 1) >> 2) * HALF + ((g + 1) & 3) * 16) * DM;
; #pragma unroll
;                 for (int bj = 0; bj < 2; ++bj)
; #pragma unroll
;                     for (int n = 0; n < 2; ++n) nb[bj][n] = *(const f32x4*)(nrow + bj * HALF + n * 16); }
; #pragma unroll
;             for (int bj = 0; bj < 2; ++bj)
; #pragma unroll
;                 for (int n = 0; n < 2; ++n) {
;                     const f32x4 o = b[bj][n] + acc[ai][bj][m][n] * alpha;
;                     *(f32x4*)(out + off + bj * HALF + n * 16) = o;
; template <class Epi, class Sched>
; __device__ __forceinline__ void gemm_phase(LAS unsigned char* lds, const Gemm g, const Sched& S, const Epi& E) {
;     ...
;             PG8_BAR; PG8_WAIT_L(0); PG8_MMA(1, 0, At, B0); PG8_BAR; PG8_SCHED;
;             PG8_STAGE(PG8_SB(1, 1), b3 + hstepB, voffB);
;             PG8_WAIT_V(6); PG8_BAR; PG8_MMA(1, 1, At, B1); PG8_BAR;
	s_waitcnt lgkmcnt(0)
	s_setprio 1
	v_mfma_f32_16x16x32_bf16 v[60:63], v[140:143], v[164:167], v[60:63]
	v_mfma_f32_16x16x32_bf16 v[56:59], v[156:159], v[164:167], v[56:59]
	v_mfma_f32_16x16x32_bf16 v[52:55], v[140:143], v[172:175], v[52:55]
	v_mfma_f32_16x16x32_bf16 v[48:51], v[156:159], v[172:175], v[48:51]
	v_mfma_f32_16x16x32_bf16 v[28:31], v[140:143], v[182:185], v[28:31]
	v_mfma_f32_16x16x32_bf16 v[24:27], v[156:159], v[182:185], v[24:27]
	v_mfma_f32_16x16x32_bf16 v[20:23], v[140:143], v[190:193], v[20:23]
	v_mfma_f32_16x16x32_bf16 v[16:19], v[156:159], v[190:193], v[16:19]
	v_mfma_f32_16x16x32_bf16 v[60:63], v[152:155], v[168:171], v[60:63]
	v_mfma_f32_16x16x32_bf16 v[56:59], v[160:163], v[168:171], v[56:59]
	v_mfma_f32_16x16x32_bf16 v[52:55], v[152:155], v[178:181], v[52:55]
	v_mfma_f32_16x16x32_bf16 v[48:51], v[160:163], v[178:181], v[48:51]
	v_mfma_f32_16x16x32_bf16 v[28:31], v[152:155], v[186:189], v[28:31]
	v_mfma_f32_16x16x32_bf16 v[24:27], v[160:163], v[186:189], v[24:27]
	v_mfma_f32_16x16x32_bf16 v[20:23], v[152:155], v[194:197], v[20:23]
	v_mfma_f32_16x16x32_bf16 v[16:19], v[160:163], v[194:197], v[16:19]
	s_setprio 0
	s_barrier
	s_add_u32 s14, s14, 0x158080
	s_addc_u32 s15, s15, 0
	s_add_i32 s16, s16, s19
	v_lshl_add_u64 v[140:141], s[14:15], 0, v[130:131]
	s_mov_b32 m0, s16
	s_nop 0
	global_load_lds_dwordx4 v[140:141], off
	v_lshl_add_u64 v[140:141], s[14:15], 0, v[128:129]
	s_add_i32 m0, s16, 0x2000
	s_nop 0
	global_load_lds_dwordx4 v[140:141], off
	s_waitcnt vmcnt(6)
	s_barrier
	s_setprio 1
	v_mfma_f32_16x16x32_bf16 v[44:47], v[198:201], v[164:167], v[44:47]
	v_mfma_f32_16x16x32_bf16 v[40:43], v[206:209], v[164:167], v[40:43]
	v_mfma_f32_16x16x32_bf16 v[36:39], v[198:201], v[172:175], v[36:39]
	v_mfma_f32_16x16x32_bf16 v[32:35], v[206:209], v[172:175], v[32:35]
	v_mfma_f32_16x16x32_bf16 v[12:15], v[198:201], v[182:185], v[12:15]
	v_mfma_f32_16x16x32_bf16 v[8:11], v[206:209], v[182:185], v[8:11]
	v_mfma_f32_16x16x32_bf16 v[4:7], v[198:201], v[190:193], v[4:7]
	v_mfma_f32_16x16x32_bf16 v[0:3], v[206:209], v[190:193], v[0:3]
	v_mfma_f32_16x16x32_bf16 v[44:47], v[202:205], v[168:171], v[44:47]
	v_mfma_f32_16x16x32_bf16 v[40:43], v[210:213], v[168:171], v[40:43]
	v_mfma_f32_16x16x32_bf16 v[36:39], v[202:205], v[178:181], v[36:39]
	v_mfma_f32_16x16x32_bf16 v[32:35], v[210:213], v[178:181], v[32:35]
	v_mfma_f32_16x16x32_bf16 v[12:15], v[202:205], v[186:189], v[12:15]
	v_mfma_f32_16x16x32_bf16 v[8:11], v[210:213], v[186:189], v[8:11]
	v_mfma_f32_16x16x32_bf16 v[4:7], v[202:205], v[194:197], v[4:7]
	v_mfma_f32_16x16x32_bf16 v[0:3], v[210:213], v[194:197], v[0:3]
	s_setprio 0
	s_add_i32 s45, s45, 2
	s_add_u32 s12, s12, 0x100
	s_addc_u32 s13, s13, 0
	s_add_u32 s43, s43, 0x100
	s_addc_u32 s44, s44, 0
	s_cmpk_gt_u32 s45, 0x53
	s_barrier
	s_cbranch_scc0 .LBB0_936
	v_lshl_add_u32 v140, s41, 8, v146
	v_lshl_or_b32 v142, s42, 8, v148
	v_ashrrev_i32_e32 v141, 31, v140
	v_lshlrev_b64 v[144:145], 13, v[140:141]
	v_ashrrev_i32_e32 v143, 31, v142
	v_lshl_add_u64 v[144:145], s[68:69], 0, v[144:145]
	v_lshlrev_b64 v[142:143], 2, v[142:143]
	v_lshl_add_u64 v[144:145], v[144:145], 0, v[142:143]
	v_mov_b32_e32 v232, 0x20000
	v_mov_b32_e32 v233, 0
	v_lshl_add_u64 v[218:219], v[144:145], 0, v[232:233]
	v_mov_b32_e32 v232, 0x40000
	v_lshl_add_u64 v[220:221], v[144:145], 0, v[232:233]
	v_mov_b32_e32 v232, 0x60000
	v_lshl_add_u64 v[222:223], v[144:145], 0, v[232:233]
	v_mov_b32_e32 v232, 0x100000
	v_lshl_add_u64 v[224:225], v[144:145], 0, v[232:233]
	v_mov_b32_e32 v232, 0x120000
	v_lshl_add_u64 v[226:227], v[144:145], 0, v[232:233]
	v_mov_b32_e32 v232, 0x140000
	v_lshl_add_u64 v[228:229], v[144:145], 0, v[232:233]
	v_mov_b32_e32 v232, 0x160000
	v_lshl_add_u64 v[230:231], v[144:145], 0, v[232:233]
	global_load_dwordx4 v[152:155], v[144:145], off
	global_load_dwordx4 v[156:159], v[144:145], off offset:64
	global_load_dwordx4 v[160:163], v[144:145], off offset:512
	global_load_dwordx4 v[164:167], v[144:145], off offset:576
	global_load_dwordx4 v[168:171], v[218:219], off
	global_load_dwordx4 v[172:175], v[218:219], off offset:64
	global_load_dwordx4 v[178:181], v[218:219], off offset:512
	global_load_dwordx4 v[182:185], v[218:219], off offset:576
	global_load_dwordx4 v[186:189], v[220:221], off
	global_load_dwordx4 v[190:193], v[220:221], off offset:64
	global_load_dwordx4 v[194:197], v[220:221], off offset:512
	global_load_dwordx4 v[198:201], v[220:221], off offset:576
	global_load_dwordx4 v[202:205], v[222:223], off
	global_load_dwordx4 v[206:209], v[222:223], off offset:64
	global_load_dwordx4 v[210:213], v[222:223], off offset:512
	global_load_dwordx4 v[214:217], v[222:223], off offset:576
	s_mov_b32 s42, s39
	s_mov_b32 s41, s40
	s_mov_b64 s[14:15], s[6:7]
	s_mov_b64 s[12:13], s[4:5]
	s_waitcnt vmcnt(12)
	v_pk_fma_f32 v[124:125], v[124:125], 0.5, v[152:153] op_sel_hi:[1,0,1]
	v_pk_fma_f32 v[126:127], v[126:127], 0.5, v[154:155] op_sel_hi:[1,0,1]
	v_pk_fma_f32 v[120:121], v[120:121], 0.5, v[156:157] op_sel_hi:[1,0,1]
	v_pk_fma_f32 v[122:123], v[122:123], 0.5, v[158:159] op_sel_hi:[1,0,1]
	v_pk_fma_f32 v[108:109], v[108:109], 0.5, v[160:161] op_sel_hi:[1,0,1]
	v_pk_fma_f32 v[110:111], v[110:111], 0.5, v[162:163] op_sel_hi:[1,0,1]
	v_pk_fma_f32 v[104:105], v[104:105], 0.5, v[164:165] op_sel_hi:[1,0,1]
	v_pk_fma_f32 v[106:107], v[106:107], 0.5, v[166:167] op_sel_hi:[1,0,1]
	global_store_dwordx4 v[144:145], v[124:127], off sc0 sc1
	global_store_dwordx4 v[144:145], v[120:123], off offset:64 sc0 sc1
	global_store_dwordx4 v[144:145], v[108:111], off offset:512 sc0 sc1
	global_store_dwordx4 v[144:145], v[104:107], off offset:576 sc0 sc1
	global_load_dwordx4 v[152:155], v[224:225], off
	global_load_dwordx4 v[156:159], v[224:225], off offset:64
	global_load_dwordx4 v[160:163], v[224:225], off offset:512
	global_load_dwordx4 v[164:167], v[224:225], off offset:576
	s_waitcnt vmcnt(16)
; __device__ __forceinline__ unsigned cvt_pk_bf16(float lo, float hi) { unsigned r; asm volatile("v_cvt_pk_bf16_f32 %0, %1, %2" : "=v"(r) : "v"(lo), "v"(hi)); return r; }
; #define PG8_WAIT_V(n) asm volatile("s_waitcnt vmcnt(" #n ")" ::: "memory")
; #define PG8_BAR __builtin_amdgcn_s_barrier()
;     __device__ __forceinline__ void operator()(const f32x4 (&acc)[2][2][4][2], const Unit& u, int wr, int wc, int fr, int fq) const {
;     ...
;         for (int g = 0; g < 8; ++g) {
;             const int ai = g >> 2, m = g & 3;
;             const int r = row0 + ai * HALF + m * 16; const size_t off = (size_t)r * DM + col0; float s = 0.f;
;             if (g < 7) { const float* nrow = base + (size_t)(((g + 1) >> 2) * HALF + ((g + 1) & 3) * 16) * DM;
; #pragma unroll
;                 for (int bj = 0; bj < 2; ++bj)
; #pragma unroll
;                     for (int n = 0; n < 2; ++n) nb[bj][n] = *(const f32x4*)(nrow + bj * HALF + n * 16); }
; #pragma unroll
;             for (int bj = 0; bj < 2; ++bj)
; #pragma unroll
;                 for (int n = 0; n < 2; ++n) {
;                     const f32x4 o = b[bj][n] + acc[ai][bj][m][n] * alpha;
;                     *(f32x4*)(out + off + bj * HALF + n * 16) = o;
;                     if (WITH_SSQ) s += (o[0] * o[0] + o[1] * o[1]) + (o[2] * o[2] + o[3] * o[3]);
;                     if (WITH_HB) { u32x2 w; w.x = cvt_pk_bf16(o[0], o[1]); w.y = cvt_pk_bf16(o[2], o[3]); *(u32x2*)(hb + off + bj * HALF + n * 16) = w; }
;                 }
;             if (WITH_SSQ) { s += __shfl_xor(s, 16); s += __shfl_xor(s, 32); if (fq == 0) atomicAdd(ssq + r, s); }
;             asm volatile("" ::: "memory");
; #pragma unroll
;             for (int bj = 0; bj < 2; ++bj)
; #pragma unroll
;                 for (int n = 0; n < 2; ++n) b[bj][n] = nb[bj][n];
;         }
; template <class Epi, class Sched>
; __device__ __forceinline__ void gemm_phase(LAS unsigned char* lds, const Gemm g, const Sched& S, const Epi& E) {
;     ...
;     PG8_WAIT_V(0);
;     if (wr == 0) PG8_BAR;
;     PG8_BAR;
	v_pk_fma_f32 v[116:117], v[116:117], 0.5, v[168:169] op_sel_hi:[1,0,1]
	v_pk_fma_f32 v[118:119], v[118:119], 0.5, v[170:171] op_sel_hi:[1,0,1]
	v_pk_fma_f32 v[112:113], v[112:113], 0.5, v[172:173] op_sel_hi:[1,0,1]
	v_pk_fma_f32 v[114:115], v[114:115], 0.5, v[174:175] op_sel_hi:[1,0,1]
	v_pk_fma_f32 v[100:101], v[100:101], 0.5, v[178:179] op_sel_hi:[1,0,1]
	v_pk_fma_f32 v[102:103], v[102:103], 0.5, v[180:181] op_sel_hi:[1,0,1]
	v_pk_fma_f32 v[96:97], v[96:97], 0.5, v[182:183] op_sel_hi:[1,0,1]
	v_pk_fma_f32 v[98:99], v[98:99], 0.5, v[184:185] op_sel_hi:[1,0,1]
	global_store_dwordx4 v[218:219], v[116:119], off sc0 sc1
	global_store_dwordx4 v[218:219], v[112:115], off offset:64 sc0 sc1
	global_store_dwordx4 v[218:219], v[100:103], off offset:512 sc0 sc1
	global_store_dwordx4 v[218:219], v[96:99], off offset:576 sc0 sc1
	global_load_dwordx4 v[168:171], v[226:227], off
	global_load_dwordx4 v[172:175], v[226:227], off offset:64
	global_load_dwordx4 v[178:181], v[226:227], off offset:512
	global_load_dwordx4 v[182:185], v[226:227], off offset:576
	s_waitcnt vmcnt(20)
	v_pk_fma_f32 v[92:93], v[92:93], 0.5, v[186:187] op_sel_hi:[1,0,1]
	v_pk_fma_f32 v[94:95], v[94:95], 0.5, v[188:189] op_sel_hi:[1,0,1]
	v_pk_fma_f32 v[88:89], v[88:89], 0.5, v[190:191] op_sel_hi:[1,0,1]
	v_pk_fma_f32 v[90:91], v[90:91], 0.5, v[192:193] op_sel_hi:[1,0,1]
	v_pk_fma_f32 v[76:77], v[76:77], 0.5, v[194:195] op_sel_hi:[1,0,1]
	v_pk_fma_f32 v[78:79], v[78:79], 0.5, v[196:197] op_sel_hi:[1,0,1]
	v_pk_fma_f32 v[72:73], v[72:73], 0.5, v[198:199] op_sel_hi:[1,0,1]
	v_pk_fma_f32 v[74:75], v[74:75], 0.5, v[200:201] op_sel_hi:[1,0,1]
	global_store_dwordx4 v[220:221], v[92:95], off sc0 sc1
	global_store_dwordx4 v[220:221], v[88:91], off offset:64 sc0 sc1
	global_store_dwordx4 v[220:221], v[76:79], off offset:512 sc0 sc1
	global_store_dwordx4 v[220:221], v[72:75], off offset:576 sc0 sc1
	global_load_dwordx4 v[186:189], v[228:229], off
	global_load_dwordx4 v[190:193], v[228:229], off offset:64
	global_load_dwordx4 v[194:197], v[228:229], off offset:512
	global_load_dwordx4 v[198:201], v[228:229], off offset:576
	s_waitcnt vmcnt(24)
	v_pk_fma_f32 v[84:85], v[84:85], 0.5, v[202:203] op_sel_hi:[1,0,1]
	v_pk_fma_f32 v[86:87], v[86:87], 0.5, v[204:205] op_sel_hi:[1,0,1]
	v_pk_fma_f32 v[80:81], v[80:81], 0.5, v[206:207] op_sel_hi:[1,0,1]
	v_pk_fma_f32 v[82:83], v[82:83], 0.5, v[208:209] op_sel_hi:[1,0,1]
	v_pk_fma_f32 v[68:69], v[68:69], 0.5, v[210:211] op_sel_hi:[1,0,1]
	v_pk_fma_f32 v[70:71], v[70:71], 0.5, v[212:213] op_sel_hi:[1,0,1]
	v_pk_fma_f32 v[64:65], v[64:65], 0.5, v[214:215] op_sel_hi:[1,0,1]
	v_pk_fma_f32 v[66:67], v[66:67], 0.5, v[216:217] op_sel_hi:[1,0,1]
	global_store_dwordx4 v[222:223], v[84:87], off sc0 sc1
	global_store_dwordx4 v[222:223], v[80:83], off offset:64 sc0 sc1
	global_store_dwordx4 v[222:223], v[68:71], off offset:512 sc0 sc1
	global_store_dwordx4 v[222:223], v[64:67], off offset:576 sc0 sc1
	global_load_dwordx4 v[202:205], v[230:231], off
	global_load_dwordx4 v[206:209], v[230:231], off offset:64
	global_load_dwordx4 v[210:213], v[230:231], off offset:512
	global_load_dwordx4 v[214:217], v[230:231], off offset:576
	s_waitcnt vmcnt(24)
	v_pk_fma_f32 v[60:61], v[60:61], 0.5, v[152:153] op_sel_hi:[1,0,1]
	v_pk_fma_f32 v[62:63], v[62:63], 0.5, v[154:155] op_sel_hi:[1,0,1]
	v_pk_fma_f32 v[56:57], v[56:57], 0.5, v[156:157] op_sel_hi:[1,0,1]
	v_pk_fma_f32 v[58:59], v[58:59], 0.5, v[158:159] op_sel_hi:[1,0,1]
	v_pk_fma_f32 v[44:45], v[44:45], 0.5, v[160:161] op_sel_hi:[1,0,1]
	v_pk_fma_f32 v[46:47], v[46:47], 0.5, v[162:163] op_sel_hi:[1,0,1]
	v_pk_fma_f32 v[40:41], v[40:41], 0.5, v[164:165] op_sel_hi:[1,0,1]
	v_pk_fma_f32 v[42:43], v[42:43], 0.5, v[166:167] op_sel_hi:[1,0,1]
	global_store_dwordx4 v[224:225], v[60:63], off sc0 sc1
	global_store_dwordx4 v[224:225], v[56:59], off offset:64 sc0 sc1
	global_store_dwordx4 v[224:225], v[44:47], off offset:512 sc0 sc1
	global_store_dwordx4 v[224:225], v[40:43], off offset:576 sc0 sc1
	s_waitcnt vmcnt(20)
	v_pk_fma_f32 v[52:53], v[52:53], 0.5, v[168:169] op_sel_hi:[1,0,1]
	v_pk_fma_f32 v[54:55], v[54:55], 0.5, v[170:171] op_sel_hi:[1,0,1]
	v_pk_fma_f32 v[48:49], v[48:49], 0.5, v[172:173] op_sel_hi:[1,0,1]
	v_pk_fma_f32 v[50:51], v[50:51], 0.5, v[174:175] op_sel_hi:[1,0,1]
	v_pk_fma_f32 v[36:37], v[36:37], 0.5, v[178:179] op_sel_hi:[1,0,1]
	v_pk_fma_f32 v[38:39], v[38:39], 0.5, v[180:181] op_sel_hi:[1,0,1]
	v_pk_fma_f32 v[32:33], v[32:33], 0.5, v[182:183] op_sel_hi:[1,0,1]
	v_pk_fma_f32 v[34:35], v[34:35], 0.5, v[184:185] op_sel_hi:[1,0,1]
	global_store_dwordx4 v[226:227], v[52:55], off sc0 sc1
	global_store_dwordx4 v[226:227], v[48:51], off offset:64 sc0 sc1
	global_store_dwordx4 v[226:227], v[36:39], off offset:512 sc0 sc1
	global_store_dwordx4 v[226:227], v[32:35], off offset:576 sc0 sc1
	s_waitcnt vmcnt(16)
	v_pk_fma_f32 v[28:29], v[28:29], 0.5, v[186:187] op_sel_hi:[1,0,1]
	v_pk_fma_f32 v[30:31], v[30:31], 0.5, v[188:189] op_sel_hi:[1,0,1]
	v_pk_fma_f32 v[24:25], v[24:25], 0.5, v[190:191] op_sel_hi:[1,0,1]
	v_pk_fma_f32 v[26:27], v[26:27], 0.5, v[192:193] op_sel_hi:[1,0,1]
	v_pk_fma_f32 v[12:13], v[12:13], 0.5, v[194:195] op_sel_hi:[1,0,1]
	v_pk_fma_f32 v[14:15], v[14:15], 0.5, v[196:197] op_sel_hi:[1,0,1]
	v_pk_fma_f32 v[8:9], v[8:9], 0.5, v[198:199] op_sel_hi:[1,0,1]
	v_pk_fma_f32 v[10:11], v[10:11], 0.5, v[200:201] op_sel_hi:[1,0,1]
	global_store_dwordx4 v[228:229], v[28:31], off sc0 sc1
	global_store_dwordx4 v[228:229], v[24:27], off offset:64 sc0 sc1
	global_store_dwordx4 v[228:229], v[12:15], off offset:512 sc0 sc1
	global_store_dwordx4 v[228:229], v[8:11], off offset:576 sc0 sc1
	s_waitcnt vmcnt(12)
	v_pk_fma_f32 v[20:21], v[20:21], 0.5, v[202:203] op_sel_hi:[1,0,1]
	v_pk_fma_f32 v[22:23], v[22:23], 0.5, v[204:205] op_sel_hi:[1,0,1]
	v_pk_fma_f32 v[16:17], v[16:17], 0.5, v[206:207] op_sel_hi:[1,0,1]
	v_pk_fma_f32 v[18:19], v[18:19], 0.5, v[208:209] op_sel_hi:[1,0,1]
	v_pk_fma_f32 v[4:5], v[4:5], 0.5, v[210:211] op_sel_hi:[1,0,1]
	v_pk_fma_f32 v[6:7], v[6:7], 0.5, v[212:213] op_sel_hi:[1,0,1]
	v_pk_fma_f32 v[0:1], v[0:1], 0.5, v[214:215] op_sel_hi:[1,0,1]
	v_pk_fma_f32 v[2:3], v[2:3], 0.5, v[216:217] op_sel_hi:[1,0,1]
	global_store_dwordx4 v[230:231], v[20:23], off sc0 sc1
	global_store_dwordx4 v[230:231], v[16:19], off offset:64 sc0 sc1
	global_store_dwordx4 v[230:231], v[4:7], off offset:512 sc0 sc1
	global_store_dwordx4 v[230:231], v[0:3], off offset:576 sc0 sc1
	s_and_b64 vcc, exec, s[0:1]
	s_cbranch_vccz .LBB0_929
	s_waitcnt vmcnt(0)
	s_cmpk_gt_u32 s18, 0xff
	s_cbranch_scc1 .LBB0_940
	s_barrier
